# GEMM K-loops: the 84 mid-burst 's_setprio 0; s_setprio 1' pairs removed (priority stays 1 across each 32-MFMA block)
# speedup vs baseline: 1.0075x; 1.0075x over previous
; #define PG8_STAGE(bufoff, gbase, voff) do { _Pragma("unroll") for (int _i = 0; _i < 2; ++_i) \
;         __builtin_amdgcn_global_load_lds((const unsigned*)((const char*)(gbase) + (voff)[_i]), (PG8_LAS unsigned*)(lds + (bufoff) + ldsw + _i * 8192), 16, 0, 0); } while (0)
; #define PG8_LDA(dst, b, h) do { _Pragma("unroll") for (int m = 0; m < 4; ++m) _Pragma("unroll") for (int k = 0; k < 2; ++k) dst[m][k] = *(const PG8_LAS bf16x8*)(lds + PG8_SA(b, h) + aoff + m * 2048 + k * 1024); } while (0)
; #define PG8_LDB(dst, b, h) do { _Pragma("unroll") for (int n = 0; n < 2; ++n) _Pragma("unroll") for (int k = 0; k < 2; ++k) dst[n][k] = *(const PG8_LAS bf16x8*)(lds + PG8_SB(b, h) + boff + n * 2048 + k * 1024); } while (0)
; #define PG8_MMA(ai, bj, At, Bt) do { __builtin_amdgcn_s_setprio(1); _Pragma("unroll") for (int m = 0; m < 4; ++m) _Pragma("unroll") for (int n = 0; n < 2; ++n) _Pragma("unroll") for (int k = 0; k < 2; ++k) \
;         acc[ai][bj][m][n] = __builtin_amdgcn_mfma_f32_16x16x32_bf16(Bt[n][k], At[m][k], acc[ai][bj][m][n], 0, 0, 0); __builtin_amdgcn_s_setprio(0); } while (0)
; #define PG8_WAIT_V(n) asm volatile("s_waitcnt vmcnt(" #n ")" ::: "memory")
; #define PG8_WAIT_L(n) asm volatile("s_waitcnt lgkmcnt(" #n ")" ::: "memory")
; #define PG8_BAR __builtin_amdgcn_s_barrier()
; #define PG8_SCHED __builtin_amdgcn_sched_barrier(0)
; template <class Epi, class Sched, bool ALIGN_EPI = false, bool SP2 = false>
; __device__ __forceinline__ void gemm_phase(PG8_LAS unsigned char* lds, const Gemm g, const Sched& S, const Epi& E) {
;     ...
;             PG8_LDB(B0, 0, 0); PG8_LDB(B1, 0, 1); PG8_SCHED; PG8_LDA(At, 0, 0); PG8_STAGE(PG8_SA(1, 1), a1 + hstepA, voffA);
;             PG8_WAIT_V(8); PG8_WAIT_L(0); PG8_BAR; PG8_MMA(0, 0, At, B0); PG8_MMA(0, 1, At, B1); PG8_BAR; PG8_SCHED;
;             PG8_LDA(At, 0, 1); PG8_STAGE(PG8_SB(0, 0), b2, voffB); PG8_STAGE(PG8_SB(0, 1), b2 + hstepB, voffB); PG8_STAGE(PG8_SA(0, 0), a2, voffA);
;             PG8_WAIT_V(8); PG8_WAIT_L(0); PG8_BAR; PG8_MMA(1, 0, At, B0); PG8_MMA(1, 1, At, B1); PG8_BAR; PG8_SCHED;
.LBB0_318:
	ds_read_b128 v[156:159], v153
	ds_read_b128 v[160:163], v153 offset:1024
	ds_read_b128 v[164:167], v153 offset:2048
	ds_read_b128 v[168:171], v153 offset:3072
	ds_read_b128 v[172:175], v154
	ds_read_b128 v[176:179], v154 offset:1024
	ds_read_b128 v[180:183], v154 offset:2048
	ds_read_b128 v[184:187], v154 offset:3072
	s_add_u32 s8, s6, 0xfffc0080
	s_addc_u32 s9, s7, -1
	s_cmp_eq_u32 s36, 12
	s_cselect_b32 s31, s1, s9
	s_cselect_b32 s30, s5, s8
	s_cselect_b32 s9, s23, s35
	s_cselect_b32 s8, s25, s34
	s_add_i32 m0, s42, 0xc000
	ds_read_b128 v[188:191], v155
	ds_read_b128 v[192:195], v155 offset:1024
	ds_read_b128 v[196:199], v155 offset:2048
	ds_read_b128 v[200:203], v155 offset:3072
	ds_read_b128 v[204:207], v155 offset:4096
	ds_read_b128 v[208:211], v155 offset:5120
	ds_read_b128 v[212:215], v155 offset:6144
	ds_read_b128 v[216:219], v155 offset:7168
	global_load_lds_dwordx4 v140, s[6:7]
	s_add_i32 m0, s42, 0xe000
	s_nop 0
	global_load_lds_dwordx4 v142, s[6:7]
	s_waitcnt vmcnt(8)
	s_waitcnt lgkmcnt(0)
	s_barrier
	s_setprio 1
	s_waitcnt lgkmcnt(0)
	v_mfma_f32_16x16x32_bf16 v[126:129], v[156:159], v[188:191], v[126:129]
	v_mfma_f32_16x16x32_bf16 v[122:125], v[164:167], v[188:191], v[122:125]
	v_mfma_f32_16x16x32_bf16 v[110:113], v[156:159], v[196:199], v[110:113]
	v_mfma_f32_16x16x32_bf16 v[106:109], v[164:167], v[196:199], v[106:109]
	v_mfma_f32_16x16x32_bf16 v[94:97], v[156:159], v[204:207], v[94:97]
	v_mfma_f32_16x16x32_bf16 v[90:93], v[164:167], v[204:207], v[90:93]
	v_mfma_f32_16x16x32_bf16 v[78:81], v[156:159], v[212:215], v[78:81]
	v_mfma_f32_16x16x32_bf16 v[74:77], v[164:167], v[212:215], v[74:77]
	v_mfma_f32_16x16x32_bf16 v[126:129], v[160:163], v[192:195], v[126:129]
	v_mfma_f32_16x16x32_bf16 v[122:125], v[168:171], v[192:195], v[122:125]
	v_mfma_f32_16x16x32_bf16 v[110:113], v[160:163], v[200:203], v[110:113]
	v_mfma_f32_16x16x32_bf16 v[106:109], v[168:171], v[200:203], v[106:109]
	v_mfma_f32_16x16x32_bf16 v[94:97], v[160:163], v[208:211], v[94:97]
	v_mfma_f32_16x16x32_bf16 v[90:93], v[168:171], v[208:211], v[90:93]
	v_mfma_f32_16x16x32_bf16 v[78:81], v[160:163], v[216:219], v[78:81]
	v_mfma_f32_16x16x32_bf16 v[74:77], v[168:171], v[216:219], v[74:77]
	v_mfma_f32_16x16x32_bf16 v[118:121], v[172:175], v[188:191], v[118:121]
	v_mfma_f32_16x16x32_bf16 v[114:117], v[180:183], v[188:191], v[114:117]
	v_mfma_f32_16x16x32_bf16 v[102:105], v[172:175], v[196:199], v[102:105]
	v_mfma_f32_16x16x32_bf16 v[98:101], v[180:183], v[196:199], v[98:101]
	v_mfma_f32_16x16x32_bf16 v[86:89], v[172:175], v[204:207], v[86:89]
	v_mfma_f32_16x16x32_bf16 v[82:85], v[180:183], v[204:207], v[82:85]
	v_mfma_f32_16x16x32_bf16 v[70:73], v[172:175], v[212:215], v[70:73]
	v_mfma_f32_16x16x32_bf16 v[66:69], v[180:183], v[212:215], v[66:69]
	v_mfma_f32_16x16x32_bf16 v[118:121], v[176:179], v[192:195], v[118:121]
	v_mfma_f32_16x16x32_bf16 v[114:117], v[184:187], v[192:195], v[114:117]
	v_mfma_f32_16x16x32_bf16 v[102:105], v[176:179], v[200:203], v[102:105]
	v_mfma_f32_16x16x32_bf16 v[98:101], v[184:187], v[200:203], v[98:101]
	v_mfma_f32_16x16x32_bf16 v[86:89], v[176:179], v[208:211], v[86:89]
	v_mfma_f32_16x16x32_bf16 v[82:85], v[184:187], v[208:211], v[82:85]
	v_mfma_f32_16x16x32_bf16 v[70:73], v[176:179], v[216:219], v[70:73]
	v_mfma_f32_16x16x32_bf16 v[66:69], v[184:187], v[216:219], v[66:69]
	s_setprio 0
	s_barrier
	s_add_i32 s37, s59, s41
	s_add_u32 s98, s8, 0x80
	s_addc_u32 s99, s9, 0
	s_mov_b32 m0, s37
	ds_read_b128 v[188:191], v155 offset:16384
	ds_read_b128 v[192:195], v155 offset:17408
	ds_read_b128 v[196:199], v155 offset:18432
	ds_read_b128 v[200:203], v155 offset:19456
	ds_read_b128 v[204:207], v155 offset:20480
	ds_read_b128 v[208:211], v155 offset:21504
	ds_read_b128 v[212:215], v155 offset:22528
	ds_read_b128 v[216:219], v155 offset:23552
	global_load_lds_dwordx4 v132, s[8:9]
	s_add_i32 m0, s37, 0x2000
	s_add_u32 s72, s8, 0x40000
	s_addc_u32 s73, s9, 0
	s_add_i32 s37, s60, s41
	global_load_lds_dwordx4 v136, s[8:9]
	s_mov_b32 m0, s37
	s_nop 0
	global_load_lds_dwordx4 v132, s[72:73]
	s_add_i32 m0, s37, 0x2000
	s_nop 0
	global_load_lds_dwordx4 v136, s[72:73]
	s_add_u32 s100, s30, 0x80
	s_addc_u32 s101, s31, 0
	s_mov_b32 m0, s42
	s_nop 0
	global_load_lds_dwordx4 v130, s[30:31]
	s_mov_b32 m0, s43
	s_nop 0
	global_load_lds_dwordx4 v134, s[30:31]
	s_waitcnt vmcnt(8)
	s_waitcnt lgkmcnt(0)
	s_barrier
	s_setprio 1
	s_waitcnt lgkmcnt(0)
	v_mfma_f32_16x16x32_bf16 v[62:65], v[156:159], v[188:191], v[62:65]
	v_mfma_f32_16x16x32_bf16 v[58:61], v[164:167], v[188:191], v[58:61]
	v_mfma_f32_16x16x32_bf16 v[46:49], v[156:159], v[196:199], v[46:49]
	v_mfma_f32_16x16x32_bf16 v[42:45], v[164:167], v[196:199], v[42:45]
	v_mfma_f32_16x16x32_bf16 v[30:33], v[156:159], v[204:207], v[30:33]
	v_mfma_f32_16x16x32_bf16 v[26:29], v[164:167], v[204:207], v[26:29]
	v_mfma_f32_16x16x32_bf16 v[14:17], v[156:159], v[212:215], v[14:17]
	v_mfma_f32_16x16x32_bf16 v[10:13], v[164:167], v[212:215], v[10:13]
	v_mfma_f32_16x16x32_bf16 v[62:65], v[160:163], v[192:195], v[62:65]
	v_mfma_f32_16x16x32_bf16 v[58:61], v[168:171], v[192:195], v[58:61]
	v_mfma_f32_16x16x32_bf16 v[46:49], v[160:163], v[200:203], v[46:49]
	v_mfma_f32_16x16x32_bf16 v[42:45], v[168:171], v[200:203], v[42:45]
	v_mfma_f32_16x16x32_bf16 v[30:33], v[160:163], v[208:211], v[30:33]
	v_mfma_f32_16x16x32_bf16 v[26:29], v[168:171], v[208:211], v[26:29]
	v_mfma_f32_16x16x32_bf16 v[14:17], v[160:163], v[216:219], v[14:17]
	v_mfma_f32_16x16x32_bf16 v[10:13], v[168:171], v[216:219], v[10:13]
	v_mfma_f32_16x16x32_bf16 v[54:57], v[172:175], v[188:191], v[54:57]
	v_mfma_f32_16x16x32_bf16 v[50:53], v[180:183], v[188:191], v[50:53]
	v_mfma_f32_16x16x32_bf16 v[38:41], v[172:175], v[196:199], v[38:41]
	v_mfma_f32_16x16x32_bf16 v[34:37], v[180:183], v[196:199], v[34:37]
	v_mfma_f32_16x16x32_bf16 v[22:25], v[172:175], v[204:207], v[22:25]
	v_mfma_f32_16x16x32_bf16 v[18:21], v[180:183], v[204:207], v[18:21]
	v_mfma_f32_16x16x32_bf16 v[6:9], v[172:175], v[212:215], v[6:9]
	v_mfma_f32_16x16x32_bf16 v[2:5], v[180:183], v[212:215], v[2:5]
	v_mfma_f32_16x16x32_bf16 v[54:57], v[176:179], v[192:195], v[54:57]
	v_mfma_f32_16x16x32_bf16 v[50:53], v[184:187], v[192:195], v[50:53]
	v_mfma_f32_16x16x32_bf16 v[38:41], v[176:179], v[200:203], v[38:41]
	v_mfma_f32_16x16x32_bf16 v[34:37], v[184:187], v[200:203], v[34:37]
	v_mfma_f32_16x16x32_bf16 v[22:25], v[176:179], v[208:211], v[22:25]
	v_mfma_f32_16x16x32_bf16 v[18:21], v[184:187], v[208:211], v[18:21]
	v_mfma_f32_16x16x32_bf16 v[6:9], v[176:179], v[216:219], v[6:9]
	v_mfma_f32_16x16x32_bf16 v[2:5], v[184:187], v[216:219], v[2:5]
	s_setprio 0
	s_barrier
; #define PG8_STAGE(bufoff, gbase, voff) do { _Pragma("unroll") for (int _i = 0; _i < 2; ++_i) \
;         __builtin_amdgcn_global_load_lds((const unsigned*)((const char*)(gbase) + (voff)[_i]), (PG8_LAS unsigned*)(lds + (bufoff) + ldsw + _i * 8192), 16, 0, 0); } while (0)
; #define PG8_LDA(dst, b, h) do { _Pragma("unroll") for (int m = 0; m < 4; ++m) _Pragma("unroll") for (int k = 0; k < 2; ++k) dst[m][k] = *(const PG8_LAS bf16x8*)(lds + PG8_SA(b, h) + aoff + m * 2048 + k * 1024); } while (0)
; #define PG8_LDB(dst, b, h) do { _Pragma("unroll") for (int n = 0; n < 2; ++n) _Pragma("unroll") for (int k = 0; k < 2; ++k) dst[n][k] = *(const PG8_LAS bf16x8*)(lds + PG8_SB(b, h) + boff + n * 2048 + k * 1024); } while (0)
; #define PG8_MMA(ai, bj, At, Bt) do { __builtin_amdgcn_s_setprio(1); _Pragma("unroll") for (int m = 0; m < 4; ++m) _Pragma("unroll") for (int n = 0; n < 2; ++n) _Pragma("unroll") for (int k = 0; k < 2; ++k) \
;         acc[ai][bj][m][n] = __builtin_amdgcn_mfma_f32_16x16x32_bf16(Bt[n][k], At[m][k], acc[ai][bj][m][n], 0, 0, 0); __builtin_amdgcn_s_setprio(0); } while (0)
; #define PG8_WAIT_V(n) asm volatile("s_waitcnt vmcnt(" #n ")" ::: "memory")
; #define PG8_WAIT_L(n) asm volatile("s_waitcnt lgkmcnt(" #n ")" ::: "memory")
; #define PG8_BAR __builtin_amdgcn_s_barrier()
; #define PG8_SCHED __builtin_amdgcn_sched_barrier(0)
; template <class Epi, class Sched, bool ALIGN_EPI = false, bool SP2 = false>
; __device__ __forceinline__ void gemm_phase(PG8_LAS unsigned char* lds, const Gemm g, const Sched& S, const Epi& E) {
;     ...
;         for (int t = 0; t < nt; t += 2) {
;     ...
;             PG8_LDB(B0, 1, 0); PG8_LDB(B1, 1, 1); PG8_SCHED; PG8_LDA(At, 1, 0); PG8_STAGE(PG8_SA(0, 1), a2 + hstepA, voffA);
;             PG8_WAIT_V(8); PG8_WAIT_L(0); PG8_BAR; PG8_MMA(0, 0, At, B0); PG8_MMA(0, 1, At, B1); PG8_BAR; PG8_SCHED;
;             PG8_LDA(At, 1, 1); PG8_STAGE(PG8_SB(1, 0), b3, voffB); PG8_STAGE(PG8_SB(1, 1), b3 + hstepB, voffB); PG8_STAGE(PG8_SA(1, 0), a3, voffA);
;             PG8_WAIT_V(8); PG8_WAIT_L(0); PG8_BAR; PG8_MMA(1, 0, At, B0); PG8_MMA(1, 1, At, B1); PG8_BAR; PG8_SCHED;
	s_add_i32 s37, 0, 0x18000
	v_add_u32_e32 v138, s37, v152
	s_add_i32 s71, 0, 0x1c000
	ds_read_b128 v[156:159], v138
	ds_read_b128 v[160:163], v138 offset:1024
	ds_read_b128 v[164:167], v138 offset:2048
	ds_read_b128 v[168:171], v138 offset:3072
	v_add_u32_e32 v138, s71, v152
	ds_read_b128 v[172:175], v138
	ds_read_b128 v[176:179], v138 offset:1024
	ds_read_b128 v[180:183], v138 offset:2048
	ds_read_b128 v[184:187], v138 offset:3072
	s_add_u32 s30, s30, 0x40000
	s_addc_u32 s31, s31, 0
	s_mov_b32 m0, s44
	ds_read_b128 v[188:191], v155 offset:32768
	ds_read_b128 v[192:195], v155 offset:33792
	ds_read_b128 v[196:199], v155 offset:34816
	ds_read_b128 v[200:203], v155 offset:35840
	ds_read_b128 v[204:207], v155 offset:36864
	ds_read_b128 v[208:211], v155 offset:37888
	ds_read_b128 v[212:215], v155 offset:38912
	ds_read_b128 v[216:219], v155 offset:39936
	global_load_lds_dwordx4 v130, s[30:31]
	s_mov_b32 m0, s45
	s_nop 0
	global_load_lds_dwordx4 v134, s[30:31]
	s_waitcnt vmcnt(8)
	s_waitcnt lgkmcnt(0)
	s_barrier
	s_setprio 1
	s_waitcnt lgkmcnt(0)
	v_mfma_f32_16x16x32_bf16 v[126:129], v[156:159], v[188:191], v[126:129]
	v_mfma_f32_16x16x32_bf16 v[122:125], v[164:167], v[188:191], v[122:125]
	v_mfma_f32_16x16x32_bf16 v[110:113], v[156:159], v[196:199], v[110:113]
	v_mfma_f32_16x16x32_bf16 v[106:109], v[164:167], v[196:199], v[106:109]
	v_mfma_f32_16x16x32_bf16 v[94:97], v[156:159], v[204:207], v[94:97]
	v_mfma_f32_16x16x32_bf16 v[90:93], v[164:167], v[204:207], v[90:93]
	v_mfma_f32_16x16x32_bf16 v[78:81], v[156:159], v[212:215], v[78:81]
	v_mfma_f32_16x16x32_bf16 v[74:77], v[164:167], v[212:215], v[74:77]
	v_mfma_f32_16x16x32_bf16 v[126:129], v[160:163], v[192:195], v[126:129]
	v_mfma_f32_16x16x32_bf16 v[122:125], v[168:171], v[192:195], v[122:125]
	v_mfma_f32_16x16x32_bf16 v[110:113], v[160:163], v[200:203], v[110:113]
	v_mfma_f32_16x16x32_bf16 v[106:109], v[168:171], v[200:203], v[106:109]
	v_mfma_f32_16x16x32_bf16 v[94:97], v[160:163], v[208:211], v[94:97]
	v_mfma_f32_16x16x32_bf16 v[90:93], v[168:171], v[208:211], v[90:93]
	v_mfma_f32_16x16x32_bf16 v[78:81], v[160:163], v[216:219], v[78:81]
	v_mfma_f32_16x16x32_bf16 v[74:77], v[168:171], v[216:219], v[74:77]
	v_mfma_f32_16x16x32_bf16 v[118:121], v[172:175], v[188:191], v[118:121]
	v_mfma_f32_16x16x32_bf16 v[114:117], v[180:183], v[188:191], v[114:117]
	v_mfma_f32_16x16x32_bf16 v[102:105], v[172:175], v[196:199], v[102:105]
	v_mfma_f32_16x16x32_bf16 v[98:101], v[180:183], v[196:199], v[98:101]
	v_mfma_f32_16x16x32_bf16 v[86:89], v[172:175], v[204:207], v[86:89]
	v_mfma_f32_16x16x32_bf16 v[82:85], v[180:183], v[204:207], v[82:85]
	v_mfma_f32_16x16x32_bf16 v[70:73], v[172:175], v[212:215], v[70:73]
	v_mfma_f32_16x16x32_bf16 v[66:69], v[180:183], v[212:215], v[66:69]
	v_mfma_f32_16x16x32_bf16 v[118:121], v[176:179], v[192:195], v[118:121]
	v_mfma_f32_16x16x32_bf16 v[114:117], v[184:187], v[192:195], v[114:117]
	v_mfma_f32_16x16x32_bf16 v[102:105], v[176:179], v[200:203], v[102:105]
	v_mfma_f32_16x16x32_bf16 v[98:101], v[184:187], v[200:203], v[98:101]
	v_mfma_f32_16x16x32_bf16 v[86:89], v[176:179], v[208:211], v[86:89]
	v_mfma_f32_16x16x32_bf16 v[82:85], v[184:187], v[208:211], v[82:85]
	v_mfma_f32_16x16x32_bf16 v[70:73], v[176:179], v[216:219], v[70:73]
	v_mfma_f32_16x16x32_bf16 v[66:69], v[184:187], v[216:219], v[66:69]
	s_setprio 0
	s_barrier
	s_add_i32 s30, s37, s41
	s_mov_b32 m0, s30
	ds_read_b128 v[188:191], v155 offset:49152
	ds_read_b128 v[192:195], v155 offset:50176
	ds_read_b128 v[196:199], v155 offset:51200
	ds_read_b128 v[200:203], v155 offset:52224
	ds_read_b128 v[204:207], v155 offset:53248
	ds_read_b128 v[208:211], v155 offset:54272
	ds_read_b128 v[212:215], v155 offset:55296
	ds_read_b128 v[216:219], v155 offset:56320
	global_load_lds_dwordx4 v132, s[98:99]
	s_add_i32 m0, s30, 0x2000
	s_add_u32 s8, s8, 0x40080
	s_addc_u32 s9, s9, 0
	s_add_i32 s30, s71, s41
	global_load_lds_dwordx4 v136, s[98:99]
	s_mov_b32 m0, s30
	s_nop 0
	global_load_lds_dwordx4 v132, s[8:9]
	s_add_i32 m0, s30, 0x2000
	s_nop 0
	global_load_lds_dwordx4 v136, s[8:9]
	s_mov_b32 m0, s54
	s_nop 0
	global_load_lds_dwordx4 v130, s[100:101]
	s_mov_b32 m0, s55
	s_nop 0
	global_load_lds_dwordx4 v134, s[100:101]
	s_waitcnt vmcnt(8)
	s_waitcnt lgkmcnt(0)
	s_barrier
	s_setprio 1
	s_waitcnt lgkmcnt(0)
	v_mfma_f32_16x16x32_bf16 v[62:65], v[156:159], v[188:191], v[62:65]
	v_mfma_f32_16x16x32_bf16 v[58:61], v[164:167], v[188:191], v[58:61]
	v_mfma_f32_16x16x32_bf16 v[46:49], v[156:159], v[196:199], v[46:49]
	v_mfma_f32_16x16x32_bf16 v[42:45], v[164:167], v[196:199], v[42:45]
	v_mfma_f32_16x16x32_bf16 v[30:33], v[156:159], v[204:207], v[30:33]
	v_mfma_f32_16x16x32_bf16 v[26:29], v[164:167], v[204:207], v[26:29]
	v_mfma_f32_16x16x32_bf16 v[14:17], v[156:159], v[212:215], v[14:17]
	v_mfma_f32_16x16x32_bf16 v[10:13], v[164:167], v[212:215], v[10:13]
	v_mfma_f32_16x16x32_bf16 v[62:65], v[160:163], v[192:195], v[62:65]
	v_mfma_f32_16x16x32_bf16 v[58:61], v[168:171], v[192:195], v[58:61]
	v_mfma_f32_16x16x32_bf16 v[46:49], v[160:163], v[200:203], v[46:49]
	v_mfma_f32_16x16x32_bf16 v[42:45], v[168:171], v[200:203], v[42:45]
	v_mfma_f32_16x16x32_bf16 v[30:33], v[160:163], v[208:211], v[30:33]
	v_mfma_f32_16x16x32_bf16 v[26:29], v[168:171], v[208:211], v[26:29]
	v_mfma_f32_16x16x32_bf16 v[14:17], v[160:163], v[216:219], v[14:17]
	v_mfma_f32_16x16x32_bf16 v[10:13], v[168:171], v[216:219], v[10:13]
	v_mfma_f32_16x16x32_bf16 v[54:57], v[172:175], v[188:191], v[54:57]
	v_mfma_f32_16x16x32_bf16 v[50:53], v[180:183], v[188:191], v[50:53]
	v_mfma_f32_16x16x32_bf16 v[38:41], v[172:175], v[196:199], v[38:41]
	v_mfma_f32_16x16x32_bf16 v[34:37], v[180:183], v[196:199], v[34:37]
	v_mfma_f32_16x16x32_bf16 v[22:25], v[172:175], v[204:207], v[22:25]
	v_mfma_f32_16x16x32_bf16 v[18:21], v[180:183], v[204:207], v[18:21]
	v_mfma_f32_16x16x32_bf16 v[6:9], v[172:175], v[212:215], v[6:9]
	v_mfma_f32_16x16x32_bf16 v[2:5], v[180:183], v[212:215], v[2:5]
	v_mfma_f32_16x16x32_bf16 v[54:57], v[176:179], v[192:195], v[54:57]
	v_mfma_f32_16x16x32_bf16 v[50:53], v[184:187], v[192:195], v[50:53]
	v_mfma_f32_16x16x32_bf16 v[38:41], v[176:179], v[200:203], v[38:41]
	v_mfma_f32_16x16x32_bf16 v[34:37], v[184:187], v[200:203], v[34:37]
	v_mfma_f32_16x16x32_bf16 v[22:25], v[176:179], v[208:211], v[22:25]
	v_mfma_f32_16x16x32_bf16 v[18:21], v[184:187], v[208:211], v[18:21]
	v_mfma_f32_16x16x32_bf16 v[6:9], v[176:179], v[216:219], v[6:9]
	v_mfma_f32_16x16x32_bf16 v[2:5], v[184:187], v[216:219], v[2:5]
	s_setprio 0
	s_barrier
	s_add_i32 s36, s36, 2
	s_add_u32 s6, s6, 0x100
	s_addc_u32 s7, s7, 0
	s_add_u32 s34, s34, 0x100
	s_addc_u32 s35, s35, 0
	s_cmp_gt_u32 s36, 13
	s_cbranch_scc0 .LBB0_318
	s_and_b64 vcc, exec, s[18:19]
	s_cbranch_vccz .LBB0_321
	s_barrier

; #define PG8_STAGE(bufoff, gbase, voff) do { _Pragma("unroll") for (int _i = 0; _i < 2; ++_i) \
;         __builtin_amdgcn_global_load_lds((const unsigned*)((const char*)(gbase) + (voff)[_i]), (PG8_LAS unsigned*)(lds + (bufoff) + ldsw + _i * 8192), 16, 0, 0); } while (0)
; #define PG8_LDA(dst, b, h) do { _Pragma("unroll") for (int m = 0; m < 4; ++m) _Pragma("unroll") for (int k = 0; k < 2; ++k) dst[m][k] = *(const PG8_LAS bf16x8*)(lds + PG8_SA(b, h) + aoff + m * 2048 + k * 1024); } while (0)
; #define PG8_LDB(dst, b, h) do { _Pragma("unroll") for (int n = 0; n < 2; ++n) _Pragma("unroll") for (int k = 0; k < 2; ++k) dst[n][k] = *(const PG8_LAS bf16x8*)(lds + PG8_SB(b, h) + boff + n * 2048 + k * 1024); } while (0)
; #define PG8_MMA(ai, bj, At, Bt) do { __builtin_amdgcn_s_setprio(1); _Pragma("unroll") for (int m = 0; m < 4; ++m) _Pragma("unroll") for (int n = 0; n < 2; ++n) _Pragma("unroll") for (int k = 0; k < 2; ++k) \
;         acc[ai][bj][m][n] = __builtin_amdgcn_mfma_f32_16x16x32_bf16(Bt[n][k], At[m][k], acc[ai][bj][m][n], 0, 0, 0); __builtin_amdgcn_s_setprio(0); } while (0)
; #define PG8_WAIT_V(n) asm volatile("s_waitcnt vmcnt(" #n ")" ::: "memory")
; #define PG8_WAIT_L(n) asm volatile("s_waitcnt lgkmcnt(" #n ")" ::: "memory")
; #define PG8_BAR __builtin_amdgcn_s_barrier()
; #define PG8_SCHED __builtin_amdgcn_sched_barrier(0)
; template <class Epi, class Sched, bool ALIGN_EPI = false, bool SP2 = false>
; __device__ __forceinline__ void gemm_phase(PG8_LAS unsigned char* lds, const Gemm g, const Sched& S, const Epi& E) {
;     ...
;             PG8_LDB(B0, 0, 0); PG8_LDB(B1, 0, 1); PG8_SCHED; PG8_LDA(At, 0, 0); PG8_STAGE(PG8_SA(1, 1), a1 + hstepA, voffA);
;             PG8_WAIT_V(8); PG8_WAIT_L(0); PG8_BAR; PG8_MMA(0, 0, At, B0); PG8_MMA(0, 1, At, B1); PG8_BAR; PG8_SCHED;
;             PG8_LDA(At, 0, 1); PG8_STAGE(PG8_SB(0, 0), b2, voffB); PG8_STAGE(PG8_SB(0, 1), b2 + hstepB, voffB); PG8_STAGE(PG8_SA(0, 0), a2, voffA);
;             PG8_WAIT_V(8); PG8_WAIT_L(0); PG8_BAR; PG8_MMA(1, 0, At, B0); PG8_MMA(1, 1, At, B1); PG8_BAR; PG8_SCHED;
.LBB0_780:
	ds_read_b128 v[148:151], v165
	ds_read_b128 v[152:155], v165 offset:1024
	ds_read_b128 v[156:159], v165 offset:2048
	ds_read_b128 v[170:173], v165 offset:3072
	ds_read_b128 v[174:177], v166
	ds_read_b128 v[178:181], v166 offset:1024
	ds_read_b128 v[182:185], v166 offset:2048
	ds_read_b128 v[186:189], v166 offset:3072
	s_add_u32 s0, s6, 0x100
	s_addc_u32 s1, s7, 0
	s_cmp_eq_u32 s66, 2
	s_cselect_b32 s29, s25, s1
	s_cselect_b32 s28, s24, s0
	s_cselect_b32 s9, s27, s65
	s_cselect_b32 s8, s26, s64
	v_lshl_add_u64 v[222:223], s[6:7], 0, v[140:141]
	s_add_i32 m0, s36, 0xc000
	ds_read_b128 v[190:193], v167
	ds_read_b128 v[194:197], v167 offset:1024
	ds_read_b128 v[198:201], v167 offset:2048
	ds_read_b128 v[202:205], v167 offset:3072
	ds_read_b128 v[206:209], v167 offset:4096
	ds_read_b128 v[210:213], v167 offset:5120
	ds_read_b128 v[214:217], v167 offset:6144
	ds_read_b128 v[218:221], v167 offset:7168
	global_load_lds_dwordx4 v[222:223], off
	v_lshl_add_u64 v[222:223], s[6:7], 0, v[142:143]
	s_add_i32 m0, s36, 0xe000
	s_nop 0
	global_load_lds_dwordx4 v[222:223], off
	s_waitcnt vmcnt(8)
	s_waitcnt lgkmcnt(0)
	s_barrier
	s_setprio 1
	s_waitcnt lgkmcnt(0)
	v_mfma_f32_16x16x32_bf16 v[126:129], v[148:151], v[190:193], v[126:129]
	v_mfma_f32_16x16x32_bf16 v[122:125], v[156:159], v[190:193], v[122:125]
	v_mfma_f32_16x16x32_bf16 v[110:113], v[148:151], v[198:201], v[110:113]
	v_mfma_f32_16x16x32_bf16 v[106:109], v[156:159], v[198:201], v[106:109]
	v_mfma_f32_16x16x32_bf16 v[94:97], v[148:151], v[206:209], v[94:97]
	v_mfma_f32_16x16x32_bf16 v[90:93], v[156:159], v[206:209], v[90:93]
	v_mfma_f32_16x16x32_bf16 v[78:81], v[148:151], v[214:217], v[78:81]
	v_mfma_f32_16x16x32_bf16 v[74:77], v[156:159], v[214:217], v[74:77]
	v_mfma_f32_16x16x32_bf16 v[126:129], v[152:155], v[194:197], v[126:129]
	v_mfma_f32_16x16x32_bf16 v[122:125], v[170:173], v[194:197], v[122:125]
	v_mfma_f32_16x16x32_bf16 v[110:113], v[152:155], v[202:205], v[110:113]
	v_mfma_f32_16x16x32_bf16 v[106:109], v[170:173], v[202:205], v[106:109]
	v_mfma_f32_16x16x32_bf16 v[94:97], v[152:155], v[210:213], v[94:97]
	v_mfma_f32_16x16x32_bf16 v[90:93], v[170:173], v[210:213], v[90:93]
	v_mfma_f32_16x16x32_bf16 v[78:81], v[152:155], v[218:221], v[78:81]
	v_mfma_f32_16x16x32_bf16 v[74:77], v[170:173], v[218:221], v[74:77]
	v_mfma_f32_16x16x32_bf16 v[118:121], v[174:177], v[190:193], v[118:121]
	v_mfma_f32_16x16x32_bf16 v[114:117], v[182:185], v[190:193], v[114:117]
	v_mfma_f32_16x16x32_bf16 v[102:105], v[174:177], v[198:201], v[102:105]
	v_mfma_f32_16x16x32_bf16 v[98:101], v[182:185], v[198:201], v[98:101]
	v_mfma_f32_16x16x32_bf16 v[86:89], v[174:177], v[206:209], v[86:89]
	v_mfma_f32_16x16x32_bf16 v[82:85], v[182:185], v[206:209], v[82:85]
	v_mfma_f32_16x16x32_bf16 v[70:73], v[174:177], v[214:217], v[70:73]
	v_mfma_f32_16x16x32_bf16 v[66:69], v[182:185], v[214:217], v[66:69]
	v_mfma_f32_16x16x32_bf16 v[118:121], v[178:181], v[194:197], v[118:121]
	v_mfma_f32_16x16x32_bf16 v[114:117], v[186:189], v[194:197], v[114:117]
	v_mfma_f32_16x16x32_bf16 v[102:105], v[178:181], v[202:205], v[102:105]
	v_mfma_f32_16x16x32_bf16 v[98:101], v[186:189], v[202:205], v[98:101]
	v_mfma_f32_16x16x32_bf16 v[86:89], v[178:181], v[210:213], v[86:89]
	v_mfma_f32_16x16x32_bf16 v[82:85], v[186:189], v[210:213], v[82:85]
	v_mfma_f32_16x16x32_bf16 v[70:73], v[178:181], v[218:221], v[70:73]
	v_mfma_f32_16x16x32_bf16 v[66:69], v[186:189], v[218:221], v[66:69]
	s_setprio 0
	s_barrier
	s_add_i32 s6, s48, s35
	s_add_u32 s98, s8, 0x80
	s_addc_u32 s99, s9, 0
	s_mov_b32 m0, s6
	ds_read_b128 v[190:193], v167 offset:16384
	ds_read_b128 v[194:197], v167 offset:17408
	ds_read_b128 v[198:201], v167 offset:18432
	ds_read_b128 v[202:205], v167 offset:19456
	ds_read_b128 v[206:209], v167 offset:20480
	ds_read_b128 v[210:213], v167 offset:21504
	ds_read_b128 v[214:217], v167 offset:22528
	ds_read_b128 v[218:221], v167 offset:23552
	global_load_lds_dwordx4 v132, s[8:9]
	s_add_i32 m0, s6, 0x2000
	s_add_u32 s6, s8, 0x18000
	s_addc_u32 s7, s9, 0
	s_add_i32 s67, s49, s35
	global_load_lds_dwordx4 v136, s[8:9]
	s_mov_b32 m0, s67
	s_nop 0
	global_load_lds_dwordx4 v132, s[6:7]
	s_add_i32 m0, s67, 0x2000
	s_nop 0
	global_load_lds_dwordx4 v136, s[6:7]
	s_add_u32 s100, s28, 0x80
	s_addc_u32 s101, s29, 0
	s_mov_b32 m0, s36
	s_nop 0
	global_load_lds_dwordx4 v130, s[28:29]
	s_mov_b32 m0, s37
	s_nop 0
	global_load_lds_dwordx4 v134, s[28:29]
	s_waitcnt vmcnt(8)
	s_waitcnt lgkmcnt(0)
	s_barrier
	s_setprio 1
	s_waitcnt lgkmcnt(0)
	v_mfma_f32_16x16x32_bf16 v[62:65], v[148:151], v[190:193], v[62:65]
	v_mfma_f32_16x16x32_bf16 v[58:61], v[156:159], v[190:193], v[58:61]
	v_mfma_f32_16x16x32_bf16 v[46:49], v[148:151], v[198:201], v[46:49]
	v_mfma_f32_16x16x32_bf16 v[42:45], v[156:159], v[198:201], v[42:45]
	v_mfma_f32_16x16x32_bf16 v[30:33], v[148:151], v[206:209], v[30:33]
	v_mfma_f32_16x16x32_bf16 v[26:29], v[156:159], v[206:209], v[26:29]
	v_mfma_f32_16x16x32_bf16 v[14:17], v[148:151], v[214:217], v[14:17]
	v_mfma_f32_16x16x32_bf16 v[10:13], v[156:159], v[214:217], v[10:13]
	v_mfma_f32_16x16x32_bf16 v[62:65], v[152:155], v[194:197], v[62:65]
	v_mfma_f32_16x16x32_bf16 v[58:61], v[170:173], v[194:197], v[58:61]
	v_mfma_f32_16x16x32_bf16 v[46:49], v[152:155], v[202:205], v[46:49]
	v_mfma_f32_16x16x32_bf16 v[42:45], v[170:173], v[202:205], v[42:45]
	v_mfma_f32_16x16x32_bf16 v[30:33], v[152:155], v[210:213], v[30:33]
	v_mfma_f32_16x16x32_bf16 v[26:29], v[170:173], v[210:213], v[26:29]
	v_mfma_f32_16x16x32_bf16 v[14:17], v[152:155], v[218:221], v[14:17]
	v_mfma_f32_16x16x32_bf16 v[10:13], v[170:173], v[218:221], v[10:13]
	v_mfma_f32_16x16x32_bf16 v[54:57], v[174:177], v[190:193], v[54:57]
	v_mfma_f32_16x16x32_bf16 v[50:53], v[182:185], v[190:193], v[50:53]
	v_mfma_f32_16x16x32_bf16 v[38:41], v[174:177], v[198:201], v[38:41]
	v_mfma_f32_16x16x32_bf16 v[34:37], v[182:185], v[198:201], v[34:37]
	v_mfma_f32_16x16x32_bf16 v[22:25], v[174:177], v[206:209], v[22:25]
	v_mfma_f32_16x16x32_bf16 v[18:21], v[182:185], v[206:209], v[18:21]
	v_mfma_f32_16x16x32_bf16 v[6:9], v[174:177], v[214:217], v[6:9]
	v_mfma_f32_16x16x32_bf16 v[2:5], v[182:185], v[214:217], v[2:5]
	v_mfma_f32_16x16x32_bf16 v[54:57], v[178:181], v[194:197], v[54:57]
	v_mfma_f32_16x16x32_bf16 v[50:53], v[186:189], v[194:197], v[50:53]
	v_mfma_f32_16x16x32_bf16 v[38:41], v[178:181], v[202:205], v[38:41]
	v_mfma_f32_16x16x32_bf16 v[34:37], v[186:189], v[202:205], v[34:37]
	v_mfma_f32_16x16x32_bf16 v[22:25], v[178:181], v[210:213], v[22:25]
	v_mfma_f32_16x16x32_bf16 v[18:21], v[186:189], v[210:213], v[18:21]
	v_mfma_f32_16x16x32_bf16 v[6:9], v[178:181], v[218:221], v[6:9]
	v_mfma_f32_16x16x32_bf16 v[2:5], v[186:189], v[218:221], v[2:5]
	s_setprio 0
	s_barrier
; #define PG8_STAGE(bufoff, gbase, voff) do { _Pragma("unroll") for (int _i = 0; _i < 2; ++_i) \
;         __builtin_amdgcn_global_load_lds((const unsigned*)((const char*)(gbase) + (voff)[_i]), (PG8_LAS unsigned*)(lds + (bufoff) + ldsw + _i * 8192), 16, 0, 0); } while (0)
; #define PG8_LDA(dst, b, h) do { _Pragma("unroll") for (int m = 0; m < 4; ++m) _Pragma("unroll") for (int k = 0; k < 2; ++k) dst[m][k] = *(const PG8_LAS bf16x8*)(lds + PG8_SA(b, h) + aoff + m * 2048 + k * 1024); } while (0)
; #define PG8_LDB(dst, b, h) do { _Pragma("unroll") for (int n = 0; n < 2; ++n) _Pragma("unroll") for (int k = 0; k < 2; ++k) dst[n][k] = *(const PG8_LAS bf16x8*)(lds + PG8_SB(b, h) + boff + n * 2048 + k * 1024); } while (0)
; #define PG8_MMA(ai, bj, At, Bt) do { __builtin_amdgcn_s_setprio(1); _Pragma("unroll") for (int m = 0; m < 4; ++m) _Pragma("unroll") for (int n = 0; n < 2; ++n) _Pragma("unroll") for (int k = 0; k < 2; ++k) \
;         acc[ai][bj][m][n] = __builtin_amdgcn_mfma_f32_16x16x32_bf16(Bt[n][k], At[m][k], acc[ai][bj][m][n], 0, 0, 0); __builtin_amdgcn_s_setprio(0); } while (0)
; #define PG8_WAIT_V(n) asm volatile("s_waitcnt vmcnt(" #n ")" ::: "memory")
; #define PG8_WAIT_L(n) asm volatile("s_waitcnt lgkmcnt(" #n ")" ::: "memory")
; #define PG8_BAR __builtin_amdgcn_s_barrier()
; #define PG8_SCHED __builtin_amdgcn_sched_barrier(0)
; template <class Epi, class Sched, bool ALIGN_EPI = false, bool SP2 = false>
; __device__ __forceinline__ void gemm_phase(PG8_LAS unsigned char* lds, const Gemm g, const Sched& S, const Epi& E) {
;     ...
;         for (int t = 0; t < nt; t += 2) {
;     ...
;             PG8_LDB(B0, 1, 0); PG8_LDB(B1, 1, 1); PG8_SCHED; PG8_LDA(At, 1, 0); PG8_STAGE(PG8_SA(0, 1), a2 + hstepA, voffA);
;             PG8_WAIT_V(8); PG8_WAIT_L(0); PG8_BAR; PG8_MMA(0, 0, At, B0); PG8_MMA(0, 1, At, B1); PG8_BAR; PG8_SCHED;
;             PG8_LDA(At, 1, 1); PG8_STAGE(PG8_SB(1, 0), b3, voffB); PG8_STAGE(PG8_SB(1, 1), b3 + hstepB, voffB); PG8_STAGE(PG8_SA(1, 0), a3, voffA);
;             PG8_WAIT_V(8); PG8_WAIT_L(0); PG8_BAR; PG8_MMA(1, 0, At, B0); PG8_MMA(1, 1, At, B1); PG8_BAR; PG8_SCHED;
	s_add_i32 s67, 0, 0x18000
	v_add_u32_e32 v138, s67, v160
	s_add_i32 s68, 0, 0x1c000
	ds_read_b128 v[148:151], v138
	ds_read_b128 v[152:155], v138 offset:1024
	ds_read_b128 v[156:159], v138 offset:2048
	ds_read_b128 v[170:173], v138 offset:3072
	v_add_u32_e32 v138, s68, v160
	ds_read_b128 v[174:177], v138
	ds_read_b128 v[178:181], v138 offset:1024
	ds_read_b128 v[182:185], v138 offset:2048
	ds_read_b128 v[186:189], v138 offset:3072
	s_add_u32 s6, s28, 0x2a000
	s_addc_u32 s7, s29, 0
	s_mov_b32 m0, s38
	ds_read_b128 v[190:193], v167 offset:32768
	ds_read_b128 v[194:197], v167 offset:33792
	ds_read_b128 v[198:201], v167 offset:34816
	ds_read_b128 v[202:205], v167 offset:35840
	ds_read_b128 v[206:209], v167 offset:36864
	ds_read_b128 v[210:213], v167 offset:37888
	ds_read_b128 v[214:217], v167 offset:38912
	ds_read_b128 v[218:221], v167 offset:39936
	global_load_lds_dwordx4 v130, s[6:7]
	s_mov_b32 m0, s39
	s_nop 0
	global_load_lds_dwordx4 v134, s[6:7]
	s_waitcnt vmcnt(8)
	s_waitcnt lgkmcnt(0)
	s_barrier
	s_setprio 1
	s_waitcnt lgkmcnt(0)
	v_mfma_f32_16x16x32_bf16 v[126:129], v[148:151], v[190:193], v[126:129]
	v_mfma_f32_16x16x32_bf16 v[122:125], v[156:159], v[190:193], v[122:125]
	v_mfma_f32_16x16x32_bf16 v[110:113], v[148:151], v[198:201], v[110:113]
	v_mfma_f32_16x16x32_bf16 v[106:109], v[156:159], v[198:201], v[106:109]
	v_mfma_f32_16x16x32_bf16 v[94:97], v[148:151], v[206:209], v[94:97]
	v_mfma_f32_16x16x32_bf16 v[90:93], v[156:159], v[206:209], v[90:93]
	v_mfma_f32_16x16x32_bf16 v[78:81], v[148:151], v[214:217], v[78:81]
	v_mfma_f32_16x16x32_bf16 v[74:77], v[156:159], v[214:217], v[74:77]
	v_mfma_f32_16x16x32_bf16 v[126:129], v[152:155], v[194:197], v[126:129]
	v_mfma_f32_16x16x32_bf16 v[122:125], v[170:173], v[194:197], v[122:125]
	v_mfma_f32_16x16x32_bf16 v[110:113], v[152:155], v[202:205], v[110:113]
	v_mfma_f32_16x16x32_bf16 v[106:109], v[170:173], v[202:205], v[106:109]
	v_mfma_f32_16x16x32_bf16 v[94:97], v[152:155], v[210:213], v[94:97]
	v_mfma_f32_16x16x32_bf16 v[90:93], v[170:173], v[210:213], v[90:93]
	v_mfma_f32_16x16x32_bf16 v[78:81], v[152:155], v[218:221], v[78:81]
	v_mfma_f32_16x16x32_bf16 v[74:77], v[170:173], v[218:221], v[74:77]
	v_mfma_f32_16x16x32_bf16 v[118:121], v[174:177], v[190:193], v[118:121]
	v_mfma_f32_16x16x32_bf16 v[114:117], v[182:185], v[190:193], v[114:117]
	v_mfma_f32_16x16x32_bf16 v[102:105], v[174:177], v[198:201], v[102:105]
	v_mfma_f32_16x16x32_bf16 v[98:101], v[182:185], v[198:201], v[98:101]
	v_mfma_f32_16x16x32_bf16 v[86:89], v[174:177], v[206:209], v[86:89]
	v_mfma_f32_16x16x32_bf16 v[82:85], v[182:185], v[206:209], v[82:85]
	v_mfma_f32_16x16x32_bf16 v[70:73], v[174:177], v[214:217], v[70:73]
	v_mfma_f32_16x16x32_bf16 v[66:69], v[182:185], v[214:217], v[66:69]
	v_mfma_f32_16x16x32_bf16 v[118:121], v[178:181], v[194:197], v[118:121]
	v_mfma_f32_16x16x32_bf16 v[114:117], v[186:189], v[194:197], v[114:117]
	v_mfma_f32_16x16x32_bf16 v[102:105], v[178:181], v[202:205], v[102:105]
	v_mfma_f32_16x16x32_bf16 v[98:101], v[186:189], v[202:205], v[98:101]
	v_mfma_f32_16x16x32_bf16 v[86:89], v[178:181], v[210:213], v[86:89]
	v_mfma_f32_16x16x32_bf16 v[82:85], v[186:189], v[210:213], v[82:85]
	v_mfma_f32_16x16x32_bf16 v[70:73], v[178:181], v[218:221], v[70:73]
	v_mfma_f32_16x16x32_bf16 v[66:69], v[186:189], v[218:221], v[66:69]
	s_setprio 0
	s_barrier
	s_add_i32 s6, s67, s35
	s_mov_b32 m0, s6
	ds_read_b128 v[190:193], v167 offset:49152
	ds_read_b128 v[194:197], v167 offset:50176
	ds_read_b128 v[198:201], v167 offset:51200
	ds_read_b128 v[202:205], v167 offset:52224
	ds_read_b128 v[206:209], v167 offset:53248
	ds_read_b128 v[210:213], v167 offset:54272
	ds_read_b128 v[214:217], v167 offset:55296
	ds_read_b128 v[218:221], v167 offset:56320
	global_load_lds_dwordx4 v132, s[98:99]
	s_add_i32 m0, s6, 0x2000
	s_add_u32 s6, s8, 0x18080
	s_addc_u32 s7, s9, 0
	s_add_i32 s8, s68, s35
	global_load_lds_dwordx4 v136, s[98:99]
	s_mov_b32 m0, s8
	s_nop 0
	global_load_lds_dwordx4 v132, s[6:7]
	s_add_i32 m0, s8, 0x2000
	s_nop 0
	global_load_lds_dwordx4 v136, s[6:7]
	s_mov_b32 m0, s45
	s_nop 0
	global_load_lds_dwordx4 v130, s[100:101]
	s_mov_b32 m0, s46
	s_nop 0
	global_load_lds_dwordx4 v134, s[100:101]
	s_waitcnt vmcnt(8)
	s_waitcnt lgkmcnt(0)
	s_barrier
	s_setprio 1
	s_waitcnt lgkmcnt(0)
	v_mfma_f32_16x16x32_bf16 v[62:65], v[148:151], v[190:193], v[62:65]
	v_mfma_f32_16x16x32_bf16 v[58:61], v[156:159], v[190:193], v[58:61]
	v_mfma_f32_16x16x32_bf16 v[46:49], v[148:151], v[198:201], v[46:49]
	v_mfma_f32_16x16x32_bf16 v[42:45], v[156:159], v[198:201], v[42:45]
	v_mfma_f32_16x16x32_bf16 v[30:33], v[148:151], v[206:209], v[30:33]
	v_mfma_f32_16x16x32_bf16 v[26:29], v[156:159], v[206:209], v[26:29]
	v_mfma_f32_16x16x32_bf16 v[14:17], v[148:151], v[214:217], v[14:17]
	v_mfma_f32_16x16x32_bf16 v[10:13], v[156:159], v[214:217], v[10:13]
	v_mfma_f32_16x16x32_bf16 v[62:65], v[152:155], v[194:197], v[62:65]
	v_mfma_f32_16x16x32_bf16 v[58:61], v[170:173], v[194:197], v[58:61]
	v_mfma_f32_16x16x32_bf16 v[46:49], v[152:155], v[202:205], v[46:49]
	v_mfma_f32_16x16x32_bf16 v[42:45], v[170:173], v[202:205], v[42:45]
	v_mfma_f32_16x16x32_bf16 v[30:33], v[152:155], v[210:213], v[30:33]
	v_mfma_f32_16x16x32_bf16 v[26:29], v[170:173], v[210:213], v[26:29]
	v_mfma_f32_16x16x32_bf16 v[14:17], v[152:155], v[218:221], v[14:17]
	v_mfma_f32_16x16x32_bf16 v[10:13], v[170:173], v[218:221], v[10:13]
	v_mfma_f32_16x16x32_bf16 v[54:57], v[174:177], v[190:193], v[54:57]
	v_mfma_f32_16x16x32_bf16 v[50:53], v[182:185], v[190:193], v[50:53]
	v_mfma_f32_16x16x32_bf16 v[38:41], v[174:177], v[198:201], v[38:41]
	v_mfma_f32_16x16x32_bf16 v[34:37], v[182:185], v[198:201], v[34:37]
	v_mfma_f32_16x16x32_bf16 v[22:25], v[174:177], v[206:209], v[22:25]
	v_mfma_f32_16x16x32_bf16 v[18:21], v[182:185], v[206:209], v[18:21]
	v_mfma_f32_16x16x32_bf16 v[6:9], v[174:177], v[214:217], v[6:9]
	v_mfma_f32_16x16x32_bf16 v[2:5], v[182:185], v[214:217], v[2:5]
	v_mfma_f32_16x16x32_bf16 v[54:57], v[178:181], v[194:197], v[54:57]
	v_mfma_f32_16x16x32_bf16 v[50:53], v[186:189], v[194:197], v[50:53]
	v_mfma_f32_16x16x32_bf16 v[38:41], v[178:181], v[202:205], v[38:41]
	v_mfma_f32_16x16x32_bf16 v[34:37], v[186:189], v[202:205], v[34:37]
	v_mfma_f32_16x16x32_bf16 v[22:25], v[178:181], v[210:213], v[22:25]
	v_mfma_f32_16x16x32_bf16 v[18:21], v[186:189], v[210:213], v[18:21]
	v_mfma_f32_16x16x32_bf16 v[6:9], v[178:181], v[218:221], v[6:9]
	v_mfma_f32_16x16x32_bf16 v[2:5], v[186:189], v[218:221], v[2:5]
	s_setprio 0
	s_barrier
	s_add_i32 s66, s66, 2
	s_add_u32 s64, s64, 0x100
	s_addc_u32 s65, s65, 0
	s_cmp_gt_u32 s66, 3
	s_mov_b64 s[6:7], s[0:1]
	s_cbranch_scc0 .LBB0_780
	s_and_b64 vcc, exec, s[20:21]
	s_cbranch_vccz .LBB0_783
	s_barrier

; #define PG8_STAGE(bufoff, gbase, voff) do { _Pragma("unroll") for (int _i = 0; _i < 2; ++_i) \
;         __builtin_amdgcn_global_load_lds((const unsigned*)((const char*)(gbase) + (voff)[_i]), (PG8_LAS unsigned*)(lds + (bufoff) + ldsw + _i * 8192), 16, 0, 0); } while (0)
; #define PG8_LDA(dst, b, h) do { _Pragma("unroll") for (int m = 0; m < 4; ++m) _Pragma("unroll") for (int k = 0; k < 2; ++k) dst[m][k] = *(const PG8_LAS bf16x8*)(lds + PG8_SA(b, h) + aoff + m * 2048 + k * 1024); } while (0)
; #define PG8_LDB(dst, b, h) do { _Pragma("unroll") for (int n = 0; n < 2; ++n) _Pragma("unroll") for (int k = 0; k < 2; ++k) dst[n][k] = *(const PG8_LAS bf16x8*)(lds + PG8_SB(b, h) + boff + n * 2048 + k * 1024); } while (0)
; #define PG8_MMA(ai, bj, At, Bt) do { __builtin_amdgcn_s_setprio(1); _Pragma("unroll") for (int m = 0; m < 4; ++m) _Pragma("unroll") for (int n = 0; n < 2; ++n) _Pragma("unroll") for (int k = 0; k < 2; ++k) \
;         acc[ai][bj][m][n] = __builtin_amdgcn_mfma_f32_16x16x32_bf16(Bt[n][k], At[m][k], acc[ai][bj][m][n], 0, 0, 0); __builtin_amdgcn_s_setprio(0); } while (0)
; #define PG8_WAIT_V(n) asm volatile("s_waitcnt vmcnt(" #n ")" ::: "memory")
; #define PG8_WAIT_L(n) asm volatile("s_waitcnt lgkmcnt(" #n ")" ::: "memory")
; #define PG8_BAR __builtin_amdgcn_s_barrier()
; #define PG8_SCHED __builtin_amdgcn_sched_barrier(0)
; template <class Epi, class Sched, bool ALIGN_EPI = false, bool SP2 = false>
; __device__ __forceinline__ void gemm_phase(PG8_LAS unsigned char* lds, const Gemm g, const Sched& S, const Epi& E) {
;     ...
;             PG8_LDB(B0, 0, 0); PG8_LDB(B1, 0, 1); PG8_SCHED; PG8_LDA(At, 0, 0); PG8_STAGE(PG8_SA(1, 1), a1 + hstepA, voffA);
;             PG8_WAIT_V(8); PG8_WAIT_L(0); PG8_BAR; PG8_MMA(0, 0, At, B0); PG8_MMA(0, 1, At, B1); PG8_BAR; PG8_SCHED;
;             PG8_LDA(At, 0, 1); PG8_STAGE(PG8_SB(0, 0), b2, voffB); PG8_STAGE(PG8_SB(0, 1), b2 + hstepB, voffB); PG8_STAGE(PG8_SA(0, 0), a2, voffA);
;             PG8_WAIT_V(8); PG8_WAIT_L(0); PG8_BAR; PG8_MMA(1, 0, At, B0); PG8_MMA(1, 1, At, B1); PG8_BAR; PG8_SCHED;
.LBB0_832:
	s_add_u32 s36, s24, s28
	s_addc_u32 s37, s25, s29
	s_add_u32 s34, s36, 0x100
	s_addc_u32 s35, s37, 0
	s_and_b64 s[30:31], s[26:27], exec
	s_cselect_b32 s31, s19, s35
	s_cselect_b32 s30, s18, s34
	s_add_u32 s28, s22, s28
	s_addc_u32 s29, s23, s29
	s_add_u32 s28, s28, 0x100
	s_addc_u32 s29, s29, 0
	s_and_b64 s[26:27], s[26:27], exec
	s_cselect_b32 s35, s5, s29
	s_cselect_b32 s34, s17, s28
	s_add_u32 s38, s36, 0x2a080
	ds_read_b128 v[162:165], v151
	ds_read_b128 v[166:169], v151 offset:1024
	ds_read_b128 v[170:173], v151 offset:2048
	ds_read_b128 v[174:177], v151 offset:3072
	ds_read_b128 v[178:181], v152
	ds_read_b128 v[182:185], v152 offset:1024
	ds_read_b128 v[186:189], v152 offset:2048
	ds_read_b128 v[190:193], v152 offset:3072
	s_addc_u32 s39, s37, 0
	s_add_i32 s73, s55, s45
	s_add_i32 m0, s46, 0xc000
	s_add_i32 s76, s46, 0xe000
	s_add_i32 s70, s73, 0x2000
	s_add_u32 s36, s34, 0x10000
	s_addc_u32 s37, s35, 0
	s_add_i32 s72, s56, s45
	s_add_i32 s71, s72, 0x2000
	s_add_i32 s69, 0, 0x18000
	s_add_i32 s68, 0, 0x1c000
	s_add_u32 s28, s30, 0x2a000
	s_addc_u32 s29, s31, 0
	s_add_i32 s67, s69, s45
	s_add_i32 s66, s67, 0x2000
	s_add_u32 s26, s34, 0x10080
	s_addc_u32 s27, s35, 0
	s_add_i32 s75, s68, s45
	s_add_i32 s74, s75, 0x2000
	v_lshl_add_u64 v[148:149], s[38:39], 0, v[130:131]
	ds_read_b128 v[194:197], v153
	ds_read_b128 v[198:201], v153 offset:1024
	ds_read_b128 v[202:205], v153 offset:2048
	ds_read_b128 v[206:209], v153 offset:3072
	ds_read_b128 v[210:213], v153 offset:4096
	ds_read_b128 v[214:217], v153 offset:5120
	ds_read_b128 v[218:221], v153 offset:6144
	ds_read_b128 v[222:225], v153 offset:7168
	global_load_lds_dwordx4 v[148:149], off
	v_lshl_add_u64 v[148:149], s[38:39], 0, v[134:135]
	s_mov_b32 m0, s76
	s_nop 0
	global_load_lds_dwordx4 v[148:149], off
	s_waitcnt vmcnt(8)
	s_waitcnt lgkmcnt(0)
	s_barrier
	s_setprio 1
	s_waitcnt lgkmcnt(0)
	v_mfma_f32_16x16x32_bf16 v[126:129], v[162:165], v[194:197], v[126:129]
	v_mfma_f32_16x16x32_bf16 v[122:125], v[170:173], v[194:197], v[122:125]
	v_mfma_f32_16x16x32_bf16 v[110:113], v[162:165], v[202:205], v[110:113]
	v_mfma_f32_16x16x32_bf16 v[106:109], v[170:173], v[202:205], v[106:109]
	v_mfma_f32_16x16x32_bf16 v[94:97], v[162:165], v[210:213], v[94:97]
	v_mfma_f32_16x16x32_bf16 v[90:93], v[170:173], v[210:213], v[90:93]
	v_mfma_f32_16x16x32_bf16 v[78:81], v[162:165], v[218:221], v[78:81]
	v_mfma_f32_16x16x32_bf16 v[74:77], v[170:173], v[218:221], v[74:77]
	v_mfma_f32_16x16x32_bf16 v[126:129], v[166:169], v[198:201], v[126:129]
	v_mfma_f32_16x16x32_bf16 v[122:125], v[174:177], v[198:201], v[122:125]
	v_mfma_f32_16x16x32_bf16 v[110:113], v[166:169], v[206:209], v[110:113]
	v_mfma_f32_16x16x32_bf16 v[106:109], v[174:177], v[206:209], v[106:109]
	v_mfma_f32_16x16x32_bf16 v[94:97], v[166:169], v[214:217], v[94:97]
	v_mfma_f32_16x16x32_bf16 v[90:93], v[174:177], v[214:217], v[90:93]
	v_mfma_f32_16x16x32_bf16 v[78:81], v[166:169], v[222:225], v[78:81]
	v_mfma_f32_16x16x32_bf16 v[74:77], v[174:177], v[222:225], v[74:77]
	v_mfma_f32_16x16x32_bf16 v[118:121], v[178:181], v[194:197], v[118:121]
	v_mfma_f32_16x16x32_bf16 v[114:117], v[186:189], v[194:197], v[114:117]
	v_mfma_f32_16x16x32_bf16 v[102:105], v[178:181], v[202:205], v[102:105]
	v_mfma_f32_16x16x32_bf16 v[98:101], v[186:189], v[202:205], v[98:101]
	v_mfma_f32_16x16x32_bf16 v[86:89], v[178:181], v[210:213], v[86:89]
	v_mfma_f32_16x16x32_bf16 v[82:85], v[186:189], v[210:213], v[82:85]
	v_mfma_f32_16x16x32_bf16 v[70:73], v[178:181], v[218:221], v[70:73]
	v_mfma_f32_16x16x32_bf16 v[66:69], v[186:189], v[218:221], v[66:69]
	v_mfma_f32_16x16x32_bf16 v[118:121], v[182:185], v[198:201], v[118:121]
	v_mfma_f32_16x16x32_bf16 v[114:117], v[190:193], v[198:201], v[114:117]
	v_mfma_f32_16x16x32_bf16 v[102:105], v[182:185], v[206:209], v[102:105]
	v_mfma_f32_16x16x32_bf16 v[98:101], v[190:193], v[206:209], v[98:101]
	v_mfma_f32_16x16x32_bf16 v[86:89], v[182:185], v[214:217], v[86:89]
	v_mfma_f32_16x16x32_bf16 v[82:85], v[190:193], v[214:217], v[82:85]
	v_mfma_f32_16x16x32_bf16 v[70:73], v[182:185], v[222:225], v[70:73]
	v_mfma_f32_16x16x32_bf16 v[66:69], v[190:193], v[222:225], v[66:69]
	s_setprio 0
	s_barrier
	s_mov_b32 m0, s73
	v_lshl_add_u64 v[148:149], s[34:35], 0, v[132:133]
	ds_read_b128 v[194:197], v153 offset:16384
	ds_read_b128 v[198:201], v153 offset:17408
	ds_read_b128 v[202:205], v153 offset:18432
	ds_read_b128 v[206:209], v153 offset:19456
	ds_read_b128 v[210:213], v153 offset:20480
	ds_read_b128 v[214:217], v153 offset:21504
	ds_read_b128 v[218:221], v153 offset:22528
	ds_read_b128 v[222:225], v153 offset:23552
	global_load_lds_dwordx4 v[148:149], off
	v_lshl_add_u64 v[226:227], s[34:35], 0, v[136:137]
	s_mov_b32 m0, s70
	v_lshl_add_u64 v[228:229], s[36:37], 0, v[132:133]
	global_load_lds_dwordx4 v[226:227], off
	s_mov_b32 m0, s72
	v_lshl_add_u64 v[230:231], s[30:31], 0, v[134:135]
	global_load_lds_dwordx4 v[228:229], off
	v_lshl_add_u64 v[228:229], s[36:37], 0, v[136:137]
	s_mov_b32 m0, s71
	s_nop 0
	global_load_lds_dwordx4 v[228:229], off
	v_lshl_add_u64 v[228:229], s[30:31], 0, v[130:131]
	s_mov_b32 m0, s46
	s_nop 0
	global_load_lds_dwordx4 v[228:229], off
	s_mov_b32 m0, s47
	s_nop 0
	global_load_lds_dwordx4 v[230:231], off
	s_waitcnt vmcnt(8)
	s_waitcnt lgkmcnt(0)
	s_barrier
; #define PG8_STAGE(bufoff, gbase, voff) do { _Pragma("unroll") for (int _i = 0; _i < 2; ++_i) \
;         __builtin_amdgcn_global_load_lds((const unsigned*)((const char*)(gbase) + (voff)[_i]), (PG8_LAS unsigned*)(lds + (bufoff) + ldsw + _i * 8192), 16, 0, 0); } while (0)
; #define PG8_LDA(dst, b, h) do { _Pragma("unroll") for (int m = 0; m < 4; ++m) _Pragma("unroll") for (int k = 0; k < 2; ++k) dst[m][k] = *(const PG8_LAS bf16x8*)(lds + PG8_SA(b, h) + aoff + m * 2048 + k * 1024); } while (0)
; #define PG8_LDB(dst, b, h) do { _Pragma("unroll") for (int n = 0; n < 2; ++n) _Pragma("unroll") for (int k = 0; k < 2; ++k) dst[n][k] = *(const PG8_LAS bf16x8*)(lds + PG8_SB(b, h) + boff + n * 2048 + k * 1024); } while (0)
; #define PG8_MMA(ai, bj, At, Bt) do { __builtin_amdgcn_s_setprio(1); _Pragma("unroll") for (int m = 0; m < 4; ++m) _Pragma("unroll") for (int n = 0; n < 2; ++n) _Pragma("unroll") for (int k = 0; k < 2; ++k) \
;         acc[ai][bj][m][n] = __builtin_amdgcn_mfma_f32_16x16x32_bf16(Bt[n][k], At[m][k], acc[ai][bj][m][n], 0, 0, 0); __builtin_amdgcn_s_setprio(0); } while (0)
; #define PG8_WAIT_V(n) asm volatile("s_waitcnt vmcnt(" #n ")" ::: "memory")
; #define PG8_WAIT_L(n) asm volatile("s_waitcnt lgkmcnt(" #n ")" ::: "memory")
; #define PG8_BAR __builtin_amdgcn_s_barrier()
; #define PG8_SCHED __builtin_amdgcn_sched_barrier(0)
; template <class Epi, class Sched, bool ALIGN_EPI = false, bool SP2 = false>
; __device__ __forceinline__ void gemm_phase(PG8_LAS unsigned char* lds, const Gemm g, const Sched& S, const Epi& E) {
;     ...
;             PG8_WAIT_V(8); PG8_WAIT_L(0); PG8_BAR; PG8_MMA(1, 0, At, B0); PG8_MMA(1, 1, At, B1); PG8_BAR; PG8_SCHED;
;             PG8_LDB(B0, 1, 0); PG8_LDB(B1, 1, 1); PG8_SCHED; PG8_LDA(At, 1, 0); PG8_STAGE(PG8_SA(0, 1), a2 + hstepA, voffA);
;             PG8_WAIT_V(8); PG8_WAIT_L(0); PG8_BAR; PG8_MMA(0, 0, At, B0); PG8_MMA(0, 1, At, B1); PG8_BAR; PG8_SCHED;
	s_setprio 1
	s_waitcnt lgkmcnt(0)
	v_mfma_f32_16x16x32_bf16 v[62:65], v[162:165], v[194:197], v[62:65]
	v_mfma_f32_16x16x32_bf16 v[58:61], v[170:173], v[194:197], v[58:61]
	v_mfma_f32_16x16x32_bf16 v[46:49], v[162:165], v[202:205], v[46:49]
	v_mfma_f32_16x16x32_bf16 v[42:45], v[170:173], v[202:205], v[42:45]
	v_mfma_f32_16x16x32_bf16 v[30:33], v[162:165], v[210:213], v[30:33]
	v_mfma_f32_16x16x32_bf16 v[26:29], v[170:173], v[210:213], v[26:29]
	v_mfma_f32_16x16x32_bf16 v[14:17], v[162:165], v[218:221], v[14:17]
	v_mfma_f32_16x16x32_bf16 v[10:13], v[170:173], v[218:221], v[10:13]
	v_mfma_f32_16x16x32_bf16 v[62:65], v[166:169], v[198:201], v[62:65]
	v_mfma_f32_16x16x32_bf16 v[58:61], v[174:177], v[198:201], v[58:61]
	v_mfma_f32_16x16x32_bf16 v[46:49], v[166:169], v[206:209], v[46:49]
	v_mfma_f32_16x16x32_bf16 v[42:45], v[174:177], v[206:209], v[42:45]
	v_mfma_f32_16x16x32_bf16 v[30:33], v[166:169], v[214:217], v[30:33]
	v_mfma_f32_16x16x32_bf16 v[26:29], v[174:177], v[214:217], v[26:29]
	v_mfma_f32_16x16x32_bf16 v[14:17], v[166:169], v[222:225], v[14:17]
	v_mfma_f32_16x16x32_bf16 v[10:13], v[174:177], v[222:225], v[10:13]
	v_mfma_f32_16x16x32_bf16 v[54:57], v[178:181], v[194:197], v[54:57]
	v_mfma_f32_16x16x32_bf16 v[50:53], v[186:189], v[194:197], v[50:53]
	v_mfma_f32_16x16x32_bf16 v[38:41], v[178:181], v[202:205], v[38:41]
	v_mfma_f32_16x16x32_bf16 v[34:37], v[186:189], v[202:205], v[34:37]
	v_mfma_f32_16x16x32_bf16 v[22:25], v[178:181], v[210:213], v[22:25]
	v_mfma_f32_16x16x32_bf16 v[18:21], v[186:189], v[210:213], v[18:21]
	v_mfma_f32_16x16x32_bf16 v[6:9], v[178:181], v[218:221], v[6:9]
	v_mfma_f32_16x16x32_bf16 v[2:5], v[186:189], v[218:221], v[2:5]
	v_mfma_f32_16x16x32_bf16 v[54:57], v[182:185], v[198:201], v[54:57]
	v_mfma_f32_16x16x32_bf16 v[50:53], v[190:193], v[198:201], v[50:53]
	v_mfma_f32_16x16x32_bf16 v[38:41], v[182:185], v[206:209], v[38:41]
	v_mfma_f32_16x16x32_bf16 v[34:37], v[190:193], v[206:209], v[34:37]
	v_mfma_f32_16x16x32_bf16 v[22:25], v[182:185], v[214:217], v[22:25]
	v_mfma_f32_16x16x32_bf16 v[18:21], v[190:193], v[214:217], v[18:21]
	v_mfma_f32_16x16x32_bf16 v[6:9], v[182:185], v[222:225], v[6:9]
	v_mfma_f32_16x16x32_bf16 v[2:5], v[190:193], v[222:225], v[2:5]
	s_setprio 0
	s_barrier
	v_add_u32_e32 v138, s69, v150
	ds_read_b128 v[162:165], v138
	ds_read_b128 v[166:169], v138 offset:1024
	ds_read_b128 v[170:173], v138 offset:2048
	ds_read_b128 v[174:177], v138 offset:3072
	v_add_u32_e32 v138, s68, v150
	ds_read_b128 v[178:181], v138
	ds_read_b128 v[182:185], v138 offset:1024
	ds_read_b128 v[186:189], v138 offset:2048
	ds_read_b128 v[190:193], v138 offset:3072
	s_mov_b32 m0, s48
	v_lshl_add_u64 v[232:233], s[28:29], 0, v[130:131]
	ds_read_b128 v[194:197], v153 offset:32768
	ds_read_b128 v[198:201], v153 offset:33792
	ds_read_b128 v[202:205], v153 offset:34816
	ds_read_b128 v[206:209], v153 offset:35840
	ds_read_b128 v[210:213], v153 offset:36864
	ds_read_b128 v[214:217], v153 offset:37888
	ds_read_b128 v[218:221], v153 offset:38912
	ds_read_b128 v[222:225], v153 offset:39936
	global_load_lds_dwordx4 v[232:233], off
	v_lshl_add_u64 v[232:233], s[28:29], 0, v[134:135]
	s_mov_b32 m0, s49
	s_nop 0
	global_load_lds_dwordx4 v[232:233], off
	s_waitcnt vmcnt(8)
	s_waitcnt lgkmcnt(0)
	s_barrier
	s_setprio 1
	s_waitcnt lgkmcnt(0)
	v_mfma_f32_16x16x32_bf16 v[126:129], v[162:165], v[194:197], v[126:129]
	v_mfma_f32_16x16x32_bf16 v[122:125], v[170:173], v[194:197], v[122:125]
	v_mfma_f32_16x16x32_bf16 v[110:113], v[162:165], v[202:205], v[110:113]
	v_mfma_f32_16x16x32_bf16 v[106:109], v[170:173], v[202:205], v[106:109]
	v_mfma_f32_16x16x32_bf16 v[94:97], v[162:165], v[210:213], v[94:97]
	v_mfma_f32_16x16x32_bf16 v[90:93], v[170:173], v[210:213], v[90:93]
	v_mfma_f32_16x16x32_bf16 v[78:81], v[162:165], v[218:221], v[78:81]
	v_mfma_f32_16x16x32_bf16 v[74:77], v[170:173], v[218:221], v[74:77]
	v_mfma_f32_16x16x32_bf16 v[126:129], v[166:169], v[198:201], v[126:129]
	v_mfma_f32_16x16x32_bf16 v[122:125], v[174:177], v[198:201], v[122:125]
	v_mfma_f32_16x16x32_bf16 v[110:113], v[166:169], v[206:209], v[110:113]
	v_mfma_f32_16x16x32_bf16 v[106:109], v[174:177], v[206:209], v[106:109]
	v_mfma_f32_16x16x32_bf16 v[94:97], v[166:169], v[214:217], v[94:97]
	v_mfma_f32_16x16x32_bf16 v[90:93], v[174:177], v[214:217], v[90:93]
	v_mfma_f32_16x16x32_bf16 v[78:81], v[166:169], v[222:225], v[78:81]
	v_mfma_f32_16x16x32_bf16 v[74:77], v[174:177], v[222:225], v[74:77]
	v_mfma_f32_16x16x32_bf16 v[118:121], v[178:181], v[194:197], v[118:121]
	v_mfma_f32_16x16x32_bf16 v[114:117], v[186:189], v[194:197], v[114:117]
	v_mfma_f32_16x16x32_bf16 v[102:105], v[178:181], v[202:205], v[102:105]
	v_mfma_f32_16x16x32_bf16 v[98:101], v[186:189], v[202:205], v[98:101]
	v_mfma_f32_16x16x32_bf16 v[86:89], v[178:181], v[210:213], v[86:89]
	v_mfma_f32_16x16x32_bf16 v[82:85], v[186:189], v[210:213], v[82:85]
	v_mfma_f32_16x16x32_bf16 v[70:73], v[178:181], v[218:221], v[70:73]
	v_mfma_f32_16x16x32_bf16 v[66:69], v[186:189], v[218:221], v[66:69]
	v_mfma_f32_16x16x32_bf16 v[118:121], v[182:185], v[198:201], v[118:121]
	v_mfma_f32_16x16x32_bf16 v[114:117], v[190:193], v[198:201], v[114:117]
	v_mfma_f32_16x16x32_bf16 v[102:105], v[182:185], v[206:209], v[102:105]
	v_mfma_f32_16x16x32_bf16 v[98:101], v[190:193], v[206:209], v[98:101]
	v_mfma_f32_16x16x32_bf16 v[86:89], v[182:185], v[214:217], v[86:89]
	v_mfma_f32_16x16x32_bf16 v[82:85], v[190:193], v[214:217], v[82:85]
	v_mfma_f32_16x16x32_bf16 v[70:73], v[182:185], v[222:225], v[70:73]
	v_mfma_f32_16x16x32_bf16 v[66:69], v[190:193], v[222:225], v[66:69]
	s_setprio 0
	s_barrier
; #define PG8_STAGE(bufoff, gbase, voff) do { _Pragma("unroll") for (int _i = 0; _i < 2; ++_i) \
;         __builtin_amdgcn_global_load_lds((const unsigned*)((const char*)(gbase) + (voff)[_i]), (PG8_LAS unsigned*)(lds + (bufoff) + ldsw + _i * 8192), 16, 0, 0); } while (0)
; #define PG8_LDA(dst, b, h) do { _Pragma("unroll") for (int m = 0; m < 4; ++m) _Pragma("unroll") for (int k = 0; k < 2; ++k) dst[m][k] = *(const PG8_LAS bf16x8*)(lds + PG8_SA(b, h) + aoff + m * 2048 + k * 1024); } while (0)
; #define PG8_MMA(ai, bj, At, Bt) do { __builtin_amdgcn_s_setprio(1); _Pragma("unroll") for (int m = 0; m < 4; ++m) _Pragma("unroll") for (int n = 0; n < 2; ++n) _Pragma("unroll") for (int k = 0; k < 2; ++k) \
;         acc[ai][bj][m][n] = __builtin_amdgcn_mfma_f32_16x16x32_bf16(Bt[n][k], At[m][k], acc[ai][bj][m][n], 0, 0, 0); __builtin_amdgcn_s_setprio(0); } while (0)
; #define PG8_WAIT_V(n) asm volatile("s_waitcnt vmcnt(" #n ")" ::: "memory")
; #define PG8_WAIT_L(n) asm volatile("s_waitcnt lgkmcnt(" #n ")" ::: "memory")
; #define PG8_BAR __builtin_amdgcn_s_barrier()
; #define PG8_SCHED __builtin_amdgcn_sched_barrier(0)
; template <class Epi, class Sched, bool ALIGN_EPI = false, bool SP2 = false>
; __device__ __forceinline__ void gemm_phase(PG8_LAS unsigned char* lds, const Gemm g, const Sched& S, const Epi& E) {
;     ...
;         for (int t = 0; t < nt; t += 2) {
;     ...
;             PG8_LDA(At, 1, 1); PG8_STAGE(PG8_SB(1, 0), b3, voffB); PG8_STAGE(PG8_SB(1, 1), b3 + hstepB, voffB); PG8_STAGE(PG8_SA(1, 0), a3, voffA);
;             PG8_WAIT_V(8); PG8_WAIT_L(0); PG8_BAR; PG8_MMA(1, 0, At, B0); PG8_MMA(1, 1, At, B1); PG8_BAR; PG8_SCHED;
	s_mov_b32 m0, s67
	v_lshl_add_u64 v[148:149], v[148:149], 0, s[8:9]
	ds_read_b128 v[194:197], v153 offset:49152
	ds_read_b128 v[198:201], v153 offset:50176
	ds_read_b128 v[202:205], v153 offset:51200
	ds_read_b128 v[206:209], v153 offset:52224
	ds_read_b128 v[210:213], v153 offset:53248
	ds_read_b128 v[214:217], v153 offset:54272
	ds_read_b128 v[218:221], v153 offset:55296
	ds_read_b128 v[222:225], v153 offset:56320
	global_load_lds_dwordx4 v[148:149], off
	v_lshl_add_u64 v[148:149], v[226:227], 0, s[8:9]
	s_mov_b32 m0, s66
	s_nop 0
	global_load_lds_dwordx4 v[148:149], off
	v_lshl_add_u64 v[148:149], s[26:27], 0, v[132:133]
	s_mov_b32 m0, s75
	s_nop 0
	global_load_lds_dwordx4 v[148:149], off
	v_lshl_add_u64 v[148:149], s[26:27], 0, v[136:137]
	s_mov_b32 m0, s74
	s_nop 0
	global_load_lds_dwordx4 v[148:149], off
	v_lshl_add_u64 v[148:149], v[228:229], 0, s[8:9]
	s_mov_b32 m0, s53
	s_nop 0
	global_load_lds_dwordx4 v[148:149], off
	v_lshl_add_u64 v[148:149], v[230:231], 0, s[8:9]
	s_mov_b32 m0, s54
	s_nop 0
	global_load_lds_dwordx4 v[148:149], off
	s_waitcnt vmcnt(8)
	s_waitcnt lgkmcnt(0)
	s_barrier
	s_setprio 1
	s_waitcnt lgkmcnt(0)
	v_mfma_f32_16x16x32_bf16 v[62:65], v[162:165], v[194:197], v[62:65]
	v_mfma_f32_16x16x32_bf16 v[58:61], v[170:173], v[194:197], v[58:61]
	v_mfma_f32_16x16x32_bf16 v[46:49], v[162:165], v[202:205], v[46:49]
	v_mfma_f32_16x16x32_bf16 v[42:45], v[170:173], v[202:205], v[42:45]
	v_mfma_f32_16x16x32_bf16 v[30:33], v[162:165], v[210:213], v[30:33]
	v_mfma_f32_16x16x32_bf16 v[26:29], v[170:173], v[210:213], v[26:29]
	v_mfma_f32_16x16x32_bf16 v[14:17], v[162:165], v[218:221], v[14:17]
	v_mfma_f32_16x16x32_bf16 v[10:13], v[170:173], v[218:221], v[10:13]
	v_mfma_f32_16x16x32_bf16 v[62:65], v[166:169], v[198:201], v[62:65]
	v_mfma_f32_16x16x32_bf16 v[58:61], v[174:177], v[198:201], v[58:61]
	v_mfma_f32_16x16x32_bf16 v[46:49], v[166:169], v[206:209], v[46:49]
	v_mfma_f32_16x16x32_bf16 v[42:45], v[174:177], v[206:209], v[42:45]
	v_mfma_f32_16x16x32_bf16 v[30:33], v[166:169], v[214:217], v[30:33]
	v_mfma_f32_16x16x32_bf16 v[26:29], v[174:177], v[214:217], v[26:29]
	v_mfma_f32_16x16x32_bf16 v[14:17], v[166:169], v[222:225], v[14:17]
	v_mfma_f32_16x16x32_bf16 v[10:13], v[174:177], v[222:225], v[10:13]
	v_mfma_f32_16x16x32_bf16 v[54:57], v[178:181], v[194:197], v[54:57]
	v_mfma_f32_16x16x32_bf16 v[50:53], v[186:189], v[194:197], v[50:53]
	v_mfma_f32_16x16x32_bf16 v[38:41], v[178:181], v[202:205], v[38:41]
	v_mfma_f32_16x16x32_bf16 v[34:37], v[186:189], v[202:205], v[34:37]
	v_mfma_f32_16x16x32_bf16 v[22:25], v[178:181], v[210:213], v[22:25]
	v_mfma_f32_16x16x32_bf16 v[18:21], v[186:189], v[210:213], v[18:21]
	v_mfma_f32_16x16x32_bf16 v[6:9], v[178:181], v[218:221], v[6:9]
	v_mfma_f32_16x16x32_bf16 v[2:5], v[186:189], v[218:221], v[2:5]
	v_mfma_f32_16x16x32_bf16 v[54:57], v[182:185], v[198:201], v[54:57]
	v_mfma_f32_16x16x32_bf16 v[50:53], v[190:193], v[198:201], v[50:53]
	v_mfma_f32_16x16x32_bf16 v[38:41], v[182:185], v[206:209], v[38:41]
	v_mfma_f32_16x16x32_bf16 v[34:37], v[190:193], v[206:209], v[34:37]
	v_mfma_f32_16x16x32_bf16 v[22:25], v[182:185], v[214:217], v[22:25]
	v_mfma_f32_16x16x32_bf16 v[18:21], v[190:193], v[214:217], v[18:21]
	v_mfma_f32_16x16x32_bf16 v[6:9], v[182:185], v[222:225], v[6:9]
	v_mfma_f32_16x16x32_bf16 v[2:5], v[190:193], v[222:225], v[2:5]
	s_setprio 0
	s_barrier
	s_andn2_b64 vcc, exec, s[0:1]
	s_mov_b64 s[26:27], -1
	s_mov_b64 s[0:1], 0
	s_mov_b64 s[28:29], 0x100
	s_cbranch_vccz .LBB0_832
	s_and_b64 vcc, exec, s[12:13]
	s_cbranch_vccz .LBB0_835
	s_barrier

; #define PG8_STAGE(bufoff, gbase, voff) do { _Pragma("unroll") for (int _i = 0; _i < 2; ++_i) \
;         __builtin_amdgcn_global_load_lds((const unsigned*)((const char*)(gbase) + (voff)[_i]), (PG8_LAS unsigned*)(lds + (bufoff) + ldsw + _i * 8192), 16, 0, 0); } while (0)
; #define PG8_LDA(dst, b, h) do { _Pragma("unroll") for (int m = 0; m < 4; ++m) _Pragma("unroll") for (int k = 0; k < 2; ++k) dst[m][k] = *(const PG8_LAS bf16x8*)(lds + PG8_SA(b, h) + aoff + m * 2048 + k * 1024); } while (0)
; #define PG8_LDB(dst, b, h) do { _Pragma("unroll") for (int n = 0; n < 2; ++n) _Pragma("unroll") for (int k = 0; k < 2; ++k) dst[n][k] = *(const PG8_LAS bf16x8*)(lds + PG8_SB(b, h) + boff + n * 2048 + k * 1024); } while (0)
; #define PG8_MMA(ai, bj, At, Bt) do { __builtin_amdgcn_s_setprio(1); _Pragma("unroll") for (int m = 0; m < 4; ++m) _Pragma("unroll") for (int n = 0; n < 2; ++n) _Pragma("unroll") for (int k = 0; k < 2; ++k) \
;         acc[ai][bj][m][n] = __builtin_amdgcn_mfma_f32_16x16x32_bf16(Bt[n][k], At[m][k], acc[ai][bj][m][n], 0, 0, 0); __builtin_amdgcn_s_setprio(0); } while (0)
; #define PG8_WAIT_V(n) asm volatile("s_waitcnt vmcnt(" #n ")" ::: "memory")
; #define PG8_WAIT_L(n) asm volatile("s_waitcnt lgkmcnt(" #n ")" ::: "memory")
; #define PG8_BAR __builtin_amdgcn_s_barrier()
; #define PG8_SCHED __builtin_amdgcn_sched_barrier(0)
; template <class Epi, class Sched, bool ALIGN_EPI = false, bool SP2 = false>
; __device__ __forceinline__ void gemm_phase(PG8_LAS unsigned char* lds, const Gemm g, const Sched& S, const Epi& E) {
;     ...
;             PG8_LDB(B0, 0, 0); PG8_LDB(B1, 0, 1); PG8_SCHED; PG8_LDA(At, 0, 0); PG8_STAGE(PG8_SA(1, 1), a1 + hstepA, voffA);
;             PG8_WAIT_V(8); PG8_WAIT_L(0); PG8_BAR; PG8_MMA(0, 0, At, B0); PG8_MMA(0, 1, At, B1); PG8_BAR; PG8_SCHED;
;             PG8_LDA(At, 0, 1); PG8_STAGE(PG8_SB(0, 0), b2, voffB); PG8_STAGE(PG8_SB(0, 1), b2 + hstepB, voffB); PG8_STAGE(PG8_SA(0, 0), a2, voffA);
;             PG8_WAIT_V(8); PG8_WAIT_L(0); PG8_BAR; PG8_MMA(1, 0, At, B0); PG8_MMA(1, 1, At, B1); PG8_BAR; PG8_SCHED;
.LBB0_1086:
	ds_read_b128 v[130:133], v168
	ds_read_b128 v[134:137], v168 offset:1024
	ds_read_b128 v[138:141], v168 offset:2048
	ds_read_b128 v[158:161], v168 offset:3072
	ds_read_b128 v[162:165], v169
	ds_read_b128 v[172:175], v169 offset:1024
	ds_read_b128 v[176:179], v169 offset:2048
	ds_read_b128 v[180:183], v169 offset:3072
	s_add_u32 s26, s24, 0xfffe0080
	s_addc_u32 s27, s25, -1
	s_cmp_eq_u32 s49, 4
	s_cselect_b32 s29, s17, s27
	s_cselect_b32 s28, s45, s26
	s_cselect_b32 s27, s15, s48
	s_cselect_b32 s26, s46, s47
	s_add_i32 m0, s23, 0xc000
	ds_read_b128 v[184:187], v170
	ds_read_b128 v[188:191], v170 offset:1024
	ds_read_b128 v[192:195], v170 offset:2048
	ds_read_b128 v[196:199], v170 offset:3072
	ds_read_b128 v[200:203], v170 offset:4096
	ds_read_b128 v[204:207], v170 offset:5120
	ds_read_b128 v[208:211], v170 offset:6144
	ds_read_b128 v[212:215], v170 offset:7168
	global_load_lds_dwordx4 v150, s[24:25]
	s_add_i32 m0, s23, 0xe000
	s_nop 0
	global_load_lds_dwordx4 v152, s[24:25]
	s_waitcnt vmcnt(8)
	s_waitcnt lgkmcnt(0)
	s_barrier
	s_setprio 1
	s_waitcnt lgkmcnt(0)
	v_mfma_f32_16x16x32_bf16 v[126:129], v[130:133], v[184:187], v[126:129]
	v_mfma_f32_16x16x32_bf16 v[122:125], v[138:141], v[184:187], v[122:125]
	v_mfma_f32_16x16x32_bf16 v[110:113], v[130:133], v[192:195], v[110:113]
	v_mfma_f32_16x16x32_bf16 v[106:109], v[138:141], v[192:195], v[106:109]
	v_mfma_f32_16x16x32_bf16 v[94:97], v[130:133], v[200:203], v[94:97]
	v_mfma_f32_16x16x32_bf16 v[90:93], v[138:141], v[200:203], v[90:93]
	v_mfma_f32_16x16x32_bf16 v[78:81], v[130:133], v[208:211], v[78:81]
	v_mfma_f32_16x16x32_bf16 v[74:77], v[138:141], v[208:211], v[74:77]
	v_mfma_f32_16x16x32_bf16 v[126:129], v[134:137], v[188:191], v[126:129]
	v_mfma_f32_16x16x32_bf16 v[122:125], v[158:161], v[188:191], v[122:125]
	v_mfma_f32_16x16x32_bf16 v[110:113], v[134:137], v[196:199], v[110:113]
	v_mfma_f32_16x16x32_bf16 v[106:109], v[158:161], v[196:199], v[106:109]
	v_mfma_f32_16x16x32_bf16 v[94:97], v[134:137], v[204:207], v[94:97]
	v_mfma_f32_16x16x32_bf16 v[90:93], v[158:161], v[204:207], v[90:93]
	v_mfma_f32_16x16x32_bf16 v[78:81], v[134:137], v[212:215], v[78:81]
	v_mfma_f32_16x16x32_bf16 v[74:77], v[158:161], v[212:215], v[74:77]
	v_mfma_f32_16x16x32_bf16 v[118:121], v[162:165], v[184:187], v[118:121]
	v_mfma_f32_16x16x32_bf16 v[114:117], v[176:179], v[184:187], v[114:117]
	v_mfma_f32_16x16x32_bf16 v[102:105], v[162:165], v[192:195], v[102:105]
	v_mfma_f32_16x16x32_bf16 v[98:101], v[176:179], v[192:195], v[98:101]
	v_mfma_f32_16x16x32_bf16 v[86:89], v[162:165], v[200:203], v[86:89]
	v_mfma_f32_16x16x32_bf16 v[82:85], v[176:179], v[200:203], v[82:85]
	v_mfma_f32_16x16x32_bf16 v[70:73], v[162:165], v[208:211], v[70:73]
	v_mfma_f32_16x16x32_bf16 v[66:69], v[176:179], v[208:211], v[66:69]
	v_mfma_f32_16x16x32_bf16 v[118:121], v[172:175], v[188:191], v[118:121]
	v_mfma_f32_16x16x32_bf16 v[114:117], v[180:183], v[188:191], v[114:117]
	v_mfma_f32_16x16x32_bf16 v[102:105], v[172:175], v[196:199], v[102:105]
	v_mfma_f32_16x16x32_bf16 v[98:101], v[180:183], v[196:199], v[98:101]
	v_mfma_f32_16x16x32_bf16 v[86:89], v[172:175], v[204:207], v[86:89]
	v_mfma_f32_16x16x32_bf16 v[82:85], v[180:183], v[204:207], v[82:85]
	v_mfma_f32_16x16x32_bf16 v[70:73], v[172:175], v[212:215], v[70:73]
	v_mfma_f32_16x16x32_bf16 v[66:69], v[180:183], v[212:215], v[66:69]
	s_setprio 0
	s_barrier
	s_add_i32 s50, s42, s34
	s_add_u32 s98, s26, 0x80
	s_addc_u32 s99, s27, 0
	s_mov_b32 m0, s50
	ds_read_b128 v[184:187], v170 offset:16384
	ds_read_b128 v[188:191], v170 offset:17408
	ds_read_b128 v[192:195], v170 offset:18432
	ds_read_b128 v[196:199], v170 offset:19456
	ds_read_b128 v[200:203], v170 offset:20480
	ds_read_b128 v[204:207], v170 offset:21504
	ds_read_b128 v[208:211], v170 offset:22528
	ds_read_b128 v[212:215], v170 offset:23552
	global_load_lds_dwordx4 v144, s[26:27]
	s_add_i32 m0, s50, 0x2000
	s_add_u32 s50, s26, 0x20000
	s_addc_u32 s51, s27, 0
	s_add_i32 s52, s43, s34
	global_load_lds_dwordx4 v148, s[26:27]
	s_mov_b32 m0, s52
	s_nop 0
	global_load_lds_dwordx4 v144, s[50:51]
	s_add_i32 m0, s52, 0x2000
	s_nop 0
	global_load_lds_dwordx4 v148, s[50:51]
	s_add_u32 s100, s28, 0x80
	s_addc_u32 s101, s29, 0
	s_mov_b32 m0, s23
	s_nop 0
	global_load_lds_dwordx4 v142, s[28:29]
	s_mov_b32 m0, s35
	s_nop 0
	global_load_lds_dwordx4 v146, s[28:29]
	s_waitcnt vmcnt(8)
	s_waitcnt lgkmcnt(0)
	s_barrier
	s_setprio 1
	s_waitcnt lgkmcnt(0)
	v_mfma_f32_16x16x32_bf16 v[62:65], v[130:133], v[184:187], v[62:65]
	v_mfma_f32_16x16x32_bf16 v[58:61], v[138:141], v[184:187], v[58:61]
	v_mfma_f32_16x16x32_bf16 v[46:49], v[130:133], v[192:195], v[46:49]
	v_mfma_f32_16x16x32_bf16 v[42:45], v[138:141], v[192:195], v[42:45]
	v_mfma_f32_16x16x32_bf16 v[30:33], v[130:133], v[200:203], v[30:33]
	v_mfma_f32_16x16x32_bf16 v[26:29], v[138:141], v[200:203], v[26:29]
	v_mfma_f32_16x16x32_bf16 v[14:17], v[130:133], v[208:211], v[14:17]
	v_mfma_f32_16x16x32_bf16 v[10:13], v[138:141], v[208:211], v[10:13]
	v_mfma_f32_16x16x32_bf16 v[62:65], v[134:137], v[188:191], v[62:65]
	v_mfma_f32_16x16x32_bf16 v[58:61], v[158:161], v[188:191], v[58:61]
	v_mfma_f32_16x16x32_bf16 v[46:49], v[134:137], v[196:199], v[46:49]
	v_mfma_f32_16x16x32_bf16 v[42:45], v[158:161], v[196:199], v[42:45]
	v_mfma_f32_16x16x32_bf16 v[30:33], v[134:137], v[204:207], v[30:33]
	v_mfma_f32_16x16x32_bf16 v[26:29], v[158:161], v[204:207], v[26:29]
	v_mfma_f32_16x16x32_bf16 v[14:17], v[134:137], v[212:215], v[14:17]
	v_mfma_f32_16x16x32_bf16 v[10:13], v[158:161], v[212:215], v[10:13]
	v_mfma_f32_16x16x32_bf16 v[54:57], v[162:165], v[184:187], v[54:57]
	v_mfma_f32_16x16x32_bf16 v[50:53], v[176:179], v[184:187], v[50:53]
	v_mfma_f32_16x16x32_bf16 v[38:41], v[162:165], v[192:195], v[38:41]
	v_mfma_f32_16x16x32_bf16 v[34:37], v[176:179], v[192:195], v[34:37]
	v_mfma_f32_16x16x32_bf16 v[22:25], v[162:165], v[200:203], v[22:25]
	v_mfma_f32_16x16x32_bf16 v[18:21], v[176:179], v[200:203], v[18:21]
	v_mfma_f32_16x16x32_bf16 v[6:9], v[162:165], v[208:211], v[6:9]
	v_mfma_f32_16x16x32_bf16 v[2:5], v[176:179], v[208:211], v[2:5]
	v_mfma_f32_16x16x32_bf16 v[54:57], v[172:175], v[188:191], v[54:57]
	v_mfma_f32_16x16x32_bf16 v[50:53], v[180:183], v[188:191], v[50:53]
	v_mfma_f32_16x16x32_bf16 v[38:41], v[172:175], v[196:199], v[38:41]
	v_mfma_f32_16x16x32_bf16 v[34:37], v[180:183], v[196:199], v[34:37]
	v_mfma_f32_16x16x32_bf16 v[22:25], v[172:175], v[204:207], v[22:25]
	v_mfma_f32_16x16x32_bf16 v[18:21], v[180:183], v[204:207], v[18:21]
	v_mfma_f32_16x16x32_bf16 v[6:9], v[172:175], v[212:215], v[6:9]
	v_mfma_f32_16x16x32_bf16 v[2:5], v[180:183], v[212:215], v[2:5]
	s_setprio 0
	s_barrier
; #define PG8_STAGE(bufoff, gbase, voff) do { _Pragma("unroll") for (int _i = 0; _i < 2; ++_i) \
;         __builtin_amdgcn_global_load_lds((const unsigned*)((const char*)(gbase) + (voff)[_i]), (PG8_LAS unsigned*)(lds + (bufoff) + ldsw + _i * 8192), 16, 0, 0); } while (0)
; #define PG8_LDA(dst, b, h) do { _Pragma("unroll") for (int m = 0; m < 4; ++m) _Pragma("unroll") for (int k = 0; k < 2; ++k) dst[m][k] = *(const PG8_LAS bf16x8*)(lds + PG8_SA(b, h) + aoff + m * 2048 + k * 1024); } while (0)
; #define PG8_LDB(dst, b, h) do { _Pragma("unroll") for (int n = 0; n < 2; ++n) _Pragma("unroll") for (int k = 0; k < 2; ++k) dst[n][k] = *(const PG8_LAS bf16x8*)(lds + PG8_SB(b, h) + boff + n * 2048 + k * 1024); } while (0)
; #define PG8_MMA(ai, bj, At, Bt) do { __builtin_amdgcn_s_setprio(1); _Pragma("unroll") for (int m = 0; m < 4; ++m) _Pragma("unroll") for (int n = 0; n < 2; ++n) _Pragma("unroll") for (int k = 0; k < 2; ++k) \
;         acc[ai][bj][m][n] = __builtin_amdgcn_mfma_f32_16x16x32_bf16(Bt[n][k], At[m][k], acc[ai][bj][m][n], 0, 0, 0); __builtin_amdgcn_s_setprio(0); } while (0)
; #define PG8_WAIT_V(n) asm volatile("s_waitcnt vmcnt(" #n ")" ::: "memory")
; #define PG8_WAIT_L(n) asm volatile("s_waitcnt lgkmcnt(" #n ")" ::: "memory")
; #define PG8_BAR __builtin_amdgcn_s_barrier()
; #define PG8_SCHED __builtin_amdgcn_sched_barrier(0)
; template <class Epi, class Sched, bool ALIGN_EPI = false, bool SP2 = false>
; __device__ __forceinline__ void gemm_phase(PG8_LAS unsigned char* lds, const Gemm g, const Sched& S, const Epi& E) {
;     ...
;         for (int t = 0; t < nt; t += 2) {
;     ...
;             PG8_LDB(B0, 1, 0); PG8_LDB(B1, 1, 1); PG8_SCHED; PG8_LDA(At, 1, 0); PG8_STAGE(PG8_SA(0, 1), a2 + hstepA, voffA);
;             PG8_WAIT_V(8); PG8_WAIT_L(0); PG8_BAR; PG8_MMA(0, 0, At, B0); PG8_MMA(0, 1, At, B1); PG8_BAR; PG8_SCHED;
;             PG8_LDA(At, 1, 1); PG8_STAGE(PG8_SB(1, 0), b3, voffB); PG8_STAGE(PG8_SB(1, 1), b3 + hstepB, voffB); PG8_STAGE(PG8_SA(1, 0), a3, voffA);
;             PG8_WAIT_V(8); PG8_WAIT_L(0); PG8_BAR; PG8_MMA(1, 0, At, B0); PG8_MMA(1, 1, At, B1); PG8_BAR; PG8_SCHED;
	s_add_i32 s50, 0, 0x18000
	s_add_i32 s51, 0, 0x1c000
	v_add_u32_e32 v158, s50, v166
	v_add_u32_e32 v171, s51, v166
	ds_read_b128 v[130:133], v158
	ds_read_b128 v[134:137], v158 offset:1024
	ds_read_b128 v[138:141], v158 offset:2048
	ds_read_b128 v[158:161], v158 offset:3072
	ds_read_b128 v[162:165], v171
	ds_read_b128 v[172:175], v171 offset:1024
	ds_read_b128 v[176:179], v171 offset:2048
	ds_read_b128 v[180:183], v171 offset:3072
	s_add_u32 s28, s28, 0x20000
	s_addc_u32 s29, s29, 0
	s_mov_b32 m0, s36
	ds_read_b128 v[184:187], v170 offset:32768
	ds_read_b128 v[188:191], v170 offset:33792
	ds_read_b128 v[192:195], v170 offset:34816
	ds_read_b128 v[196:199], v170 offset:35840
	ds_read_b128 v[200:203], v170 offset:36864
	ds_read_b128 v[204:207], v170 offset:37888
	ds_read_b128 v[208:211], v170 offset:38912
	ds_read_b128 v[212:215], v170 offset:39936
	global_load_lds_dwordx4 v142, s[28:29]
	s_mov_b32 m0, s37
	s_nop 0
	global_load_lds_dwordx4 v146, s[28:29]
	s_waitcnt vmcnt(8)
	s_waitcnt lgkmcnt(0)
	s_barrier
	s_setprio 1
	s_waitcnt lgkmcnt(0)
	v_mfma_f32_16x16x32_bf16 v[126:129], v[130:133], v[184:187], v[126:129]
	v_mfma_f32_16x16x32_bf16 v[122:125], v[138:141], v[184:187], v[122:125]
	v_mfma_f32_16x16x32_bf16 v[110:113], v[130:133], v[192:195], v[110:113]
	v_mfma_f32_16x16x32_bf16 v[106:109], v[138:141], v[192:195], v[106:109]
	v_mfma_f32_16x16x32_bf16 v[94:97], v[130:133], v[200:203], v[94:97]
	v_mfma_f32_16x16x32_bf16 v[90:93], v[138:141], v[200:203], v[90:93]
	v_mfma_f32_16x16x32_bf16 v[78:81], v[130:133], v[208:211], v[78:81]
	v_mfma_f32_16x16x32_bf16 v[74:77], v[138:141], v[208:211], v[74:77]
	v_mfma_f32_16x16x32_bf16 v[126:129], v[134:137], v[188:191], v[126:129]
	v_mfma_f32_16x16x32_bf16 v[122:125], v[158:161], v[188:191], v[122:125]
	v_mfma_f32_16x16x32_bf16 v[110:113], v[134:137], v[196:199], v[110:113]
	v_mfma_f32_16x16x32_bf16 v[106:109], v[158:161], v[196:199], v[106:109]
	v_mfma_f32_16x16x32_bf16 v[94:97], v[134:137], v[204:207], v[94:97]
	v_mfma_f32_16x16x32_bf16 v[90:93], v[158:161], v[204:207], v[90:93]
	v_mfma_f32_16x16x32_bf16 v[78:81], v[134:137], v[212:215], v[78:81]
	v_mfma_f32_16x16x32_bf16 v[74:77], v[158:161], v[212:215], v[74:77]
	v_mfma_f32_16x16x32_bf16 v[118:121], v[162:165], v[184:187], v[118:121]
	v_mfma_f32_16x16x32_bf16 v[114:117], v[176:179], v[184:187], v[114:117]
	v_mfma_f32_16x16x32_bf16 v[102:105], v[162:165], v[192:195], v[102:105]
	v_mfma_f32_16x16x32_bf16 v[98:101], v[176:179], v[192:195], v[98:101]
	v_mfma_f32_16x16x32_bf16 v[86:89], v[162:165], v[200:203], v[86:89]
	v_mfma_f32_16x16x32_bf16 v[82:85], v[176:179], v[200:203], v[82:85]
	v_mfma_f32_16x16x32_bf16 v[70:73], v[162:165], v[208:211], v[70:73]
	v_mfma_f32_16x16x32_bf16 v[66:69], v[176:179], v[208:211], v[66:69]
	v_mfma_f32_16x16x32_bf16 v[118:121], v[172:175], v[188:191], v[118:121]
	v_mfma_f32_16x16x32_bf16 v[114:117], v[180:183], v[188:191], v[114:117]
	v_mfma_f32_16x16x32_bf16 v[102:105], v[172:175], v[196:199], v[102:105]
	v_mfma_f32_16x16x32_bf16 v[98:101], v[180:183], v[196:199], v[98:101]
	v_mfma_f32_16x16x32_bf16 v[86:89], v[172:175], v[204:207], v[86:89]
	v_mfma_f32_16x16x32_bf16 v[82:85], v[180:183], v[204:207], v[82:85]
	v_mfma_f32_16x16x32_bf16 v[70:73], v[172:175], v[212:215], v[70:73]
	v_mfma_f32_16x16x32_bf16 v[66:69], v[180:183], v[212:215], v[66:69]
	s_setprio 0
	s_barrier
	s_add_i32 s28, s50, s34
	s_mov_b32 m0, s28
	ds_read_b128 v[184:187], v170 offset:49152
	ds_read_b128 v[188:191], v170 offset:50176
	ds_read_b128 v[192:195], v170 offset:51200
	ds_read_b128 v[196:199], v170 offset:52224
	ds_read_b128 v[200:203], v170 offset:53248
	ds_read_b128 v[204:207], v170 offset:54272
	ds_read_b128 v[208:211], v170 offset:55296
	ds_read_b128 v[212:215], v170 offset:56320
	global_load_lds_dwordx4 v144, s[98:99]
	s_add_i32 m0, s28, 0x2000
	s_add_u32 s26, s26, 0x20080
	s_addc_u32 s27, s27, 0
	s_add_i32 s28, s51, s34
	global_load_lds_dwordx4 v148, s[98:99]
	s_mov_b32 m0, s28
	s_nop 0
	global_load_lds_dwordx4 v144, s[26:27]
	s_add_i32 m0, s28, 0x2000
	s_nop 0
	global_load_lds_dwordx4 v148, s[26:27]
	s_mov_b32 m0, s39
	s_nop 0
	global_load_lds_dwordx4 v142, s[100:101]
	s_mov_b32 m0, s40
	s_nop 0
	global_load_lds_dwordx4 v146, s[100:101]
	s_waitcnt vmcnt(8)
	s_waitcnt lgkmcnt(0)
	s_barrier
	s_setprio 1
	s_waitcnt lgkmcnt(0)
	v_mfma_f32_16x16x32_bf16 v[62:65], v[130:133], v[184:187], v[62:65]
	v_mfma_f32_16x16x32_bf16 v[58:61], v[138:141], v[184:187], v[58:61]
	v_mfma_f32_16x16x32_bf16 v[46:49], v[130:133], v[192:195], v[46:49]
	v_mfma_f32_16x16x32_bf16 v[42:45], v[138:141], v[192:195], v[42:45]
	v_mfma_f32_16x16x32_bf16 v[30:33], v[130:133], v[200:203], v[30:33]
	v_mfma_f32_16x16x32_bf16 v[26:29], v[138:141], v[200:203], v[26:29]
	v_mfma_f32_16x16x32_bf16 v[14:17], v[130:133], v[208:211], v[14:17]
	v_mfma_f32_16x16x32_bf16 v[10:13], v[138:141], v[208:211], v[10:13]
	v_mfma_f32_16x16x32_bf16 v[62:65], v[134:137], v[188:191], v[62:65]
	v_mfma_f32_16x16x32_bf16 v[58:61], v[158:161], v[188:191], v[58:61]
	v_mfma_f32_16x16x32_bf16 v[46:49], v[134:137], v[196:199], v[46:49]
	v_mfma_f32_16x16x32_bf16 v[42:45], v[158:161], v[196:199], v[42:45]
	v_mfma_f32_16x16x32_bf16 v[30:33], v[134:137], v[204:207], v[30:33]
	v_mfma_f32_16x16x32_bf16 v[26:29], v[158:161], v[204:207], v[26:29]
	v_mfma_f32_16x16x32_bf16 v[14:17], v[134:137], v[212:215], v[14:17]
	v_mfma_f32_16x16x32_bf16 v[10:13], v[158:161], v[212:215], v[10:13]
	v_mfma_f32_16x16x32_bf16 v[54:57], v[162:165], v[184:187], v[54:57]
	v_mfma_f32_16x16x32_bf16 v[50:53], v[176:179], v[184:187], v[50:53]
	v_mfma_f32_16x16x32_bf16 v[38:41], v[162:165], v[192:195], v[38:41]
	v_mfma_f32_16x16x32_bf16 v[34:37], v[176:179], v[192:195], v[34:37]
	v_mfma_f32_16x16x32_bf16 v[22:25], v[162:165], v[200:203], v[22:25]
	v_mfma_f32_16x16x32_bf16 v[18:21], v[176:179], v[200:203], v[18:21]
	v_mfma_f32_16x16x32_bf16 v[6:9], v[162:165], v[208:211], v[6:9]
	v_mfma_f32_16x16x32_bf16 v[2:5], v[176:179], v[208:211], v[2:5]
	v_mfma_f32_16x16x32_bf16 v[54:57], v[172:175], v[188:191], v[54:57]
	v_mfma_f32_16x16x32_bf16 v[50:53], v[180:183], v[188:191], v[50:53]
	v_mfma_f32_16x16x32_bf16 v[38:41], v[172:175], v[196:199], v[38:41]
	v_mfma_f32_16x16x32_bf16 v[34:37], v[180:183], v[196:199], v[34:37]
	v_mfma_f32_16x16x32_bf16 v[22:25], v[172:175], v[204:207], v[22:25]
	v_mfma_f32_16x16x32_bf16 v[18:21], v[180:183], v[204:207], v[18:21]
	v_mfma_f32_16x16x32_bf16 v[6:9], v[172:175], v[212:215], v[6:9]
	v_mfma_f32_16x16x32_bf16 v[2:5], v[180:183], v[212:215], v[2:5]
	s_setprio 0
	s_barrier
	s_add_i32 s49, s49, 2
	s_add_u32 s24, s24, 0x100
	s_addc_u32 s25, s25, 0
	s_add_u32 s47, s47, 0x100
	s_addc_u32 s48, s48, 0
	s_cmp_gt_u32 s49, 5
	s_cbranch_scc0 .LBB0_1086
	s_and_b64 vcc, exec, s[12:13]
	s_cbranch_vccz .LBB0_1089
	s_barrier

; #define PG8_STAGE(bufoff, gbase, voff) do { _Pragma("unroll") for (int _i = 0; _i < 2; ++_i) \
;         __builtin_amdgcn_global_load_lds((const unsigned*)((const char*)(gbase) + (voff)[_i]), (PG8_LAS unsigned*)(lds + (bufoff) + ldsw + _i * 8192), 16, 0, 0); } while (0)
; #define PG8_LDA(dst, b, h) do { _Pragma("unroll") for (int m = 0; m < 4; ++m) _Pragma("unroll") for (int k = 0; k < 2; ++k) dst[m][k] = *(const PG8_LAS bf16x8*)(lds + PG8_SA(b, h) + aoff + m * 2048 + k * 1024); } while (0)
; #define PG8_LDB(dst, b, h) do { _Pragma("unroll") for (int n = 0; n < 2; ++n) _Pragma("unroll") for (int k = 0; k < 2; ++k) dst[n][k] = *(const PG8_LAS bf16x8*)(lds + PG8_SB(b, h) + boff + n * 2048 + k * 1024); } while (0)
; #define PG8_MMA(ai, bj, At, Bt) do { __builtin_amdgcn_s_setprio(1); _Pragma("unroll") for (int m = 0; m < 4; ++m) _Pragma("unroll") for (int n = 0; n < 2; ++n) _Pragma("unroll") for (int k = 0; k < 2; ++k) \
;         acc[ai][bj][m][n] = __builtin_amdgcn_mfma_f32_16x16x32_bf16(Bt[n][k], At[m][k], acc[ai][bj][m][n], 0, 0, 0); __builtin_amdgcn_s_setprio(0); } while (0)
; #define PG8_WAIT_V(n) asm volatile("s_waitcnt vmcnt(" #n ")" ::: "memory")
; #define PG8_WAIT_L(n) asm volatile("s_waitcnt lgkmcnt(" #n ")" ::: "memory")
; #define PG8_BAR __builtin_amdgcn_s_barrier()
; #define PG8_SCHED __builtin_amdgcn_sched_barrier(0)
; template <class Epi, class Sched, bool ALIGN_EPI = false, bool SP2 = false>
; __device__ __forceinline__ void gemm_phase(PG8_LAS unsigned char* lds, const Gemm g, const Sched& S, const Epi& E) {
;     ...
;             PG8_LDB(B0, 0, 0); PG8_LDB(B1, 0, 1); PG8_SCHED; PG8_LDA(At, 0, 0); PG8_STAGE(PG8_SA(1, 1), a1 + hstepA, voffA);
;             PG8_WAIT_V(8); PG8_WAIT_L(0); PG8_BAR; PG8_MMA(0, 0, At, B0); PG8_MMA(0, 1, At, B1); PG8_BAR; PG8_SCHED;
;             PG8_LDA(At, 0, 1); PG8_STAGE(PG8_SB(0, 0), b2, voffB); PG8_STAGE(PG8_SB(0, 1), b2 + hstepB, voffB); PG8_STAGE(PG8_SA(0, 0), a2, voffA);
;             PG8_WAIT_V(8); PG8_WAIT_L(0); PG8_BAR; PG8_MMA(1, 0, At, B0); PG8_MMA(1, 1, At, B1); PG8_BAR; PG8_SCHED;
.LBB0_1269:
	v_add_u32_e32 v24, s56, v22
	ds_read_b128 v[50:53], v24
	ds_read_b128 v[54:57], v24 offset:1024
	ds_read_b128 v[70:73], v24 offset:2048
	ds_read_b128 v[74:77], v24 offset:3072
	v_add_u32_e32 v24, s57, v22
	s_add_u32 s36, s20, s34
	ds_read_b128 v[78:81], v24
	ds_read_b128 v[90:93], v24 offset:1024
	ds_read_b128 v[94:97], v24 offset:2048
	ds_read_b128 v[154:157], v24 offset:3072
	s_addc_u32 s37, s21, s35
	s_add_u32 s36, s36, 0x100
	s_addc_u32 s37, s37, 0
	s_add_u32 s64, s59, s34
	s_addc_u32 s65, s60, s35
	s_cmpk_eq_i32 s34, 0x700
	s_cselect_b32 s39, s27, s37
	s_cselect_b32 s38, s61, s36
	s_cselect_b32 s37, s25, s65
	s_cselect_b32 s36, s62, s64
	v_lshl_add_u64 v[24:25], v[18:19], 0, s[34:35]
	s_add_i32 m0, s48, 0xc000
	ds_read_b128 v[158:161], v23
	ds_read_b128 v[178:181], v23 offset:1024
	ds_read_b128 v[194:197], v23 offset:2048
	ds_read_b128 v[198:201], v23 offset:3072
	ds_read_b128 v[202:205], v23 offset:4096
	ds_read_b128 v[206:209], v23 offset:5120
	ds_read_b128 v[210:213], v23 offset:6144
	ds_read_b128 v[214:217], v23 offset:7168
	global_load_lds_dwordx4 v[24:25], off
	v_lshl_add_u64 v[24:25], v[20:21], 0, s[34:35]
	s_add_i32 m0, s48, 0xe000
	s_nop 0
	global_load_lds_dwordx4 v[24:25], off
	s_waitcnt vmcnt(8)
	s_waitcnt lgkmcnt(0)
	s_barrier
	s_setprio 1
	s_waitcnt lgkmcnt(0)
	v_mfma_f32_16x16x32_bf16 v[62:65], v[50:53], v[158:161], v[62:65]
	v_mfma_f32_16x16x32_bf16 v[170:173], v[70:73], v[158:161], v[170:173]
	v_mfma_f32_16x16x32_bf16 v[166:169], v[50:53], v[194:197], v[166:169]
	v_mfma_f32_16x16x32_bf16 v[162:165], v[70:73], v[194:197], v[162:165]
	v_mfma_f32_16x16x32_bf16 v[174:177], v[50:53], v[202:205], v[174:177]
	v_mfma_f32_16x16x32_bf16 v[190:193], v[70:73], v[202:205], v[190:193]
	v_mfma_f32_16x16x32_bf16 v[186:189], v[50:53], v[210:213], v[186:189]
	v_mfma_f32_16x16x32_bf16 v[182:185], v[70:73], v[210:213], v[182:185]
	v_mfma_f32_16x16x32_bf16 v[62:65], v[54:57], v[178:181], v[62:65]
	v_mfma_f32_16x16x32_bf16 v[170:173], v[74:77], v[178:181], v[170:173]
	v_mfma_f32_16x16x32_bf16 v[166:169], v[54:57], v[198:201], v[166:169]
	v_mfma_f32_16x16x32_bf16 v[162:165], v[74:77], v[198:201], v[162:165]
	v_mfma_f32_16x16x32_bf16 v[174:177], v[54:57], v[206:209], v[174:177]
	v_mfma_f32_16x16x32_bf16 v[190:193], v[74:77], v[206:209], v[190:193]
	v_mfma_f32_16x16x32_bf16 v[186:189], v[54:57], v[214:217], v[186:189]
	v_mfma_f32_16x16x32_bf16 v[182:185], v[74:77], v[214:217], v[182:185]
	v_mfma_f32_16x16x32_bf16 v[86:89], v[78:81], v[158:161], v[86:89]
	v_mfma_f32_16x16x32_bf16 v[82:85], v[94:97], v[158:161], v[82:85]
	v_mfma_f32_16x16x32_bf16 v[66:69], v[78:81], v[194:197], v[66:69]
	v_mfma_f32_16x16x32_bf16 v[58:61], v[94:97], v[194:197], v[58:61]
	v_mfma_f32_16x16x32_bf16 v[114:117], v[78:81], v[202:205], v[114:117]
	v_mfma_f32_16x16x32_bf16 v[110:113], v[94:97], v[202:205], v[110:113]
	v_mfma_f32_16x16x32_bf16 v[106:109], v[78:81], v[210:213], v[106:109]
	v_mfma_f32_16x16x32_bf16 v[102:105], v[94:97], v[210:213], v[102:105]
	v_mfma_f32_16x16x32_bf16 v[86:89], v[90:93], v[178:181], v[86:89]
	v_mfma_f32_16x16x32_bf16 v[82:85], v[154:157], v[178:181], v[82:85]
	v_mfma_f32_16x16x32_bf16 v[66:69], v[90:93], v[198:201], v[66:69]
	v_mfma_f32_16x16x32_bf16 v[58:61], v[154:157], v[198:201], v[58:61]
	v_mfma_f32_16x16x32_bf16 v[114:117], v[90:93], v[206:209], v[114:117]
	v_mfma_f32_16x16x32_bf16 v[110:113], v[154:157], v[206:209], v[110:113]
	v_mfma_f32_16x16x32_bf16 v[106:109], v[90:93], v[214:217], v[106:109]
	v_mfma_f32_16x16x32_bf16 v[102:105], v[154:157], v[214:217], v[102:105]
	s_setprio 0
	s_barrier
	s_add_i32 s64, s56, s47
	s_add_u32 s98, s36, 0x80
	s_addc_u32 s99, s37, 0
	s_mov_b32 m0, s64
	ds_read_b128 v[158:161], v23 offset:16384
	ds_read_b128 v[178:181], v23 offset:17408
	ds_read_b128 v[194:197], v23 offset:18432
	ds_read_b128 v[198:201], v23 offset:19456
	ds_read_b128 v[202:205], v23 offset:20480
	ds_read_b128 v[206:209], v23 offset:21504
	ds_read_b128 v[210:213], v23 offset:22528
	ds_read_b128 v[214:217], v23 offset:23552
	global_load_lds_dwordx4 v4, s[36:37]
	s_add_i32 m0, s64, 0x2000
	s_add_u32 s64, s36, 0x40000
	s_addc_u32 s65, s37, 0
	s_add_i32 s66, s57, s47
	global_load_lds_dwordx4 v8, s[36:37]
	s_mov_b32 m0, s66
	s_add_u32 s100, s38, 0x80
	s_addc_u32 s101, s39, 0
	global_load_lds_dwordx4 v4, s[64:65]
	s_add_i32 m0, s66, 0x2000
	s_nop 0
	global_load_lds_dwordx4 v8, s[64:65]
	s_mov_b32 m0, s48
	s_nop 0
	global_load_lds_dwordx4 v2, s[38:39]
	s_mov_b32 m0, s49
	s_nop 0
	global_load_lds_dwordx4 v6, s[38:39]
	s_waitcnt vmcnt(8)
	s_waitcnt lgkmcnt(0)
	s_barrier
; #define PG8_STAGE(bufoff, gbase, voff) do { _Pragma("unroll") for (int _i = 0; _i < 2; ++_i) \
;         __builtin_amdgcn_global_load_lds((const unsigned*)((const char*)(gbase) + (voff)[_i]), (PG8_LAS unsigned*)(lds + (bufoff) + ldsw + _i * 8192), 16, 0, 0); } while (0)
; #define PG8_LDA(dst, b, h) do { _Pragma("unroll") for (int m = 0; m < 4; ++m) _Pragma("unroll") for (int k = 0; k < 2; ++k) dst[m][k] = *(const PG8_LAS bf16x8*)(lds + PG8_SA(b, h) + aoff + m * 2048 + k * 1024); } while (0)
; #define PG8_LDB(dst, b, h) do { _Pragma("unroll") for (int n = 0; n < 2; ++n) _Pragma("unroll") for (int k = 0; k < 2; ++k) dst[n][k] = *(const PG8_LAS bf16x8*)(lds + PG8_SB(b, h) + boff + n * 2048 + k * 1024); } while (0)
; #define PG8_MMA(ai, bj, At, Bt) do { __builtin_amdgcn_s_setprio(1); _Pragma("unroll") for (int m = 0; m < 4; ++m) _Pragma("unroll") for (int n = 0; n < 2; ++n) _Pragma("unroll") for (int k = 0; k < 2; ++k) \
;         acc[ai][bj][m][n] = __builtin_amdgcn_mfma_f32_16x16x32_bf16(Bt[n][k], At[m][k], acc[ai][bj][m][n], 0, 0, 0); __builtin_amdgcn_s_setprio(0); } while (0)
; #define PG8_WAIT_V(n) asm volatile("s_waitcnt vmcnt(" #n ")" ::: "memory")
; #define PG8_WAIT_L(n) asm volatile("s_waitcnt lgkmcnt(" #n ")" ::: "memory")
; #define PG8_BAR __builtin_amdgcn_s_barrier()
; #define PG8_SCHED __builtin_amdgcn_sched_barrier(0)
; template <class Epi, class Sched, bool ALIGN_EPI = false, bool SP2 = false>
; __device__ __forceinline__ void gemm_phase(PG8_LAS unsigned char* lds, const Gemm g, const Sched& S, const Epi& E) {
;     ...
;             PG8_WAIT_V(8); PG8_WAIT_L(0); PG8_BAR; PG8_MMA(1, 0, At, B0); PG8_MMA(1, 1, At, B1); PG8_BAR; PG8_SCHED;
;             PG8_LDB(B0, 1, 0); PG8_LDB(B1, 1, 1); PG8_SCHED; PG8_LDA(At, 1, 0); PG8_STAGE(PG8_SA(0, 1), a2 + hstepA, voffA);
;             PG8_WAIT_V(8); PG8_WAIT_L(0); PG8_BAR; PG8_MMA(0, 0, At, B0); PG8_MMA(0, 1, At, B1); PG8_BAR; PG8_SCHED;
	s_setprio 1
	s_waitcnt lgkmcnt(0)
	v_mfma_f32_16x16x32_bf16 v[150:153], v[50:53], v[158:161], v[150:153]
	v_mfma_f32_16x16x32_bf16 v[146:149], v[70:73], v[158:161], v[146:149]
	v_mfma_f32_16x16x32_bf16 v[142:145], v[50:53], v[194:197], v[142:145]
	v_mfma_f32_16x16x32_bf16 v[138:141], v[70:73], v[194:197], v[138:141]
	v_mfma_f32_16x16x32_bf16 v[126:129], v[50:53], v[202:205], v[126:129]
	v_mfma_f32_16x16x32_bf16 v[98:101], v[70:73], v[202:205], v[98:101]
	v_mfma_f32_16x16x32_bf16 v[46:49], v[50:53], v[210:213], v[46:49]
	v_mfma_f32_16x16x32_bf16 v[42:45], v[70:73], v[210:213], v[42:45]
	v_mfma_f32_16x16x32_bf16 v[150:153], v[54:57], v[178:181], v[150:153]
	v_mfma_f32_16x16x32_bf16 v[146:149], v[74:77], v[178:181], v[146:149]
	v_mfma_f32_16x16x32_bf16 v[142:145], v[54:57], v[198:201], v[142:145]
	v_mfma_f32_16x16x32_bf16 v[138:141], v[74:77], v[198:201], v[138:141]
	v_mfma_f32_16x16x32_bf16 v[126:129], v[54:57], v[206:209], v[126:129]
	v_mfma_f32_16x16x32_bf16 v[98:101], v[74:77], v[206:209], v[98:101]
	v_mfma_f32_16x16x32_bf16 v[46:49], v[54:57], v[214:217], v[46:49]
	v_mfma_f32_16x16x32_bf16 v[42:45], v[74:77], v[214:217], v[42:45]
	v_mfma_f32_16x16x32_bf16 v[38:41], v[78:81], v[202:205], v[38:41]
	v_mfma_f32_16x16x32_bf16 v[34:37], v[94:97], v[202:205], v[34:37]
	v_mfma_f32_16x16x32_bf16 v[30:33], v[78:81], v[210:213], v[30:33]
	v_mfma_f32_16x16x32_bf16 v[24:27], v[94:97], v[210:213], v[26:29]
	v_mfma_f32_16x16x32_bf16 v[50:53], v[78:81], v[158:161], v[134:137]
	v_mfma_f32_16x16x32_bf16 v[54:57], v[94:97], v[158:161], v[130:133]
	v_mfma_f32_16x16x32_bf16 v[70:73], v[78:81], v[194:197], v[122:125]
	v_mfma_f32_16x16x32_bf16 v[74:77], v[94:97], v[194:197], v[118:121]
	v_mfma_f32_16x16x32_bf16 v[38:41], v[90:93], v[206:209], v[38:41]
	v_mfma_f32_16x16x32_bf16 v[34:37], v[154:157], v[206:209], v[34:37]
	v_mfma_f32_16x16x32_bf16 v[30:33], v[90:93], v[214:217], v[30:33]
	v_mfma_f32_16x16x32_bf16 v[24:27], v[154:157], v[214:217], v[24:27]
	v_mfma_f32_16x16x32_bf16 v[50:53], v[90:93], v[178:181], v[50:53]
	v_mfma_f32_16x16x32_bf16 v[54:57], v[154:157], v[178:181], v[54:57]
	v_mfma_f32_16x16x32_bf16 v[70:73], v[90:93], v[198:201], v[70:73]
	v_mfma_f32_16x16x32_bf16 v[74:77], v[154:157], v[198:201], v[74:77]
	s_setprio 0
	s_barrier
	s_add_i32 s64, 0, 0x18000
	v_add_u32_e32 v28, s64, v22
	s_add_i32 s65, 0, 0x1c000
	ds_read_b128 v[78:81], v28
	ds_read_b128 v[90:93], v28 offset:1024
	ds_read_b128 v[94:97], v28 offset:2048
	ds_read_b128 v[118:121], v28 offset:3072
	v_add_u32_e32 v28, s65, v22
	ds_read_b128 v[154:157], v28
	ds_read_b128 v[158:161], v28 offset:1024
	ds_read_b128 v[178:181], v28 offset:2048
	ds_read_b128 v[194:197], v28 offset:3072
	s_add_u32 s38, s38, 0x40000
	s_addc_u32 s39, s39, 0
	s_mov_b32 m0, s51
	ds_read_b128 v[122:125], v23 offset:32768
	ds_read_b128 v[130:133], v23 offset:33792
	ds_read_b128 v[134:137], v23 offset:34816
	ds_read_b128 v[198:201], v23 offset:35840
	ds_read_b128 v[202:205], v23 offset:36864
	ds_read_b128 v[206:209], v23 offset:37888
	ds_read_b128 v[210:213], v23 offset:38912
	ds_read_b128 v[214:217], v23 offset:39936
	global_load_lds_dwordx4 v2, s[38:39]
	s_mov_b32 m0, s52
	s_nop 0
	global_load_lds_dwordx4 v6, s[38:39]
	s_waitcnt vmcnt(8)
	s_waitcnt lgkmcnt(0)
	s_barrier
	s_setprio 1
	s_waitcnt lgkmcnt(0)
	v_mfma_f32_16x16x32_bf16 v[62:65], v[78:81], v[122:125], v[62:65]
	v_mfma_f32_16x16x32_bf16 v[170:173], v[94:97], v[122:125], v[170:173]
	v_mfma_f32_16x16x32_bf16 v[166:169], v[78:81], v[134:137], v[166:169]
	v_mfma_f32_16x16x32_bf16 v[162:165], v[94:97], v[134:137], v[162:165]
	v_mfma_f32_16x16x32_bf16 v[174:177], v[78:81], v[202:205], v[174:177]
	v_mfma_f32_16x16x32_bf16 v[190:193], v[94:97], v[202:205], v[190:193]
	v_mfma_f32_16x16x32_bf16 v[186:189], v[78:81], v[210:213], v[186:189]
	v_mfma_f32_16x16x32_bf16 v[182:185], v[94:97], v[210:213], v[182:185]
	v_mfma_f32_16x16x32_bf16 v[62:65], v[90:93], v[130:133], v[62:65]
	v_mfma_f32_16x16x32_bf16 v[170:173], v[118:121], v[130:133], v[170:173]
	v_mfma_f32_16x16x32_bf16 v[166:169], v[90:93], v[198:201], v[166:169]
	v_mfma_f32_16x16x32_bf16 v[162:165], v[118:121], v[198:201], v[162:165]
	v_mfma_f32_16x16x32_bf16 v[174:177], v[90:93], v[206:209], v[174:177]
	v_mfma_f32_16x16x32_bf16 v[190:193], v[118:121], v[206:209], v[190:193]
	v_mfma_f32_16x16x32_bf16 v[186:189], v[90:93], v[214:217], v[186:189]
	v_mfma_f32_16x16x32_bf16 v[182:185], v[118:121], v[214:217], v[182:185]
	v_mfma_f32_16x16x32_bf16 v[86:89], v[154:157], v[122:125], v[86:89]
	v_mfma_f32_16x16x32_bf16 v[82:85], v[178:181], v[122:125], v[82:85]
	v_mfma_f32_16x16x32_bf16 v[66:69], v[154:157], v[134:137], v[66:69]
	v_mfma_f32_16x16x32_bf16 v[58:61], v[178:181], v[134:137], v[58:61]
	v_mfma_f32_16x16x32_bf16 v[114:117], v[154:157], v[202:205], v[114:117]
	v_mfma_f32_16x16x32_bf16 v[110:113], v[178:181], v[202:205], v[110:113]
	v_mfma_f32_16x16x32_bf16 v[106:109], v[154:157], v[210:213], v[106:109]
	v_mfma_f32_16x16x32_bf16 v[102:105], v[178:181], v[210:213], v[102:105]
	v_mfma_f32_16x16x32_bf16 v[86:89], v[158:161], v[130:133], v[86:89]
	v_mfma_f32_16x16x32_bf16 v[82:85], v[194:197], v[130:133], v[82:85]
	v_mfma_f32_16x16x32_bf16 v[66:69], v[158:161], v[198:201], v[66:69]
	v_mfma_f32_16x16x32_bf16 v[58:61], v[194:197], v[198:201], v[58:61]
	v_mfma_f32_16x16x32_bf16 v[114:117], v[158:161], v[206:209], v[114:117]
	v_mfma_f32_16x16x32_bf16 v[110:113], v[194:197], v[206:209], v[110:113]
	v_mfma_f32_16x16x32_bf16 v[106:109], v[158:161], v[214:217], v[106:109]
	v_mfma_f32_16x16x32_bf16 v[102:105], v[194:197], v[214:217], v[102:105]
	s_setprio 0
	s_barrier
; #define PG8_STAGE(bufoff, gbase, voff) do { _Pragma("unroll") for (int _i = 0; _i < 2; ++_i) \
;         __builtin_amdgcn_global_load_lds((const unsigned*)((const char*)(gbase) + (voff)[_i]), (PG8_LAS unsigned*)(lds + (bufoff) + ldsw + _i * 8192), 16, 0, 0); } while (0)
; #define PG8_LDA(dst, b, h) do { _Pragma("unroll") for (int m = 0; m < 4; ++m) _Pragma("unroll") for (int k = 0; k < 2; ++k) dst[m][k] = *(const PG8_LAS bf16x8*)(lds + PG8_SA(b, h) + aoff + m * 2048 + k * 1024); } while (0)
; #define PG8_MMA(ai, bj, At, Bt) do { __builtin_amdgcn_s_setprio(1); _Pragma("unroll") for (int m = 0; m < 4; ++m) _Pragma("unroll") for (int n = 0; n < 2; ++n) _Pragma("unroll") for (int k = 0; k < 2; ++k) \
;         acc[ai][bj][m][n] = __builtin_amdgcn_mfma_f32_16x16x32_bf16(Bt[n][k], At[m][k], acc[ai][bj][m][n], 0, 0, 0); __builtin_amdgcn_s_setprio(0); } while (0)
; #define PG8_WAIT_V(n) asm volatile("s_waitcnt vmcnt(" #n ")" ::: "memory")
; #define PG8_WAIT_L(n) asm volatile("s_waitcnt lgkmcnt(" #n ")" ::: "memory")
; #define PG8_BAR __builtin_amdgcn_s_barrier()
; #define PG8_SCHED __builtin_amdgcn_sched_barrier(0)
; template <class Epi, class Sched, bool ALIGN_EPI = false, bool SP2 = false>
; __device__ __forceinline__ void gemm_phase(PG8_LAS unsigned char* lds, const Gemm g, const Sched& S, const Epi& E) {
;     ...
;         for (int t = 0; t < nt; t += 2) {
;     ...
;             PG8_LDA(At, 1, 1); PG8_STAGE(PG8_SB(1, 0), b3, voffB); PG8_STAGE(PG8_SB(1, 1), b3 + hstepB, voffB); PG8_STAGE(PG8_SA(1, 0), a3, voffA);
;             PG8_WAIT_V(8); PG8_WAIT_L(0); PG8_BAR; PG8_MMA(1, 0, At, B0); PG8_MMA(1, 1, At, B1); PG8_BAR; PG8_SCHED;
;     ...
; #pragma unroll
;         for (int a = 0; a < 2; ++a)
; #pragma unroll
;             for (int b = 0; b < 2; ++b)
; #pragma unroll
;                 for (int m = 0; m < 4; ++m)
; #pragma unroll
;                     for (int n = 0; n < 2; ++n) acc[a][b][m][n] = (f32x4){0.f, 0.f, 0.f, 0.f};
	s_add_i32 s38, s64, s47
	s_mov_b32 m0, s38
	ds_read_b128 v[122:125], v23 offset:49152
	ds_read_b128 v[130:133], v23 offset:50176
	ds_read_b128 v[198:201], v23 offset:51200
	ds_read_b128 v[202:205], v23 offset:52224
	ds_read_b128 v[206:209], v23 offset:53248
	ds_read_b128 v[210:213], v23 offset:54272
	ds_read_b128 v[214:217], v23 offset:55296
	ds_read_b128 v[218:221], v23 offset:56320
	global_load_lds_dwordx4 v4, s[98:99]
	s_add_i32 m0, s38, 0x2000
	s_add_u32 s36, s36, 0x40080
	s_addc_u32 s37, s37, 0
	s_add_i32 s38, s65, s47
	global_load_lds_dwordx4 v8, s[98:99]
	s_mov_b32 m0, s38
	s_nop 0
	global_load_lds_dwordx4 v4, s[36:37]
	s_add_i32 m0, s38, 0x2000
	s_nop 0
	global_load_lds_dwordx4 v8, s[36:37]
	s_mov_b32 m0, s54
	s_nop 0
	global_load_lds_dwordx4 v2, s[100:101]
	s_mov_b32 m0, s55
	s_nop 0
	global_load_lds_dwordx4 v6, s[100:101]
	s_waitcnt vmcnt(8)
	s_waitcnt lgkmcnt(0)
	s_barrier
	s_setprio 1
	s_waitcnt lgkmcnt(0)
	v_mfma_f32_16x16x32_bf16 v[134:137], v[78:81], v[122:125], v[150:153]
	v_mfma_f32_16x16x32_bf16 v[150:153], v[90:93], v[130:133], v[134:137]
	v_mfma_f32_16x16x32_bf16 v[134:137], v[94:97], v[122:125], v[146:149]
	v_mfma_f32_16x16x32_bf16 v[146:149], v[118:121], v[130:133], v[134:137]
	v_mfma_f32_16x16x32_bf16 v[134:137], v[78:81], v[198:201], v[142:145]
	v_mfma_f32_16x16x32_bf16 v[142:145], v[90:93], v[202:205], v[134:137]
	v_mfma_f32_16x16x32_bf16 v[134:137], v[94:97], v[198:201], v[138:141]
	v_mfma_f32_16x16x32_bf16 v[126:129], v[78:81], v[206:209], v[126:129]
	v_mfma_f32_16x16x32_bf16 v[98:101], v[94:97], v[206:209], v[98:101]
	v_mfma_f32_16x16x32_bf16 v[46:49], v[78:81], v[214:217], v[46:49]
	v_mfma_f32_16x16x32_bf16 v[42:45], v[94:97], v[214:217], v[42:45]
	v_mfma_f32_16x16x32_bf16 v[138:141], v[118:121], v[202:205], v[134:137]
	v_mfma_f32_16x16x32_bf16 v[126:129], v[90:93], v[210:213], v[126:129]
	v_mfma_f32_16x16x32_bf16 v[98:101], v[118:121], v[210:213], v[98:101]
	v_mfma_f32_16x16x32_bf16 v[46:49], v[90:93], v[218:221], v[46:49]
	v_mfma_f32_16x16x32_bf16 v[42:45], v[118:121], v[218:221], v[42:45]
	v_mfma_f32_16x16x32_bf16 v[50:53], v[154:157], v[122:125], v[50:53]
	v_mfma_f32_16x16x32_bf16 v[134:137], v[158:161], v[130:133], v[50:53]
	v_mfma_f32_16x16x32_bf16 v[50:53], v[178:181], v[122:125], v[54:57]
	v_mfma_f32_16x16x32_bf16 v[130:133], v[194:197], v[130:133], v[50:53]
	v_mfma_f32_16x16x32_bf16 v[50:53], v[154:157], v[198:201], v[70:73]
	v_mfma_f32_16x16x32_bf16 v[122:125], v[158:161], v[202:205], v[50:53]
	v_mfma_f32_16x16x32_bf16 v[50:53], v[178:181], v[198:201], v[74:77]
	v_mfma_f32_16x16x32_bf16 v[38:41], v[154:157], v[206:209], v[38:41]
	v_mfma_f32_16x16x32_bf16 v[34:37], v[178:181], v[206:209], v[34:37]
	v_mfma_f32_16x16x32_bf16 v[28:31], v[154:157], v[214:217], v[30:33]
	v_mfma_f32_16x16x32_bf16 v[24:27], v[178:181], v[214:217], v[24:27]
	v_mfma_f32_16x16x32_bf16 v[118:121], v[194:197], v[202:205], v[50:53]
	v_mfma_f32_16x16x32_bf16 v[38:41], v[158:161], v[210:213], v[38:41]
	v_mfma_f32_16x16x32_bf16 v[34:37], v[194:197], v[210:213], v[34:37]
	v_mfma_f32_16x16x32_bf16 v[30:33], v[158:161], v[218:221], v[28:31]
	v_mfma_f32_16x16x32_bf16 v[26:29], v[194:197], v[218:221], v[24:27]
	s_setprio 0
	s_barrier
	s_add_i32 s63, s63, 2
	s_add_u32 s34, s34, 0x100
	s_addc_u32 s35, s35, 0
	s_cmp_gt_u32 s63, 13
	s_cbranch_scc0 .LBB0_1269
	s_add_u32 s34, s59, 0xffffff00
	s_addc_u32 s35, s60, -1
	s_andn2_b64 vcc, exec, s[4:5]
	s_cbranch_vccnz .LBB0_1260
	v_mov_b32_e32 v26, 0
	s_mov_b32 s14, s24
	s_mov_b32 s12, s26
	s_mov_b64 s[20:21], s[30:31]
	s_mov_b32 s53, s58
	v_mov_b32_e32 v27, v26
	v_mov_b32_e32 v28, v26
	v_mov_b32_e32 v29, v26
	v_mov_b32_e32 v30, v26
	v_mov_b32_e32 v31, v26
	v_mov_b32_e32 v32, v26
	v_mov_b32_e32 v33, v26
	v_mov_b32_e32 v34, v26
	v_mov_b32_e32 v35, v26
	v_mov_b32_e32 v36, v26
	v_mov_b32_e32 v37, v26
	v_mov_b32_e32 v38, v26
	v_mov_b32_e32 v39, v26
	v_mov_b32_e32 v40, v26
	v_mov_b32_e32 v41, v26
	v_mov_b32_e32 v118, v26
	v_mov_b32_e32 v119, v26
	v_mov_b32_e32 v120, v26
	v_mov_b32_e32 v121, v26
	v_mov_b32_e32 v122, v26
	v_mov_b32_e32 v123, v26
	v_mov_b32_e32 v124, v26
	v_mov_b32_e32 v125, v26
	v_mov_b32_e32 v130, v26
	v_mov_b32_e32 v131, v26
	v_mov_b32_e32 v132, v26
	v_mov_b32_e32 v133, v26
	v_mov_b32_e32 v134, v26
	v_mov_b32_e32 v135, v26
	v_mov_b32_e32 v136, v26
	v_mov_b32_e32 v137, v26
	v_mov_b32_e32 v42, v26
	v_mov_b32_e32 v43, v26
	v_mov_b32_e32 v44, v26
	v_mov_b32_e32 v45, v26
	v_mov_b32_e32 v46, v26
	v_mov_b32_e32 v47, v26
	v_mov_b32_e32 v48, v26
	v_mov_b32_e32 v49, v26
	v_mov_b32_e32 v98, v26
	v_mov_b32_e32 v99, v26
	v_mov_b32_e32 v100, v26
	v_mov_b32_e32 v101, v26
	v_mov_b32_e32 v126, v26
	v_mov_b32_e32 v127, v26
	v_mov_b32_e32 v128, v26
	v_mov_b32_e32 v129, v26
	v_mov_b32_e32 v138, v26
	v_mov_b32_e32 v139, v26
	v_mov_b32_e32 v140, v26
	v_mov_b32_e32 v141, v26
	v_mov_b32_e32 v142, v26
	v_mov_b32_e32 v143, v26
	v_mov_b32_e32 v144, v26
	v_mov_b32_e32 v145, v26
	v_mov_b32_e32 v146, v26
	v_mov_b32_e32 v147, v26
	v_mov_b32_e32 v148, v26
	v_mov_b32_e32 v149, v26
	v_mov_b32_e32 v150, v26
	v_mov_b32_e32 v151, v26
	v_mov_b32_e32 v152, v26
	v_mov_b32_e32 v153, v26
	v_mov_b32_e32 v102, v26
	v_mov_b32_e32 v103, v26
	v_mov_b32_e32 v104, v26
	v_mov_b32_e32 v105, v26
	v_mov_b32_e32 v106, v26
	v_mov_b32_e32 v107, v26
	v_mov_b32_e32 v108, v26
	v_mov_b32_e32 v109, v26
	v_mov_b32_e32 v110, v26
	v_mov_b32_e32 v111, v26
	v_mov_b32_e32 v112, v26
	v_mov_b32_e32 v113, v26
	v_mov_b32_e32 v114, v26
	v_mov_b32_e32 v115, v26
	v_mov_b32_e32 v116, v26
	v_mov_b32_e32 v117, v26
	v_mov_b32_e32 v58, v26
	v_mov_b32_e32 v59, v26
	v_mov_b32_e32 v60, v26
	v_mov_b32_e32 v61, v26
	v_mov_b32_e32 v66, v26
	v_mov_b32_e32 v67, v26
	v_mov_b32_e32 v68, v26
	v_mov_b32_e32 v69, v26
	v_mov_b32_e32 v82, v26
	v_mov_b32_e32 v83, v26
	v_mov_b32_e32 v84, v26
	v_mov_b32_e32 v85, v26
	v_mov_b32_e32 v86, v26
	v_mov_b32_e32 v87, v26
	v_mov_b32_e32 v88, v26
	v_mov_b32_e32 v89, v26
	v_mov_b32_e32 v182, v26
	v_mov_b32_e32 v183, v26
	v_mov_b32_e32 v184, v26
	v_mov_b32_e32 v185, v26
	v_mov_b32_e32 v186, v26
	v_mov_b32_e32 v187, v26
	v_mov_b32_e32 v188, v26
	v_mov_b32_e32 v189, v26
	v_mov_b32_e32 v190, v26
	v_mov_b32_e32 v191, v26
	v_mov_b32_e32 v192, v26
	v_mov_b32_e32 v193, v26
	v_mov_b32_e32 v174, v26
	v_mov_b32_e32 v175, v26
	v_mov_b32_e32 v176, v26
	v_mov_b32_e32 v177, v26
	v_mov_b32_e32 v162, v26
	v_mov_b32_e32 v163, v26
	v_mov_b32_e32 v164, v26
	v_mov_b32_e32 v165, v26
	v_mov_b32_e32 v166, v26
	v_mov_b32_e32 v167, v26
	v_mov_b32_e32 v168, v26
	v_mov_b32_e32 v169, v26
	v_mov_b32_e32 v170, v26
	v_mov_b32_e32 v171, v26
	v_mov_b32_e32 v172, v26
	v_mov_b32_e32 v173, v26
	v_mov_b32_e32 v62, v26
	v_mov_b32_e32 v63, v26
	v_mov_b32_e32 v64, v26
	v_mov_b32_e32 v65, v26
	s_andn2_b64 vcc, exec, s[2:3]
	s_cbranch_vccnz .LBB0_1261

; #define PG8_STAGE(bufoff, gbase, voff) do { _Pragma("unroll") for (int _i = 0; _i < 2; ++_i) \
;         __builtin_amdgcn_global_load_lds((const unsigned*)((const char*)(gbase) + (voff)[_i]), (PG8_LAS unsigned*)(lds + (bufoff) + ldsw + _i * 8192), 16, 0, 0); } while (0)
; #define PG8_LDA(dst, b, h) do { _Pragma("unroll") for (int m = 0; m < 4; ++m) _Pragma("unroll") for (int k = 0; k < 2; ++k) dst[m][k] = *(const PG8_LAS bf16x8*)(lds + PG8_SA(b, h) + aoff + m * 2048 + k * 1024); } while (0)
; #define PG8_LDB(dst, b, h) do { _Pragma("unroll") for (int n = 0; n < 2; ++n) _Pragma("unroll") for (int k = 0; k < 2; ++k) dst[n][k] = *(const PG8_LAS bf16x8*)(lds + PG8_SB(b, h) + boff + n * 2048 + k * 1024); } while (0)
; #define PG8_MMA(ai, bj, At, Bt) do { __builtin_amdgcn_s_setprio(1); _Pragma("unroll") for (int m = 0; m < 4; ++m) _Pragma("unroll") for (int n = 0; n < 2; ++n) _Pragma("unroll") for (int k = 0; k < 2; ++k) \
;         acc[ai][bj][m][n] = __builtin_amdgcn_mfma_f32_16x16x32_bf16(Bt[n][k], At[m][k], acc[ai][bj][m][n], 0, 0, 0); __builtin_amdgcn_s_setprio(0); } while (0)
; #define PG8_WAIT_V(n) asm volatile("s_waitcnt vmcnt(" #n ")" ::: "memory")
; #define PG8_WAIT_L(n) asm volatile("s_waitcnt lgkmcnt(" #n ")" ::: "memory")
; #define PG8_BAR __builtin_amdgcn_s_barrier()
; #define PG8_SCHED __builtin_amdgcn_sched_barrier(0)
; template <class Epi, class Sched, bool ALIGN_EPI = false, bool SP2 = false>
; __device__ __forceinline__ void gemm_phase(PG8_LAS unsigned char* lds, const Gemm g, const Sched& S, const Epi& E) {
;     ...
;             PG8_LDB(B0, 0, 0); PG8_LDB(B1, 0, 1); PG8_SCHED; PG8_LDA(At, 0, 0); PG8_STAGE(PG8_SA(1, 1), a1 + hstepA, voffA);
;             PG8_WAIT_V(8); PG8_WAIT_L(0); PG8_BAR; PG8_MMA(0, 0, At, B0); PG8_MMA(0, 1, At, B1); PG8_BAR; PG8_SCHED;
;             PG8_LDA(At, 0, 1); PG8_STAGE(PG8_SB(0, 0), b2, voffB); PG8_STAGE(PG8_SB(0, 1), b2 + hstepB, voffB); PG8_STAGE(PG8_SA(0, 0), a2, voffA);
;             PG8_WAIT_V(8); PG8_WAIT_L(0); PG8_BAR; PG8_MMA(1, 0, At, B0); PG8_MMA(1, 1, At, B1); PG8_BAR; PG8_SCHED;
.LBB0_1324:
	s_add_u32 s37, s28, s36
	s_addc_u32 s42, s29, 0
	s_add_u32 s40, s37, 0x100
	s_addc_u32 s41, s42, 0
	s_and_b64 s[38:39], s[34:35], exec
	s_cselect_b32 s39, s17, s41
	s_cselect_b32 s38, s78, s40
	s_add_u32 s36, s26, s36
	s_addc_u32 s40, s27, 0
	s_add_u32 s36, s36, 0x100
	s_addc_u32 s40, s40, 0
	s_and_b64 s[34:35], s[34:35], exec
	s_cselect_b32 s41, s15, s40
	s_cselect_b32 s40, s79, s36
	s_add_u32 s44, s37, 0x40080
	ds_read_b128 v[130:133], v158
	ds_read_b128 v[134:137], v158 offset:1024
	ds_read_b128 v[138:141], v158 offset:2048
	ds_read_b128 v[142:145], v158 offset:3072
	ds_read_b128 v[152:155], v159
	ds_read_b128 v[162:165], v159 offset:1024
	ds_read_b128 v[166:169], v159 offset:2048
	ds_read_b128 v[170:173], v159 offset:3072
	s_addc_u32 s45, s42, 0
	s_add_i32 s87, s69, s56
	s_add_i32 m0, s25, 0xc000
	s_add_i32 s90, s25, 0xe000
	s_add_i32 s84, s87, 0x2000
	s_add_u32 s42, s40, 0x40000
	s_addc_u32 s43, s41, 0
	s_add_i32 s86, s70, s56
	s_add_i32 s85, s86, 0x2000
	s_add_i32 s83, 0, 0x18000
	s_add_i32 s82, 0, 0x1c000
	s_add_u32 s36, s38, 0x40000
	s_addc_u32 s37, s39, 0
	s_add_i32 s81, s83, s56
	s_add_i32 s80, s81, 0x2000
	s_add_u32 s34, s40, 0x40080
	s_addc_u32 s35, s41, 0
	s_add_i32 s89, s82, s56
	s_add_i32 s88, s89, 0x2000
	v_lshl_add_u64 v[206:207], s[44:45], 0, v[148:149]
	ds_read_b128 v[174:177], v160
	ds_read_b128 v[178:181], v160 offset:1024
	ds_read_b128 v[182:185], v160 offset:2048
	ds_read_b128 v[186:189], v160 offset:3072
	ds_read_b128 v[190:193], v160 offset:4096
	ds_read_b128 v[194:197], v160 offset:5120
	ds_read_b128 v[198:201], v160 offset:6144
	ds_read_b128 v[202:205], v160 offset:7168
	global_load_lds_dwordx4 v[206:207], off
	v_lshl_add_u64 v[206:207], s[44:45], 0, v[146:147]
	s_mov_b32 m0, s90
	s_nop 0
	global_load_lds_dwordx4 v[206:207], off
	s_waitcnt vmcnt(8)
	s_waitcnt lgkmcnt(0)
	s_barrier
	s_setprio 1
	s_waitcnt lgkmcnt(0)
	v_mfma_f32_16x16x32_bf16 v[126:129], v[130:133], v[174:177], v[126:129]
	v_mfma_f32_16x16x32_bf16 v[122:125], v[138:141], v[174:177], v[122:125]
	v_mfma_f32_16x16x32_bf16 v[118:121], v[130:133], v[182:185], v[118:121]
	v_mfma_f32_16x16x32_bf16 v[114:117], v[138:141], v[182:185], v[114:117]
	v_mfma_f32_16x16x32_bf16 v[102:105], v[130:133], v[190:193], v[102:105]
	v_mfma_f32_16x16x32_bf16 v[90:93], v[138:141], v[190:193], v[90:93]
	v_mfma_f32_16x16x32_bf16 v[82:85], v[130:133], v[198:201], v[82:85]
	v_mfma_f32_16x16x32_bf16 v[74:77], v[138:141], v[198:201], v[74:77]
	v_mfma_f32_16x16x32_bf16 v[126:129], v[134:137], v[178:181], v[126:129]
	v_mfma_f32_16x16x32_bf16 v[122:125], v[142:145], v[178:181], v[122:125]
	v_mfma_f32_16x16x32_bf16 v[118:121], v[134:137], v[186:189], v[118:121]
	v_mfma_f32_16x16x32_bf16 v[114:117], v[142:145], v[186:189], v[114:117]
	v_mfma_f32_16x16x32_bf16 v[102:105], v[134:137], v[194:197], v[102:105]
	v_mfma_f32_16x16x32_bf16 v[90:93], v[142:145], v[194:197], v[90:93]
	v_mfma_f32_16x16x32_bf16 v[82:85], v[134:137], v[202:205], v[82:85]
	v_mfma_f32_16x16x32_bf16 v[74:77], v[142:145], v[202:205], v[74:77]
	v_mfma_f32_16x16x32_bf16 v[110:113], v[152:155], v[174:177], v[110:113]
	v_mfma_f32_16x16x32_bf16 v[106:109], v[166:169], v[174:177], v[106:109]
	v_mfma_f32_16x16x32_bf16 v[98:101], v[152:155], v[182:185], v[98:101]
	v_mfma_f32_16x16x32_bf16 v[94:97], v[166:169], v[182:185], v[94:97]
	v_mfma_f32_16x16x32_bf16 v[86:89], v[152:155], v[190:193], v[86:89]
	v_mfma_f32_16x16x32_bf16 v[78:81], v[166:169], v[190:193], v[78:81]
	v_mfma_f32_16x16x32_bf16 v[70:73], v[152:155], v[198:201], v[70:73]
	v_mfma_f32_16x16x32_bf16 v[66:69], v[166:169], v[198:201], v[66:69]
	v_mfma_f32_16x16x32_bf16 v[110:113], v[162:165], v[178:181], v[110:113]
	v_mfma_f32_16x16x32_bf16 v[106:109], v[170:173], v[178:181], v[106:109]
	v_mfma_f32_16x16x32_bf16 v[98:101], v[162:165], v[186:189], v[98:101]
	v_mfma_f32_16x16x32_bf16 v[94:97], v[170:173], v[186:189], v[94:97]
	v_mfma_f32_16x16x32_bf16 v[86:89], v[162:165], v[194:197], v[86:89]
	v_mfma_f32_16x16x32_bf16 v[78:81], v[170:173], v[194:197], v[78:81]
	v_mfma_f32_16x16x32_bf16 v[70:73], v[162:165], v[202:205], v[70:73]
	v_mfma_f32_16x16x32_bf16 v[66:69], v[170:173], v[202:205], v[66:69]
	s_setprio 0
	s_barrier
	s_mov_b32 m0, s87
	v_lshl_add_u64 v[206:207], s[40:41], 0, v[148:149]
	ds_read_b128 v[174:177], v160 offset:16384
	ds_read_b128 v[178:181], v160 offset:17408
	ds_read_b128 v[182:185], v160 offset:18432
	ds_read_b128 v[186:189], v160 offset:19456
	ds_read_b128 v[190:193], v160 offset:20480
	ds_read_b128 v[194:197], v160 offset:21504
	ds_read_b128 v[198:201], v160 offset:22528
	ds_read_b128 v[202:205], v160 offset:23552
	global_load_lds_dwordx4 v[206:207], off
	v_lshl_add_u64 v[208:209], s[40:41], 0, v[146:147]
	s_mov_b32 m0, s84
	v_lshl_add_u64 v[210:211], s[42:43], 0, v[148:149]
	global_load_lds_dwordx4 v[208:209], off
	s_mov_b32 m0, s86
	v_lshl_add_u64 v[212:213], s[38:39], 0, v[146:147]
	global_load_lds_dwordx4 v[210:211], off
	v_lshl_add_u64 v[210:211], s[42:43], 0, v[146:147]
	s_mov_b32 m0, s85
	s_nop 0
	global_load_lds_dwordx4 v[210:211], off
	v_lshl_add_u64 v[210:211], s[38:39], 0, v[148:149]
	s_mov_b32 m0, s25
	s_nop 0
	global_load_lds_dwordx4 v[210:211], off
	s_mov_b32 m0, s58
	s_nop 0
	global_load_lds_dwordx4 v[212:213], off
	s_waitcnt vmcnt(8)
	s_waitcnt lgkmcnt(0)
	s_barrier
; #define PG8_STAGE(bufoff, gbase, voff) do { _Pragma("unroll") for (int _i = 0; _i < 2; ++_i) \
;         __builtin_amdgcn_global_load_lds((const unsigned*)((const char*)(gbase) + (voff)[_i]), (PG8_LAS unsigned*)(lds + (bufoff) + ldsw + _i * 8192), 16, 0, 0); } while (0)
; #define PG8_LDA(dst, b, h) do { _Pragma("unroll") for (int m = 0; m < 4; ++m) _Pragma("unroll") for (int k = 0; k < 2; ++k) dst[m][k] = *(const PG8_LAS bf16x8*)(lds + PG8_SA(b, h) + aoff + m * 2048 + k * 1024); } while (0)
; #define PG8_LDB(dst, b, h) do { _Pragma("unroll") for (int n = 0; n < 2; ++n) _Pragma("unroll") for (int k = 0; k < 2; ++k) dst[n][k] = *(const PG8_LAS bf16x8*)(lds + PG8_SB(b, h) + boff + n * 2048 + k * 1024); } while (0)
; #define PG8_MMA(ai, bj, At, Bt) do { __builtin_amdgcn_s_setprio(1); _Pragma("unroll") for (int m = 0; m < 4; ++m) _Pragma("unroll") for (int n = 0; n < 2; ++n) _Pragma("unroll") for (int k = 0; k < 2; ++k) \
;         acc[ai][bj][m][n] = __builtin_amdgcn_mfma_f32_16x16x32_bf16(Bt[n][k], At[m][k], acc[ai][bj][m][n], 0, 0, 0); __builtin_amdgcn_s_setprio(0); } while (0)
; #define PG8_WAIT_V(n) asm volatile("s_waitcnt vmcnt(" #n ")" ::: "memory")
; #define PG8_WAIT_L(n) asm volatile("s_waitcnt lgkmcnt(" #n ")" ::: "memory")
; #define PG8_BAR __builtin_amdgcn_s_barrier()
; #define PG8_SCHED __builtin_amdgcn_sched_barrier(0)
; template <class Epi, class Sched, bool ALIGN_EPI = false, bool SP2 = false>
; __device__ __forceinline__ void gemm_phase(PG8_LAS unsigned char* lds, const Gemm g, const Sched& S, const Epi& E) {
;     ...
;             PG8_WAIT_V(8); PG8_WAIT_L(0); PG8_BAR; PG8_MMA(1, 0, At, B0); PG8_MMA(1, 1, At, B1); PG8_BAR; PG8_SCHED;
;             PG8_LDB(B0, 1, 0); PG8_LDB(B1, 1, 1); PG8_SCHED; PG8_LDA(At, 1, 0); PG8_STAGE(PG8_SA(0, 1), a2 + hstepA, voffA);
;             PG8_WAIT_V(8); PG8_WAIT_L(0); PG8_BAR; PG8_MMA(0, 0, At, B0); PG8_MMA(0, 1, At, B1); PG8_BAR; PG8_SCHED;
	s_setprio 1
	s_waitcnt lgkmcnt(0)
	v_mfma_f32_16x16x32_bf16 v[62:65], v[130:133], v[174:177], v[62:65]
	v_mfma_f32_16x16x32_bf16 v[58:61], v[138:141], v[174:177], v[58:61]
	v_mfma_f32_16x16x32_bf16 v[54:57], v[130:133], v[182:185], v[54:57]
	v_mfma_f32_16x16x32_bf16 v[50:53], v[138:141], v[182:185], v[50:53]
	v_mfma_f32_16x16x32_bf16 v[46:49], v[130:133], v[190:193], v[46:49]
	v_mfma_f32_16x16x32_bf16 v[38:41], v[138:141], v[190:193], v[38:41]
	v_mfma_f32_16x16x32_bf16 v[18:21], v[130:133], v[198:201], v[18:21]
	v_mfma_f32_16x16x32_bf16 v[10:13], v[138:141], v[198:201], v[10:13]
	v_mfma_f32_16x16x32_bf16 v[62:65], v[134:137], v[178:181], v[62:65]
	v_mfma_f32_16x16x32_bf16 v[58:61], v[142:145], v[178:181], v[58:61]
	v_mfma_f32_16x16x32_bf16 v[54:57], v[134:137], v[186:189], v[54:57]
	v_mfma_f32_16x16x32_bf16 v[50:53], v[142:145], v[186:189], v[50:53]
	v_mfma_f32_16x16x32_bf16 v[46:49], v[134:137], v[194:197], v[46:49]
	v_mfma_f32_16x16x32_bf16 v[38:41], v[142:145], v[194:197], v[38:41]
	v_mfma_f32_16x16x32_bf16 v[18:21], v[134:137], v[202:205], v[18:21]
	v_mfma_f32_16x16x32_bf16 v[10:13], v[142:145], v[202:205], v[10:13]
	v_mfma_f32_16x16x32_bf16 v[42:45], v[152:155], v[174:177], v[42:45]
	v_mfma_f32_16x16x32_bf16 v[34:37], v[166:169], v[174:177], v[34:37]
	v_mfma_f32_16x16x32_bf16 v[30:33], v[152:155], v[182:185], v[30:33]
	v_mfma_f32_16x16x32_bf16 v[26:29], v[166:169], v[182:185], v[26:29]
	v_mfma_f32_16x16x32_bf16 v[22:25], v[152:155], v[190:193], v[22:25]
	v_mfma_f32_16x16x32_bf16 v[14:17], v[166:169], v[190:193], v[14:17]
	v_mfma_f32_16x16x32_bf16 v[6:9], v[152:155], v[198:201], v[6:9]
	v_mfma_f32_16x16x32_bf16 v[2:5], v[166:169], v[198:201], v[2:5]
	v_mfma_f32_16x16x32_bf16 v[42:45], v[162:165], v[178:181], v[42:45]
	v_mfma_f32_16x16x32_bf16 v[34:37], v[170:173], v[178:181], v[34:37]
	v_mfma_f32_16x16x32_bf16 v[30:33], v[162:165], v[186:189], v[30:33]
	v_mfma_f32_16x16x32_bf16 v[26:29], v[170:173], v[186:189], v[26:29]
	v_mfma_f32_16x16x32_bf16 v[22:25], v[162:165], v[194:197], v[22:25]
	v_mfma_f32_16x16x32_bf16 v[14:17], v[170:173], v[194:197], v[14:17]
	v_mfma_f32_16x16x32_bf16 v[6:9], v[162:165], v[202:205], v[6:9]
	v_mfma_f32_16x16x32_bf16 v[2:5], v[170:173], v[202:205], v[2:5]
	s_setprio 0
	s_barrier
	v_add_u32_e32 v142, s83, v1
	v_add_u32_e32 v170, s82, v1
	ds_read_b128 v[130:133], v142
	ds_read_b128 v[134:137], v142 offset:1024
	ds_read_b128 v[138:141], v142 offset:2048
	ds_read_b128 v[142:145], v142 offset:3072
	ds_read_b128 v[152:155], v170
	ds_read_b128 v[162:165], v170 offset:1024
	ds_read_b128 v[166:169], v170 offset:2048
	ds_read_b128 v[170:173], v170 offset:3072
	s_mov_b32 m0, s59
	v_lshl_add_u64 v[214:215], s[36:37], 0, v[148:149]
	ds_read_b128 v[174:177], v160 offset:32768
	ds_read_b128 v[178:181], v160 offset:33792
	ds_read_b128 v[182:185], v160 offset:34816
	ds_read_b128 v[186:189], v160 offset:35840
	ds_read_b128 v[190:193], v160 offset:36864
	ds_read_b128 v[194:197], v160 offset:37888
	ds_read_b128 v[198:201], v160 offset:38912
	ds_read_b128 v[202:205], v160 offset:39936
	global_load_lds_dwordx4 v[214:215], off
	v_lshl_add_u64 v[214:215], s[36:37], 0, v[146:147]
	s_mov_b32 m0, s60
	s_nop 0
	global_load_lds_dwordx4 v[214:215], off
	s_waitcnt vmcnt(8)
	s_waitcnt lgkmcnt(0)
	s_barrier
	s_setprio 1
	s_waitcnt lgkmcnt(0)
	v_mfma_f32_16x16x32_bf16 v[126:129], v[130:133], v[174:177], v[126:129]
	v_mfma_f32_16x16x32_bf16 v[122:125], v[138:141], v[174:177], v[122:125]
	v_mfma_f32_16x16x32_bf16 v[118:121], v[130:133], v[182:185], v[118:121]
	v_mfma_f32_16x16x32_bf16 v[114:117], v[138:141], v[182:185], v[114:117]
	v_mfma_f32_16x16x32_bf16 v[102:105], v[130:133], v[190:193], v[102:105]
	v_mfma_f32_16x16x32_bf16 v[90:93], v[138:141], v[190:193], v[90:93]
	v_mfma_f32_16x16x32_bf16 v[82:85], v[130:133], v[198:201], v[82:85]
	v_mfma_f32_16x16x32_bf16 v[74:77], v[138:141], v[198:201], v[74:77]
	v_mfma_f32_16x16x32_bf16 v[126:129], v[134:137], v[178:181], v[126:129]
	v_mfma_f32_16x16x32_bf16 v[122:125], v[142:145], v[178:181], v[122:125]
	v_mfma_f32_16x16x32_bf16 v[118:121], v[134:137], v[186:189], v[118:121]
	v_mfma_f32_16x16x32_bf16 v[114:117], v[142:145], v[186:189], v[114:117]
	v_mfma_f32_16x16x32_bf16 v[102:105], v[134:137], v[194:197], v[102:105]
	v_mfma_f32_16x16x32_bf16 v[90:93], v[142:145], v[194:197], v[90:93]
	v_mfma_f32_16x16x32_bf16 v[82:85], v[134:137], v[202:205], v[82:85]
	v_mfma_f32_16x16x32_bf16 v[74:77], v[142:145], v[202:205], v[74:77]
	v_mfma_f32_16x16x32_bf16 v[110:113], v[152:155], v[174:177], v[110:113]
	v_mfma_f32_16x16x32_bf16 v[106:109], v[166:169], v[174:177], v[106:109]
	v_mfma_f32_16x16x32_bf16 v[98:101], v[152:155], v[182:185], v[98:101]
	v_mfma_f32_16x16x32_bf16 v[94:97], v[166:169], v[182:185], v[94:97]
	v_mfma_f32_16x16x32_bf16 v[86:89], v[152:155], v[190:193], v[86:89]
	v_mfma_f32_16x16x32_bf16 v[78:81], v[166:169], v[190:193], v[78:81]
	v_mfma_f32_16x16x32_bf16 v[70:73], v[152:155], v[198:201], v[70:73]
	v_mfma_f32_16x16x32_bf16 v[66:69], v[166:169], v[198:201], v[66:69]
	v_mfma_f32_16x16x32_bf16 v[110:113], v[162:165], v[178:181], v[110:113]
	v_mfma_f32_16x16x32_bf16 v[106:109], v[170:173], v[178:181], v[106:109]
	v_mfma_f32_16x16x32_bf16 v[98:101], v[162:165], v[186:189], v[98:101]
	v_mfma_f32_16x16x32_bf16 v[94:97], v[170:173], v[186:189], v[94:97]
	v_mfma_f32_16x16x32_bf16 v[86:89], v[162:165], v[194:197], v[86:89]
	v_mfma_f32_16x16x32_bf16 v[78:81], v[170:173], v[194:197], v[78:81]
	v_mfma_f32_16x16x32_bf16 v[70:73], v[162:165], v[202:205], v[70:73]
	v_mfma_f32_16x16x32_bf16 v[66:69], v[170:173], v[202:205], v[66:69]
	s_setprio 0
	s_barrier
; #define PG8_STAGE(bufoff, gbase, voff) do { _Pragma("unroll") for (int _i = 0; _i < 2; ++_i) \
;         __builtin_amdgcn_global_load_lds((const unsigned*)((const char*)(gbase) + (voff)[_i]), (PG8_LAS unsigned*)(lds + (bufoff) + ldsw + _i * 8192), 16, 0, 0); } while (0)
; #define PG8_LDA(dst, b, h) do { _Pragma("unroll") for (int m = 0; m < 4; ++m) _Pragma("unroll") for (int k = 0; k < 2; ++k) dst[m][k] = *(const PG8_LAS bf16x8*)(lds + PG8_SA(b, h) + aoff + m * 2048 + k * 1024); } while (0)
; #define PG8_MMA(ai, bj, At, Bt) do { __builtin_amdgcn_s_setprio(1); _Pragma("unroll") for (int m = 0; m < 4; ++m) _Pragma("unroll") for (int n = 0; n < 2; ++n) _Pragma("unroll") for (int k = 0; k < 2; ++k) \
;         acc[ai][bj][m][n] = __builtin_amdgcn_mfma_f32_16x16x32_bf16(Bt[n][k], At[m][k], acc[ai][bj][m][n], 0, 0, 0); __builtin_amdgcn_s_setprio(0); } while (0)
; #define PG8_WAIT_V(n) asm volatile("s_waitcnt vmcnt(" #n ")" ::: "memory")
; #define PG8_WAIT_L(n) asm volatile("s_waitcnt lgkmcnt(" #n ")" ::: "memory")
; #define PG8_BAR __builtin_amdgcn_s_barrier()
; #define PG8_SCHED __builtin_amdgcn_sched_barrier(0)
; template <class Epi, class Sched, bool ALIGN_EPI = false, bool SP2 = false>
; __device__ __forceinline__ void gemm_phase(PG8_LAS unsigned char* lds, const Gemm g, const Sched& S, const Epi& E) {
;     ...
;         for (int t = 0; t < nt; t += 2) {
;     ...
;             PG8_LDA(At, 1, 1); PG8_STAGE(PG8_SB(1, 0), b3, voffB); PG8_STAGE(PG8_SB(1, 1), b3 + hstepB, voffB); PG8_STAGE(PG8_SA(1, 0), a3, voffA);
;             PG8_WAIT_V(8); PG8_WAIT_L(0); PG8_BAR; PG8_MMA(1, 0, At, B0); PG8_MMA(1, 1, At, B1); PG8_BAR; PG8_SCHED;
	s_mov_b32 m0, s81
	v_lshl_add_u64 v[206:207], v[206:207], 0, s[4:5]
	ds_read_b128 v[174:177], v160 offset:49152
	ds_read_b128 v[178:181], v160 offset:50176
	ds_read_b128 v[182:185], v160 offset:51200
	ds_read_b128 v[186:189], v160 offset:52224
	ds_read_b128 v[190:193], v160 offset:53248
	ds_read_b128 v[194:197], v160 offset:54272
	ds_read_b128 v[198:201], v160 offset:55296
	ds_read_b128 v[202:205], v160 offset:56320
	global_load_lds_dwordx4 v[206:207], off
	v_lshl_add_u64 v[206:207], v[208:209], 0, s[4:5]
	s_mov_b32 m0, s80
	s_nop 0
	global_load_lds_dwordx4 v[206:207], off
	v_lshl_add_u64 v[206:207], s[34:35], 0, v[148:149]
	s_mov_b32 m0, s89
	s_nop 0
	global_load_lds_dwordx4 v[206:207], off
	v_lshl_add_u64 v[206:207], s[34:35], 0, v[146:147]
	s_mov_b32 m0, s88
	s_nop 0
	global_load_lds_dwordx4 v[206:207], off
	v_lshl_add_u64 v[206:207], v[210:211], 0, s[4:5]
	s_mov_b32 m0, s66
	s_nop 0
	global_load_lds_dwordx4 v[206:207], off
	v_lshl_add_u64 v[206:207], v[212:213], 0, s[4:5]
	s_mov_b32 m0, s67
	s_nop 0
	global_load_lds_dwordx4 v[206:207], off
	s_waitcnt vmcnt(8)
	s_waitcnt lgkmcnt(0)
	s_barrier
	s_setprio 1
	s_waitcnt lgkmcnt(0)
	v_mfma_f32_16x16x32_bf16 v[62:65], v[130:133], v[174:177], v[62:65]
	v_mfma_f32_16x16x32_bf16 v[58:61], v[138:141], v[174:177], v[58:61]
	v_mfma_f32_16x16x32_bf16 v[54:57], v[130:133], v[182:185], v[54:57]
	v_mfma_f32_16x16x32_bf16 v[50:53], v[138:141], v[182:185], v[50:53]
	v_mfma_f32_16x16x32_bf16 v[46:49], v[130:133], v[190:193], v[46:49]
	v_mfma_f32_16x16x32_bf16 v[38:41], v[138:141], v[190:193], v[38:41]
	v_mfma_f32_16x16x32_bf16 v[18:21], v[130:133], v[198:201], v[18:21]
	v_mfma_f32_16x16x32_bf16 v[10:13], v[138:141], v[198:201], v[10:13]
	v_mfma_f32_16x16x32_bf16 v[62:65], v[134:137], v[178:181], v[62:65]
	v_mfma_f32_16x16x32_bf16 v[58:61], v[142:145], v[178:181], v[58:61]
	v_mfma_f32_16x16x32_bf16 v[54:57], v[134:137], v[186:189], v[54:57]
	v_mfma_f32_16x16x32_bf16 v[50:53], v[142:145], v[186:189], v[50:53]
	v_mfma_f32_16x16x32_bf16 v[46:49], v[134:137], v[194:197], v[46:49]
	v_mfma_f32_16x16x32_bf16 v[38:41], v[142:145], v[194:197], v[38:41]
	v_mfma_f32_16x16x32_bf16 v[18:21], v[134:137], v[202:205], v[18:21]
	v_mfma_f32_16x16x32_bf16 v[10:13], v[142:145], v[202:205], v[10:13]
	v_mfma_f32_16x16x32_bf16 v[42:45], v[152:155], v[174:177], v[42:45]
	v_mfma_f32_16x16x32_bf16 v[34:37], v[166:169], v[174:177], v[34:37]
	v_mfma_f32_16x16x32_bf16 v[30:33], v[152:155], v[182:185], v[30:33]
	v_mfma_f32_16x16x32_bf16 v[26:29], v[166:169], v[182:185], v[26:29]
	v_mfma_f32_16x16x32_bf16 v[22:25], v[152:155], v[190:193], v[22:25]
	v_mfma_f32_16x16x32_bf16 v[14:17], v[166:169], v[190:193], v[14:17]
	v_mfma_f32_16x16x32_bf16 v[6:9], v[152:155], v[198:201], v[6:9]
	v_mfma_f32_16x16x32_bf16 v[2:5], v[166:169], v[198:201], v[2:5]
	v_mfma_f32_16x16x32_bf16 v[42:45], v[162:165], v[178:181], v[42:45]
	v_mfma_f32_16x16x32_bf16 v[34:37], v[170:173], v[178:181], v[34:37]
	v_mfma_f32_16x16x32_bf16 v[30:33], v[162:165], v[186:189], v[30:33]
	v_mfma_f32_16x16x32_bf16 v[26:29], v[170:173], v[186:189], v[26:29]
	v_mfma_f32_16x16x32_bf16 v[22:25], v[162:165], v[194:197], v[22:25]
	v_mfma_f32_16x16x32_bf16 v[14:17], v[170:173], v[194:197], v[14:17]
	v_mfma_f32_16x16x32_bf16 v[6:9], v[162:165], v[202:205], v[6:9]
	v_mfma_f32_16x16x32_bf16 v[2:5], v[170:173], v[202:205], v[2:5]
	s_setprio 0
	s_barrier
	s_movk_i32 s36, 0x100
	s_andn2_b64 vcc, exec, s[30:31]
	s_mov_b64 s[34:35], -1
	s_mov_b64 s[30:31], 0
	s_cbranch_vccz .LBB0_1324
	s_and_b64 vcc, exec, s[8:9]
	s_cbranch_vccz .LBB0_1327
	s_barrier

; #define PG8_STAGE(bufoff, gbase, voff) do { _Pragma("unroll") for (int _i = 0; _i < 2; ++_i) \
;         __builtin_amdgcn_global_load_lds((const unsigned*)((const char*)(gbase) + (voff)[_i]), (PG8_LAS unsigned*)(lds + (bufoff) + ldsw + _i * 8192), 16, 0, 0); } while (0)
; #define PG8_LDA(dst, b, h) do { _Pragma("unroll") for (int m = 0; m < 4; ++m) _Pragma("unroll") for (int k = 0; k < 2; ++k) dst[m][k] = *(const PG8_LAS bf16x8*)(lds + PG8_SA(b, h) + aoff + m * 2048 + k * 1024); } while (0)
; #define PG8_LDB(dst, b, h) do { _Pragma("unroll") for (int n = 0; n < 2; ++n) _Pragma("unroll") for (int k = 0; k < 2; ++k) dst[n][k] = *(const PG8_LAS bf16x8*)(lds + PG8_SB(b, h) + boff + n * 2048 + k * 1024); } while (0)
; #define PG8_MMA(ai, bj, At, Bt) do { __builtin_amdgcn_s_setprio(1); _Pragma("unroll") for (int m = 0; m < 4; ++m) _Pragma("unroll") for (int n = 0; n < 2; ++n) _Pragma("unroll") for (int k = 0; k < 2; ++k) \
;         acc[ai][bj][m][n] = __builtin_amdgcn_mfma_f32_16x16x32_bf16(Bt[n][k], At[m][k], acc[ai][bj][m][n], 0, 0, 0); __builtin_amdgcn_s_setprio(0); } while (0)
; #define PG8_WAIT_V(n) asm volatile("s_waitcnt vmcnt(" #n ")" ::: "memory")
; #define PG8_WAIT_L(n) asm volatile("s_waitcnt lgkmcnt(" #n ")" ::: "memory")
; #define PG8_BAR __builtin_amdgcn_s_barrier()
; #define PG8_SCHED __builtin_amdgcn_sched_barrier(0)
; template <class Epi, class Sched, bool ALIGN_EPI = false, bool SP2 = false>
; __device__ __forceinline__ void gemm_phase(PG8_LAS unsigned char* lds, const Gemm g, const Sched& S, const Epi& E) {
;     ...
;             PG8_LDB(B0, 0, 0); PG8_LDB(B1, 0, 1); PG8_SCHED; PG8_LDA(At, 0, 0); PG8_STAGE(PG8_SA(1, 1), a1 + hstepA, voffA);
;             PG8_WAIT_V(8); PG8_WAIT_L(0); PG8_BAR; PG8_MMA(0, 0, At, B0); PG8_MMA(0, 1, At, B1); PG8_BAR; PG8_SCHED;
;             PG8_LDA(At, 0, 1); PG8_STAGE(PG8_SB(0, 0), b2, voffB); PG8_STAGE(PG8_SB(0, 1), b2 + hstepB, voffB); PG8_STAGE(PG8_SA(0, 0), a2, voffA);
;             PG8_WAIT_V(8); PG8_WAIT_L(0); PG8_BAR; PG8_MMA(1, 0, At, B0); PG8_MMA(1, 1, At, B1); PG8_BAR; PG8_SCHED;
.LBB0_1344:
	s_add_u32 s72, s28, s71
	ds_read_b128 v[130:133], v158
	ds_read_b128 v[134:137], v158 offset:1024
	ds_read_b128 v[138:141], v158 offset:2048
	ds_read_b128 v[142:145], v158 offset:3072
	ds_read_b128 v[152:155], v159
	ds_read_b128 v[162:165], v159 offset:1024
	ds_read_b128 v[166:169], v159 offset:2048
	ds_read_b128 v[170:173], v159 offset:3072
	s_addc_u32 s73, s29, 0
	s_add_u32 s74, s72, 0x100
	s_addc_u32 s75, s73, 0
	s_and_b64 s[36:37], s[34:35], exec
	s_cselect_b32 s37, s17, s75
	s_cselect_b32 s36, s69, s74
	s_add_u32 s71, s26, s71
	s_addc_u32 s74, s27, 0
	s_add_u32 s71, s71, 0x100
	s_addc_u32 s74, s74, 0
	s_and_b64 s[34:35], s[34:35], exec
	s_cselect_b32 s35, s15, s74
	s_cselect_b32 s34, s70, s71
	s_add_u32 s72, s72, 0x40080
	s_addc_u32 s73, s73, 0
	v_lshl_add_u64 v[206:207], s[72:73], 0, v[148:149]
	s_add_i32 m0, s49, 0xc000
	ds_read_b128 v[174:177], v160
	ds_read_b128 v[178:181], v160 offset:1024
	ds_read_b128 v[182:185], v160 offset:2048
	ds_read_b128 v[186:189], v160 offset:3072
	ds_read_b128 v[190:193], v160 offset:4096
	ds_read_b128 v[194:197], v160 offset:5120
	ds_read_b128 v[198:201], v160 offset:6144
	ds_read_b128 v[202:205], v160 offset:7168
	global_load_lds_dwordx4 v[206:207], off
	v_lshl_add_u64 v[206:207], s[72:73], 0, v[146:147]
	s_add_i32 m0, s49, 0xe000
	s_nop 0
	global_load_lds_dwordx4 v[206:207], off
	s_waitcnt vmcnt(8)
	s_waitcnt lgkmcnt(0)
	s_barrier
	s_setprio 1
	s_waitcnt lgkmcnt(0)
	v_mfma_f32_16x16x32_bf16 v[126:129], v[130:133], v[174:177], v[126:129]
	v_mfma_f32_16x16x32_bf16 v[122:125], v[138:141], v[174:177], v[122:125]
	v_mfma_f32_16x16x32_bf16 v[118:121], v[130:133], v[182:185], v[118:121]
	v_mfma_f32_16x16x32_bf16 v[114:117], v[138:141], v[182:185], v[114:117]
	v_mfma_f32_16x16x32_bf16 v[102:105], v[130:133], v[190:193], v[102:105]
	v_mfma_f32_16x16x32_bf16 v[90:93], v[138:141], v[190:193], v[90:93]
	v_mfma_f32_16x16x32_bf16 v[82:85], v[130:133], v[198:201], v[82:85]
	v_mfma_f32_16x16x32_bf16 v[74:77], v[138:141], v[198:201], v[74:77]
	v_mfma_f32_16x16x32_bf16 v[126:129], v[134:137], v[178:181], v[126:129]
	v_mfma_f32_16x16x32_bf16 v[122:125], v[142:145], v[178:181], v[122:125]
	v_mfma_f32_16x16x32_bf16 v[118:121], v[134:137], v[186:189], v[118:121]
	v_mfma_f32_16x16x32_bf16 v[114:117], v[142:145], v[186:189], v[114:117]
	v_mfma_f32_16x16x32_bf16 v[102:105], v[134:137], v[194:197], v[102:105]
	v_mfma_f32_16x16x32_bf16 v[90:93], v[142:145], v[194:197], v[90:93]
	v_mfma_f32_16x16x32_bf16 v[82:85], v[134:137], v[202:205], v[82:85]
	v_mfma_f32_16x16x32_bf16 v[74:77], v[142:145], v[202:205], v[74:77]
	v_mfma_f32_16x16x32_bf16 v[110:113], v[152:155], v[174:177], v[110:113]
	v_mfma_f32_16x16x32_bf16 v[106:109], v[166:169], v[174:177], v[106:109]
	v_mfma_f32_16x16x32_bf16 v[98:101], v[152:155], v[182:185], v[98:101]
	v_mfma_f32_16x16x32_bf16 v[94:97], v[166:169], v[182:185], v[94:97]
	v_mfma_f32_16x16x32_bf16 v[86:89], v[152:155], v[190:193], v[86:89]
	v_mfma_f32_16x16x32_bf16 v[78:81], v[166:169], v[190:193], v[78:81]
	v_mfma_f32_16x16x32_bf16 v[70:73], v[152:155], v[198:201], v[70:73]
	v_mfma_f32_16x16x32_bf16 v[66:69], v[166:169], v[198:201], v[66:69]
	v_mfma_f32_16x16x32_bf16 v[110:113], v[162:165], v[178:181], v[110:113]
	v_mfma_f32_16x16x32_bf16 v[106:109], v[170:173], v[178:181], v[106:109]
	v_mfma_f32_16x16x32_bf16 v[98:101], v[162:165], v[186:189], v[98:101]
	v_mfma_f32_16x16x32_bf16 v[94:97], v[170:173], v[186:189], v[94:97]
	v_mfma_f32_16x16x32_bf16 v[86:89], v[162:165], v[194:197], v[86:89]
	v_mfma_f32_16x16x32_bf16 v[78:81], v[170:173], v[194:197], v[78:81]
	v_mfma_f32_16x16x32_bf16 v[70:73], v[162:165], v[202:205], v[70:73]
	v_mfma_f32_16x16x32_bf16 v[66:69], v[170:173], v[202:205], v[66:69]
	s_setprio 0
	s_barrier
	s_add_i32 s71, s61, s45
	v_lshl_add_u64 v[206:207], s[34:35], 0, v[148:149]
	s_mov_b32 m0, s71
	ds_read_b128 v[174:177], v160 offset:16384
	ds_read_b128 v[178:181], v160 offset:17408
	ds_read_b128 v[182:185], v160 offset:18432
	ds_read_b128 v[186:189], v160 offset:19456
	ds_read_b128 v[190:193], v160 offset:20480
	ds_read_b128 v[194:197], v160 offset:21504
	ds_read_b128 v[198:201], v160 offset:22528
	ds_read_b128 v[202:205], v160 offset:23552
	global_load_lds_dwordx4 v[206:207], off
	s_add_i32 m0, s71, 0x2000
	s_add_u32 s72, s34, 0x40000
	v_lshl_add_u64 v[208:209], s[34:35], 0, v[146:147]
	s_addc_u32 s73, s35, 0
	s_add_i32 s71, s62, s45
	global_load_lds_dwordx4 v[208:209], off
	v_lshl_add_u64 v[210:211], s[72:73], 0, v[148:149]
	s_mov_b32 m0, s71
	v_lshl_add_u64 v[212:213], s[36:37], 0, v[146:147]
	global_load_lds_dwordx4 v[210:211], off
	v_lshl_add_u64 v[210:211], s[72:73], 0, v[146:147]
	s_add_i32 m0, s71, 0x2000
	s_nop 0
	global_load_lds_dwordx4 v[210:211], off
	v_lshl_add_u64 v[210:211], s[36:37], 0, v[148:149]
	s_mov_b32 m0, s49
	s_nop 0
	global_load_lds_dwordx4 v[210:211], off
	s_mov_b32 m0, s50
	s_nop 0
	global_load_lds_dwordx4 v[212:213], off
	s_waitcnt vmcnt(8)
	s_waitcnt lgkmcnt(0)
	s_barrier
; #define PG8_STAGE(bufoff, gbase, voff) do { _Pragma("unroll") for (int _i = 0; _i < 2; ++_i) \
;         __builtin_amdgcn_global_load_lds((const unsigned*)((const char*)(gbase) + (voff)[_i]), (PG8_LAS unsigned*)(lds + (bufoff) + ldsw + _i * 8192), 16, 0, 0); } while (0)
; #define PG8_LDA(dst, b, h) do { _Pragma("unroll") for (int m = 0; m < 4; ++m) _Pragma("unroll") for (int k = 0; k < 2; ++k) dst[m][k] = *(const PG8_LAS bf16x8*)(lds + PG8_SA(b, h) + aoff + m * 2048 + k * 1024); } while (0)
; #define PG8_LDB(dst, b, h) do { _Pragma("unroll") for (int n = 0; n < 2; ++n) _Pragma("unroll") for (int k = 0; k < 2; ++k) dst[n][k] = *(const PG8_LAS bf16x8*)(lds + PG8_SB(b, h) + boff + n * 2048 + k * 1024); } while (0)
; #define PG8_MMA(ai, bj, At, Bt) do { __builtin_amdgcn_s_setprio(1); _Pragma("unroll") for (int m = 0; m < 4; ++m) _Pragma("unroll") for (int n = 0; n < 2; ++n) _Pragma("unroll") for (int k = 0; k < 2; ++k) \
;         acc[ai][bj][m][n] = __builtin_amdgcn_mfma_f32_16x16x32_bf16(Bt[n][k], At[m][k], acc[ai][bj][m][n], 0, 0, 0); __builtin_amdgcn_s_setprio(0); } while (0)
; #define PG8_WAIT_V(n) asm volatile("s_waitcnt vmcnt(" #n ")" ::: "memory")
; #define PG8_WAIT_L(n) asm volatile("s_waitcnt lgkmcnt(" #n ")" ::: "memory")
; #define PG8_BAR __builtin_amdgcn_s_barrier()
; #define PG8_SCHED __builtin_amdgcn_sched_barrier(0)
; template <class Epi, class Sched, bool ALIGN_EPI = false, bool SP2 = false>
; __device__ __forceinline__ void gemm_phase(PG8_LAS unsigned char* lds, const Gemm g, const Sched& S, const Epi& E) {
;     ...
;             PG8_WAIT_V(8); PG8_WAIT_L(0); PG8_BAR; PG8_MMA(1, 0, At, B0); PG8_MMA(1, 1, At, B1); PG8_BAR; PG8_SCHED;
;             PG8_LDB(B0, 1, 0); PG8_LDB(B1, 1, 1); PG8_SCHED; PG8_LDA(At, 1, 0); PG8_STAGE(PG8_SA(0, 1), a2 + hstepA, voffA);
;             PG8_WAIT_V(8); PG8_WAIT_L(0); PG8_BAR; PG8_MMA(0, 0, At, B0); PG8_MMA(0, 1, At, B1); PG8_BAR; PG8_SCHED;
	s_setprio 1
	s_waitcnt lgkmcnt(0)
	v_mfma_f32_16x16x32_bf16 v[62:65], v[130:133], v[174:177], v[62:65]
	v_mfma_f32_16x16x32_bf16 v[58:61], v[138:141], v[174:177], v[58:61]
	v_mfma_f32_16x16x32_bf16 v[54:57], v[130:133], v[182:185], v[54:57]
	v_mfma_f32_16x16x32_bf16 v[50:53], v[138:141], v[182:185], v[50:53]
	v_mfma_f32_16x16x32_bf16 v[46:49], v[130:133], v[190:193], v[46:49]
	v_mfma_f32_16x16x32_bf16 v[38:41], v[138:141], v[190:193], v[38:41]
	v_mfma_f32_16x16x32_bf16 v[18:21], v[130:133], v[198:201], v[18:21]
	v_mfma_f32_16x16x32_bf16 v[10:13], v[138:141], v[198:201], v[10:13]
	v_mfma_f32_16x16x32_bf16 v[62:65], v[134:137], v[178:181], v[62:65]
	v_mfma_f32_16x16x32_bf16 v[58:61], v[142:145], v[178:181], v[58:61]
	v_mfma_f32_16x16x32_bf16 v[54:57], v[134:137], v[186:189], v[54:57]
	v_mfma_f32_16x16x32_bf16 v[50:53], v[142:145], v[186:189], v[50:53]
	v_mfma_f32_16x16x32_bf16 v[46:49], v[134:137], v[194:197], v[46:49]
	v_mfma_f32_16x16x32_bf16 v[38:41], v[142:145], v[194:197], v[38:41]
	v_mfma_f32_16x16x32_bf16 v[18:21], v[134:137], v[202:205], v[18:21]
	v_mfma_f32_16x16x32_bf16 v[10:13], v[142:145], v[202:205], v[10:13]
	v_mfma_f32_16x16x32_bf16 v[42:45], v[152:155], v[174:177], v[42:45]
	v_mfma_f32_16x16x32_bf16 v[34:37], v[166:169], v[174:177], v[34:37]
	v_mfma_f32_16x16x32_bf16 v[30:33], v[152:155], v[182:185], v[30:33]
	v_mfma_f32_16x16x32_bf16 v[26:29], v[166:169], v[182:185], v[26:29]
	v_mfma_f32_16x16x32_bf16 v[22:25], v[152:155], v[190:193], v[22:25]
	v_mfma_f32_16x16x32_bf16 v[14:17], v[166:169], v[190:193], v[14:17]
	v_mfma_f32_16x16x32_bf16 v[6:9], v[152:155], v[198:201], v[6:9]
	v_mfma_f32_16x16x32_bf16 v[2:5], v[166:169], v[198:201], v[2:5]
	v_mfma_f32_16x16x32_bf16 v[42:45], v[162:165], v[178:181], v[42:45]
	v_mfma_f32_16x16x32_bf16 v[34:37], v[170:173], v[178:181], v[34:37]
	v_mfma_f32_16x16x32_bf16 v[30:33], v[162:165], v[186:189], v[30:33]
	v_mfma_f32_16x16x32_bf16 v[26:29], v[170:173], v[186:189], v[26:29]
	v_mfma_f32_16x16x32_bf16 v[22:25], v[162:165], v[194:197], v[22:25]
	v_mfma_f32_16x16x32_bf16 v[14:17], v[170:173], v[194:197], v[14:17]
	v_mfma_f32_16x16x32_bf16 v[6:9], v[162:165], v[202:205], v[6:9]
	v_mfma_f32_16x16x32_bf16 v[2:5], v[170:173], v[202:205], v[2:5]
	s_setprio 0
	s_barrier
	s_add_i32 s71, 0, 0x18000
	s_add_i32 s72, 0, 0x1c000
	v_add_u32_e32 v142, s71, v1
	v_add_u32_e32 v170, s72, v1
	ds_read_b128 v[130:133], v142
	ds_read_b128 v[134:137], v142 offset:1024
	ds_read_b128 v[138:141], v142 offset:2048
	ds_read_b128 v[142:145], v142 offset:3072
	ds_read_b128 v[152:155], v170
	ds_read_b128 v[162:165], v170 offset:1024
	ds_read_b128 v[166:169], v170 offset:2048
	ds_read_b128 v[170:173], v170 offset:3072
	s_add_u32 s36, s36, 0x40000
	s_addc_u32 s37, s37, 0
	s_mov_b32 m0, s51
	v_lshl_add_u64 v[214:215], s[36:37], 0, v[148:149]
	ds_read_b128 v[174:177], v160 offset:32768
	ds_read_b128 v[178:181], v160 offset:33792
	ds_read_b128 v[182:185], v160 offset:34816
	ds_read_b128 v[186:189], v160 offset:35840
	ds_read_b128 v[190:193], v160 offset:36864
	ds_read_b128 v[194:197], v160 offset:37888
	ds_read_b128 v[198:201], v160 offset:38912
	ds_read_b128 v[202:205], v160 offset:39936
	global_load_lds_dwordx4 v[214:215], off
	v_lshl_add_u64 v[214:215], s[36:37], 0, v[146:147]
	s_mov_b32 m0, s52
	s_nop 0
	global_load_lds_dwordx4 v[214:215], off
	s_waitcnt vmcnt(8)
	s_waitcnt lgkmcnt(0)
	s_barrier
	s_setprio 1
	s_waitcnt lgkmcnt(0)
	v_mfma_f32_16x16x32_bf16 v[126:129], v[130:133], v[174:177], v[126:129]
	v_mfma_f32_16x16x32_bf16 v[122:125], v[138:141], v[174:177], v[122:125]
	v_mfma_f32_16x16x32_bf16 v[118:121], v[130:133], v[182:185], v[118:121]
	v_mfma_f32_16x16x32_bf16 v[114:117], v[138:141], v[182:185], v[114:117]
	v_mfma_f32_16x16x32_bf16 v[102:105], v[130:133], v[190:193], v[102:105]
	v_mfma_f32_16x16x32_bf16 v[90:93], v[138:141], v[190:193], v[90:93]
	v_mfma_f32_16x16x32_bf16 v[82:85], v[130:133], v[198:201], v[82:85]
	v_mfma_f32_16x16x32_bf16 v[74:77], v[138:141], v[198:201], v[74:77]
	v_mfma_f32_16x16x32_bf16 v[126:129], v[134:137], v[178:181], v[126:129]
	v_mfma_f32_16x16x32_bf16 v[122:125], v[142:145], v[178:181], v[122:125]
	v_mfma_f32_16x16x32_bf16 v[118:121], v[134:137], v[186:189], v[118:121]
	v_mfma_f32_16x16x32_bf16 v[114:117], v[142:145], v[186:189], v[114:117]
	v_mfma_f32_16x16x32_bf16 v[102:105], v[134:137], v[194:197], v[102:105]
	v_mfma_f32_16x16x32_bf16 v[90:93], v[142:145], v[194:197], v[90:93]
	v_mfma_f32_16x16x32_bf16 v[82:85], v[134:137], v[202:205], v[82:85]
	v_mfma_f32_16x16x32_bf16 v[74:77], v[142:145], v[202:205], v[74:77]
	v_mfma_f32_16x16x32_bf16 v[110:113], v[152:155], v[174:177], v[110:113]
	v_mfma_f32_16x16x32_bf16 v[106:109], v[166:169], v[174:177], v[106:109]
	v_mfma_f32_16x16x32_bf16 v[98:101], v[152:155], v[182:185], v[98:101]
	v_mfma_f32_16x16x32_bf16 v[94:97], v[166:169], v[182:185], v[94:97]
	v_mfma_f32_16x16x32_bf16 v[86:89], v[152:155], v[190:193], v[86:89]
	v_mfma_f32_16x16x32_bf16 v[78:81], v[166:169], v[190:193], v[78:81]
	v_mfma_f32_16x16x32_bf16 v[70:73], v[152:155], v[198:201], v[70:73]
	v_mfma_f32_16x16x32_bf16 v[66:69], v[166:169], v[198:201], v[66:69]
	v_mfma_f32_16x16x32_bf16 v[110:113], v[162:165], v[178:181], v[110:113]
	v_mfma_f32_16x16x32_bf16 v[106:109], v[170:173], v[178:181], v[106:109]
	v_mfma_f32_16x16x32_bf16 v[98:101], v[162:165], v[186:189], v[98:101]
	v_mfma_f32_16x16x32_bf16 v[94:97], v[170:173], v[186:189], v[94:97]
	v_mfma_f32_16x16x32_bf16 v[86:89], v[162:165], v[194:197], v[86:89]
	v_mfma_f32_16x16x32_bf16 v[78:81], v[170:173], v[194:197], v[78:81]
	v_mfma_f32_16x16x32_bf16 v[70:73], v[162:165], v[202:205], v[70:73]
	v_mfma_f32_16x16x32_bf16 v[66:69], v[170:173], v[202:205], v[66:69]
	s_setprio 0
	s_barrier
; #define PG8_STAGE(bufoff, gbase, voff) do { _Pragma("unroll") for (int _i = 0; _i < 2; ++_i) \
;         __builtin_amdgcn_global_load_lds((const unsigned*)((const char*)(gbase) + (voff)[_i]), (PG8_LAS unsigned*)(lds + (bufoff) + ldsw + _i * 8192), 16, 0, 0); } while (0)
; #define PG8_LDA(dst, b, h) do { _Pragma("unroll") for (int m = 0; m < 4; ++m) _Pragma("unroll") for (int k = 0; k < 2; ++k) dst[m][k] = *(const PG8_LAS bf16x8*)(lds + PG8_SA(b, h) + aoff + m * 2048 + k * 1024); } while (0)
; #define PG8_MMA(ai, bj, At, Bt) do { __builtin_amdgcn_s_setprio(1); _Pragma("unroll") for (int m = 0; m < 4; ++m) _Pragma("unroll") for (int n = 0; n < 2; ++n) _Pragma("unroll") for (int k = 0; k < 2; ++k) \
;         acc[ai][bj][m][n] = __builtin_amdgcn_mfma_f32_16x16x32_bf16(Bt[n][k], At[m][k], acc[ai][bj][m][n], 0, 0, 0); __builtin_amdgcn_s_setprio(0); } while (0)
; #define PG8_WAIT_V(n) asm volatile("s_waitcnt vmcnt(" #n ")" ::: "memory")
; #define PG8_WAIT_L(n) asm volatile("s_waitcnt lgkmcnt(" #n ")" ::: "memory")
; #define PG8_BAR __builtin_amdgcn_s_barrier()
; #define PG8_SCHED __builtin_amdgcn_sched_barrier(0)
; template <class Epi, class Sched, bool ALIGN_EPI = false, bool SP2 = false>
; __device__ __forceinline__ void gemm_phase(PG8_LAS unsigned char* lds, const Gemm g, const Sched& S, const Epi& E) {
;     ...
;         for (int t = 0; t < nt; t += 2) {
;             const bool last = (t == nt - 2);
;             const char* a1 = cA + (size_t)(t + 1) * kstep;
;             const char* a2 = last ? nA : cA + (size_t)(t + 2) * kstep; const char* b2 = last ? nB : cB + (size_t)(t + 2) * kstep;
;             const char* a3 = a2 + kstep; const char* b3 = b2 + kstep;
;             if (last && has_next) S.a_ready(nxt);
;     ...
;             PG8_LDA(At, 1, 1); PG8_STAGE(PG8_SB(1, 0), b3, voffB); PG8_STAGE(PG8_SB(1, 1), b3 + hstepB, voffB); PG8_STAGE(PG8_SA(1, 0), a3, voffA);
;             PG8_WAIT_V(8); PG8_WAIT_L(0); PG8_BAR; PG8_MMA(1, 0, At, B0); PG8_MMA(1, 1, At, B1); PG8_BAR; PG8_SCHED;
	s_add_i32 s36, s71, s45
	v_lshl_add_u64 v[206:207], v[206:207], 0, s[4:5]
	s_mov_b32 m0, s36
	ds_read_b128 v[174:177], v160 offset:49152
	ds_read_b128 v[178:181], v160 offset:50176
	ds_read_b128 v[182:185], v160 offset:51200
	ds_read_b128 v[186:189], v160 offset:52224
	ds_read_b128 v[190:193], v160 offset:53248
	ds_read_b128 v[194:197], v160 offset:54272
	ds_read_b128 v[198:201], v160 offset:55296
	ds_read_b128 v[202:205], v160 offset:56320
	global_load_lds_dwordx4 v[206:207], off
	s_add_i32 m0, s36, 0x2000
	s_add_u32 s34, s34, 0x40080
	v_lshl_add_u64 v[206:207], v[208:209], 0, s[4:5]
	s_addc_u32 s35, s35, 0
	s_add_i32 s36, s72, s45
	global_load_lds_dwordx4 v[206:207], off
	v_lshl_add_u64 v[206:207], s[34:35], 0, v[148:149]
	s_mov_b32 m0, s36
	s_nop 0
	global_load_lds_dwordx4 v[206:207], off
	v_lshl_add_u64 v[206:207], s[34:35], 0, v[146:147]
	s_add_i32 m0, s36, 0x2000
	s_nop 0
	global_load_lds_dwordx4 v[206:207], off
	v_lshl_add_u64 v[206:207], v[210:211], 0, s[4:5]
	s_mov_b32 m0, s59
	s_nop 0
	global_load_lds_dwordx4 v[206:207], off
	v_lshl_add_u64 v[206:207], v[212:213], 0, s[4:5]
	s_mov_b32 m0, s60
	s_nop 0
	global_load_lds_dwordx4 v[206:207], off
	s_waitcnt vmcnt(8)
	s_waitcnt lgkmcnt(0)
	s_barrier
	s_setprio 1
	s_waitcnt lgkmcnt(0)
	v_mfma_f32_16x16x32_bf16 v[62:65], v[130:133], v[174:177], v[62:65]
	v_mfma_f32_16x16x32_bf16 v[58:61], v[138:141], v[174:177], v[58:61]
	v_mfma_f32_16x16x32_bf16 v[54:57], v[130:133], v[182:185], v[54:57]
	v_mfma_f32_16x16x32_bf16 v[50:53], v[138:141], v[182:185], v[50:53]
	v_mfma_f32_16x16x32_bf16 v[46:49], v[130:133], v[190:193], v[46:49]
	v_mfma_f32_16x16x32_bf16 v[38:41], v[138:141], v[190:193], v[38:41]
	v_mfma_f32_16x16x32_bf16 v[18:21], v[130:133], v[198:201], v[18:21]
	v_mfma_f32_16x16x32_bf16 v[10:13], v[138:141], v[198:201], v[10:13]
	v_mfma_f32_16x16x32_bf16 v[62:65], v[134:137], v[178:181], v[62:65]
	v_mfma_f32_16x16x32_bf16 v[58:61], v[142:145], v[178:181], v[58:61]
	v_mfma_f32_16x16x32_bf16 v[54:57], v[134:137], v[186:189], v[54:57]
	v_mfma_f32_16x16x32_bf16 v[50:53], v[142:145], v[186:189], v[50:53]
	v_mfma_f32_16x16x32_bf16 v[46:49], v[134:137], v[194:197], v[46:49]
	v_mfma_f32_16x16x32_bf16 v[38:41], v[142:145], v[194:197], v[38:41]
	v_mfma_f32_16x16x32_bf16 v[18:21], v[134:137], v[202:205], v[18:21]
	v_mfma_f32_16x16x32_bf16 v[10:13], v[142:145], v[202:205], v[10:13]
	v_mfma_f32_16x16x32_bf16 v[42:45], v[152:155], v[174:177], v[42:45]
	v_mfma_f32_16x16x32_bf16 v[34:37], v[166:169], v[174:177], v[34:37]
	v_mfma_f32_16x16x32_bf16 v[30:33], v[152:155], v[182:185], v[30:33]
	v_mfma_f32_16x16x32_bf16 v[26:29], v[166:169], v[182:185], v[26:29]
	v_mfma_f32_16x16x32_bf16 v[22:25], v[152:155], v[190:193], v[22:25]
	v_mfma_f32_16x16x32_bf16 v[14:17], v[166:169], v[190:193], v[14:17]
	v_mfma_f32_16x16x32_bf16 v[6:9], v[152:155], v[198:201], v[6:9]
	v_mfma_f32_16x16x32_bf16 v[2:5], v[166:169], v[198:201], v[2:5]
	v_mfma_f32_16x16x32_bf16 v[42:45], v[162:165], v[178:181], v[42:45]
	v_mfma_f32_16x16x32_bf16 v[34:37], v[170:173], v[178:181], v[34:37]
	v_mfma_f32_16x16x32_bf16 v[30:33], v[162:165], v[186:189], v[30:33]
	v_mfma_f32_16x16x32_bf16 v[26:29], v[170:173], v[186:189], v[26:29]
	v_mfma_f32_16x16x32_bf16 v[22:25], v[162:165], v[194:197], v[22:25]
	v_mfma_f32_16x16x32_bf16 v[14:17], v[170:173], v[194:197], v[14:17]
	v_mfma_f32_16x16x32_bf16 v[6:9], v[162:165], v[202:205], v[6:9]
	v_mfma_f32_16x16x32_bf16 v[2:5], v[170:173], v[202:205], v[2:5]
	s_setprio 0
	s_barrier
	s_movk_i32 s71, 0x100
	s_and_b64 vcc, exec, s[30:31]
	s_mov_b64 s[34:35], -1
	s_mov_b64 s[30:31], 0
	s_cbranch_vccnz .LBB0_1344
	s_andn2_b64 vcc, exec, s[8:9]
	s_cbranch_vccnz .LBB0_1347
	s_barrier

; #define PG8_STAGE(bufoff, gbase, voff) do { _Pragma("unroll") for (int _i = 0; _i < 2; ++_i) \
;         __builtin_amdgcn_global_load_lds((const unsigned*)((const char*)(gbase) + (voff)[_i]), (PG8_LAS unsigned*)(lds + (bufoff) + ldsw + _i * 8192), 16, 0, 0); } while (0)
; #define PG8_LDA(dst, b, h) do { _Pragma("unroll") for (int m = 0; m < 4; ++m) _Pragma("unroll") for (int k = 0; k < 2; ++k) dst[m][k] = *(const PG8_LAS bf16x8*)(lds + PG8_SA(b, h) + aoff + m * 2048 + k * 1024); } while (0)
; #define PG8_LDB(dst, b, h) do { _Pragma("unroll") for (int n = 0; n < 2; ++n) _Pragma("unroll") for (int k = 0; k < 2; ++k) dst[n][k] = *(const PG8_LAS bf16x8*)(lds + PG8_SB(b, h) + boff + n * 2048 + k * 1024); } while (0)
; #define PG8_MMA(ai, bj, At, Bt) do { __builtin_amdgcn_s_setprio(1); _Pragma("unroll") for (int m = 0; m < 4; ++m) _Pragma("unroll") for (int n = 0; n < 2; ++n) _Pragma("unroll") for (int k = 0; k < 2; ++k) \
;         acc[ai][bj][m][n] = __builtin_amdgcn_mfma_f32_16x16x32_bf16(Bt[n][k], At[m][k], acc[ai][bj][m][n], 0, 0, 0); __builtin_amdgcn_s_setprio(0); } while (0)
; template <class Epi, class Sched, bool ALIGN_EPI = false, bool SP2 = false>
; __device__ __forceinline__ void gemm_phase(PG8_LAS unsigned char* lds, const Gemm g, const Sched& S, const Epi& E) {
;     ...
;         const bool has_next = S.next(ui + 1, nxt);
;         const char* nA = has_next ? (const char*)g.A + (size_t)nxt.pm * tstepA : cA; const char* nB = has_next ? (const char*)g.Bt + (size_t)nxt.pn * tstepB : cB;
; #pragma unroll 1
;         for (int t = 0; t < nt; t += 2) {
;             const bool last = (t == nt - 2);
;             const char* a1 = cA + (size_t)(t + 1) * kstep;
;             const char* a2 = last ? nA : cA + (size_t)(t + 2) * kstep; const char* b2 = last ? nB : cB + (size_t)(t + 2) * kstep;
;             const char* a3 = a2 + kstep; const char* b3 = b2 + kstep;
;             if (last && has_next) S.a_ready(nxt);
;             if constexpr (SP2) {
;             PG8_LDB(B0, 0, 0); PG8_LDB(B1, 0, 1); PG8_SCHED; PG8_LDA(At, 0, 0); PG8_STAGE(PG8_SA(1, 1), a1 + hstepA, voffA);
;             PG8_WAIT_V(8); PG8_WAIT_L(0); PG8_BAR; PG8_MMA(0, 0, At, B0); PG8_MMA(0, 1, At, B1); PG8_BAR; PG8_SCHED;
;             PG8_LDA(At, 0, 1); PG8_STAGE(PG8_SB(0, 0), b2, voffB); PG8_STAGE(PG8_SB(0, 1), b2 + hstepB, voffB); PG8_STAGE(PG8_SA(0, 0), a2, voffA);
.LBB0_1364:
	s_add_u32 s73, s28, s72
	ds_read_b128 v[130:133], v158
	ds_read_b128 v[134:137], v158 offset:1024
	ds_read_b128 v[138:141], v158 offset:2048
	ds_read_b128 v[142:145], v158 offset:3072
	ds_read_b128 v[152:155], v159
	ds_read_b128 v[162:165], v159 offset:1024
	ds_read_b128 v[166:169], v159 offset:2048
	ds_read_b128 v[170:173], v159 offset:3072
	s_addc_u32 s74, s29, 0
	s_add_u32 s75, s73, 0x100
	s_addc_u32 s76, s74, 0
	s_and_b64 s[36:37], s[34:35], exec
	s_cselect_b32 s37, s17, s76
	s_cselect_b32 s36, s70, s75
	s_add_u32 s72, s26, s72
	s_addc_u32 s75, s27, 0
	s_add_u32 s72, s72, 0x100
	s_addc_u32 s75, s75, 0
	s_and_b64 s[34:35], s[34:35], exec
	s_cselect_b32 s35, s15, s75
	s_cselect_b32 s34, s71, s72
	s_add_u32 s72, s73, 0x40080
	s_addc_u32 s73, s74, 0
	v_lshl_add_u64 v[206:207], s[72:73], 0, v[148:149]
	s_add_i32 m0, s50, 0xc000
	ds_read_b128 v[174:177], v160
	ds_read_b128 v[178:181], v160 offset:1024
	ds_read_b128 v[182:185], v160 offset:2048
	ds_read_b128 v[186:189], v160 offset:3072
	ds_read_b128 v[190:193], v160 offset:4096
	ds_read_b128 v[194:197], v160 offset:5120
	ds_read_b128 v[198:201], v160 offset:6144
	ds_read_b128 v[202:205], v160 offset:7168
	global_load_lds_dwordx4 v[206:207], off
	v_lshl_add_u64 v[206:207], s[72:73], 0, v[146:147]
	s_add_i32 m0, s50, 0xe000
	s_nop 0
	global_load_lds_dwordx4 v[206:207], off
	s_waitcnt vmcnt(8)
	s_waitcnt lgkmcnt(0)
	s_barrier
	s_setprio 1
	s_waitcnt lgkmcnt(0)
	v_mfma_f32_16x16x32_bf16 v[126:129], v[130:133], v[174:177], v[126:129]
	v_mfma_f32_16x16x32_bf16 v[122:125], v[138:141], v[174:177], v[122:125]
	v_mfma_f32_16x16x32_bf16 v[118:121], v[130:133], v[182:185], v[118:121]
	v_mfma_f32_16x16x32_bf16 v[114:117], v[138:141], v[182:185], v[114:117]
	v_mfma_f32_16x16x32_bf16 v[102:105], v[130:133], v[190:193], v[102:105]
	v_mfma_f32_16x16x32_bf16 v[90:93], v[138:141], v[190:193], v[90:93]
	v_mfma_f32_16x16x32_bf16 v[82:85], v[130:133], v[198:201], v[82:85]
	v_mfma_f32_16x16x32_bf16 v[74:77], v[138:141], v[198:201], v[74:77]
	v_mfma_f32_16x16x32_bf16 v[126:129], v[134:137], v[178:181], v[126:129]
	v_mfma_f32_16x16x32_bf16 v[122:125], v[142:145], v[178:181], v[122:125]
	v_mfma_f32_16x16x32_bf16 v[118:121], v[134:137], v[186:189], v[118:121]
	v_mfma_f32_16x16x32_bf16 v[114:117], v[142:145], v[186:189], v[114:117]
	v_mfma_f32_16x16x32_bf16 v[102:105], v[134:137], v[194:197], v[102:105]
	v_mfma_f32_16x16x32_bf16 v[90:93], v[142:145], v[194:197], v[90:93]
	v_mfma_f32_16x16x32_bf16 v[82:85], v[134:137], v[202:205], v[82:85]
	v_mfma_f32_16x16x32_bf16 v[74:77], v[142:145], v[202:205], v[74:77]
	v_mfma_f32_16x16x32_bf16 v[110:113], v[152:155], v[174:177], v[110:113]
	v_mfma_f32_16x16x32_bf16 v[106:109], v[166:169], v[174:177], v[106:109]
	v_mfma_f32_16x16x32_bf16 v[98:101], v[152:155], v[182:185], v[98:101]
	v_mfma_f32_16x16x32_bf16 v[94:97], v[166:169], v[182:185], v[94:97]
	v_mfma_f32_16x16x32_bf16 v[86:89], v[152:155], v[190:193], v[86:89]
	v_mfma_f32_16x16x32_bf16 v[78:81], v[166:169], v[190:193], v[78:81]
	v_mfma_f32_16x16x32_bf16 v[70:73], v[152:155], v[198:201], v[70:73]
	v_mfma_f32_16x16x32_bf16 v[66:69], v[166:169], v[198:201], v[66:69]
	v_mfma_f32_16x16x32_bf16 v[110:113], v[162:165], v[178:181], v[110:113]
	v_mfma_f32_16x16x32_bf16 v[106:109], v[170:173], v[178:181], v[106:109]
	v_mfma_f32_16x16x32_bf16 v[98:101], v[162:165], v[186:189], v[98:101]
	v_mfma_f32_16x16x32_bf16 v[94:97], v[170:173], v[186:189], v[94:97]
	v_mfma_f32_16x16x32_bf16 v[86:89], v[162:165], v[194:197], v[86:89]
	v_mfma_f32_16x16x32_bf16 v[78:81], v[170:173], v[194:197], v[78:81]
	v_mfma_f32_16x16x32_bf16 v[70:73], v[162:165], v[202:205], v[70:73]
	v_mfma_f32_16x16x32_bf16 v[66:69], v[170:173], v[202:205], v[66:69]
	s_setprio 0
	s_barrier
	s_add_i32 s72, s62, s48
	v_lshl_add_u64 v[206:207], s[34:35], 0, v[148:149]
	s_mov_b32 m0, s72
	ds_read_b128 v[174:177], v160 offset:16384
	ds_read_b128 v[178:181], v160 offset:17408
	ds_read_b128 v[182:185], v160 offset:18432
	ds_read_b128 v[186:189], v160 offset:19456
	ds_read_b128 v[190:193], v160 offset:20480
	ds_read_b128 v[194:197], v160 offset:21504
	ds_read_b128 v[198:201], v160 offset:22528
	ds_read_b128 v[202:205], v160 offset:23552
	global_load_lds_dwordx4 v[206:207], off
	s_add_i32 m0, s72, 0x2000
	s_add_u32 s72, s34, 0x40000
	v_lshl_add_u64 v[208:209], s[34:35], 0, v[146:147]
	s_addc_u32 s73, s35, 0
	s_add_i32 s74, s63, s48
	global_load_lds_dwordx4 v[208:209], off
	v_lshl_add_u64 v[210:211], s[72:73], 0, v[148:149]
	s_mov_b32 m0, s74
	v_lshl_add_u64 v[212:213], s[36:37], 0, v[146:147]
	global_load_lds_dwordx4 v[210:211], off
	v_lshl_add_u64 v[210:211], s[72:73], 0, v[146:147]
	s_add_i32 m0, s74, 0x2000
	s_nop 0
	global_load_lds_dwordx4 v[210:211], off
	v_lshl_add_u64 v[210:211], s[36:37], 0, v[148:149]
	s_mov_b32 m0, s50
	s_nop 0
	global_load_lds_dwordx4 v[210:211], off
	s_mov_b32 m0, s51
	s_nop 0
	global_load_lds_dwordx4 v[212:213], off
	s_waitcnt vmcnt(8)
	s_waitcnt lgkmcnt(0)
	s_barrier
; #define PG8_STAGE(bufoff, gbase, voff) do { _Pragma("unroll") for (int _i = 0; _i < 2; ++_i) \
;         __builtin_amdgcn_global_load_lds((const unsigned*)((const char*)(gbase) + (voff)[_i]), (PG8_LAS unsigned*)(lds + (bufoff) + ldsw + _i * 8192), 16, 0, 0); } while (0)
; #define PG8_LDA(dst, b, h) do { _Pragma("unroll") for (int m = 0; m < 4; ++m) _Pragma("unroll") for (int k = 0; k < 2; ++k) dst[m][k] = *(const PG8_LAS bf16x8*)(lds + PG8_SA(b, h) + aoff + m * 2048 + k * 1024); } while (0)
; #define PG8_LDB(dst, b, h) do { _Pragma("unroll") for (int n = 0; n < 2; ++n) _Pragma("unroll") for (int k = 0; k < 2; ++k) dst[n][k] = *(const PG8_LAS bf16x8*)(lds + PG8_SB(b, h) + boff + n * 2048 + k * 1024); } while (0)
; #define PG8_MMA(ai, bj, At, Bt) do { __builtin_amdgcn_s_setprio(1); _Pragma("unroll") for (int m = 0; m < 4; ++m) _Pragma("unroll") for (int n = 0; n < 2; ++n) _Pragma("unroll") for (int k = 0; k < 2; ++k) \
;         acc[ai][bj][m][n] = __builtin_amdgcn_mfma_f32_16x16x32_bf16(Bt[n][k], At[m][k], acc[ai][bj][m][n], 0, 0, 0); __builtin_amdgcn_s_setprio(0); } while (0)
; #define PG8_WAIT_V(n) asm volatile("s_waitcnt vmcnt(" #n ")" ::: "memory")
; #define PG8_WAIT_L(n) asm volatile("s_waitcnt lgkmcnt(" #n ")" ::: "memory")
; #define PG8_BAR __builtin_amdgcn_s_barrier()
; #define PG8_SCHED __builtin_amdgcn_sched_barrier(0)
; template <class Epi, class Sched, bool ALIGN_EPI = false, bool SP2 = false>
; __device__ __forceinline__ void gemm_phase(PG8_LAS unsigned char* lds, const Gemm g, const Sched& S, const Epi& E) {
;     ...
;             PG8_WAIT_V(8); PG8_WAIT_L(0); PG8_BAR; PG8_MMA(1, 0, At, B0); PG8_MMA(1, 1, At, B1); PG8_BAR; PG8_SCHED;
;             PG8_LDB(B0, 1, 0); PG8_LDB(B1, 1, 1); PG8_SCHED; PG8_LDA(At, 1, 0); PG8_STAGE(PG8_SA(0, 1), a2 + hstepA, voffA);
;             PG8_WAIT_V(8); PG8_WAIT_L(0); PG8_BAR; PG8_MMA(0, 0, At, B0); PG8_MMA(0, 1, At, B1); PG8_BAR; PG8_SCHED;
	s_setprio 1
	s_waitcnt lgkmcnt(0)
	v_mfma_f32_16x16x32_bf16 v[62:65], v[130:133], v[174:177], v[62:65]
	v_mfma_f32_16x16x32_bf16 v[58:61], v[138:141], v[174:177], v[58:61]
	v_mfma_f32_16x16x32_bf16 v[54:57], v[130:133], v[182:185], v[54:57]
	v_mfma_f32_16x16x32_bf16 v[50:53], v[138:141], v[182:185], v[50:53]
	v_mfma_f32_16x16x32_bf16 v[46:49], v[130:133], v[190:193], v[46:49]
	v_mfma_f32_16x16x32_bf16 v[38:41], v[138:141], v[190:193], v[38:41]
	v_mfma_f32_16x16x32_bf16 v[18:21], v[130:133], v[198:201], v[18:21]
	v_mfma_f32_16x16x32_bf16 v[10:13], v[138:141], v[198:201], v[10:13]
	v_mfma_f32_16x16x32_bf16 v[62:65], v[134:137], v[178:181], v[62:65]
	v_mfma_f32_16x16x32_bf16 v[58:61], v[142:145], v[178:181], v[58:61]
	v_mfma_f32_16x16x32_bf16 v[54:57], v[134:137], v[186:189], v[54:57]
	v_mfma_f32_16x16x32_bf16 v[50:53], v[142:145], v[186:189], v[50:53]
	v_mfma_f32_16x16x32_bf16 v[46:49], v[134:137], v[194:197], v[46:49]
	v_mfma_f32_16x16x32_bf16 v[38:41], v[142:145], v[194:197], v[38:41]
	v_mfma_f32_16x16x32_bf16 v[18:21], v[134:137], v[202:205], v[18:21]
	v_mfma_f32_16x16x32_bf16 v[10:13], v[142:145], v[202:205], v[10:13]
	v_mfma_f32_16x16x32_bf16 v[42:45], v[152:155], v[174:177], v[42:45]
	v_mfma_f32_16x16x32_bf16 v[34:37], v[166:169], v[174:177], v[34:37]
	v_mfma_f32_16x16x32_bf16 v[30:33], v[152:155], v[182:185], v[30:33]
	v_mfma_f32_16x16x32_bf16 v[26:29], v[166:169], v[182:185], v[26:29]
	v_mfma_f32_16x16x32_bf16 v[22:25], v[152:155], v[190:193], v[22:25]
	v_mfma_f32_16x16x32_bf16 v[14:17], v[166:169], v[190:193], v[14:17]
	v_mfma_f32_16x16x32_bf16 v[6:9], v[152:155], v[198:201], v[6:9]
	v_mfma_f32_16x16x32_bf16 v[2:5], v[166:169], v[198:201], v[2:5]
	v_mfma_f32_16x16x32_bf16 v[42:45], v[162:165], v[178:181], v[42:45]
	v_mfma_f32_16x16x32_bf16 v[34:37], v[170:173], v[178:181], v[34:37]
	v_mfma_f32_16x16x32_bf16 v[30:33], v[162:165], v[186:189], v[30:33]
	v_mfma_f32_16x16x32_bf16 v[26:29], v[170:173], v[186:189], v[26:29]
	v_mfma_f32_16x16x32_bf16 v[22:25], v[162:165], v[194:197], v[22:25]
	v_mfma_f32_16x16x32_bf16 v[14:17], v[170:173], v[194:197], v[14:17]
	v_mfma_f32_16x16x32_bf16 v[6:9], v[162:165], v[202:205], v[6:9]
	v_mfma_f32_16x16x32_bf16 v[2:5], v[170:173], v[202:205], v[2:5]
	s_setprio 0
	s_barrier
	s_add_i32 s72, 0, 0x18000
	s_add_i32 s73, 0, 0x1c000
	v_add_u32_e32 v142, s72, v1
	v_add_u32_e32 v170, s73, v1
	ds_read_b128 v[130:133], v142
	ds_read_b128 v[134:137], v142 offset:1024
	ds_read_b128 v[138:141], v142 offset:2048
	ds_read_b128 v[142:145], v142 offset:3072
	ds_read_b128 v[152:155], v170
	ds_read_b128 v[162:165], v170 offset:1024
	ds_read_b128 v[166:169], v170 offset:2048
	ds_read_b128 v[170:173], v170 offset:3072
	s_add_u32 s36, s36, 0x40000
	s_addc_u32 s37, s37, 0
	s_mov_b32 m0, s52
	v_lshl_add_u64 v[214:215], s[36:37], 0, v[148:149]
	ds_read_b128 v[174:177], v160 offset:32768
	ds_read_b128 v[178:181], v160 offset:33792
	ds_read_b128 v[182:185], v160 offset:34816
	ds_read_b128 v[186:189], v160 offset:35840
	ds_read_b128 v[190:193], v160 offset:36864
	ds_read_b128 v[194:197], v160 offset:37888
	ds_read_b128 v[198:201], v160 offset:38912
	ds_read_b128 v[202:205], v160 offset:39936
	global_load_lds_dwordx4 v[214:215], off
	v_lshl_add_u64 v[214:215], s[36:37], 0, v[146:147]
	s_mov_b32 m0, s53
	s_nop 0
	global_load_lds_dwordx4 v[214:215], off
	s_waitcnt vmcnt(8)
	s_waitcnt lgkmcnt(0)
	s_barrier
	s_setprio 1
	s_waitcnt lgkmcnt(0)
	v_mfma_f32_16x16x32_bf16 v[126:129], v[130:133], v[174:177], v[126:129]
	v_mfma_f32_16x16x32_bf16 v[122:125], v[138:141], v[174:177], v[122:125]
	v_mfma_f32_16x16x32_bf16 v[118:121], v[130:133], v[182:185], v[118:121]
	v_mfma_f32_16x16x32_bf16 v[114:117], v[138:141], v[182:185], v[114:117]
	v_mfma_f32_16x16x32_bf16 v[102:105], v[130:133], v[190:193], v[102:105]
	v_mfma_f32_16x16x32_bf16 v[90:93], v[138:141], v[190:193], v[90:93]
	v_mfma_f32_16x16x32_bf16 v[82:85], v[130:133], v[198:201], v[82:85]
	v_mfma_f32_16x16x32_bf16 v[74:77], v[138:141], v[198:201], v[74:77]
	v_mfma_f32_16x16x32_bf16 v[126:129], v[134:137], v[178:181], v[126:129]
	v_mfma_f32_16x16x32_bf16 v[122:125], v[142:145], v[178:181], v[122:125]
	v_mfma_f32_16x16x32_bf16 v[118:121], v[134:137], v[186:189], v[118:121]
	v_mfma_f32_16x16x32_bf16 v[114:117], v[142:145], v[186:189], v[114:117]
	v_mfma_f32_16x16x32_bf16 v[102:105], v[134:137], v[194:197], v[102:105]
	v_mfma_f32_16x16x32_bf16 v[90:93], v[142:145], v[194:197], v[90:93]
	v_mfma_f32_16x16x32_bf16 v[82:85], v[134:137], v[202:205], v[82:85]
	v_mfma_f32_16x16x32_bf16 v[74:77], v[142:145], v[202:205], v[74:77]
	v_mfma_f32_16x16x32_bf16 v[110:113], v[152:155], v[174:177], v[110:113]
	v_mfma_f32_16x16x32_bf16 v[106:109], v[166:169], v[174:177], v[106:109]
	v_mfma_f32_16x16x32_bf16 v[98:101], v[152:155], v[182:185], v[98:101]
	v_mfma_f32_16x16x32_bf16 v[94:97], v[166:169], v[182:185], v[94:97]
	v_mfma_f32_16x16x32_bf16 v[86:89], v[152:155], v[190:193], v[86:89]
	v_mfma_f32_16x16x32_bf16 v[78:81], v[166:169], v[190:193], v[78:81]
	v_mfma_f32_16x16x32_bf16 v[70:73], v[152:155], v[198:201], v[70:73]
	v_mfma_f32_16x16x32_bf16 v[66:69], v[166:169], v[198:201], v[66:69]
	v_mfma_f32_16x16x32_bf16 v[110:113], v[162:165], v[178:181], v[110:113]
	v_mfma_f32_16x16x32_bf16 v[106:109], v[170:173], v[178:181], v[106:109]
	v_mfma_f32_16x16x32_bf16 v[98:101], v[162:165], v[186:189], v[98:101]
	v_mfma_f32_16x16x32_bf16 v[94:97], v[170:173], v[186:189], v[94:97]
	v_mfma_f32_16x16x32_bf16 v[86:89], v[162:165], v[194:197], v[86:89]
	v_mfma_f32_16x16x32_bf16 v[78:81], v[170:173], v[194:197], v[78:81]
	v_mfma_f32_16x16x32_bf16 v[70:73], v[162:165], v[202:205], v[70:73]
	v_mfma_f32_16x16x32_bf16 v[66:69], v[170:173], v[202:205], v[66:69]
	s_setprio 0
	s_barrier
; #define PG8_STAGE(bufoff, gbase, voff) do { _Pragma("unroll") for (int _i = 0; _i < 2; ++_i) \
;         __builtin_amdgcn_global_load_lds((const unsigned*)((const char*)(gbase) + (voff)[_i]), (PG8_LAS unsigned*)(lds + (bufoff) + ldsw + _i * 8192), 16, 0, 0); } while (0)
; #define PG8_LDA(dst, b, h) do { _Pragma("unroll") for (int m = 0; m < 4; ++m) _Pragma("unroll") for (int k = 0; k < 2; ++k) dst[m][k] = *(const PG8_LAS bf16x8*)(lds + PG8_SA(b, h) + aoff + m * 2048 + k * 1024); } while (0)
; #define PG8_MMA(ai, bj, At, Bt) do { __builtin_amdgcn_s_setprio(1); _Pragma("unroll") for (int m = 0; m < 4; ++m) _Pragma("unroll") for (int n = 0; n < 2; ++n) _Pragma("unroll") for (int k = 0; k < 2; ++k) \
;         acc[ai][bj][m][n] = __builtin_amdgcn_mfma_f32_16x16x32_bf16(Bt[n][k], At[m][k], acc[ai][bj][m][n], 0, 0, 0); __builtin_amdgcn_s_setprio(0); } while (0)
; #define PG8_WAIT_V(n) asm volatile("s_waitcnt vmcnt(" #n ")" ::: "memory")
; #define PG8_WAIT_L(n) asm volatile("s_waitcnt lgkmcnt(" #n ")" ::: "memory")
; #define PG8_BAR __builtin_amdgcn_s_barrier()
; #define PG8_SCHED __builtin_amdgcn_sched_barrier(0)
; template <class Epi, class Sched, bool ALIGN_EPI = false, bool SP2 = false>
; __device__ __forceinline__ void gemm_phase(PG8_LAS unsigned char* lds, const Gemm g, const Sched& S, const Epi& E) {
;     ...
;         for (int t = 0; t < nt; t += 2) {
;             const bool last = (t == nt - 2);
;             const char* a1 = cA + (size_t)(t + 1) * kstep;
;             const char* a2 = last ? nA : cA + (size_t)(t + 2) * kstep; const char* b2 = last ? nB : cB + (size_t)(t + 2) * kstep;
;             const char* a3 = a2 + kstep; const char* b3 = b2 + kstep;
;             if (last && has_next) S.a_ready(nxt);
;     ...
;             PG8_LDA(At, 1, 1); PG8_STAGE(PG8_SB(1, 0), b3, voffB); PG8_STAGE(PG8_SB(1, 1), b3 + hstepB, voffB); PG8_STAGE(PG8_SA(1, 0), a3, voffA);
;             PG8_WAIT_V(8); PG8_WAIT_L(0); PG8_BAR; PG8_MMA(1, 0, At, B0); PG8_MMA(1, 1, At, B1); PG8_BAR; PG8_SCHED;
	s_add_i32 s36, s72, s48
	v_lshl_add_u64 v[206:207], v[206:207], 0, s[4:5]
	s_mov_b32 m0, s36
	ds_read_b128 v[174:177], v160 offset:49152
	ds_read_b128 v[178:181], v160 offset:50176
	ds_read_b128 v[182:185], v160 offset:51200
	ds_read_b128 v[186:189], v160 offset:52224
	ds_read_b128 v[190:193], v160 offset:53248
	ds_read_b128 v[194:197], v160 offset:54272
	ds_read_b128 v[198:201], v160 offset:55296
	ds_read_b128 v[202:205], v160 offset:56320
	global_load_lds_dwordx4 v[206:207], off
	s_add_i32 m0, s36, 0x2000
	s_add_u32 s34, s34, 0x40080
	v_lshl_add_u64 v[206:207], v[208:209], 0, s[4:5]
	s_addc_u32 s35, s35, 0
	s_add_i32 s36, s73, s48
	global_load_lds_dwordx4 v[206:207], off
	v_lshl_add_u64 v[206:207], s[34:35], 0, v[148:149]
	s_mov_b32 m0, s36
	s_nop 0
	global_load_lds_dwordx4 v[206:207], off
	v_lshl_add_u64 v[206:207], s[34:35], 0, v[146:147]
	s_add_i32 m0, s36, 0x2000
	s_nop 0
	global_load_lds_dwordx4 v[206:207], off
	v_lshl_add_u64 v[206:207], v[210:211], 0, s[4:5]
	s_mov_b32 m0, s59
	s_nop 0
	global_load_lds_dwordx4 v[206:207], off
	v_lshl_add_u64 v[206:207], v[212:213], 0, s[4:5]
	s_mov_b32 m0, s60
	s_nop 0
	global_load_lds_dwordx4 v[206:207], off
	s_waitcnt vmcnt(8)
	s_waitcnt lgkmcnt(0)
	s_barrier
	s_setprio 1
	s_waitcnt lgkmcnt(0)
	v_mfma_f32_16x16x32_bf16 v[62:65], v[130:133], v[174:177], v[62:65]
	v_mfma_f32_16x16x32_bf16 v[58:61], v[138:141], v[174:177], v[58:61]
	v_mfma_f32_16x16x32_bf16 v[54:57], v[130:133], v[182:185], v[54:57]
	v_mfma_f32_16x16x32_bf16 v[50:53], v[138:141], v[182:185], v[50:53]
	v_mfma_f32_16x16x32_bf16 v[46:49], v[130:133], v[190:193], v[46:49]
	v_mfma_f32_16x16x32_bf16 v[38:41], v[138:141], v[190:193], v[38:41]
	v_mfma_f32_16x16x32_bf16 v[18:21], v[130:133], v[198:201], v[18:21]
	v_mfma_f32_16x16x32_bf16 v[10:13], v[138:141], v[198:201], v[10:13]
	v_mfma_f32_16x16x32_bf16 v[62:65], v[134:137], v[178:181], v[62:65]
	v_mfma_f32_16x16x32_bf16 v[58:61], v[142:145], v[178:181], v[58:61]
	v_mfma_f32_16x16x32_bf16 v[54:57], v[134:137], v[186:189], v[54:57]
	v_mfma_f32_16x16x32_bf16 v[50:53], v[142:145], v[186:189], v[50:53]
	v_mfma_f32_16x16x32_bf16 v[46:49], v[134:137], v[194:197], v[46:49]
	v_mfma_f32_16x16x32_bf16 v[38:41], v[142:145], v[194:197], v[38:41]
	v_mfma_f32_16x16x32_bf16 v[18:21], v[134:137], v[202:205], v[18:21]
	v_mfma_f32_16x16x32_bf16 v[10:13], v[142:145], v[202:205], v[10:13]
	v_mfma_f32_16x16x32_bf16 v[42:45], v[152:155], v[174:177], v[42:45]
	v_mfma_f32_16x16x32_bf16 v[34:37], v[166:169], v[174:177], v[34:37]
	v_mfma_f32_16x16x32_bf16 v[30:33], v[152:155], v[182:185], v[30:33]
	v_mfma_f32_16x16x32_bf16 v[26:29], v[166:169], v[182:185], v[26:29]
	v_mfma_f32_16x16x32_bf16 v[22:25], v[152:155], v[190:193], v[22:25]
	v_mfma_f32_16x16x32_bf16 v[14:17], v[166:169], v[190:193], v[14:17]
	v_mfma_f32_16x16x32_bf16 v[6:9], v[152:155], v[198:201], v[6:9]
	v_mfma_f32_16x16x32_bf16 v[2:5], v[166:169], v[198:201], v[2:5]
	v_mfma_f32_16x16x32_bf16 v[42:45], v[162:165], v[178:181], v[42:45]
	v_mfma_f32_16x16x32_bf16 v[34:37], v[170:173], v[178:181], v[34:37]
	v_mfma_f32_16x16x32_bf16 v[30:33], v[162:165], v[186:189], v[30:33]
	v_mfma_f32_16x16x32_bf16 v[26:29], v[170:173], v[186:189], v[26:29]
	v_mfma_f32_16x16x32_bf16 v[22:25], v[162:165], v[194:197], v[22:25]
	v_mfma_f32_16x16x32_bf16 v[14:17], v[170:173], v[194:197], v[14:17]
	v_mfma_f32_16x16x32_bf16 v[6:9], v[162:165], v[202:205], v[6:9]
	v_mfma_f32_16x16x32_bf16 v[2:5], v[170:173], v[202:205], v[2:5]
	s_setprio 0
	s_barrier
	s_movk_i32 s72, 0x100
	s_and_b64 vcc, exec, s[30:31]
	s_mov_b64 s[34:35], -1
	s_mov_b64 s[30:31], 0
	s_cbranch_vccnz .LBB0_1364
	s_andn2_b64 vcc, exec, s[8:9]
	s_cbranch_vccnz .LBB0_1367
	s_barrier

; #define PG8_STAGE(bufoff, gbase, voff) do { _Pragma("unroll") for (int _i = 0; _i < 2; ++_i) \
;         __builtin_amdgcn_global_load_lds((const unsigned*)((const char*)(gbase) + (voff)[_i]), (PG8_LAS unsigned*)(lds + (bufoff) + ldsw + _i * 8192), 16, 0, 0); } while (0)
; #define PG8_LDA(dst, b, h) do { _Pragma("unroll") for (int m = 0; m < 4; ++m) _Pragma("unroll") for (int k = 0; k < 2; ++k) dst[m][k] = *(const PG8_LAS bf16x8*)(lds + PG8_SA(b, h) + aoff + m * 2048 + k * 1024); } while (0)
; #define PG8_LDB(dst, b, h) do { _Pragma("unroll") for (int n = 0; n < 2; ++n) _Pragma("unroll") for (int k = 0; k < 2; ++k) dst[n][k] = *(const PG8_LAS bf16x8*)(lds + PG8_SB(b, h) + boff + n * 2048 + k * 1024); } while (0)
; #define PG8_MMA(ai, bj, At, Bt) do { __builtin_amdgcn_s_setprio(1); _Pragma("unroll") for (int m = 0; m < 4; ++m) _Pragma("unroll") for (int n = 0; n < 2; ++n) _Pragma("unroll") for (int k = 0; k < 2; ++k) \
;         acc[ai][bj][m][n] = __builtin_amdgcn_mfma_f32_16x16x32_bf16(Bt[n][k], At[m][k], acc[ai][bj][m][n], 0, 0, 0); __builtin_amdgcn_s_setprio(0); } while (0)
; template <class Epi, class Sched, bool ALIGN_EPI = false, bool SP2 = false>
; __device__ __forceinline__ void gemm_phase(PG8_LAS unsigned char* lds, const Gemm g, const Sched& S, const Epi& E) {
;     ...
;         const bool has_next = S.next(ui + 1, nxt);
;         const char* nA = has_next ? (const char*)g.A + (size_t)nxt.pm * tstepA : cA; const char* nB = has_next ? (const char*)g.Bt + (size_t)nxt.pn * tstepB : cB;
; #pragma unroll 1
;         for (int t = 0; t < nt; t += 2) {
;             const bool last = (t == nt - 2);
;             const char* a1 = cA + (size_t)(t + 1) * kstep;
;             const char* a2 = last ? nA : cA + (size_t)(t + 2) * kstep; const char* b2 = last ? nB : cB + (size_t)(t + 2) * kstep;
;             const char* a3 = a2 + kstep; const char* b3 = b2 + kstep;
;             if (last && has_next) S.a_ready(nxt);
;             if constexpr (SP2) {
;             PG8_LDB(B0, 0, 0); PG8_LDB(B1, 0, 1); PG8_SCHED; PG8_LDA(At, 0, 0); PG8_STAGE(PG8_SA(1, 1), a1 + hstepA, voffA);
;             PG8_WAIT_V(8); PG8_WAIT_L(0); PG8_BAR; PG8_MMA(0, 0, At, B0); PG8_MMA(0, 1, At, B1); PG8_BAR; PG8_SCHED;
;             PG8_LDA(At, 0, 1); PG8_STAGE(PG8_SB(0, 0), b2, voffB); PG8_STAGE(PG8_SB(0, 1), b2 + hstepB, voffB); PG8_STAGE(PG8_SA(0, 0), a2, voffA);
.LBB0_1384:
	s_add_u32 s70, s28, s69
	ds_read_b128 v[130:133], v158
	ds_read_b128 v[134:137], v158 offset:1024
	ds_read_b128 v[138:141], v158 offset:2048
	ds_read_b128 v[142:145], v158 offset:3072
	ds_read_b128 v[152:155], v159
	ds_read_b128 v[162:165], v159 offset:1024
	ds_read_b128 v[166:169], v159 offset:2048
	ds_read_b128 v[170:173], v159 offset:3072
	s_addc_u32 s71, s29, 0
	s_add_u32 s72, s70, 0x100
	s_addc_u32 s73, s71, 0
	s_and_b64 s[36:37], s[34:35], exec
	s_cselect_b32 s37, s17, s73
	s_cselect_b32 s36, s67, s72
	s_add_u32 s69, s26, s69
	s_addc_u32 s72, s27, 0
	s_add_u32 s69, s69, 0x100
	s_addc_u32 s72, s72, 0
	s_and_b64 s[34:35], s[34:35], exec
	s_cselect_b32 s35, s15, s72
	s_cselect_b32 s34, s68, s69
	s_add_u32 s70, s70, 0x40080
	s_addc_u32 s71, s71, 0
	v_lshl_add_u64 v[206:207], s[70:71], 0, v[148:149]
	s_add_i32 m0, s47, 0xc000
	ds_read_b128 v[174:177], v160
	ds_read_b128 v[178:181], v160 offset:1024
	ds_read_b128 v[182:185], v160 offset:2048
	ds_read_b128 v[186:189], v160 offset:3072
	ds_read_b128 v[190:193], v160 offset:4096
	ds_read_b128 v[194:197], v160 offset:5120
	ds_read_b128 v[198:201], v160 offset:6144
	ds_read_b128 v[202:205], v160 offset:7168
	global_load_lds_dwordx4 v[206:207], off
	v_lshl_add_u64 v[206:207], s[70:71], 0, v[146:147]
	s_add_i32 m0, s47, 0xe000
	s_nop 0
	global_load_lds_dwordx4 v[206:207], off
	s_waitcnt vmcnt(8)
	s_waitcnt lgkmcnt(0)
	s_barrier
	s_setprio 1
	s_waitcnt lgkmcnt(0)
	v_mfma_f32_16x16x32_bf16 v[126:129], v[130:133], v[174:177], v[126:129]
	v_mfma_f32_16x16x32_bf16 v[122:125], v[138:141], v[174:177], v[122:125]
	v_mfma_f32_16x16x32_bf16 v[118:121], v[130:133], v[182:185], v[118:121]
	v_mfma_f32_16x16x32_bf16 v[114:117], v[138:141], v[182:185], v[114:117]
	v_mfma_f32_16x16x32_bf16 v[102:105], v[130:133], v[190:193], v[102:105]
	v_mfma_f32_16x16x32_bf16 v[90:93], v[138:141], v[190:193], v[90:93]
	v_mfma_f32_16x16x32_bf16 v[82:85], v[130:133], v[198:201], v[82:85]
	v_mfma_f32_16x16x32_bf16 v[74:77], v[138:141], v[198:201], v[74:77]
	v_mfma_f32_16x16x32_bf16 v[126:129], v[134:137], v[178:181], v[126:129]
	v_mfma_f32_16x16x32_bf16 v[122:125], v[142:145], v[178:181], v[122:125]
	v_mfma_f32_16x16x32_bf16 v[118:121], v[134:137], v[186:189], v[118:121]
	v_mfma_f32_16x16x32_bf16 v[114:117], v[142:145], v[186:189], v[114:117]
	v_mfma_f32_16x16x32_bf16 v[102:105], v[134:137], v[194:197], v[102:105]
	v_mfma_f32_16x16x32_bf16 v[90:93], v[142:145], v[194:197], v[90:93]
	v_mfma_f32_16x16x32_bf16 v[82:85], v[134:137], v[202:205], v[82:85]
	v_mfma_f32_16x16x32_bf16 v[74:77], v[142:145], v[202:205], v[74:77]
	v_mfma_f32_16x16x32_bf16 v[110:113], v[152:155], v[174:177], v[110:113]
	v_mfma_f32_16x16x32_bf16 v[106:109], v[166:169], v[174:177], v[106:109]
	v_mfma_f32_16x16x32_bf16 v[98:101], v[152:155], v[182:185], v[98:101]
	v_mfma_f32_16x16x32_bf16 v[94:97], v[166:169], v[182:185], v[94:97]
	v_mfma_f32_16x16x32_bf16 v[86:89], v[152:155], v[190:193], v[86:89]
	v_mfma_f32_16x16x32_bf16 v[78:81], v[166:169], v[190:193], v[78:81]
	v_mfma_f32_16x16x32_bf16 v[70:73], v[152:155], v[198:201], v[70:73]
	v_mfma_f32_16x16x32_bf16 v[66:69], v[166:169], v[198:201], v[66:69]
	v_mfma_f32_16x16x32_bf16 v[110:113], v[162:165], v[178:181], v[110:113]
	v_mfma_f32_16x16x32_bf16 v[106:109], v[170:173], v[178:181], v[106:109]
	v_mfma_f32_16x16x32_bf16 v[98:101], v[162:165], v[186:189], v[98:101]
	v_mfma_f32_16x16x32_bf16 v[94:97], v[170:173], v[186:189], v[94:97]
	v_mfma_f32_16x16x32_bf16 v[86:89], v[162:165], v[194:197], v[86:89]
	v_mfma_f32_16x16x32_bf16 v[78:81], v[170:173], v[194:197], v[78:81]
	v_mfma_f32_16x16x32_bf16 v[70:73], v[162:165], v[202:205], v[70:73]
	v_mfma_f32_16x16x32_bf16 v[66:69], v[170:173], v[202:205], v[66:69]
	s_setprio 0
	s_barrier
	s_add_i32 s69, s59, s44
	v_lshl_add_u64 v[206:207], s[34:35], 0, v[148:149]
	s_mov_b32 m0, s69
	ds_read_b128 v[174:177], v160 offset:16384
	ds_read_b128 v[178:181], v160 offset:17408
	ds_read_b128 v[182:185], v160 offset:18432
	ds_read_b128 v[186:189], v160 offset:19456
	ds_read_b128 v[190:193], v160 offset:20480
	ds_read_b128 v[194:197], v160 offset:21504
	ds_read_b128 v[198:201], v160 offset:22528
	ds_read_b128 v[202:205], v160 offset:23552
	global_load_lds_dwordx4 v[206:207], off
	s_add_i32 m0, s69, 0x2000
	s_add_u32 s70, s34, 0x40000
	v_lshl_add_u64 v[208:209], s[34:35], 0, v[146:147]
	s_addc_u32 s71, s35, 0
	s_add_i32 s69, s60, s44
	global_load_lds_dwordx4 v[208:209], off
	v_lshl_add_u64 v[210:211], s[70:71], 0, v[148:149]
	s_mov_b32 m0, s69
	v_lshl_add_u64 v[212:213], s[36:37], 0, v[146:147]
	global_load_lds_dwordx4 v[210:211], off
	v_lshl_add_u64 v[210:211], s[70:71], 0, v[146:147]
	s_add_i32 m0, s69, 0x2000
	s_nop 0
	global_load_lds_dwordx4 v[210:211], off
	v_lshl_add_u64 v[210:211], s[36:37], 0, v[148:149]
	s_mov_b32 m0, s47
	s_nop 0
	global_load_lds_dwordx4 v[210:211], off
	s_mov_b32 m0, s48
	s_nop 0
	global_load_lds_dwordx4 v[212:213], off
	s_waitcnt vmcnt(8)
	s_waitcnt lgkmcnt(0)
	s_barrier
; #define PG8_STAGE(bufoff, gbase, voff) do { _Pragma("unroll") for (int _i = 0; _i < 2; ++_i) \
;         __builtin_amdgcn_global_load_lds((const unsigned*)((const char*)(gbase) + (voff)[_i]), (PG8_LAS unsigned*)(lds + (bufoff) + ldsw + _i * 8192), 16, 0, 0); } while (0)
; #define PG8_LDA(dst, b, h) do { _Pragma("unroll") for (int m = 0; m < 4; ++m) _Pragma("unroll") for (int k = 0; k < 2; ++k) dst[m][k] = *(const PG8_LAS bf16x8*)(lds + PG8_SA(b, h) + aoff + m * 2048 + k * 1024); } while (0)
; #define PG8_LDB(dst, b, h) do { _Pragma("unroll") for (int n = 0; n < 2; ++n) _Pragma("unroll") for (int k = 0; k < 2; ++k) dst[n][k] = *(const PG8_LAS bf16x8*)(lds + PG8_SB(b, h) + boff + n * 2048 + k * 1024); } while (0)
; #define PG8_MMA(ai, bj, At, Bt) do { __builtin_amdgcn_s_setprio(1); _Pragma("unroll") for (int m = 0; m < 4; ++m) _Pragma("unroll") for (int n = 0; n < 2; ++n) _Pragma("unroll") for (int k = 0; k < 2; ++k) \
;         acc[ai][bj][m][n] = __builtin_amdgcn_mfma_f32_16x16x32_bf16(Bt[n][k], At[m][k], acc[ai][bj][m][n], 0, 0, 0); __builtin_amdgcn_s_setprio(0); } while (0)
; #define PG8_WAIT_V(n) asm volatile("s_waitcnt vmcnt(" #n ")" ::: "memory")
; #define PG8_WAIT_L(n) asm volatile("s_waitcnt lgkmcnt(" #n ")" ::: "memory")
; #define PG8_BAR __builtin_amdgcn_s_barrier()
; #define PG8_SCHED __builtin_amdgcn_sched_barrier(0)
; template <class Epi, class Sched, bool ALIGN_EPI = false, bool SP2 = false>
; __device__ __forceinline__ void gemm_phase(PG8_LAS unsigned char* lds, const Gemm g, const Sched& S, const Epi& E) {
;     ...
;             PG8_WAIT_V(8); PG8_WAIT_L(0); PG8_BAR; PG8_MMA(1, 0, At, B0); PG8_MMA(1, 1, At, B1); PG8_BAR; PG8_SCHED;
;             PG8_LDB(B0, 1, 0); PG8_LDB(B1, 1, 1); PG8_SCHED; PG8_LDA(At, 1, 0); PG8_STAGE(PG8_SA(0, 1), a2 + hstepA, voffA);
;             PG8_WAIT_V(8); PG8_WAIT_L(0); PG8_BAR; PG8_MMA(0, 0, At, B0); PG8_MMA(0, 1, At, B1); PG8_BAR; PG8_SCHED;
	s_setprio 1
	s_waitcnt lgkmcnt(0)
	v_mfma_f32_16x16x32_bf16 v[62:65], v[130:133], v[174:177], v[62:65]
	v_mfma_f32_16x16x32_bf16 v[58:61], v[138:141], v[174:177], v[58:61]
	v_mfma_f32_16x16x32_bf16 v[54:57], v[130:133], v[182:185], v[54:57]
	v_mfma_f32_16x16x32_bf16 v[50:53], v[138:141], v[182:185], v[50:53]
	v_mfma_f32_16x16x32_bf16 v[46:49], v[130:133], v[190:193], v[46:49]
	v_mfma_f32_16x16x32_bf16 v[38:41], v[138:141], v[190:193], v[38:41]
	v_mfma_f32_16x16x32_bf16 v[18:21], v[130:133], v[198:201], v[18:21]
	v_mfma_f32_16x16x32_bf16 v[10:13], v[138:141], v[198:201], v[10:13]
	v_mfma_f32_16x16x32_bf16 v[62:65], v[134:137], v[178:181], v[62:65]
	v_mfma_f32_16x16x32_bf16 v[58:61], v[142:145], v[178:181], v[58:61]
	v_mfma_f32_16x16x32_bf16 v[54:57], v[134:137], v[186:189], v[54:57]
	v_mfma_f32_16x16x32_bf16 v[50:53], v[142:145], v[186:189], v[50:53]
	v_mfma_f32_16x16x32_bf16 v[46:49], v[134:137], v[194:197], v[46:49]
	v_mfma_f32_16x16x32_bf16 v[38:41], v[142:145], v[194:197], v[38:41]
	v_mfma_f32_16x16x32_bf16 v[18:21], v[134:137], v[202:205], v[18:21]
	v_mfma_f32_16x16x32_bf16 v[10:13], v[142:145], v[202:205], v[10:13]
	v_mfma_f32_16x16x32_bf16 v[42:45], v[152:155], v[174:177], v[42:45]
	v_mfma_f32_16x16x32_bf16 v[34:37], v[166:169], v[174:177], v[34:37]
	v_mfma_f32_16x16x32_bf16 v[30:33], v[152:155], v[182:185], v[30:33]
	v_mfma_f32_16x16x32_bf16 v[26:29], v[166:169], v[182:185], v[26:29]
	v_mfma_f32_16x16x32_bf16 v[22:25], v[152:155], v[190:193], v[22:25]
	v_mfma_f32_16x16x32_bf16 v[14:17], v[166:169], v[190:193], v[14:17]
	v_mfma_f32_16x16x32_bf16 v[6:9], v[152:155], v[198:201], v[6:9]
	v_mfma_f32_16x16x32_bf16 v[2:5], v[166:169], v[198:201], v[2:5]
	v_mfma_f32_16x16x32_bf16 v[42:45], v[162:165], v[178:181], v[42:45]
	v_mfma_f32_16x16x32_bf16 v[34:37], v[170:173], v[178:181], v[34:37]
	v_mfma_f32_16x16x32_bf16 v[30:33], v[162:165], v[186:189], v[30:33]
	v_mfma_f32_16x16x32_bf16 v[26:29], v[170:173], v[186:189], v[26:29]
	v_mfma_f32_16x16x32_bf16 v[22:25], v[162:165], v[194:197], v[22:25]
	v_mfma_f32_16x16x32_bf16 v[14:17], v[170:173], v[194:197], v[14:17]
	v_mfma_f32_16x16x32_bf16 v[6:9], v[162:165], v[202:205], v[6:9]
	v_mfma_f32_16x16x32_bf16 v[2:5], v[170:173], v[202:205], v[2:5]
	s_setprio 0
	s_barrier
	s_add_i32 s69, 0, 0x18000
	s_add_i32 s70, 0, 0x1c000
	v_add_u32_e32 v142, s69, v1
	v_add_u32_e32 v170, s70, v1
	ds_read_b128 v[130:133], v142
	ds_read_b128 v[134:137], v142 offset:1024
	ds_read_b128 v[138:141], v142 offset:2048
	ds_read_b128 v[142:145], v142 offset:3072
	ds_read_b128 v[152:155], v170
	ds_read_b128 v[162:165], v170 offset:1024
	ds_read_b128 v[166:169], v170 offset:2048
	ds_read_b128 v[170:173], v170 offset:3072
	s_add_u32 s36, s36, 0x40000
	s_addc_u32 s37, s37, 0
	s_mov_b32 m0, s49
	v_lshl_add_u64 v[214:215], s[36:37], 0, v[148:149]
	ds_read_b128 v[174:177], v160 offset:32768
	ds_read_b128 v[178:181], v160 offset:33792
	ds_read_b128 v[182:185], v160 offset:34816
	ds_read_b128 v[186:189], v160 offset:35840
	ds_read_b128 v[190:193], v160 offset:36864
	ds_read_b128 v[194:197], v160 offset:37888
	ds_read_b128 v[198:201], v160 offset:38912
	ds_read_b128 v[202:205], v160 offset:39936
	global_load_lds_dwordx4 v[214:215], off
	v_lshl_add_u64 v[214:215], s[36:37], 0, v[146:147]
	s_mov_b32 m0, s50
	s_nop 0
	global_load_lds_dwordx4 v[214:215], off
	s_waitcnt vmcnt(8)
	s_waitcnt lgkmcnt(0)
	s_barrier
	s_setprio 1
	s_waitcnt lgkmcnt(0)
	v_mfma_f32_16x16x32_bf16 v[126:129], v[130:133], v[174:177], v[126:129]
	v_mfma_f32_16x16x32_bf16 v[122:125], v[138:141], v[174:177], v[122:125]
	v_mfma_f32_16x16x32_bf16 v[118:121], v[130:133], v[182:185], v[118:121]
	v_mfma_f32_16x16x32_bf16 v[114:117], v[138:141], v[182:185], v[114:117]
	v_mfma_f32_16x16x32_bf16 v[102:105], v[130:133], v[190:193], v[102:105]
	v_mfma_f32_16x16x32_bf16 v[90:93], v[138:141], v[190:193], v[90:93]
	v_mfma_f32_16x16x32_bf16 v[82:85], v[130:133], v[198:201], v[82:85]
	v_mfma_f32_16x16x32_bf16 v[74:77], v[138:141], v[198:201], v[74:77]
	v_mfma_f32_16x16x32_bf16 v[126:129], v[134:137], v[178:181], v[126:129]
	v_mfma_f32_16x16x32_bf16 v[122:125], v[142:145], v[178:181], v[122:125]
	v_mfma_f32_16x16x32_bf16 v[118:121], v[134:137], v[186:189], v[118:121]
	v_mfma_f32_16x16x32_bf16 v[114:117], v[142:145], v[186:189], v[114:117]
	v_mfma_f32_16x16x32_bf16 v[102:105], v[134:137], v[194:197], v[102:105]
	v_mfma_f32_16x16x32_bf16 v[90:93], v[142:145], v[194:197], v[90:93]
	v_mfma_f32_16x16x32_bf16 v[82:85], v[134:137], v[202:205], v[82:85]
	v_mfma_f32_16x16x32_bf16 v[74:77], v[142:145], v[202:205], v[74:77]
	v_mfma_f32_16x16x32_bf16 v[110:113], v[152:155], v[174:177], v[110:113]
	v_mfma_f32_16x16x32_bf16 v[106:109], v[166:169], v[174:177], v[106:109]
	v_mfma_f32_16x16x32_bf16 v[98:101], v[152:155], v[182:185], v[98:101]
	v_mfma_f32_16x16x32_bf16 v[94:97], v[166:169], v[182:185], v[94:97]
	v_mfma_f32_16x16x32_bf16 v[86:89], v[152:155], v[190:193], v[86:89]
	v_mfma_f32_16x16x32_bf16 v[78:81], v[166:169], v[190:193], v[78:81]
	v_mfma_f32_16x16x32_bf16 v[70:73], v[152:155], v[198:201], v[70:73]
	v_mfma_f32_16x16x32_bf16 v[66:69], v[166:169], v[198:201], v[66:69]
	v_mfma_f32_16x16x32_bf16 v[110:113], v[162:165], v[178:181], v[110:113]
	v_mfma_f32_16x16x32_bf16 v[106:109], v[170:173], v[178:181], v[106:109]
	v_mfma_f32_16x16x32_bf16 v[98:101], v[162:165], v[186:189], v[98:101]
	v_mfma_f32_16x16x32_bf16 v[94:97], v[170:173], v[186:189], v[94:97]
	v_mfma_f32_16x16x32_bf16 v[86:89], v[162:165], v[194:197], v[86:89]
	v_mfma_f32_16x16x32_bf16 v[78:81], v[170:173], v[194:197], v[78:81]
	v_mfma_f32_16x16x32_bf16 v[70:73], v[162:165], v[202:205], v[70:73]
	v_mfma_f32_16x16x32_bf16 v[66:69], v[170:173], v[202:205], v[66:69]
	s_setprio 0
	s_barrier
; #define PG8_STAGE(bufoff, gbase, voff) do { _Pragma("unroll") for (int _i = 0; _i < 2; ++_i) \
;         __builtin_amdgcn_global_load_lds((const unsigned*)((const char*)(gbase) + (voff)[_i]), (PG8_LAS unsigned*)(lds + (bufoff) + ldsw + _i * 8192), 16, 0, 0); } while (0)
; #define PG8_LDA(dst, b, h) do { _Pragma("unroll") for (int m = 0; m < 4; ++m) _Pragma("unroll") for (int k = 0; k < 2; ++k) dst[m][k] = *(const PG8_LAS bf16x8*)(lds + PG8_SA(b, h) + aoff + m * 2048 + k * 1024); } while (0)
; #define PG8_MMA(ai, bj, At, Bt) do { __builtin_amdgcn_s_setprio(1); _Pragma("unroll") for (int m = 0; m < 4; ++m) _Pragma("unroll") for (int n = 0; n < 2; ++n) _Pragma("unroll") for (int k = 0; k < 2; ++k) \
;         acc[ai][bj][m][n] = __builtin_amdgcn_mfma_f32_16x16x32_bf16(Bt[n][k], At[m][k], acc[ai][bj][m][n], 0, 0, 0); __builtin_amdgcn_s_setprio(0); } while (0)
; #define PG8_WAIT_V(n) asm volatile("s_waitcnt vmcnt(" #n ")" ::: "memory")
; #define PG8_WAIT_L(n) asm volatile("s_waitcnt lgkmcnt(" #n ")" ::: "memory")
; #define PG8_BAR __builtin_amdgcn_s_barrier()
; #define PG8_SCHED __builtin_amdgcn_sched_barrier(0)
; template <class Epi, class Sched, bool ALIGN_EPI = false, bool SP2 = false>
; __device__ __forceinline__ void gemm_phase(PG8_LAS unsigned char* lds, const Gemm g, const Sched& S, const Epi& E) {
;     ...
;         for (int t = 0; t < nt; t += 2) {
;             const bool last = (t == nt - 2);
;             const char* a1 = cA + (size_t)(t + 1) * kstep;
;             const char* a2 = last ? nA : cA + (size_t)(t + 2) * kstep; const char* b2 = last ? nB : cB + (size_t)(t + 2) * kstep;
;             const char* a3 = a2 + kstep; const char* b3 = b2 + kstep;
;             if (last && has_next) S.a_ready(nxt);
;     ...
;             PG8_LDA(At, 1, 1); PG8_STAGE(PG8_SB(1, 0), b3, voffB); PG8_STAGE(PG8_SB(1, 1), b3 + hstepB, voffB); PG8_STAGE(PG8_SA(1, 0), a3, voffA);
;             PG8_WAIT_V(8); PG8_WAIT_L(0); PG8_BAR; PG8_MMA(1, 0, At, B0); PG8_MMA(1, 1, At, B1); PG8_BAR; PG8_SCHED;
	s_add_i32 s36, s69, s44
	v_lshl_add_u64 v[206:207], v[206:207], 0, s[4:5]
	s_mov_b32 m0, s36
	ds_read_b128 v[174:177], v160 offset:49152
	ds_read_b128 v[178:181], v160 offset:50176
	ds_read_b128 v[182:185], v160 offset:51200
	ds_read_b128 v[186:189], v160 offset:52224
	ds_read_b128 v[190:193], v160 offset:53248
	ds_read_b128 v[194:197], v160 offset:54272
	ds_read_b128 v[198:201], v160 offset:55296
	ds_read_b128 v[202:205], v160 offset:56320
	global_load_lds_dwordx4 v[206:207], off
	s_add_i32 m0, s36, 0x2000
	s_add_u32 s34, s34, 0x40080
	v_lshl_add_u64 v[206:207], v[208:209], 0, s[4:5]
	s_addc_u32 s35, s35, 0
	s_add_i32 s36, s70, s44
	global_load_lds_dwordx4 v[206:207], off
	v_lshl_add_u64 v[206:207], s[34:35], 0, v[148:149]
	s_mov_b32 m0, s36
	s_nop 0
	global_load_lds_dwordx4 v[206:207], off
	v_lshl_add_u64 v[206:207], s[34:35], 0, v[146:147]
	s_add_i32 m0, s36, 0x2000
	s_nop 0
	global_load_lds_dwordx4 v[206:207], off
	v_lshl_add_u64 v[206:207], v[210:211], 0, s[4:5]
	s_mov_b32 m0, s57
	s_nop 0
	global_load_lds_dwordx4 v[206:207], off
	v_lshl_add_u64 v[206:207], v[212:213], 0, s[4:5]
	s_mov_b32 m0, s58
	s_nop 0
	global_load_lds_dwordx4 v[206:207], off
	s_waitcnt vmcnt(8)
	s_waitcnt lgkmcnt(0)
	s_barrier
	s_setprio 1
	s_waitcnt lgkmcnt(0)
	v_mfma_f32_16x16x32_bf16 v[62:65], v[130:133], v[174:177], v[62:65]
	v_mfma_f32_16x16x32_bf16 v[58:61], v[138:141], v[174:177], v[58:61]
	v_mfma_f32_16x16x32_bf16 v[54:57], v[130:133], v[182:185], v[54:57]
	v_mfma_f32_16x16x32_bf16 v[50:53], v[138:141], v[182:185], v[50:53]
	v_mfma_f32_16x16x32_bf16 v[46:49], v[130:133], v[190:193], v[46:49]
	v_mfma_f32_16x16x32_bf16 v[38:41], v[138:141], v[190:193], v[38:41]
	v_mfma_f32_16x16x32_bf16 v[18:21], v[130:133], v[198:201], v[18:21]
	v_mfma_f32_16x16x32_bf16 v[10:13], v[138:141], v[198:201], v[10:13]
	v_mfma_f32_16x16x32_bf16 v[62:65], v[134:137], v[178:181], v[62:65]
	v_mfma_f32_16x16x32_bf16 v[58:61], v[142:145], v[178:181], v[58:61]
	v_mfma_f32_16x16x32_bf16 v[54:57], v[134:137], v[186:189], v[54:57]
	v_mfma_f32_16x16x32_bf16 v[50:53], v[142:145], v[186:189], v[50:53]
	v_mfma_f32_16x16x32_bf16 v[46:49], v[134:137], v[194:197], v[46:49]
	v_mfma_f32_16x16x32_bf16 v[38:41], v[142:145], v[194:197], v[38:41]
	v_mfma_f32_16x16x32_bf16 v[18:21], v[134:137], v[202:205], v[18:21]
	v_mfma_f32_16x16x32_bf16 v[10:13], v[142:145], v[202:205], v[10:13]
	v_mfma_f32_16x16x32_bf16 v[42:45], v[152:155], v[174:177], v[42:45]
	v_mfma_f32_16x16x32_bf16 v[34:37], v[166:169], v[174:177], v[34:37]
	v_mfma_f32_16x16x32_bf16 v[30:33], v[152:155], v[182:185], v[30:33]
	v_mfma_f32_16x16x32_bf16 v[26:29], v[166:169], v[182:185], v[26:29]
	v_mfma_f32_16x16x32_bf16 v[22:25], v[152:155], v[190:193], v[22:25]
	v_mfma_f32_16x16x32_bf16 v[14:17], v[166:169], v[190:193], v[14:17]
	v_mfma_f32_16x16x32_bf16 v[6:9], v[152:155], v[198:201], v[6:9]
	v_mfma_f32_16x16x32_bf16 v[2:5], v[166:169], v[198:201], v[2:5]
	v_mfma_f32_16x16x32_bf16 v[42:45], v[162:165], v[178:181], v[42:45]
	v_mfma_f32_16x16x32_bf16 v[34:37], v[170:173], v[178:181], v[34:37]
	v_mfma_f32_16x16x32_bf16 v[30:33], v[162:165], v[186:189], v[30:33]
	v_mfma_f32_16x16x32_bf16 v[26:29], v[170:173], v[186:189], v[26:29]
	v_mfma_f32_16x16x32_bf16 v[22:25], v[162:165], v[194:197], v[22:25]
	v_mfma_f32_16x16x32_bf16 v[14:17], v[170:173], v[194:197], v[14:17]
	v_mfma_f32_16x16x32_bf16 v[6:9], v[162:165], v[202:205], v[6:9]
	v_mfma_f32_16x16x32_bf16 v[2:5], v[170:173], v[202:205], v[2:5]
	s_setprio 0
	s_barrier
	s_movk_i32 s69, 0x100
	s_and_b64 vcc, exec, s[30:31]
	s_mov_b64 s[34:35], -1
	s_mov_b64 s[30:31], 0
	s_cbranch_vccnz .LBB0_1384
	s_andn2_b64 vcc, exec, s[8:9]
	s_cbranch_vccnz .LBB0_1387
	s_barrier

; #define PG8_STAGE(bufoff, gbase, voff) do { _Pragma("unroll") for (int _i = 0; _i < 2; ++_i) \
;         __builtin_amdgcn_global_load_lds((const unsigned*)((const char*)(gbase) + (voff)[_i]), (PG8_LAS unsigned*)(lds + (bufoff) + ldsw + _i * 8192), 16, 0, 0); } while (0)
; #define PG8_LDA(dst, b, h) do { _Pragma("unroll") for (int m = 0; m < 4; ++m) _Pragma("unroll") for (int k = 0; k < 2; ++k) dst[m][k] = *(const PG8_LAS bf16x8*)(lds + PG8_SA(b, h) + aoff + m * 2048 + k * 1024); } while (0)
; #define PG8_LDB(dst, b, h) do { _Pragma("unroll") for (int n = 0; n < 2; ++n) _Pragma("unroll") for (int k = 0; k < 2; ++k) dst[n][k] = *(const PG8_LAS bf16x8*)(lds + PG8_SB(b, h) + boff + n * 2048 + k * 1024); } while (0)
; #define PG8_MMA(ai, bj, At, Bt) do { __builtin_amdgcn_s_setprio(1); _Pragma("unroll") for (int m = 0; m < 4; ++m) _Pragma("unroll") for (int n = 0; n < 2; ++n) _Pragma("unroll") for (int k = 0; k < 2; ++k) \
;         acc[ai][bj][m][n] = __builtin_amdgcn_mfma_f32_16x16x32_bf16(Bt[n][k], At[m][k], acc[ai][bj][m][n], 0, 0, 0); __builtin_amdgcn_s_setprio(0); } while (0)
; #define PG8_WAIT_V(n) asm volatile("s_waitcnt vmcnt(" #n ")" ::: "memory")
; #define PG8_WAIT_L(n) asm volatile("s_waitcnt lgkmcnt(" #n ")" ::: "memory")
; #define PG8_BAR __builtin_amdgcn_s_barrier()
; #define PG8_SCHED __builtin_amdgcn_sched_barrier(0)
; template <class Epi, class Sched, bool ALIGN_EPI = false, bool SP2 = false>
; __device__ __forceinline__ void gemm_phase(PG8_LAS unsigned char* lds, const Gemm g, const Sched& S, const Epi& E) {
;     ...
;             PG8_LDB(B0, 0, 0); PG8_LDB(B1, 0, 1); PG8_SCHED; PG8_LDA(At, 0, 0); PG8_STAGE(PG8_SA(1, 1), a1 + hstepA, voffA);
;             PG8_WAIT_V(8); PG8_WAIT_L(0); PG8_BAR; PG8_MMA(0, 0, At, B0); PG8_MMA(0, 1, At, B1); PG8_BAR; PG8_SCHED;
;             PG8_LDA(At, 0, 1); PG8_STAGE(PG8_SB(0, 0), b2, voffB); PG8_STAGE(PG8_SB(0, 1), b2 + hstepB, voffB); PG8_STAGE(PG8_SA(0, 0), a2, voffA);
;             PG8_WAIT_V(8); PG8_WAIT_L(0); PG8_BAR; PG8_MMA(1, 0, At, B0); PG8_MMA(1, 1, At, B1); PG8_BAR; PG8_SCHED;
;             PG8_LDB(B0, 1, 0); PG8_LDB(B1, 1, 1); PG8_SCHED; PG8_LDA(At, 1, 0); PG8_STAGE(PG8_SA(0, 1), a2 + hstepA, voffA);
;             PG8_WAIT_V(8); PG8_WAIT_L(0); PG8_BAR; PG8_MMA(0, 0, At, B0); PG8_MMA(0, 1, At, B1); PG8_BAR; PG8_SCHED;
.LBB0_1528:
	ds_read_b128 v[130:133], v182
	ds_read_b128 v[134:137], v182 offset:1024
	ds_read_b128 v[154:157], v182 offset:2048
	ds_read_b128 v[158:161], v182 offset:3072
	ds_read_b128 v[162:165], v183
	ds_read_b128 v[166:169], v183 offset:1024
	ds_read_b128 v[170:173], v183 offset:2048
	ds_read_b128 v[186:189], v183 offset:3072
	s_add_u32 s44, s42, 0xfffc0080
	s_addc_u32 s45, s43, -1
	s_cmp_eq_u32 s69, 12
	s_cselect_b32 s47, s31, s45
	s_cselect_b32 s46, s39, s44
	s_cselect_b32 s45, s29, s68
	s_cselect_b32 s44, s66, s67
	s_add_i32 m0, s41, 0xc000
	ds_read_b128 v[190:193], v184
	ds_read_b128 v[194:197], v184 offset:1024
	ds_read_b128 v[198:201], v184 offset:2048
	ds_read_b128 v[202:205], v184 offset:3072
	ds_read_b128 v[206:209], v184 offset:4096
	ds_read_b128 v[210:213], v184 offset:5120
	ds_read_b128 v[214:217], v184 offset:6144
	ds_read_b128 v[218:221], v184 offset:7168
	global_load_lds_dwordx4 v146, s[42:43]
	s_add_i32 m0, s41, 0xe000
	s_nop 0
	global_load_lds_dwordx4 v148, s[42:43]
	s_waitcnt vmcnt(8)
	s_waitcnt lgkmcnt(0)
	s_barrier
	s_setprio 1
	s_waitcnt lgkmcnt(0)
	v_mfma_f32_16x16x32_bf16 v[126:129], v[130:133], v[190:193], v[126:129]
	v_mfma_f32_16x16x32_bf16 v[94:97], v[154:157], v[190:193], v[94:97]
	v_mfma_f32_16x16x32_bf16 v[118:121], v[130:133], v[198:201], v[118:121]
	v_mfma_f32_16x16x32_bf16 v[86:89], v[154:157], v[198:201], v[86:89]
	v_mfma_f32_16x16x32_bf16 v[114:117], v[130:133], v[206:209], v[114:117]
	v_mfma_f32_16x16x32_bf16 v[82:85], v[154:157], v[206:209], v[82:85]
	v_mfma_f32_16x16x32_bf16 v[102:105], v[130:133], v[214:217], v[102:105]
	v_mfma_f32_16x16x32_bf16 v[70:73], v[154:157], v[214:217], v[70:73]
	v_mfma_f32_16x16x32_bf16 v[126:129], v[134:137], v[194:197], v[126:129]
	v_mfma_f32_16x16x32_bf16 v[94:97], v[158:161], v[194:197], v[94:97]
	v_mfma_f32_16x16x32_bf16 v[118:121], v[134:137], v[202:205], v[118:121]
	v_mfma_f32_16x16x32_bf16 v[86:89], v[158:161], v[202:205], v[86:89]
	v_mfma_f32_16x16x32_bf16 v[114:117], v[134:137], v[210:213], v[114:117]
	v_mfma_f32_16x16x32_bf16 v[82:85], v[158:161], v[210:213], v[82:85]
	v_mfma_f32_16x16x32_bf16 v[102:105], v[134:137], v[218:221], v[102:105]
	v_mfma_f32_16x16x32_bf16 v[70:73], v[158:161], v[218:221], v[70:73]
	v_mfma_f32_16x16x32_bf16 v[122:125], v[162:165], v[190:193], v[122:125]
	v_mfma_f32_16x16x32_bf16 v[90:93], v[170:173], v[190:193], v[90:93]
	v_mfma_f32_16x16x32_bf16 v[110:113], v[162:165], v[198:201], v[110:113]
	v_mfma_f32_16x16x32_bf16 v[78:81], v[170:173], v[198:201], v[78:81]
	v_mfma_f32_16x16x32_bf16 v[106:109], v[162:165], v[206:209], v[106:109]
	v_mfma_f32_16x16x32_bf16 v[74:77], v[170:173], v[206:209], v[74:77]
	v_mfma_f32_16x16x32_bf16 v[98:101], v[162:165], v[214:217], v[98:101]
	v_mfma_f32_16x16x32_bf16 v[66:69], v[170:173], v[214:217], v[66:69]
	v_mfma_f32_16x16x32_bf16 v[122:125], v[166:169], v[194:197], v[122:125]
	v_mfma_f32_16x16x32_bf16 v[90:93], v[186:189], v[194:197], v[90:93]
	v_mfma_f32_16x16x32_bf16 v[110:113], v[166:169], v[202:205], v[110:113]
	v_mfma_f32_16x16x32_bf16 v[78:81], v[186:189], v[202:205], v[78:81]
	v_mfma_f32_16x16x32_bf16 v[106:109], v[166:169], v[210:213], v[106:109]
	v_mfma_f32_16x16x32_bf16 v[74:77], v[186:189], v[210:213], v[74:77]
	v_mfma_f32_16x16x32_bf16 v[98:101], v[166:169], v[218:221], v[98:101]
	v_mfma_f32_16x16x32_bf16 v[66:69], v[186:189], v[218:221], v[66:69]
	s_setprio 0
	s_barrier
	s_add_i32 s70, s63, s51
	s_add_u32 s98, s44, 0x80
	s_addc_u32 s99, s45, 0
	s_mov_b32 m0, s70
	ds_read_b128 v[190:193], v184 offset:16384
	ds_read_b128 v[194:197], v184 offset:17408
	ds_read_b128 v[198:201], v184 offset:18432
	ds_read_b128 v[202:205], v184 offset:19456
	ds_read_b128 v[206:209], v184 offset:20480
	ds_read_b128 v[210:213], v184 offset:21504
	ds_read_b128 v[214:217], v184 offset:22528
	ds_read_b128 v[218:221], v184 offset:23552
	global_load_lds_dwordx4 v140, s[44:45]
	s_add_i32 m0, s70, 0x2000
	s_add_u32 s70, s44, 0x40000
	s_addc_u32 s71, s45, 0
	s_add_i32 s72, s64, s51
	global_load_lds_dwordx4 v144, s[44:45]
	s_mov_b32 m0, s72
	v_lshl_add_u64 v[226:227], s[46:47], 0, v[142:143]
	global_load_lds_dwordx4 v140, s[70:71]
	s_add_i32 m0, s72, 0x2000
	s_nop 0
	global_load_lds_dwordx4 v144, s[70:71]
	s_add_u32 s100, s46, 0x80
	s_addc_u32 s101, s47, 0
	s_mov_b32 m0, s41
	s_nop 0
	global_load_lds_dwordx4 v138, s[46:47]
	s_mov_b32 m0, s52
	s_nop 0
	global_load_lds_dwordx4 v142, s[46:47]
	s_waitcnt vmcnt(8)
	s_waitcnt lgkmcnt(0)
	s_barrier
	s_setprio 1
	s_waitcnt lgkmcnt(0)
	v_mfma_f32_16x16x32_bf16 v[62:65], v[130:133], v[190:193], v[62:65]
	v_mfma_f32_16x16x32_bf16 v[30:33], v[154:157], v[190:193], v[30:33]
	v_mfma_f32_16x16x32_bf16 v[54:57], v[130:133], v[198:201], v[54:57]
	v_mfma_f32_16x16x32_bf16 v[22:25], v[154:157], v[198:201], v[22:25]
	v_mfma_f32_16x16x32_bf16 v[50:53], v[130:133], v[206:209], v[50:53]
	v_mfma_f32_16x16x32_bf16 v[18:21], v[154:157], v[206:209], v[18:21]
	v_mfma_f32_16x16x32_bf16 v[38:41], v[130:133], v[214:217], v[38:41]
	v_mfma_f32_16x16x32_bf16 v[6:9], v[154:157], v[214:217], v[6:9]
	v_mfma_f32_16x16x32_bf16 v[62:65], v[134:137], v[194:197], v[62:65]
	v_mfma_f32_16x16x32_bf16 v[30:33], v[158:161], v[194:197], v[30:33]
	v_mfma_f32_16x16x32_bf16 v[54:57], v[134:137], v[202:205], v[54:57]
	v_mfma_f32_16x16x32_bf16 v[22:25], v[158:161], v[202:205], v[22:25]
	v_mfma_f32_16x16x32_bf16 v[50:53], v[134:137], v[210:213], v[50:53]
	v_mfma_f32_16x16x32_bf16 v[18:21], v[158:161], v[210:213], v[18:21]
	v_mfma_f32_16x16x32_bf16 v[38:41], v[134:137], v[218:221], v[38:41]
	v_mfma_f32_16x16x32_bf16 v[6:9], v[158:161], v[218:221], v[6:9]
	v_mfma_f32_16x16x32_bf16 v[58:61], v[162:165], v[190:193], v[58:61]
	v_mfma_f32_16x16x32_bf16 v[26:29], v[170:173], v[190:193], v[26:29]
	v_mfma_f32_16x16x32_bf16 v[46:49], v[162:165], v[198:201], v[46:49]
	v_mfma_f32_16x16x32_bf16 v[14:17], v[170:173], v[198:201], v[14:17]
	v_mfma_f32_16x16x32_bf16 v[42:45], v[162:165], v[206:209], v[42:45]
	v_mfma_f32_16x16x32_bf16 v[10:13], v[170:173], v[206:209], v[10:13]
	v_mfma_f32_16x16x32_bf16 v[34:37], v[162:165], v[214:217], v[34:37]
	v_mfma_f32_16x16x32_bf16 v[2:5], v[170:173], v[214:217], v[2:5]
	v_mfma_f32_16x16x32_bf16 v[58:61], v[166:169], v[194:197], v[58:61]
	v_mfma_f32_16x16x32_bf16 v[26:29], v[186:189], v[194:197], v[26:29]
	v_mfma_f32_16x16x32_bf16 v[46:49], v[166:169], v[202:205], v[46:49]
	v_mfma_f32_16x16x32_bf16 v[14:17], v[186:189], v[202:205], v[14:17]
	v_mfma_f32_16x16x32_bf16 v[42:45], v[166:169], v[210:213], v[42:45]
	v_mfma_f32_16x16x32_bf16 v[10:13], v[186:189], v[210:213], v[10:13]
	v_mfma_f32_16x16x32_bf16 v[34:37], v[166:169], v[218:221], v[34:37]
	v_mfma_f32_16x16x32_bf16 v[2:5], v[186:189], v[218:221], v[2:5]
	s_setprio 0
	s_barrier
; #define PG8_STAGE(bufoff, gbase, voff) do { _Pragma("unroll") for (int _i = 0; _i < 2; ++_i) \
;         __builtin_amdgcn_global_load_lds((const unsigned*)((const char*)(gbase) + (voff)[_i]), (PG8_LAS unsigned*)(lds + (bufoff) + ldsw + _i * 8192), 16, 0, 0); } while (0)
; #define PG8_LDA(dst, b, h) do { _Pragma("unroll") for (int m = 0; m < 4; ++m) _Pragma("unroll") for (int k = 0; k < 2; ++k) dst[m][k] = *(const PG8_LAS bf16x8*)(lds + PG8_SA(b, h) + aoff + m * 2048 + k * 1024); } while (0)
; #define PG8_LDB(dst, b, h) do { _Pragma("unroll") for (int n = 0; n < 2; ++n) _Pragma("unroll") for (int k = 0; k < 2; ++k) dst[n][k] = *(const PG8_LAS bf16x8*)(lds + PG8_SB(b, h) + boff + n * 2048 + k * 1024); } while (0)
; #define PG8_MMA(ai, bj, At, Bt) do { __builtin_amdgcn_s_setprio(1); _Pragma("unroll") for (int m = 0; m < 4; ++m) _Pragma("unroll") for (int n = 0; n < 2; ++n) _Pragma("unroll") for (int k = 0; k < 2; ++k) \
;         acc[ai][bj][m][n] = __builtin_amdgcn_mfma_f32_16x16x32_bf16(Bt[n][k], At[m][k], acc[ai][bj][m][n], 0, 0, 0); __builtin_amdgcn_s_setprio(0); } while (0)
; #define PG8_WAIT_V(n) asm volatile("s_waitcnt vmcnt(" #n ")" ::: "memory")
; #define PG8_WAIT_L(n) asm volatile("s_waitcnt lgkmcnt(" #n ")" ::: "memory")
; template <class Epi, class Sched, bool ALIGN_EPI = false, bool SP2 = false>
; __device__ __forceinline__ void gemm_phase(PG8_LAS unsigned char* lds, const Gemm g, const Sched& S, const Epi& E) {
;     ...
;         for (int t = 0; t < nt; t += 2) {
;             const bool last = (t == nt - 2);
;             const char* a1 = cA + (size_t)(t + 1) * kstep;
;             const char* a2 = last ? nA : cA + (size_t)(t + 2) * kstep; const char* b2 = last ? nB : cB + (size_t)(t + 2) * kstep;
;             const char* a3 = a2 + kstep; const char* b3 = b2 + kstep;
;             if (last && has_next) S.a_ready(nxt);
;     ...
;             PG8_LDB(B0, 1, 0); PG8_LDB(B1, 1, 1); PG8_SCHED; PG8_LDA(At, 1, 0); PG8_STAGE(PG8_SA(0, 1), a2 + hstepA, voffA);
;             PG8_WAIT_V(8); PG8_WAIT_L(0); PG8_BAR; PG8_MMA(0, 0, At, B0); PG8_MMA(0, 1, At, B1); PG8_BAR; PG8_SCHED;
;             PG8_LDA(At, 1, 1); PG8_STAGE(PG8_SB(1, 0), b3, voffB); PG8_STAGE(PG8_SB(1, 1), b3 + hstepB, voffB); PG8_STAGE(PG8_SA(1, 0), a3, voffA);
;             PG8_WAIT_V(8); PG8_WAIT_L(0); PG8_BAR; PG8_MMA(1, 0, At, B0); PG8_MMA(1, 1, At, B1); PG8_BAR; PG8_SCHED;
	s_add_i32 s70, 0, 0x18000
	s_add_i32 s71, 0, 0x1c000
	v_add_u32_e32 v158, s70, v176
	v_add_u32_e32 v185, s71, v176
	ds_read_b128 v[130:133], v158
	ds_read_b128 v[134:137], v158 offset:1024
	ds_read_b128 v[154:157], v158 offset:2048
	ds_read_b128 v[158:161], v158 offset:3072
	ds_read_b128 v[162:165], v185
	ds_read_b128 v[166:169], v185 offset:1024
	ds_read_b128 v[170:173], v185 offset:2048
	ds_read_b128 v[186:189], v185 offset:3072
	s_add_u32 s46, s46, 0x40000
	s_addc_u32 s47, s47, 0
	s_mov_b32 m0, s53
	ds_read_b128 v[190:193], v184 offset:32768
	ds_read_b128 v[194:197], v184 offset:33792
	ds_read_b128 v[198:201], v184 offset:34816
	ds_read_b128 v[202:205], v184 offset:35840
	ds_read_b128 v[206:209], v184 offset:36864
	ds_read_b128 v[210:213], v184 offset:37888
	ds_read_b128 v[214:217], v184 offset:38912
	ds_read_b128 v[218:221], v184 offset:39936
	global_load_lds_dwordx4 v138, s[46:47]
	s_mov_b32 m0, s54
	s_nop 0
	global_load_lds_dwordx4 v142, s[46:47]
	s_waitcnt vmcnt(8)
	s_waitcnt lgkmcnt(0)
	s_barrier
	s_setprio 1
	s_waitcnt lgkmcnt(0)
	v_mfma_f32_16x16x32_bf16 v[126:129], v[130:133], v[190:193], v[126:129]
	v_mfma_f32_16x16x32_bf16 v[94:97], v[154:157], v[190:193], v[94:97]
	v_mfma_f32_16x16x32_bf16 v[118:121], v[130:133], v[198:201], v[118:121]
	v_mfma_f32_16x16x32_bf16 v[86:89], v[154:157], v[198:201], v[86:89]
	v_mfma_f32_16x16x32_bf16 v[114:117], v[130:133], v[206:209], v[114:117]
	v_mfma_f32_16x16x32_bf16 v[82:85], v[154:157], v[206:209], v[82:85]
	v_mfma_f32_16x16x32_bf16 v[102:105], v[130:133], v[214:217], v[102:105]
	v_mfma_f32_16x16x32_bf16 v[70:73], v[154:157], v[214:217], v[70:73]
	v_mfma_f32_16x16x32_bf16 v[126:129], v[134:137], v[194:197], v[126:129]
	v_mfma_f32_16x16x32_bf16 v[94:97], v[158:161], v[194:197], v[94:97]
	v_mfma_f32_16x16x32_bf16 v[118:121], v[134:137], v[202:205], v[118:121]
	v_mfma_f32_16x16x32_bf16 v[86:89], v[158:161], v[202:205], v[86:89]
	v_mfma_f32_16x16x32_bf16 v[114:117], v[134:137], v[210:213], v[114:117]
	v_mfma_f32_16x16x32_bf16 v[82:85], v[158:161], v[210:213], v[82:85]
	v_mfma_f32_16x16x32_bf16 v[102:105], v[134:137], v[218:221], v[102:105]
	v_mfma_f32_16x16x32_bf16 v[70:73], v[158:161], v[218:221], v[70:73]
	v_mfma_f32_16x16x32_bf16 v[122:125], v[162:165], v[190:193], v[122:125]
	v_mfma_f32_16x16x32_bf16 v[90:93], v[170:173], v[190:193], v[90:93]
	v_mfma_f32_16x16x32_bf16 v[110:113], v[162:165], v[198:201], v[110:113]
	v_mfma_f32_16x16x32_bf16 v[78:81], v[170:173], v[198:201], v[78:81]
	v_mfma_f32_16x16x32_bf16 v[106:109], v[162:165], v[206:209], v[106:109]
	v_mfma_f32_16x16x32_bf16 v[74:77], v[170:173], v[206:209], v[74:77]
	v_mfma_f32_16x16x32_bf16 v[98:101], v[162:165], v[214:217], v[98:101]
	v_mfma_f32_16x16x32_bf16 v[66:69], v[170:173], v[214:217], v[66:69]
	v_mfma_f32_16x16x32_bf16 v[122:125], v[166:169], v[194:197], v[122:125]
	v_mfma_f32_16x16x32_bf16 v[90:93], v[186:189], v[194:197], v[90:93]
	v_mfma_f32_16x16x32_bf16 v[110:113], v[166:169], v[202:205], v[110:113]
	v_mfma_f32_16x16x32_bf16 v[78:81], v[186:189], v[202:205], v[78:81]
	v_mfma_f32_16x16x32_bf16 v[106:109], v[166:169], v[210:213], v[106:109]
	v_mfma_f32_16x16x32_bf16 v[74:77], v[186:189], v[210:213], v[74:77]
	v_mfma_f32_16x16x32_bf16 v[98:101], v[166:169], v[218:221], v[98:101]
	v_mfma_f32_16x16x32_bf16 v[66:69], v[186:189], v[218:221], v[66:69]
	s_setprio 0
	s_barrier
	s_add_i32 s46, s70, s51
	s_mov_b32 m0, s46
	ds_read_b128 v[190:193], v184 offset:49152
	ds_read_b128 v[194:197], v184 offset:50176
	ds_read_b128 v[198:201], v184 offset:51200
	ds_read_b128 v[202:205], v184 offset:52224
	ds_read_b128 v[206:209], v184 offset:53248
	ds_read_b128 v[210:213], v184 offset:54272
	ds_read_b128 v[214:217], v184 offset:55296
	ds_read_b128 v[218:221], v184 offset:56320
	global_load_lds_dwordx4 v140, s[98:99]
	s_add_i32 m0, s46, 0x2000
	s_add_u32 s44, s44, 0x40080
	s_addc_u32 s45, s45, 0
	s_add_i32 s46, s71, s51
	global_load_lds_dwordx4 v144, s[98:99]
	s_mov_b32 m0, s46
	s_nop 0
	global_load_lds_dwordx4 v140, s[44:45]
	s_add_i32 m0, s46, 0x2000
	s_nop 0
	global_load_lds_dwordx4 v144, s[44:45]
	s_mov_b32 m0, s59
	s_nop 0
	global_load_lds_dwordx4 v138, s[100:101]
	v_lshl_add_u64 v[174:175], v[226:227], 0, s[24:25]
	s_mov_b32 m0, s60
	s_nop 0
	global_load_lds_dwordx4 v142, s[100:101]
	s_waitcnt vmcnt(8)
	s_waitcnt lgkmcnt(0)
	s_barrier
	s_setprio 1
	s_waitcnt lgkmcnt(0)
	v_mfma_f32_16x16x32_bf16 v[62:65], v[130:133], v[190:193], v[62:65]
	v_mfma_f32_16x16x32_bf16 v[30:33], v[154:157], v[190:193], v[30:33]
	v_mfma_f32_16x16x32_bf16 v[54:57], v[130:133], v[198:201], v[54:57]
	v_mfma_f32_16x16x32_bf16 v[22:25], v[154:157], v[198:201], v[22:25]
	v_mfma_f32_16x16x32_bf16 v[50:53], v[130:133], v[206:209], v[50:53]
	v_mfma_f32_16x16x32_bf16 v[18:21], v[154:157], v[206:209], v[18:21]
	v_mfma_f32_16x16x32_bf16 v[38:41], v[130:133], v[214:217], v[38:41]
	v_mfma_f32_16x16x32_bf16 v[6:9], v[154:157], v[214:217], v[6:9]
	v_mfma_f32_16x16x32_bf16 v[62:65], v[134:137], v[194:197], v[62:65]
	v_mfma_f32_16x16x32_bf16 v[30:33], v[158:161], v[194:197], v[30:33]
	v_mfma_f32_16x16x32_bf16 v[54:57], v[134:137], v[202:205], v[54:57]
	v_mfma_f32_16x16x32_bf16 v[22:25], v[158:161], v[202:205], v[22:25]
	v_mfma_f32_16x16x32_bf16 v[50:53], v[134:137], v[210:213], v[50:53]
	v_mfma_f32_16x16x32_bf16 v[18:21], v[158:161], v[210:213], v[18:21]
	v_mfma_f32_16x16x32_bf16 v[38:41], v[134:137], v[218:221], v[38:41]
	v_mfma_f32_16x16x32_bf16 v[6:9], v[158:161], v[218:221], v[6:9]
	v_mfma_f32_16x16x32_bf16 v[58:61], v[162:165], v[190:193], v[58:61]
	v_mfma_f32_16x16x32_bf16 v[26:29], v[170:173], v[190:193], v[26:29]
	v_mfma_f32_16x16x32_bf16 v[46:49], v[162:165], v[198:201], v[46:49]
	v_mfma_f32_16x16x32_bf16 v[14:17], v[170:173], v[198:201], v[14:17]
	v_mfma_f32_16x16x32_bf16 v[42:45], v[162:165], v[206:209], v[42:45]
	v_mfma_f32_16x16x32_bf16 v[10:13], v[170:173], v[206:209], v[10:13]
	v_mfma_f32_16x16x32_bf16 v[34:37], v[162:165], v[214:217], v[34:37]
	v_mfma_f32_16x16x32_bf16 v[2:5], v[170:173], v[214:217], v[2:5]
	v_mfma_f32_16x16x32_bf16 v[58:61], v[166:169], v[194:197], v[58:61]
	v_mfma_f32_16x16x32_bf16 v[26:29], v[186:189], v[194:197], v[26:29]
	v_mfma_f32_16x16x32_bf16 v[46:49], v[166:169], v[202:205], v[46:49]
	v_mfma_f32_16x16x32_bf16 v[14:17], v[186:189], v[202:205], v[14:17]
	v_mfma_f32_16x16x32_bf16 v[42:45], v[166:169], v[210:213], v[42:45]
	v_mfma_f32_16x16x32_bf16 v[10:13], v[186:189], v[210:213], v[10:13]
	v_mfma_f32_16x16x32_bf16 v[34:37], v[166:169], v[218:221], v[34:37]
	v_mfma_f32_16x16x32_bf16 v[2:5], v[186:189], v[218:221], v[2:5]
	s_setprio 0
	s_barrier
	s_add_i32 s69, s69, 2
	s_add_u32 s42, s42, 0x100
	s_addc_u32 s43, s43, 0
	s_add_u32 s67, s67, 0x100
	s_addc_u32 s68, s68, 0
	s_cmp_gt_u32 s69, 13
	s_cbranch_scc0 .LBB0_1528
	s_and_b64 vcc, exec, s[26:27]
	s_cbranch_vccz .LBB0_1531
	s_barrier

; #define PG8_STAGE(bufoff, gbase, voff) do { _Pragma("unroll") for (int _i = 0; _i < 2; ++_i) \
;         __builtin_amdgcn_global_load_lds((const unsigned*)((const char*)(gbase) + (voff)[_i]), (PG8_LAS unsigned*)(lds + (bufoff) + ldsw + _i * 8192), 16, 0, 0); } while (0)
; #define PG8_LDA(dst, b, h) do { _Pragma("unroll") for (int m = 0; m < 4; ++m) _Pragma("unroll") for (int k = 0; k < 2; ++k) dst[m][k] = *(const PG8_LAS bf16x8*)(lds + PG8_SA(b, h) + aoff + m * 2048 + k * 1024); } while (0)
; #define PG8_LDB(dst, b, h) do { _Pragma("unroll") for (int n = 0; n < 2; ++n) _Pragma("unroll") for (int k = 0; k < 2; ++k) dst[n][k] = *(const PG8_LAS bf16x8*)(lds + PG8_SB(b, h) + boff + n * 2048 + k * 1024); } while (0)
; #define PG8_MMA(ai, bj, At, Bt) do { __builtin_amdgcn_s_setprio(1); _Pragma("unroll") for (int m = 0; m < 4; ++m) _Pragma("unroll") for (int n = 0; n < 2; ++n) _Pragma("unroll") for (int k = 0; k < 2; ++k) \
;         acc[ai][bj][m][n] = __builtin_amdgcn_mfma_f32_16x16x32_bf16(Bt[n][k], At[m][k], acc[ai][bj][m][n], 0, 0, 0); __builtin_amdgcn_s_setprio(0); } while (0)
; #define PG8_WAIT_V(n) asm volatile("s_waitcnt vmcnt(" #n ")" ::: "memory")
; #define PG8_WAIT_L(n) asm volatile("s_waitcnt lgkmcnt(" #n ")" ::: "memory")
; #define PG8_BAR __builtin_amdgcn_s_barrier()
; #define PG8_SCHED __builtin_amdgcn_sched_barrier(0)
; template <class Epi, class Sched, bool ALIGN_EPI = false, bool SP2 = false>
; __device__ __forceinline__ void gemm_phase(PG8_LAS unsigned char* lds, const Gemm g, const Sched& S, const Epi& E) {
;     ...
;             PG8_LDB(B0, 0, 0); PG8_LDB(B1, 0, 1); PG8_SCHED; PG8_LDA(At, 0, 0); PG8_STAGE(PG8_SA(1, 1), a1 + hstepA, voffA);
;             PG8_WAIT_V(8); PG8_WAIT_L(0); PG8_BAR; PG8_MMA(0, 0, At, B0); PG8_MMA(0, 1, At, B1); PG8_BAR; PG8_SCHED;
;             PG8_LDA(At, 0, 1); PG8_STAGE(PG8_SB(0, 0), b2, voffB); PG8_STAGE(PG8_SB(0, 1), b2 + hstepB, voffB); PG8_STAGE(PG8_SA(0, 0), a2, voffA);
.LBB0_1838:
	v_add_u32_e32 v24, s50, v22
	ds_read_b128 v[34:37], v24
	ds_read_b128 v[38:41], v24 offset:1024
	ds_read_b128 v[42:45], v24 offset:2048
	ds_read_b128 v[46:49], v24 offset:3072
	v_add_u32_e32 v24, s51, v22
	s_add_u32 s22, s14, s20
	ds_read_b128 v[50:53], v24
	ds_read_b128 v[54:57], v24 offset:1024
	ds_read_b128 v[66:69], v24 offset:2048
	ds_read_b128 v[70:73], v24 offset:3072
	s_addc_u32 s23, s15, s21
	s_add_u32 s22, s22, 0x100
	s_addc_u32 s23, s23, 0
	s_add_u32 s58, s55, s20
	s_addc_u32 s59, s56, s21
	s_cmpk_eq_i32 s20, 0x1500
	s_cselect_b32 s25, s19, s23
	s_cselect_b32 s24, s18, s22
	s_cselect_b32 s23, s1, s59
	s_cselect_b32 s22, s0, s58
	v_lshl_add_u64 v[24:25], v[18:19], 0, s[20:21]
	s_add_i32 m0, s42, 0xc000
	ds_read_b128 v[162:165], v23
	ds_read_b128 v[166:169], v23 offset:1024
	ds_read_b128 v[194:197], v23 offset:2048
	ds_read_b128 v[198:201], v23 offset:3072
	ds_read_b128 v[202:205], v23 offset:4096
	ds_read_b128 v[206:209], v23 offset:5120
	ds_read_b128 v[210:213], v23 offset:6144
	ds_read_b128 v[216:219], v23 offset:7168
	global_load_lds_dwordx4 v[24:25], off
	v_lshl_add_u64 v[24:25], v[20:21], 0, s[20:21]
	s_add_i32 m0, s42, 0xe000
	s_nop 0
	global_load_lds_dwordx4 v[24:25], off
	s_waitcnt vmcnt(8)
	s_waitcnt lgkmcnt(0)
	s_barrier
	s_setprio 1
	s_waitcnt lgkmcnt(0)
	v_mfma_f32_16x16x32_bf16 v[170:173], v[34:37], v[162:165], v[170:173]
	v_mfma_f32_16x16x32_bf16 v[174:177], v[42:45], v[162:165], v[174:177]
	v_mfma_f32_16x16x32_bf16 v[178:181], v[34:37], v[194:197], v[178:181]
	v_mfma_f32_16x16x32_bf16 v[182:185], v[42:45], v[194:197], v[182:185]
	v_mfma_f32_16x16x32_bf16 v[186:189], v[34:37], v[202:205], v[186:189]
	v_mfma_f32_16x16x32_bf16 v[190:193], v[42:45], v[202:205], v[190:193]
	v_mfma_f32_16x16x32_bf16 v[158:161], v[34:37], v[210:213], v[158:161]
	v_mfma_f32_16x16x32_bf16 v[154:157], v[42:45], v[210:213], v[154:157]
	v_mfma_f32_16x16x32_bf16 v[170:173], v[38:41], v[166:169], v[170:173]
	v_mfma_f32_16x16x32_bf16 v[174:177], v[46:49], v[166:169], v[174:177]
	v_mfma_f32_16x16x32_bf16 v[178:181], v[38:41], v[198:201], v[178:181]
	v_mfma_f32_16x16x32_bf16 v[182:185], v[46:49], v[198:201], v[182:185]
	v_mfma_f32_16x16x32_bf16 v[186:189], v[38:41], v[206:209], v[186:189]
	v_mfma_f32_16x16x32_bf16 v[190:193], v[46:49], v[206:209], v[190:193]
	v_mfma_f32_16x16x32_bf16 v[158:161], v[38:41], v[216:219], v[158:161]
	v_mfma_f32_16x16x32_bf16 v[154:157], v[46:49], v[216:219], v[154:157]
	v_mfma_f32_16x16x32_bf16 v[62:65], v[50:53], v[162:165], v[62:65]
	v_mfma_f32_16x16x32_bf16 v[58:61], v[66:69], v[162:165], v[58:61]
	v_mfma_f32_16x16x32_bf16 v[74:77], v[50:53], v[194:197], v[74:77]
	v_mfma_f32_16x16x32_bf16 v[78:81], v[66:69], v[194:197], v[78:81]
	v_mfma_f32_16x16x32_bf16 v[90:93], v[50:53], v[202:205], v[90:93]
	v_mfma_f32_16x16x32_bf16 v[94:97], v[66:69], v[202:205], v[94:97]
	v_mfma_f32_16x16x32_bf16 v[106:109], v[50:53], v[210:213], v[106:109]
	v_mfma_f32_16x16x32_bf16 v[110:113], v[66:69], v[210:213], v[110:113]
	v_mfma_f32_16x16x32_bf16 v[62:65], v[54:57], v[166:169], v[62:65]
	v_mfma_f32_16x16x32_bf16 v[58:61], v[70:73], v[166:169], v[58:61]
	v_mfma_f32_16x16x32_bf16 v[74:77], v[54:57], v[198:201], v[74:77]
	v_mfma_f32_16x16x32_bf16 v[78:81], v[70:73], v[198:201], v[78:81]
	v_mfma_f32_16x16x32_bf16 v[90:93], v[54:57], v[206:209], v[90:93]
	v_mfma_f32_16x16x32_bf16 v[94:97], v[70:73], v[206:209], v[94:97]
	v_mfma_f32_16x16x32_bf16 v[106:109], v[54:57], v[216:219], v[106:109]
	v_mfma_f32_16x16x32_bf16 v[110:113], v[70:73], v[216:219], v[110:113]
	s_setprio 0
	s_barrier
	s_add_i32 s58, s50, s41
	s_add_u32 s98, s22, 0x80
	s_addc_u32 s99, s23, 0
	s_mov_b32 m0, s58
	ds_read_b128 v[162:165], v23 offset:16384
	ds_read_b128 v[166:169], v23 offset:17408
	ds_read_b128 v[194:197], v23 offset:18432
	ds_read_b128 v[198:201], v23 offset:19456
	ds_read_b128 v[202:205], v23 offset:20480
	ds_read_b128 v[206:209], v23 offset:21504
	ds_read_b128 v[210:213], v23 offset:22528
	ds_read_b128 v[216:219], v23 offset:23552
	global_load_lds_dwordx4 v4, s[22:23]
	s_add_i32 m0, s58, 0x2000
	s_add_u32 s58, s22, 0xb0000
	s_addc_u32 s59, s23, 0
	s_add_i32 s60, s51, s41
	global_load_lds_dwordx4 v8, s[22:23]
	s_mov_b32 m0, s60
	s_add_u32 s100, s24, 0x80
	s_addc_u32 s101, s25, 0
	global_load_lds_dwordx4 v4, s[58:59]
	s_add_i32 m0, s60, 0x2000
	s_nop 0
	global_load_lds_dwordx4 v8, s[58:59]
	s_mov_b32 m0, s42
	s_nop 0
	global_load_lds_dwordx4 v2, s[24:25]
	s_mov_b32 m0, s43
	s_nop 0
	global_load_lds_dwordx4 v6, s[24:25]
	s_waitcnt vmcnt(8)
	s_waitcnt lgkmcnt(0)
	s_barrier
; #define PG8_STAGE(bufoff, gbase, voff) do { _Pragma("unroll") for (int _i = 0; _i < 2; ++_i) \
;         __builtin_amdgcn_global_load_lds((const unsigned*)((const char*)(gbase) + (voff)[_i]), (PG8_LAS unsigned*)(lds + (bufoff) + ldsw + _i * 8192), 16, 0, 0); } while (0)
; #define PG8_LDA(dst, b, h) do { _Pragma("unroll") for (int m = 0; m < 4; ++m) _Pragma("unroll") for (int k = 0; k < 2; ++k) dst[m][k] = *(const PG8_LAS bf16x8*)(lds + PG8_SA(b, h) + aoff + m * 2048 + k * 1024); } while (0)
; #define PG8_LDB(dst, b, h) do { _Pragma("unroll") for (int n = 0; n < 2; ++n) _Pragma("unroll") for (int k = 0; k < 2; ++k) dst[n][k] = *(const PG8_LAS bf16x8*)(lds + PG8_SB(b, h) + boff + n * 2048 + k * 1024); } while (0)
; #define PG8_MMA(ai, bj, At, Bt) do { __builtin_amdgcn_s_setprio(1); _Pragma("unroll") for (int m = 0; m < 4; ++m) _Pragma("unroll") for (int n = 0; n < 2; ++n) _Pragma("unroll") for (int k = 0; k < 2; ++k) \
;         acc[ai][bj][m][n] = __builtin_amdgcn_mfma_f32_16x16x32_bf16(Bt[n][k], At[m][k], acc[ai][bj][m][n], 0, 0, 0); __builtin_amdgcn_s_setprio(0); } while (0)
; #define PG8_WAIT_V(n) asm volatile("s_waitcnt vmcnt(" #n ")" ::: "memory")
; #define PG8_WAIT_L(n) asm volatile("s_waitcnt lgkmcnt(" #n ")" ::: "memory")
; #define PG8_BAR __builtin_amdgcn_s_barrier()
; #define PG8_SCHED __builtin_amdgcn_sched_barrier(0)
; template <class Epi, class Sched, bool ALIGN_EPI = false, bool SP2 = false>
; __device__ __forceinline__ void gemm_phase(PG8_LAS unsigned char* lds, const Gemm g, const Sched& S, const Epi& E) {
;     ...
;             PG8_WAIT_V(8); PG8_WAIT_L(0); PG8_BAR; PG8_MMA(1, 0, At, B0); PG8_MMA(1, 1, At, B1); PG8_BAR; PG8_SCHED;
;             PG8_LDB(B0, 1, 0); PG8_LDB(B1, 1, 1); PG8_SCHED; PG8_LDA(At, 1, 0); PG8_STAGE(PG8_SA(0, 1), a2 + hstepA, voffA);
;             PG8_WAIT_V(8); PG8_WAIT_L(0); PG8_BAR; PG8_MMA(0, 0, At, B0); PG8_MMA(0, 1, At, B1); PG8_BAR; PG8_SCHED;
	s_setprio 1
	s_waitcnt lgkmcnt(0)
	v_mfma_f32_16x16x32_bf16 v[150:153], v[34:37], v[162:165], v[150:153]
	v_mfma_f32_16x16x32_bf16 v[146:149], v[42:45], v[162:165], v[146:149]
	v_mfma_f32_16x16x32_bf16 v[142:145], v[34:37], v[194:197], v[142:145]
	v_mfma_f32_16x16x32_bf16 v[138:141], v[42:45], v[194:197], v[138:141]
	v_mfma_f32_16x16x32_bf16 v[134:137], v[34:37], v[202:205], v[134:137]
	v_mfma_f32_16x16x32_bf16 v[130:133], v[42:45], v[202:205], v[130:133]
	v_mfma_f32_16x16x32_bf16 v[34:37], v[34:37], v[210:213], v[98:101]
	v_mfma_f32_16x16x32_bf16 v[150:153], v[38:41], v[166:169], v[150:153]
	v_mfma_f32_16x16x32_bf16 v[146:149], v[46:49], v[166:169], v[146:149]
	v_mfma_f32_16x16x32_bf16 v[142:145], v[38:41], v[198:201], v[142:145]
	v_mfma_f32_16x16x32_bf16 v[138:141], v[46:49], v[198:201], v[138:141]
	v_mfma_f32_16x16x32_bf16 v[134:137], v[38:41], v[206:209], v[134:137]
	v_mfma_f32_16x16x32_bf16 v[130:133], v[46:49], v[206:209], v[130:133]
	v_mfma_f32_16x16x32_bf16 v[34:37], v[38:41], v[216:219], v[34:37]
	v_mfma_f32_16x16x32_bf16 v[38:41], v[42:45], v[210:213], v[82:85]
	v_mfma_f32_16x16x32_bf16 v[38:41], v[46:49], v[216:219], v[38:41]
	v_mfma_f32_16x16x32_bf16 v[82:85], v[50:53], v[194:197], v[122:125]
	v_mfma_f32_16x16x32_bf16 v[122:125], v[54:57], v[198:201], v[82:85]
	v_mfma_f32_16x16x32_bf16 v[82:85], v[66:69], v[194:197], v[126:129]
	v_mfma_f32_16x16x32_bf16 v[126:129], v[70:73], v[198:201], v[82:85]
	v_mfma_f32_16x16x32_bf16 v[82:85], v[50:53], v[202:205], v[102:105]
	v_mfma_f32_16x16x32_bf16 v[102:105], v[54:57], v[206:209], v[82:85]
	v_mfma_f32_16x16x32_bf16 v[82:85], v[66:69], v[202:205], v[86:89]
	v_mfma_f32_16x16x32_bf16 v[30:33], v[50:53], v[210:213], v[30:33]
	v_mfma_f32_16x16x32_bf16 v[24:27], v[66:69], v[210:213], v[26:29]
	v_mfma_f32_16x16x32_bf16 v[42:45], v[50:53], v[162:165], v[114:117]
	v_mfma_f32_16x16x32_bf16 v[46:49], v[66:69], v[162:165], v[118:121]
	v_mfma_f32_16x16x32_bf16 v[86:89], v[70:73], v[206:209], v[82:85]
	v_mfma_f32_16x16x32_bf16 v[30:33], v[54:57], v[216:219], v[30:33]
	v_mfma_f32_16x16x32_bf16 v[24:27], v[70:73], v[216:219], v[24:27]
	v_mfma_f32_16x16x32_bf16 v[42:45], v[54:57], v[166:169], v[42:45]
	v_mfma_f32_16x16x32_bf16 v[46:49], v[70:73], v[166:169], v[46:49]
	s_setprio 0
	s_barrier
	s_add_i32 s58, 0, 0x18000
	v_add_u32_e32 v28, s58, v22
	s_add_i32 s59, 0, 0x1c000
	ds_read_b128 v[50:53], v28
	ds_read_b128 v[54:57], v28 offset:1024
	ds_read_b128 v[66:69], v28 offset:2048
	ds_read_b128 v[70:73], v28 offset:3072
	v_add_u32_e32 v28, s59, v22
	ds_read_b128 v[162:165], v28
	ds_read_b128 v[166:169], v28 offset:1024
	ds_read_b128 v[194:197], v28 offset:2048
	ds_read_b128 v[198:201], v28 offset:3072
	s_add_u32 s24, s24, 0xb0000
	s_addc_u32 s25, s25, 0
	s_mov_b32 m0, s45
	ds_read_b128 v[82:85], v23 offset:32768
	ds_read_b128 v[98:101], v23 offset:33792
	ds_read_b128 v[114:117], v23 offset:34816
	ds_read_b128 v[118:121], v23 offset:35840
	ds_read_b128 v[202:205], v23 offset:36864
	ds_read_b128 v[206:209], v23 offset:37888
	ds_read_b128 v[210:213], v23 offset:38912
	ds_read_b128 v[216:219], v23 offset:39936
	global_load_lds_dwordx4 v2, s[24:25]
	s_mov_b32 m0, s46
	s_nop 0
	global_load_lds_dwordx4 v6, s[24:25]
	s_waitcnt vmcnt(8)
	s_waitcnt lgkmcnt(0)
	s_barrier
	s_setprio 1
	s_waitcnt lgkmcnt(0)
	v_mfma_f32_16x16x32_bf16 v[170:173], v[50:53], v[82:85], v[170:173]
	v_mfma_f32_16x16x32_bf16 v[174:177], v[66:69], v[82:85], v[174:177]
	v_mfma_f32_16x16x32_bf16 v[178:181], v[50:53], v[114:117], v[178:181]
	v_mfma_f32_16x16x32_bf16 v[182:185], v[66:69], v[114:117], v[182:185]
	v_mfma_f32_16x16x32_bf16 v[186:189], v[50:53], v[202:205], v[186:189]
	v_mfma_f32_16x16x32_bf16 v[190:193], v[66:69], v[202:205], v[190:193]
	v_mfma_f32_16x16x32_bf16 v[158:161], v[50:53], v[210:213], v[158:161]
	v_mfma_f32_16x16x32_bf16 v[154:157], v[66:69], v[210:213], v[154:157]
	v_mfma_f32_16x16x32_bf16 v[170:173], v[54:57], v[98:101], v[170:173]
	v_mfma_f32_16x16x32_bf16 v[174:177], v[70:73], v[98:101], v[174:177]
	v_mfma_f32_16x16x32_bf16 v[178:181], v[54:57], v[118:121], v[178:181]
	v_mfma_f32_16x16x32_bf16 v[182:185], v[70:73], v[118:121], v[182:185]
	v_mfma_f32_16x16x32_bf16 v[186:189], v[54:57], v[206:209], v[186:189]
	v_mfma_f32_16x16x32_bf16 v[190:193], v[70:73], v[206:209], v[190:193]
	v_mfma_f32_16x16x32_bf16 v[158:161], v[54:57], v[216:219], v[158:161]
	v_mfma_f32_16x16x32_bf16 v[154:157], v[70:73], v[216:219], v[154:157]
	v_mfma_f32_16x16x32_bf16 v[62:65], v[162:165], v[82:85], v[62:65]
	v_mfma_f32_16x16x32_bf16 v[58:61], v[194:197], v[82:85], v[58:61]
	v_mfma_f32_16x16x32_bf16 v[82:85], v[162:165], v[202:205], v[90:93]
	v_mfma_f32_16x16x32_bf16 v[90:93], v[166:169], v[206:209], v[82:85]
	v_mfma_f32_16x16x32_bf16 v[82:85], v[194:197], v[202:205], v[94:97]
	v_mfma_f32_16x16x32_bf16 v[94:97], v[198:201], v[206:209], v[82:85]
	v_mfma_f32_16x16x32_bf16 v[82:85], v[162:165], v[210:213], v[106:109]
	v_mfma_f32_16x16x32_bf16 v[74:77], v[162:165], v[114:117], v[74:77]
	v_mfma_f32_16x16x32_bf16 v[78:81], v[194:197], v[114:117], v[78:81]
	v_mfma_f32_16x16x32_bf16 v[106:109], v[166:169], v[216:219], v[82:85]
	v_mfma_f32_16x16x32_bf16 v[82:85], v[194:197], v[210:213], v[110:113]
	v_mfma_f32_16x16x32_bf16 v[62:65], v[166:169], v[98:101], v[62:65]
	v_mfma_f32_16x16x32_bf16 v[58:61], v[198:201], v[98:101], v[58:61]
	v_mfma_f32_16x16x32_bf16 v[74:77], v[166:169], v[118:121], v[74:77]
	v_mfma_f32_16x16x32_bf16 v[78:81], v[198:201], v[118:121], v[78:81]
	v_mfma_f32_16x16x32_bf16 v[110:113], v[198:201], v[216:219], v[82:85]
	s_setprio 0
	s_barrier
; #define PG8_STAGE(bufoff, gbase, voff) do { _Pragma("unroll") for (int _i = 0; _i < 2; ++_i) \
;         __builtin_amdgcn_global_load_lds((const unsigned*)((const char*)(gbase) + (voff)[_i]), (PG8_LAS unsigned*)(lds + (bufoff) + ldsw + _i * 8192), 16, 0, 0); } while (0)
; #define PG8_LDA(dst, b, h) do { _Pragma("unroll") for (int m = 0; m < 4; ++m) _Pragma("unroll") for (int k = 0; k < 2; ++k) dst[m][k] = *(const PG8_LAS bf16x8*)(lds + PG8_SA(b, h) + aoff + m * 2048 + k * 1024); } while (0)
; #define PG8_MMA(ai, bj, At, Bt) do { __builtin_amdgcn_s_setprio(1); _Pragma("unroll") for (int m = 0; m < 4; ++m) _Pragma("unroll") for (int n = 0; n < 2; ++n) _Pragma("unroll") for (int k = 0; k < 2; ++k) \
;         acc[ai][bj][m][n] = __builtin_amdgcn_mfma_f32_16x16x32_bf16(Bt[n][k], At[m][k], acc[ai][bj][m][n], 0, 0, 0); __builtin_amdgcn_s_setprio(0); } while (0)
; #define PG8_WAIT_V(n) asm volatile("s_waitcnt vmcnt(" #n ")" ::: "memory")
; #define PG8_WAIT_L(n) asm volatile("s_waitcnt lgkmcnt(" #n ")" ::: "memory")
; #define PG8_BAR __builtin_amdgcn_s_barrier()
; #define PG8_SCHED __builtin_amdgcn_sched_barrier(0)
; template <class Epi, class Sched, bool ALIGN_EPI = false, bool SP2 = false>
; __device__ __forceinline__ void gemm_phase(PG8_LAS unsigned char* lds, const Gemm g, const Sched& S, const Epi& E) {
;     ...
;         for (int t = 0; t < nt; t += 2) {
;             const bool last = (t == nt - 2);
;             const char* a1 = cA + (size_t)(t + 1) * kstep;
;             const char* a2 = last ? nA : cA + (size_t)(t + 2) * kstep; const char* b2 = last ? nB : cB + (size_t)(t + 2) * kstep;
;             const char* a3 = a2 + kstep; const char* b3 = b2 + kstep;
;             if (last && has_next) S.a_ready(nxt);
;     ...
;             PG8_LDA(At, 1, 1); PG8_STAGE(PG8_SB(1, 0), b3, voffB); PG8_STAGE(PG8_SB(1, 1), b3 + hstepB, voffB); PG8_STAGE(PG8_SA(1, 0), a3, voffA);
;             PG8_WAIT_V(8); PG8_WAIT_L(0); PG8_BAR; PG8_MMA(1, 0, At, B0); PG8_MMA(1, 1, At, B1); PG8_BAR; PG8_SCHED;
;     ...
; #pragma unroll
;         for (int a = 0; a < 2; ++a)
; #pragma unroll
;             for (int b = 0; b < 2; ++b)
; #pragma unroll
;                 for (int m = 0; m < 4; ++m)
; #pragma unroll
;                     for (int n = 0; n < 2; ++n) acc[a][b][m][n] = (f32x4){0.f, 0.f, 0.f, 0.f};
;         cur = nxt; cA = nA; cB = nB; ++ui;
	s_add_i32 s24, s58, s41
	s_mov_b32 m0, s24
	ds_read_b128 v[118:121], v23 offset:49152
	ds_read_b128 v[202:205], v23 offset:50176
	ds_read_b128 v[206:209], v23 offset:51200
	ds_read_b128 v[210:213], v23 offset:52224
	ds_read_b128 v[216:219], v23 offset:53248
	ds_read_b128 v[220:223], v23 offset:54272
	ds_read_b128 v[224:227], v23 offset:55296
	ds_read_b128 v[228:231], v23 offset:56320
	global_load_lds_dwordx4 v4, s[98:99]
	s_add_i32 m0, s24, 0x2000
	s_add_u32 s22, s22, 0xb0080
	s_addc_u32 s23, s23, 0
	s_add_i32 s24, s59, s41
	global_load_lds_dwordx4 v8, s[98:99]
	s_mov_b32 m0, s24
	s_nop 0
	global_load_lds_dwordx4 v4, s[22:23]
	s_add_i32 m0, s24, 0x2000
	s_nop 0
	global_load_lds_dwordx4 v8, s[22:23]
	s_mov_b32 m0, s48
	s_nop 0
	global_load_lds_dwordx4 v2, s[100:101]
	s_mov_b32 m0, s49
	s_nop 0
	global_load_lds_dwordx4 v6, s[100:101]
	s_waitcnt vmcnt(8)
	s_waitcnt lgkmcnt(0)
	s_barrier
	s_setprio 1
	s_waitcnt lgkmcnt(0)
	v_mfma_f32_16x16x32_bf16 v[82:85], v[50:53], v[118:121], v[150:153]
	v_mfma_f32_16x16x32_bf16 v[150:153], v[54:57], v[202:205], v[82:85]
	v_mfma_f32_16x16x32_bf16 v[82:85], v[66:69], v[118:121], v[146:149]
	v_mfma_f32_16x16x32_bf16 v[146:149], v[70:73], v[202:205], v[82:85]
	v_mfma_f32_16x16x32_bf16 v[82:85], v[50:53], v[206:209], v[142:145]
	v_mfma_f32_16x16x32_bf16 v[142:145], v[54:57], v[210:213], v[82:85]
	v_mfma_f32_16x16x32_bf16 v[82:85], v[66:69], v[206:209], v[138:141]
	v_mfma_f32_16x16x32_bf16 v[138:141], v[70:73], v[210:213], v[82:85]
	v_mfma_f32_16x16x32_bf16 v[82:85], v[50:53], v[216:219], v[134:137]
	v_mfma_f32_16x16x32_bf16 v[34:37], v[50:53], v[224:227], v[34:37]
	v_mfma_f32_16x16x32_bf16 v[134:137], v[54:57], v[220:223], v[82:85]
	v_mfma_f32_16x16x32_bf16 v[82:85], v[66:69], v[216:219], v[130:133]
	v_mfma_f32_16x16x32_bf16 v[98:101], v[54:57], v[228:231], v[34:37]
	v_mfma_f32_16x16x32_bf16 v[34:37], v[66:69], v[224:227], v[38:41]
	v_mfma_f32_16x16x32_bf16 v[130:133], v[70:73], v[220:223], v[82:85]
	v_mfma_f32_16x16x32_bf16 v[82:85], v[70:73], v[228:231], v[34:37]
	v_mfma_f32_16x16x32_bf16 v[34:37], v[162:165], v[118:121], v[42:45]
	v_mfma_f32_16x16x32_bf16 v[114:117], v[166:169], v[202:205], v[34:37]
	v_mfma_f32_16x16x32_bf16 v[34:37], v[194:197], v[118:121], v[46:49]
	v_mfma_f32_16x16x32_bf16 v[118:121], v[198:201], v[202:205], v[34:37]
	v_mfma_f32_16x16x32_bf16 v[34:37], v[162:165], v[206:209], v[122:125]
	v_mfma_f32_16x16x32_bf16 v[122:125], v[166:169], v[210:213], v[34:37]
	v_mfma_f32_16x16x32_bf16 v[34:37], v[194:197], v[206:209], v[126:129]
	v_mfma_f32_16x16x32_bf16 v[126:129], v[198:201], v[210:213], v[34:37]
	v_mfma_f32_16x16x32_bf16 v[34:37], v[162:165], v[216:219], v[102:105]
	v_mfma_f32_16x16x32_bf16 v[102:105], v[166:169], v[220:223], v[34:37]
	v_mfma_f32_16x16x32_bf16 v[34:37], v[194:197], v[216:219], v[86:89]
	v_mfma_f32_16x16x32_bf16 v[28:31], v[162:165], v[224:227], v[30:33]
	v_mfma_f32_16x16x32_bf16 v[24:27], v[194:197], v[224:227], v[24:27]
	v_mfma_f32_16x16x32_bf16 v[86:89], v[198:201], v[220:223], v[34:37]
	v_mfma_f32_16x16x32_bf16 v[30:33], v[166:169], v[228:231], v[28:31]
	v_mfma_f32_16x16x32_bf16 v[26:29], v[198:201], v[228:231], v[24:27]
	s_setprio 0
	s_barrier
	s_add_i32 s57, s57, 2
	s_add_u32 s20, s20, 0x100
	s_addc_u32 s21, s21, 0
	s_cmp_gt_u32 s57, 41
	s_cbranch_scc0 .LBB0_1838
	s_add_u32 s20, s55, 0xffffff00
	s_addc_u32 s21, s56, -1
	s_and_b64 vcc, exec, s[4:5]
	s_cbranch_vccnz .LBB0_1825
	v_mov_b32_e32 v26, 0
	s_mov_b32 s12, s52
	s_mov_b32 s27, s53
	s_mov_b64 s[14:15], s[18:19]
	s_mov_b32 s47, s54
	v_mov_b32_e32 v27, v26
	v_mov_b32_e32 v28, v26
	v_mov_b32_e32 v29, v26
	v_mov_b32_e32 v30, v26
	v_mov_b32_e32 v31, v26
	v_mov_b32_e32 v32, v26
	v_mov_b32_e32 v33, v26
	v_mov_b32_e32 v86, v26
	v_mov_b32_e32 v87, v26
	v_mov_b32_e32 v88, v26
	v_mov_b32_e32 v89, v26
	v_mov_b32_e32 v102, v26
	v_mov_b32_e32 v103, v26
	v_mov_b32_e32 v104, v26
	v_mov_b32_e32 v105, v26
	v_mov_b32_e32 v126, v26
	v_mov_b32_e32 v127, v26
	v_mov_b32_e32 v128, v26
	v_mov_b32_e32 v129, v26
	v_mov_b32_e32 v122, v26
	v_mov_b32_e32 v123, v26
	v_mov_b32_e32 v124, v26
	v_mov_b32_e32 v125, v26
	v_mov_b32_e32 v118, v26
	v_mov_b32_e32 v119, v26
	v_mov_b32_e32 v120, v26
	v_mov_b32_e32 v121, v26
	v_mov_b32_e32 v114, v26
	v_mov_b32_e32 v115, v26
	v_mov_b32_e32 v116, v26
	v_mov_b32_e32 v117, v26
	v_mov_b32_e32 v82, v26
	v_mov_b32_e32 v83, v26
	v_mov_b32_e32 v84, v26
	v_mov_b32_e32 v85, v26
	v_mov_b32_e32 v98, v26
	v_mov_b32_e32 v99, v26
	v_mov_b32_e32 v100, v26
	v_mov_b32_e32 v101, v26
	v_mov_b32_e32 v130, v26
	v_mov_b32_e32 v131, v26
	v_mov_b32_e32 v132, v26
	v_mov_b32_e32 v133, v26
	v_mov_b32_e32 v134, v26
	v_mov_b32_e32 v135, v26
	v_mov_b32_e32 v136, v26
	v_mov_b32_e32 v137, v26
	v_mov_b32_e32 v138, v26
	v_mov_b32_e32 v139, v26
	v_mov_b32_e32 v140, v26
	v_mov_b32_e32 v141, v26
	v_mov_b32_e32 v142, v26
	v_mov_b32_e32 v143, v26
	v_mov_b32_e32 v144, v26
	v_mov_b32_e32 v145, v26
	v_mov_b32_e32 v146, v26
	v_mov_b32_e32 v147, v26
	v_mov_b32_e32 v148, v26
	v_mov_b32_e32 v149, v26
	v_mov_b32_e32 v150, v26
	v_mov_b32_e32 v151, v26
	v_mov_b32_e32 v152, v26
	v_mov_b32_e32 v153, v26
	v_mov_b32_e32 v110, v26
	v_mov_b32_e32 v111, v26
	v_mov_b32_e32 v112, v26
	v_mov_b32_e32 v113, v26
	v_mov_b32_e32 v106, v26
	v_mov_b32_e32 v107, v26
	v_mov_b32_e32 v108, v26
	v_mov_b32_e32 v109, v26
	v_mov_b32_e32 v94, v26
	v_mov_b32_e32 v95, v26
	v_mov_b32_e32 v96, v26
	v_mov_b32_e32 v97, v26
	v_mov_b32_e32 v90, v26
	v_mov_b32_e32 v91, v26
	v_mov_b32_e32 v92, v26
	v_mov_b32_e32 v93, v26
	v_mov_b32_e32 v78, v26
	v_mov_b32_e32 v79, v26
	v_mov_b32_e32 v80, v26
	v_mov_b32_e32 v81, v26
	v_mov_b32_e32 v74, v26
	v_mov_b32_e32 v75, v26
	v_mov_b32_e32 v76, v26
	v_mov_b32_e32 v77, v26
	v_mov_b32_e32 v58, v26
	v_mov_b32_e32 v59, v26
	v_mov_b32_e32 v60, v26
	v_mov_b32_e32 v61, v26
	v_mov_b32_e32 v62, v26
	v_mov_b32_e32 v63, v26
	v_mov_b32_e32 v64, v26
	v_mov_b32_e32 v65, v26
	v_mov_b32_e32 v154, v26
	v_mov_b32_e32 v155, v26
	v_mov_b32_e32 v156, v26
	v_mov_b32_e32 v157, v26
	v_mov_b32_e32 v158, v26
	v_mov_b32_e32 v159, v26
	v_mov_b32_e32 v160, v26
	v_mov_b32_e32 v161, v26
	v_mov_b32_e32 v190, v26
	v_mov_b32_e32 v191, v26
	v_mov_b32_e32 v192, v26
	v_mov_b32_e32 v193, v26
	v_mov_b32_e32 v186, v26
	v_mov_b32_e32 v187, v26
	v_mov_b32_e32 v188, v26
	v_mov_b32_e32 v189, v26
	v_mov_b32_e32 v182, v26
	v_mov_b32_e32 v183, v26
	v_mov_b32_e32 v184, v26
	v_mov_b32_e32 v185, v26
	v_mov_b32_e32 v178, v26
	v_mov_b32_e32 v179, v26
	v_mov_b32_e32 v180, v26
	v_mov_b32_e32 v181, v26
	v_mov_b32_e32 v174, v26
	v_mov_b32_e32 v175, v26
	v_mov_b32_e32 v176, v26
	v_mov_b32_e32 v177, v26
	v_mov_b32_e32 v170, v26
	v_mov_b32_e32 v171, v26
	v_mov_b32_e32 v172, v26
	v_mov_b32_e32 v173, v26
	s_andn2_b64 vcc, exec, s[2:3]
	s_cbranch_vccnz .LBB0_1826

; #define PG8_STAGE(bufoff, gbase, voff) do { _Pragma("unroll") for (int _i = 0; _i < 2; ++_i) \
;         __builtin_amdgcn_global_load_lds((const unsigned*)((const char*)(gbase) + (voff)[_i]), (PG8_LAS unsigned*)(lds + (bufoff) + ldsw + _i * 8192), 16, 0, 0); } while (0)
; #define PG8_LDA(dst, b, h) do { _Pragma("unroll") for (int m = 0; m < 4; ++m) _Pragma("unroll") for (int k = 0; k < 2; ++k) dst[m][k] = *(const PG8_LAS bf16x8*)(lds + PG8_SA(b, h) + aoff + m * 2048 + k * 1024); } while (0)
; #define PG8_LDB(dst, b, h) do { _Pragma("unroll") for (int n = 0; n < 2; ++n) _Pragma("unroll") for (int k = 0; k < 2; ++k) dst[n][k] = *(const PG8_LAS bf16x8*)(lds + PG8_SB(b, h) + boff + n * 2048 + k * 1024); } while (0)
; #define PG8_MMA(ai, bj, At, Bt) do { __builtin_amdgcn_s_setprio(1); _Pragma("unroll") for (int m = 0; m < 4; ++m) _Pragma("unroll") for (int n = 0; n < 2; ++n) _Pragma("unroll") for (int k = 0; k < 2; ++k) \
;         acc[ai][bj][m][n] = __builtin_amdgcn_mfma_f32_16x16x32_bf16(Bt[n][k], At[m][k], acc[ai][bj][m][n], 0, 0, 0); __builtin_amdgcn_s_setprio(0); } while (0)
; #define PG8_WAIT_V(n) asm volatile("s_waitcnt vmcnt(" #n ")" ::: "memory")
; #define PG8_WAIT_L(n) asm volatile("s_waitcnt lgkmcnt(" #n ")" ::: "memory")
; #define PG8_BAR __builtin_amdgcn_s_barrier()
; #define PG8_SCHED __builtin_amdgcn_sched_barrier(0)
; template <class Epi, class Sched, bool ALIGN_EPI = false, bool SP2 = false>
; __device__ __forceinline__ void gemm_phase(PG8_LAS unsigned char* lds, const Gemm g, const Sched& S, const Epi& E) {
;     ...
;             PG8_LDB(B0, 0, 0); PG8_LDB(B1, 0, 1); PG8_SCHED; PG8_LDA(At, 0, 0); PG8_STAGE(PG8_SA(1, 1), a1 + hstepA, voffA);
;             PG8_WAIT_V(8); PG8_WAIT_L(0); PG8_BAR; PG8_MMA(0, 0, At, B0); PG8_MMA(0, 1, At, B1); PG8_BAR; PG8_SCHED;
;             PG8_LDA(At, 0, 1); PG8_STAGE(PG8_SB(0, 0), b2, voffB); PG8_STAGE(PG8_SB(0, 1), b2 + hstepB, voffB); PG8_STAGE(PG8_SA(0, 0), a2, voffA);
;             PG8_WAIT_V(8); PG8_WAIT_L(0); PG8_BAR; PG8_MMA(1, 0, At, B0); PG8_MMA(1, 1, At, B1); PG8_BAR; PG8_SCHED;
;             PG8_LDB(B0, 1, 0); PG8_LDB(B1, 1, 1); PG8_SCHED; PG8_LDA(At, 1, 0); PG8_STAGE(PG8_SA(0, 1), a2 + hstepA, voffA);
;             PG8_WAIT_V(8); PG8_WAIT_L(0); PG8_BAR; PG8_MMA(0, 0, At, B0); PG8_MMA(0, 1, At, B1); PG8_BAR; PG8_SCHED;
.LBB0_1897:
	ds_read_b128 v[130:133], v162
	ds_read_b128 v[134:137], v162 offset:1024
	ds_read_b128 v[138:141], v162 offset:2048
	ds_read_b128 v[142:145], v162 offset:3072
	ds_read_b128 v[156:159], v163
	ds_read_b128 v[166:169], v163 offset:1024
	ds_read_b128 v[170:173], v163 offset:2048
	ds_read_b128 v[174:177], v163 offset:3072
	s_add_u32 s22, s20, 0x100
	s_addc_u32 s23, s21, 0
	s_cmp_eq_u32 s68, 4
	s_cselect_b32 s27, s17, s23
	s_cselect_b32 s26, s16, s22
	s_cselect_b32 s25, s19, s67
	s_cselect_b32 s24, s18, s66
	v_lshl_add_u64 v[210:211], s[20:21], 0, v[152:153]
	s_add_i32 m0, s42, 0xc000
	ds_read_b128 v[178:181], v164
	ds_read_b128 v[182:185], v164 offset:1024
	ds_read_b128 v[186:189], v164 offset:2048
	ds_read_b128 v[190:193], v164 offset:3072
	ds_read_b128 v[194:197], v164 offset:4096
	ds_read_b128 v[198:201], v164 offset:5120
	ds_read_b128 v[202:205], v164 offset:6144
	ds_read_b128 v[206:209], v164 offset:7168
	global_load_lds_dwordx4 v[210:211], off
	v_lshl_add_u64 v[210:211], s[20:21], 0, v[154:155]
	s_add_i32 m0, s42, 0xe000
	s_nop 0
	global_load_lds_dwordx4 v[210:211], off
	s_waitcnt vmcnt(8)
	s_waitcnt lgkmcnt(0)
	s_barrier
	s_setprio 1
	s_waitcnt lgkmcnt(0)
	v_mfma_f32_16x16x32_bf16 v[126:129], v[130:133], v[178:181], v[126:129]
	v_mfma_f32_16x16x32_bf16 v[122:125], v[138:141], v[178:181], v[122:125]
	v_mfma_f32_16x16x32_bf16 v[118:121], v[130:133], v[186:189], v[118:121]
	v_mfma_f32_16x16x32_bf16 v[114:117], v[138:141], v[186:189], v[114:117]
	v_mfma_f32_16x16x32_bf16 v[102:105], v[130:133], v[194:197], v[102:105]
	v_mfma_f32_16x16x32_bf16 v[90:93], v[138:141], v[194:197], v[90:93]
	v_mfma_f32_16x16x32_bf16 v[82:85], v[130:133], v[202:205], v[82:85]
	v_mfma_f32_16x16x32_bf16 v[74:77], v[138:141], v[202:205], v[74:77]
	v_mfma_f32_16x16x32_bf16 v[126:129], v[134:137], v[182:185], v[126:129]
	v_mfma_f32_16x16x32_bf16 v[122:125], v[142:145], v[182:185], v[122:125]
	v_mfma_f32_16x16x32_bf16 v[118:121], v[134:137], v[190:193], v[118:121]
	v_mfma_f32_16x16x32_bf16 v[114:117], v[142:145], v[190:193], v[114:117]
	v_mfma_f32_16x16x32_bf16 v[102:105], v[134:137], v[198:201], v[102:105]
	v_mfma_f32_16x16x32_bf16 v[90:93], v[142:145], v[198:201], v[90:93]
	v_mfma_f32_16x16x32_bf16 v[82:85], v[134:137], v[206:209], v[82:85]
	v_mfma_f32_16x16x32_bf16 v[74:77], v[142:145], v[206:209], v[74:77]
	v_mfma_f32_16x16x32_bf16 v[110:113], v[156:159], v[178:181], v[110:113]
	v_mfma_f32_16x16x32_bf16 v[106:109], v[170:173], v[178:181], v[106:109]
	v_mfma_f32_16x16x32_bf16 v[98:101], v[156:159], v[186:189], v[98:101]
	v_mfma_f32_16x16x32_bf16 v[94:97], v[170:173], v[186:189], v[94:97]
	v_mfma_f32_16x16x32_bf16 v[86:89], v[156:159], v[194:197], v[86:89]
	v_mfma_f32_16x16x32_bf16 v[78:81], v[170:173], v[194:197], v[78:81]
	v_mfma_f32_16x16x32_bf16 v[70:73], v[156:159], v[202:205], v[70:73]
	v_mfma_f32_16x16x32_bf16 v[66:69], v[170:173], v[202:205], v[66:69]
	v_mfma_f32_16x16x32_bf16 v[110:113], v[166:169], v[182:185], v[110:113]
	v_mfma_f32_16x16x32_bf16 v[106:109], v[174:177], v[182:185], v[106:109]
	v_mfma_f32_16x16x32_bf16 v[98:101], v[166:169], v[190:193], v[98:101]
	v_mfma_f32_16x16x32_bf16 v[94:97], v[174:177], v[190:193], v[94:97]
	v_mfma_f32_16x16x32_bf16 v[86:89], v[166:169], v[198:201], v[86:89]
	v_mfma_f32_16x16x32_bf16 v[78:81], v[174:177], v[198:201], v[78:81]
	v_mfma_f32_16x16x32_bf16 v[70:73], v[166:169], v[206:209], v[70:73]
	v_mfma_f32_16x16x32_bf16 v[66:69], v[174:177], v[206:209], v[66:69]
	s_setprio 0
	s_barrier
	s_add_i32 s20, s54, s40
	s_add_u32 s98, s24, 0x80
	s_addc_u32 s99, s25, 0
	s_mov_b32 m0, s20
	ds_read_b128 v[178:181], v164 offset:16384
	ds_read_b128 v[182:185], v164 offset:17408
	ds_read_b128 v[186:189], v164 offset:18432
	ds_read_b128 v[190:193], v164 offset:19456
	ds_read_b128 v[194:197], v164 offset:20480
	ds_read_b128 v[198:201], v164 offset:21504
	ds_read_b128 v[202:205], v164 offset:22528
	ds_read_b128 v[206:209], v164 offset:23552
	global_load_lds_dwordx4 v148, s[24:25]
	s_add_i32 m0, s20, 0x2000
	s_add_u32 s20, s24, 0xb0000
	s_addc_u32 s21, s25, 0
	s_add_i32 s69, s55, s40
	global_load_lds_dwordx4 v146, s[24:25]
	s_mov_b32 m0, s69
	s_nop 0
	global_load_lds_dwordx4 v148, s[20:21]
	s_add_i32 m0, s69, 0x2000
	s_nop 0
	global_load_lds_dwordx4 v146, s[20:21]
	s_add_u32 s100, s26, 0x80
	s_addc_u32 s101, s27, 0
	s_mov_b32 m0, s42
	s_nop 0
	global_load_lds_dwordx4 v148, s[26:27]
	s_mov_b32 m0, s43
	s_nop 0
	global_load_lds_dwordx4 v146, s[26:27]
	s_waitcnt vmcnt(8)
	s_waitcnt lgkmcnt(0)
	s_barrier
	s_setprio 1
	s_waitcnt lgkmcnt(0)
	v_mfma_f32_16x16x32_bf16 v[62:65], v[130:133], v[178:181], v[62:65]
	v_mfma_f32_16x16x32_bf16 v[58:61], v[138:141], v[178:181], v[58:61]
	v_mfma_f32_16x16x32_bf16 v[54:57], v[130:133], v[186:189], v[54:57]
	v_mfma_f32_16x16x32_bf16 v[50:53], v[138:141], v[186:189], v[50:53]
	v_mfma_f32_16x16x32_bf16 v[46:49], v[130:133], v[194:197], v[46:49]
	v_mfma_f32_16x16x32_bf16 v[38:41], v[138:141], v[194:197], v[38:41]
	v_mfma_f32_16x16x32_bf16 v[18:21], v[130:133], v[202:205], v[18:21]
	v_mfma_f32_16x16x32_bf16 v[10:13], v[138:141], v[202:205], v[10:13]
	v_mfma_f32_16x16x32_bf16 v[62:65], v[134:137], v[182:185], v[62:65]
	v_mfma_f32_16x16x32_bf16 v[58:61], v[142:145], v[182:185], v[58:61]
	v_mfma_f32_16x16x32_bf16 v[54:57], v[134:137], v[190:193], v[54:57]
	v_mfma_f32_16x16x32_bf16 v[50:53], v[142:145], v[190:193], v[50:53]
	v_mfma_f32_16x16x32_bf16 v[46:49], v[134:137], v[198:201], v[46:49]
	v_mfma_f32_16x16x32_bf16 v[38:41], v[142:145], v[198:201], v[38:41]
	v_mfma_f32_16x16x32_bf16 v[18:21], v[134:137], v[206:209], v[18:21]
	v_mfma_f32_16x16x32_bf16 v[10:13], v[142:145], v[206:209], v[10:13]
	v_mfma_f32_16x16x32_bf16 v[42:45], v[156:159], v[178:181], v[42:45]
	v_mfma_f32_16x16x32_bf16 v[34:37], v[170:173], v[178:181], v[34:37]
	v_mfma_f32_16x16x32_bf16 v[30:33], v[156:159], v[186:189], v[30:33]
	v_mfma_f32_16x16x32_bf16 v[26:29], v[170:173], v[186:189], v[26:29]
	v_mfma_f32_16x16x32_bf16 v[22:25], v[156:159], v[194:197], v[22:25]
	v_mfma_f32_16x16x32_bf16 v[14:17], v[170:173], v[194:197], v[14:17]
	v_mfma_f32_16x16x32_bf16 v[6:9], v[156:159], v[202:205], v[6:9]
	v_mfma_f32_16x16x32_bf16 v[2:5], v[170:173], v[202:205], v[2:5]
	v_mfma_f32_16x16x32_bf16 v[42:45], v[166:169], v[182:185], v[42:45]
	v_mfma_f32_16x16x32_bf16 v[34:37], v[174:177], v[182:185], v[34:37]
	v_mfma_f32_16x16x32_bf16 v[30:33], v[166:169], v[190:193], v[30:33]
	v_mfma_f32_16x16x32_bf16 v[26:29], v[174:177], v[190:193], v[26:29]
	v_mfma_f32_16x16x32_bf16 v[22:25], v[166:169], v[198:201], v[22:25]
	v_mfma_f32_16x16x32_bf16 v[14:17], v[174:177], v[198:201], v[14:17]
	v_mfma_f32_16x16x32_bf16 v[6:9], v[166:169], v[206:209], v[6:9]
	v_mfma_f32_16x16x32_bf16 v[2:5], v[174:177], v[206:209], v[2:5]
	s_setprio 0
	s_barrier
; #define PG8_STAGE(bufoff, gbase, voff) do { _Pragma("unroll") for (int _i = 0; _i < 2; ++_i) \
;         __builtin_amdgcn_global_load_lds((const unsigned*)((const char*)(gbase) + (voff)[_i]), (PG8_LAS unsigned*)(lds + (bufoff) + ldsw + _i * 8192), 16, 0, 0); } while (0)
; #define PG8_LDA(dst, b, h) do { _Pragma("unroll") for (int m = 0; m < 4; ++m) _Pragma("unroll") for (int k = 0; k < 2; ++k) dst[m][k] = *(const PG8_LAS bf16x8*)(lds + PG8_SA(b, h) + aoff + m * 2048 + k * 1024); } while (0)
; #define PG8_LDB(dst, b, h) do { _Pragma("unroll") for (int n = 0; n < 2; ++n) _Pragma("unroll") for (int k = 0; k < 2; ++k) dst[n][k] = *(const PG8_LAS bf16x8*)(lds + PG8_SB(b, h) + boff + n * 2048 + k * 1024); } while (0)
; #define PG8_MMA(ai, bj, At, Bt) do { __builtin_amdgcn_s_setprio(1); _Pragma("unroll") for (int m = 0; m < 4; ++m) _Pragma("unroll") for (int n = 0; n < 2; ++n) _Pragma("unroll") for (int k = 0; k < 2; ++k) \
;         acc[ai][bj][m][n] = __builtin_amdgcn_mfma_f32_16x16x32_bf16(Bt[n][k], At[m][k], acc[ai][bj][m][n], 0, 0, 0); __builtin_amdgcn_s_setprio(0); } while (0)
; #define PG8_WAIT_V(n) asm volatile("s_waitcnt vmcnt(" #n ")" ::: "memory")
; #define PG8_WAIT_L(n) asm volatile("s_waitcnt lgkmcnt(" #n ")" ::: "memory")
; template <class Epi, class Sched, bool ALIGN_EPI = false, bool SP2 = false>
; __device__ __forceinline__ void gemm_phase(PG8_LAS unsigned char* lds, const Gemm g, const Sched& S, const Epi& E) {
;     ...
;         for (int t = 0; t < nt; t += 2) {
;             const bool last = (t == nt - 2);
;             const char* a1 = cA + (size_t)(t + 1) * kstep;
;             const char* a2 = last ? nA : cA + (size_t)(t + 2) * kstep; const char* b2 = last ? nB : cB + (size_t)(t + 2) * kstep;
;             const char* a3 = a2 + kstep; const char* b3 = b2 + kstep;
;             if (last && has_next) S.a_ready(nxt);
;     ...
;             PG8_LDB(B0, 1, 0); PG8_LDB(B1, 1, 1); PG8_SCHED; PG8_LDA(At, 1, 0); PG8_STAGE(PG8_SA(0, 1), a2 + hstepA, voffA);
;             PG8_WAIT_V(8); PG8_WAIT_L(0); PG8_BAR; PG8_MMA(0, 0, At, B0); PG8_MMA(0, 1, At, B1); PG8_BAR; PG8_SCHED;
;             PG8_LDA(At, 1, 1); PG8_STAGE(PG8_SB(1, 0), b3, voffB); PG8_STAGE(PG8_SB(1, 1), b3 + hstepB, voffB); PG8_STAGE(PG8_SA(1, 0), a3, voffA);
;             PG8_WAIT_V(8); PG8_WAIT_L(0); PG8_BAR; PG8_MMA(1, 0, At, B0); PG8_MMA(1, 1, At, B1); PG8_BAR; PG8_SCHED;
	s_add_i32 s69, 0, 0x18000
	s_add_i32 s70, 0, 0x1c000
	v_add_u32_e32 v142, s69, v1
	v_add_u32_e32 v174, s70, v1
	ds_read_b128 v[130:133], v142
	ds_read_b128 v[134:137], v142 offset:1024
	ds_read_b128 v[138:141], v142 offset:2048
	ds_read_b128 v[142:145], v142 offset:3072
	ds_read_b128 v[156:159], v174
	ds_read_b128 v[166:169], v174 offset:1024
	ds_read_b128 v[170:173], v174 offset:2048
	ds_read_b128 v[174:177], v174 offset:3072
	s_add_u32 s20, s26, 0xb0000
	s_addc_u32 s21, s27, 0
	s_mov_b32 m0, s44
	ds_read_b128 v[178:181], v164 offset:32768
	ds_read_b128 v[182:185], v164 offset:33792
	ds_read_b128 v[186:189], v164 offset:34816
	ds_read_b128 v[190:193], v164 offset:35840
	ds_read_b128 v[194:197], v164 offset:36864
	ds_read_b128 v[198:201], v164 offset:37888
	ds_read_b128 v[202:205], v164 offset:38912
	ds_read_b128 v[206:209], v164 offset:39936
	global_load_lds_dwordx4 v148, s[20:21]
	s_mov_b32 m0, s45
	s_nop 0
	global_load_lds_dwordx4 v146, s[20:21]
	s_waitcnt vmcnt(8)
	s_waitcnt lgkmcnt(0)
	s_barrier
	s_setprio 1
	s_waitcnt lgkmcnt(0)
	v_mfma_f32_16x16x32_bf16 v[126:129], v[130:133], v[178:181], v[126:129]
	v_mfma_f32_16x16x32_bf16 v[122:125], v[138:141], v[178:181], v[122:125]
	v_mfma_f32_16x16x32_bf16 v[118:121], v[130:133], v[186:189], v[118:121]
	v_mfma_f32_16x16x32_bf16 v[114:117], v[138:141], v[186:189], v[114:117]
	v_mfma_f32_16x16x32_bf16 v[102:105], v[130:133], v[194:197], v[102:105]
	v_mfma_f32_16x16x32_bf16 v[90:93], v[138:141], v[194:197], v[90:93]
	v_mfma_f32_16x16x32_bf16 v[82:85], v[130:133], v[202:205], v[82:85]
	v_mfma_f32_16x16x32_bf16 v[74:77], v[138:141], v[202:205], v[74:77]
	v_mfma_f32_16x16x32_bf16 v[126:129], v[134:137], v[182:185], v[126:129]
	v_mfma_f32_16x16x32_bf16 v[122:125], v[142:145], v[182:185], v[122:125]
	v_mfma_f32_16x16x32_bf16 v[118:121], v[134:137], v[190:193], v[118:121]
	v_mfma_f32_16x16x32_bf16 v[114:117], v[142:145], v[190:193], v[114:117]
	v_mfma_f32_16x16x32_bf16 v[102:105], v[134:137], v[198:201], v[102:105]
	v_mfma_f32_16x16x32_bf16 v[90:93], v[142:145], v[198:201], v[90:93]
	v_mfma_f32_16x16x32_bf16 v[82:85], v[134:137], v[206:209], v[82:85]
	v_mfma_f32_16x16x32_bf16 v[74:77], v[142:145], v[206:209], v[74:77]
	v_mfma_f32_16x16x32_bf16 v[110:113], v[156:159], v[178:181], v[110:113]
	v_mfma_f32_16x16x32_bf16 v[106:109], v[170:173], v[178:181], v[106:109]
	v_mfma_f32_16x16x32_bf16 v[98:101], v[156:159], v[186:189], v[98:101]
	v_mfma_f32_16x16x32_bf16 v[94:97], v[170:173], v[186:189], v[94:97]
	v_mfma_f32_16x16x32_bf16 v[86:89], v[156:159], v[194:197], v[86:89]
	v_mfma_f32_16x16x32_bf16 v[78:81], v[170:173], v[194:197], v[78:81]
	v_mfma_f32_16x16x32_bf16 v[70:73], v[156:159], v[202:205], v[70:73]
	v_mfma_f32_16x16x32_bf16 v[66:69], v[170:173], v[202:205], v[66:69]
	v_mfma_f32_16x16x32_bf16 v[110:113], v[166:169], v[182:185], v[110:113]
	v_mfma_f32_16x16x32_bf16 v[106:109], v[174:177], v[182:185], v[106:109]
	v_mfma_f32_16x16x32_bf16 v[98:101], v[166:169], v[190:193], v[98:101]
	v_mfma_f32_16x16x32_bf16 v[94:97], v[174:177], v[190:193], v[94:97]
	v_mfma_f32_16x16x32_bf16 v[86:89], v[166:169], v[198:201], v[86:89]
	v_mfma_f32_16x16x32_bf16 v[78:81], v[174:177], v[198:201], v[78:81]
	v_mfma_f32_16x16x32_bf16 v[70:73], v[166:169], v[206:209], v[70:73]
	v_mfma_f32_16x16x32_bf16 v[66:69], v[174:177], v[206:209], v[66:69]
	s_setprio 0
	s_barrier
	s_add_i32 s20, s69, s40
	s_mov_b32 m0, s20
	ds_read_b128 v[178:181], v164 offset:49152
	ds_read_b128 v[182:185], v164 offset:50176
	ds_read_b128 v[186:189], v164 offset:51200
	ds_read_b128 v[190:193], v164 offset:52224
	ds_read_b128 v[194:197], v164 offset:53248
	ds_read_b128 v[198:201], v164 offset:54272
	ds_read_b128 v[202:205], v164 offset:55296
	ds_read_b128 v[206:209], v164 offset:56320
	global_load_lds_dwordx4 v148, s[98:99]
	s_add_i32 m0, s20, 0x2000
	s_add_u32 s20, s24, 0xb0080
	s_addc_u32 s21, s25, 0
	s_add_i32 s24, s70, s40
	global_load_lds_dwordx4 v146, s[98:99]
	s_mov_b32 m0, s24
	s_nop 0
	global_load_lds_dwordx4 v148, s[20:21]
	s_add_i32 m0, s24, 0x2000
	s_nop 0
	global_load_lds_dwordx4 v146, s[20:21]
	s_mov_b32 m0, s51
	s_nop 0
	global_load_lds_dwordx4 v148, s[100:101]
	s_mov_b32 m0, s52
	s_nop 0
	global_load_lds_dwordx4 v146, s[100:101]
	s_waitcnt vmcnt(8)
	s_waitcnt lgkmcnt(0)
	s_barrier
	s_setprio 1
	s_waitcnt lgkmcnt(0)
	v_mfma_f32_16x16x32_bf16 v[62:65], v[130:133], v[178:181], v[62:65]
	v_mfma_f32_16x16x32_bf16 v[58:61], v[138:141], v[178:181], v[58:61]
	v_mfma_f32_16x16x32_bf16 v[54:57], v[130:133], v[186:189], v[54:57]
	v_mfma_f32_16x16x32_bf16 v[50:53], v[138:141], v[186:189], v[50:53]
	v_mfma_f32_16x16x32_bf16 v[46:49], v[130:133], v[194:197], v[46:49]
	v_mfma_f32_16x16x32_bf16 v[38:41], v[138:141], v[194:197], v[38:41]
	v_mfma_f32_16x16x32_bf16 v[18:21], v[130:133], v[202:205], v[18:21]
	v_mfma_f32_16x16x32_bf16 v[10:13], v[138:141], v[202:205], v[10:13]
	v_mfma_f32_16x16x32_bf16 v[62:65], v[134:137], v[182:185], v[62:65]
	v_mfma_f32_16x16x32_bf16 v[58:61], v[142:145], v[182:185], v[58:61]
	v_mfma_f32_16x16x32_bf16 v[54:57], v[134:137], v[190:193], v[54:57]
	v_mfma_f32_16x16x32_bf16 v[50:53], v[142:145], v[190:193], v[50:53]
	v_mfma_f32_16x16x32_bf16 v[46:49], v[134:137], v[198:201], v[46:49]
	v_mfma_f32_16x16x32_bf16 v[38:41], v[142:145], v[198:201], v[38:41]
	v_mfma_f32_16x16x32_bf16 v[18:21], v[134:137], v[206:209], v[18:21]
	v_mfma_f32_16x16x32_bf16 v[10:13], v[142:145], v[206:209], v[10:13]
	v_mfma_f32_16x16x32_bf16 v[42:45], v[156:159], v[178:181], v[42:45]
	v_mfma_f32_16x16x32_bf16 v[34:37], v[170:173], v[178:181], v[34:37]
	v_mfma_f32_16x16x32_bf16 v[30:33], v[156:159], v[186:189], v[30:33]
	v_mfma_f32_16x16x32_bf16 v[26:29], v[170:173], v[186:189], v[26:29]
	v_mfma_f32_16x16x32_bf16 v[22:25], v[156:159], v[194:197], v[22:25]
	v_mfma_f32_16x16x32_bf16 v[14:17], v[170:173], v[194:197], v[14:17]
	v_mfma_f32_16x16x32_bf16 v[6:9], v[156:159], v[202:205], v[6:9]
	v_mfma_f32_16x16x32_bf16 v[2:5], v[170:173], v[202:205], v[2:5]
	v_mfma_f32_16x16x32_bf16 v[42:45], v[166:169], v[182:185], v[42:45]
	v_mfma_f32_16x16x32_bf16 v[34:37], v[174:177], v[182:185], v[34:37]
	v_mfma_f32_16x16x32_bf16 v[30:33], v[166:169], v[190:193], v[30:33]
	v_mfma_f32_16x16x32_bf16 v[26:29], v[174:177], v[190:193], v[26:29]
	v_mfma_f32_16x16x32_bf16 v[22:25], v[166:169], v[198:201], v[22:25]
	v_mfma_f32_16x16x32_bf16 v[14:17], v[174:177], v[198:201], v[14:17]
	v_mfma_f32_16x16x32_bf16 v[6:9], v[166:169], v[206:209], v[6:9]
	v_mfma_f32_16x16x32_bf16 v[2:5], v[174:177], v[206:209], v[2:5]
	s_setprio 0
	s_barrier
	s_add_i32 s68, s68, 2
	s_add_u32 s66, s66, 0x100
	s_addc_u32 s67, s67, 0
	s_cmp_gt_u32 s68, 5
	s_mov_b64 s[20:21], s[22:23]
	s_cbranch_scc0 .LBB0_1897
	s_and_b64 vcc, exec, s[10:11]
	s_cbranch_vccz .LBB0_1900
	s_barrier

; #define PG8_STAGE(bufoff, gbase, voff) do { _Pragma("unroll") for (int _i = 0; _i < 2; ++_i) \
;         __builtin_amdgcn_global_load_lds((const unsigned*)((const char*)(gbase) + (voff)[_i]), (PG8_LAS unsigned*)(lds + (bufoff) + ldsw + _i * 8192), 16, 0, 0); } while (0)
; #define PG8_LDA(dst, b, h) do { _Pragma("unroll") for (int m = 0; m < 4; ++m) _Pragma("unroll") for (int k = 0; k < 2; ++k) dst[m][k] = *(const PG8_LAS bf16x8*)(lds + PG8_SA(b, h) + aoff + m * 2048 + k * 1024); } while (0)
; #define PG8_LDB(dst, b, h) do { _Pragma("unroll") for (int n = 0; n < 2; ++n) _Pragma("unroll") for (int k = 0; k < 2; ++k) dst[n][k] = *(const PG8_LAS bf16x8*)(lds + PG8_SB(b, h) + boff + n * 2048 + k * 1024); } while (0)
; #define PG8_MMA(ai, bj, At, Bt) do { __builtin_amdgcn_s_setprio(1); _Pragma("unroll") for (int m = 0; m < 4; ++m) _Pragma("unroll") for (int n = 0; n < 2; ++n) _Pragma("unroll") for (int k = 0; k < 2; ++k) \
;         acc[ai][bj][m][n] = __builtin_amdgcn_mfma_f32_16x16x32_bf16(Bt[n][k], At[m][k], acc[ai][bj][m][n], 0, 0, 0); __builtin_amdgcn_s_setprio(0); } while (0)
; #define PG8_WAIT_V(n) asm volatile("s_waitcnt vmcnt(" #n ")" ::: "memory")
; #define PG8_WAIT_L(n) asm volatile("s_waitcnt lgkmcnt(" #n ")" ::: "memory")
; #define PG8_BAR __builtin_amdgcn_s_barrier()
; #define PG8_SCHED __builtin_amdgcn_sched_barrier(0)
; template <class Epi, class Sched, bool ALIGN_EPI = false, bool SP2 = false>
; __device__ __forceinline__ void gemm_phase(PG8_LAS unsigned char* lds, const Gemm g, const Sched& S, const Epi& E) {
;     ...
;             PG8_LDB(B0, 0, 0); PG8_LDB(B1, 0, 1); PG8_SCHED; PG8_LDA(At, 0, 0); PG8_STAGE(PG8_SA(1, 1), a1 + hstepA, voffA);
;             PG8_WAIT_V(8); PG8_WAIT_L(0); PG8_BAR; PG8_MMA(0, 0, At, B0); PG8_MMA(0, 1, At, B1); PG8_BAR; PG8_SCHED;
;             PG8_LDA(At, 0, 1); PG8_STAGE(PG8_SB(0, 0), b2, voffB); PG8_STAGE(PG8_SB(0, 1), b2 + hstepB, voffB); PG8_STAGE(PG8_SA(0, 0), a2, voffA);
.LBB0_1921:
	ds_read_b128 v[130:133], v162
	ds_read_b128 v[134:137], v162 offset:1024
	ds_read_b128 v[138:141], v162 offset:2048
	ds_read_b128 v[142:145], v162 offset:3072
	ds_read_b128 v[156:159], v163
	ds_read_b128 v[166:169], v163 offset:1024
	ds_read_b128 v[170:173], v163 offset:2048
	ds_read_b128 v[174:177], v163 offset:3072
	s_add_u32 s22, s20, 0x100
	s_addc_u32 s23, s21, 0
	s_cmp_eq_u32 s67, 4
	s_cselect_b32 s27, s19, s23
	s_cselect_b32 s26, s18, s22
	s_cselect_b32 s25, s1, s66
	s_cselect_b32 s24, s0, s65
	v_lshl_add_u64 v[210:211], s[20:21], 0, v[154:155]
	s_add_i32 m0, s41, 0xc000
	ds_read_b128 v[178:181], v164
	ds_read_b128 v[182:185], v164 offset:1024
	ds_read_b128 v[186:189], v164 offset:2048
	ds_read_b128 v[190:193], v164 offset:3072
	ds_read_b128 v[194:197], v164 offset:4096
	ds_read_b128 v[198:201], v164 offset:5120
	ds_read_b128 v[202:205], v164 offset:6144
	ds_read_b128 v[206:209], v164 offset:7168
	global_load_lds_dwordx4 v[210:211], off
	v_lshl_add_u64 v[210:211], s[20:21], 0, v[152:153]
	s_add_i32 m0, s41, 0xe000
	s_nop 0
	global_load_lds_dwordx4 v[210:211], off
	s_waitcnt vmcnt(8)
	s_waitcnt lgkmcnt(0)
	s_barrier
	s_setprio 1
	s_waitcnt lgkmcnt(0)
	v_mfma_f32_16x16x32_bf16 v[126:129], v[130:133], v[178:181], v[126:129]
	v_mfma_f32_16x16x32_bf16 v[122:125], v[138:141], v[178:181], v[122:125]
	v_mfma_f32_16x16x32_bf16 v[118:121], v[130:133], v[186:189], v[118:121]
	v_mfma_f32_16x16x32_bf16 v[114:117], v[138:141], v[186:189], v[114:117]
	v_mfma_f32_16x16x32_bf16 v[102:105], v[130:133], v[194:197], v[102:105]
	v_mfma_f32_16x16x32_bf16 v[90:93], v[138:141], v[194:197], v[90:93]
	v_mfma_f32_16x16x32_bf16 v[82:85], v[130:133], v[202:205], v[82:85]
	v_mfma_f32_16x16x32_bf16 v[74:77], v[138:141], v[202:205], v[74:77]
	v_mfma_f32_16x16x32_bf16 v[126:129], v[134:137], v[182:185], v[126:129]
	v_mfma_f32_16x16x32_bf16 v[122:125], v[142:145], v[182:185], v[122:125]
	v_mfma_f32_16x16x32_bf16 v[118:121], v[134:137], v[190:193], v[118:121]
	v_mfma_f32_16x16x32_bf16 v[114:117], v[142:145], v[190:193], v[114:117]
	v_mfma_f32_16x16x32_bf16 v[102:105], v[134:137], v[198:201], v[102:105]
	v_mfma_f32_16x16x32_bf16 v[90:93], v[142:145], v[198:201], v[90:93]
	v_mfma_f32_16x16x32_bf16 v[82:85], v[134:137], v[206:209], v[82:85]
	v_mfma_f32_16x16x32_bf16 v[74:77], v[142:145], v[206:209], v[74:77]
	v_mfma_f32_16x16x32_bf16 v[110:113], v[156:159], v[178:181], v[110:113]
	v_mfma_f32_16x16x32_bf16 v[106:109], v[170:173], v[178:181], v[106:109]
	v_mfma_f32_16x16x32_bf16 v[98:101], v[156:159], v[186:189], v[98:101]
	v_mfma_f32_16x16x32_bf16 v[94:97], v[170:173], v[186:189], v[94:97]
	v_mfma_f32_16x16x32_bf16 v[86:89], v[156:159], v[194:197], v[86:89]
	v_mfma_f32_16x16x32_bf16 v[78:81], v[170:173], v[194:197], v[78:81]
	v_mfma_f32_16x16x32_bf16 v[70:73], v[156:159], v[202:205], v[70:73]
	v_mfma_f32_16x16x32_bf16 v[66:69], v[170:173], v[202:205], v[66:69]
	v_mfma_f32_16x16x32_bf16 v[110:113], v[166:169], v[182:185], v[110:113]
	v_mfma_f32_16x16x32_bf16 v[106:109], v[174:177], v[182:185], v[106:109]
	v_mfma_f32_16x16x32_bf16 v[98:101], v[166:169], v[190:193], v[98:101]
	v_mfma_f32_16x16x32_bf16 v[94:97], v[174:177], v[190:193], v[94:97]
	v_mfma_f32_16x16x32_bf16 v[86:89], v[166:169], v[198:201], v[86:89]
	v_mfma_f32_16x16x32_bf16 v[78:81], v[174:177], v[198:201], v[78:81]
	v_mfma_f32_16x16x32_bf16 v[70:73], v[166:169], v[206:209], v[70:73]
	v_mfma_f32_16x16x32_bf16 v[66:69], v[174:177], v[206:209], v[66:69]
	s_setprio 0
	s_barrier
	s_add_i32 s20, s53, s39
	v_lshl_add_u64 v[210:211], s[24:25], 0, v[148:149]
	s_mov_b32 m0, s20
	ds_read_b128 v[178:181], v164 offset:16384
	ds_read_b128 v[182:185], v164 offset:17408
	ds_read_b128 v[186:189], v164 offset:18432
	ds_read_b128 v[190:193], v164 offset:19456
	ds_read_b128 v[194:197], v164 offset:20480
	ds_read_b128 v[198:201], v164 offset:21504
	ds_read_b128 v[202:205], v164 offset:22528
	ds_read_b128 v[206:209], v164 offset:23552
	global_load_lds_dwordx4 v[210:211], off
	s_add_i32 m0, s20, 0x2000
	s_add_u32 s20, s24, 0xb0000
	v_lshl_add_u64 v[212:213], s[24:25], 0, v[146:147]
	s_addc_u32 s21, s25, 0
	s_add_i32 s68, s54, s39
	global_load_lds_dwordx4 v[212:213], off
	v_lshl_add_u64 v[214:215], s[20:21], 0, v[148:149]
	s_mov_b32 m0, s68
	v_lshl_add_u64 v[216:217], s[26:27], 0, v[146:147]
	global_load_lds_dwordx4 v[214:215], off
	v_lshl_add_u64 v[214:215], s[20:21], 0, v[146:147]
	s_add_i32 m0, s68, 0x2000
	s_nop 0
	global_load_lds_dwordx4 v[214:215], off
	v_lshl_add_u64 v[214:215], s[26:27], 0, v[148:149]
	s_mov_b32 m0, s41
	s_nop 0
	global_load_lds_dwordx4 v[214:215], off
	s_mov_b32 m0, s42
	s_nop 0
	global_load_lds_dwordx4 v[216:217], off
	s_waitcnt vmcnt(8)
	s_waitcnt lgkmcnt(0)
	s_barrier
; #define PG8_STAGE(bufoff, gbase, voff) do { _Pragma("unroll") for (int _i = 0; _i < 2; ++_i) \
;         __builtin_amdgcn_global_load_lds((const unsigned*)((const char*)(gbase) + (voff)[_i]), (PG8_LAS unsigned*)(lds + (bufoff) + ldsw + _i * 8192), 16, 0, 0); } while (0)
; #define PG8_LDA(dst, b, h) do { _Pragma("unroll") for (int m = 0; m < 4; ++m) _Pragma("unroll") for (int k = 0; k < 2; ++k) dst[m][k] = *(const PG8_LAS bf16x8*)(lds + PG8_SA(b, h) + aoff + m * 2048 + k * 1024); } while (0)
; #define PG8_LDB(dst, b, h) do { _Pragma("unroll") for (int n = 0; n < 2; ++n) _Pragma("unroll") for (int k = 0; k < 2; ++k) dst[n][k] = *(const PG8_LAS bf16x8*)(lds + PG8_SB(b, h) + boff + n * 2048 + k * 1024); } while (0)
; #define PG8_MMA(ai, bj, At, Bt) do { __builtin_amdgcn_s_setprio(1); _Pragma("unroll") for (int m = 0; m < 4; ++m) _Pragma("unroll") for (int n = 0; n < 2; ++n) _Pragma("unroll") for (int k = 0; k < 2; ++k) \
;         acc[ai][bj][m][n] = __builtin_amdgcn_mfma_f32_16x16x32_bf16(Bt[n][k], At[m][k], acc[ai][bj][m][n], 0, 0, 0); __builtin_amdgcn_s_setprio(0); } while (0)
; #define PG8_WAIT_V(n) asm volatile("s_waitcnt vmcnt(" #n ")" ::: "memory")
; #define PG8_WAIT_L(n) asm volatile("s_waitcnt lgkmcnt(" #n ")" ::: "memory")
; #define PG8_BAR __builtin_amdgcn_s_barrier()
; #define PG8_SCHED __builtin_amdgcn_sched_barrier(0)
; template <class Epi, class Sched, bool ALIGN_EPI = false, bool SP2 = false>
; __device__ __forceinline__ void gemm_phase(PG8_LAS unsigned char* lds, const Gemm g, const Sched& S, const Epi& E) {
;     ...
;             PG8_WAIT_V(8); PG8_WAIT_L(0); PG8_BAR; PG8_MMA(1, 0, At, B0); PG8_MMA(1, 1, At, B1); PG8_BAR; PG8_SCHED;
;             PG8_LDB(B0, 1, 0); PG8_LDB(B1, 1, 1); PG8_SCHED; PG8_LDA(At, 1, 0); PG8_STAGE(PG8_SA(0, 1), a2 + hstepA, voffA);
;             PG8_WAIT_V(8); PG8_WAIT_L(0); PG8_BAR; PG8_MMA(0, 0, At, B0); PG8_MMA(0, 1, At, B1); PG8_BAR; PG8_SCHED;
	s_setprio 1
	s_waitcnt lgkmcnt(0)
	v_mfma_f32_16x16x32_bf16 v[62:65], v[130:133], v[178:181], v[62:65]
	v_mfma_f32_16x16x32_bf16 v[58:61], v[138:141], v[178:181], v[58:61]
	v_mfma_f32_16x16x32_bf16 v[54:57], v[130:133], v[186:189], v[54:57]
	v_mfma_f32_16x16x32_bf16 v[50:53], v[138:141], v[186:189], v[50:53]
	v_mfma_f32_16x16x32_bf16 v[46:49], v[130:133], v[194:197], v[46:49]
	v_mfma_f32_16x16x32_bf16 v[38:41], v[138:141], v[194:197], v[38:41]
	v_mfma_f32_16x16x32_bf16 v[18:21], v[130:133], v[202:205], v[18:21]
	v_mfma_f32_16x16x32_bf16 v[10:13], v[138:141], v[202:205], v[10:13]
	v_mfma_f32_16x16x32_bf16 v[62:65], v[134:137], v[182:185], v[62:65]
	v_mfma_f32_16x16x32_bf16 v[58:61], v[142:145], v[182:185], v[58:61]
	v_mfma_f32_16x16x32_bf16 v[54:57], v[134:137], v[190:193], v[54:57]
	v_mfma_f32_16x16x32_bf16 v[50:53], v[142:145], v[190:193], v[50:53]
	v_mfma_f32_16x16x32_bf16 v[46:49], v[134:137], v[198:201], v[46:49]
	v_mfma_f32_16x16x32_bf16 v[38:41], v[142:145], v[198:201], v[38:41]
	v_mfma_f32_16x16x32_bf16 v[18:21], v[134:137], v[206:209], v[18:21]
	v_mfma_f32_16x16x32_bf16 v[10:13], v[142:145], v[206:209], v[10:13]
	v_mfma_f32_16x16x32_bf16 v[42:45], v[156:159], v[178:181], v[42:45]
	v_mfma_f32_16x16x32_bf16 v[34:37], v[170:173], v[178:181], v[34:37]
	v_mfma_f32_16x16x32_bf16 v[30:33], v[156:159], v[186:189], v[30:33]
	v_mfma_f32_16x16x32_bf16 v[26:29], v[170:173], v[186:189], v[26:29]
	v_mfma_f32_16x16x32_bf16 v[22:25], v[156:159], v[194:197], v[22:25]
	v_mfma_f32_16x16x32_bf16 v[14:17], v[170:173], v[194:197], v[14:17]
	v_mfma_f32_16x16x32_bf16 v[6:9], v[156:159], v[202:205], v[6:9]
	v_mfma_f32_16x16x32_bf16 v[2:5], v[170:173], v[202:205], v[2:5]
	v_mfma_f32_16x16x32_bf16 v[42:45], v[166:169], v[182:185], v[42:45]
	v_mfma_f32_16x16x32_bf16 v[34:37], v[174:177], v[182:185], v[34:37]
	v_mfma_f32_16x16x32_bf16 v[30:33], v[166:169], v[190:193], v[30:33]
	v_mfma_f32_16x16x32_bf16 v[26:29], v[174:177], v[190:193], v[26:29]
	v_mfma_f32_16x16x32_bf16 v[22:25], v[166:169], v[198:201], v[22:25]
	v_mfma_f32_16x16x32_bf16 v[14:17], v[174:177], v[198:201], v[14:17]
	v_mfma_f32_16x16x32_bf16 v[6:9], v[166:169], v[206:209], v[6:9]
	v_mfma_f32_16x16x32_bf16 v[2:5], v[174:177], v[206:209], v[2:5]
	s_setprio 0
	s_barrier
	s_add_i32 s68, 0, 0x18000
	s_add_i32 s69, 0, 0x1c000
	v_add_u32_e32 v142, s68, v1
	v_add_u32_e32 v174, s69, v1
	ds_read_b128 v[130:133], v142
	ds_read_b128 v[134:137], v142 offset:1024
	ds_read_b128 v[138:141], v142 offset:2048
	ds_read_b128 v[142:145], v142 offset:3072
	ds_read_b128 v[156:159], v174
	ds_read_b128 v[166:169], v174 offset:1024
	ds_read_b128 v[170:173], v174 offset:2048
	ds_read_b128 v[174:177], v174 offset:3072
	s_add_u32 s20, s26, 0xb0000
	s_addc_u32 s21, s27, 0
	s_mov_b32 m0, s43
	v_lshl_add_u64 v[218:219], s[20:21], 0, v[148:149]
	ds_read_b128 v[178:181], v164 offset:32768
	ds_read_b128 v[182:185], v164 offset:33792
	ds_read_b128 v[186:189], v164 offset:34816
	ds_read_b128 v[190:193], v164 offset:35840
	ds_read_b128 v[194:197], v164 offset:36864
	ds_read_b128 v[198:201], v164 offset:37888
	ds_read_b128 v[202:205], v164 offset:38912
	ds_read_b128 v[206:209], v164 offset:39936
	global_load_lds_dwordx4 v[218:219], off
	v_lshl_add_u64 v[218:219], s[20:21], 0, v[146:147]
	s_mov_b32 m0, s44
	s_nop 0
	global_load_lds_dwordx4 v[218:219], off
	s_waitcnt vmcnt(8)
	s_waitcnt lgkmcnt(0)
	s_barrier
	s_setprio 1
	s_waitcnt lgkmcnt(0)
	v_mfma_f32_16x16x32_bf16 v[126:129], v[130:133], v[178:181], v[126:129]
	v_mfma_f32_16x16x32_bf16 v[122:125], v[138:141], v[178:181], v[122:125]
	v_mfma_f32_16x16x32_bf16 v[118:121], v[130:133], v[186:189], v[118:121]
	v_mfma_f32_16x16x32_bf16 v[114:117], v[138:141], v[186:189], v[114:117]
	v_mfma_f32_16x16x32_bf16 v[102:105], v[130:133], v[194:197], v[102:105]
	v_mfma_f32_16x16x32_bf16 v[90:93], v[138:141], v[194:197], v[90:93]
	v_mfma_f32_16x16x32_bf16 v[82:85], v[130:133], v[202:205], v[82:85]
	v_mfma_f32_16x16x32_bf16 v[74:77], v[138:141], v[202:205], v[74:77]
	v_mfma_f32_16x16x32_bf16 v[126:129], v[134:137], v[182:185], v[126:129]
	v_mfma_f32_16x16x32_bf16 v[122:125], v[142:145], v[182:185], v[122:125]
	v_mfma_f32_16x16x32_bf16 v[118:121], v[134:137], v[190:193], v[118:121]
	v_mfma_f32_16x16x32_bf16 v[114:117], v[142:145], v[190:193], v[114:117]
	v_mfma_f32_16x16x32_bf16 v[102:105], v[134:137], v[198:201], v[102:105]
	v_mfma_f32_16x16x32_bf16 v[90:93], v[142:145], v[198:201], v[90:93]
	v_mfma_f32_16x16x32_bf16 v[82:85], v[134:137], v[206:209], v[82:85]
	v_mfma_f32_16x16x32_bf16 v[74:77], v[142:145], v[206:209], v[74:77]
	v_mfma_f32_16x16x32_bf16 v[110:113], v[156:159], v[178:181], v[110:113]
	v_mfma_f32_16x16x32_bf16 v[106:109], v[170:173], v[178:181], v[106:109]
	v_mfma_f32_16x16x32_bf16 v[98:101], v[156:159], v[186:189], v[98:101]
	v_mfma_f32_16x16x32_bf16 v[94:97], v[170:173], v[186:189], v[94:97]
	v_mfma_f32_16x16x32_bf16 v[86:89], v[156:159], v[194:197], v[86:89]
	v_mfma_f32_16x16x32_bf16 v[78:81], v[170:173], v[194:197], v[78:81]
	v_mfma_f32_16x16x32_bf16 v[70:73], v[156:159], v[202:205], v[70:73]
	v_mfma_f32_16x16x32_bf16 v[66:69], v[170:173], v[202:205], v[66:69]
	v_mfma_f32_16x16x32_bf16 v[110:113], v[166:169], v[182:185], v[110:113]
	v_mfma_f32_16x16x32_bf16 v[106:109], v[174:177], v[182:185], v[106:109]
	v_mfma_f32_16x16x32_bf16 v[98:101], v[166:169], v[190:193], v[98:101]
	v_mfma_f32_16x16x32_bf16 v[94:97], v[174:177], v[190:193], v[94:97]
	v_mfma_f32_16x16x32_bf16 v[86:89], v[166:169], v[198:201], v[86:89]
	v_mfma_f32_16x16x32_bf16 v[78:81], v[174:177], v[198:201], v[78:81]
	v_mfma_f32_16x16x32_bf16 v[70:73], v[166:169], v[206:209], v[70:73]
	v_mfma_f32_16x16x32_bf16 v[66:69], v[174:177], v[206:209], v[66:69]
	s_setprio 0
	s_barrier
; #define PG8_STAGE(bufoff, gbase, voff) do { _Pragma("unroll") for (int _i = 0; _i < 2; ++_i) \
;         __builtin_amdgcn_global_load_lds((const unsigned*)((const char*)(gbase) + (voff)[_i]), (PG8_LAS unsigned*)(lds + (bufoff) + ldsw + _i * 8192), 16, 0, 0); } while (0)
; #define PG8_LDA(dst, b, h) do { _Pragma("unroll") for (int m = 0; m < 4; ++m) _Pragma("unroll") for (int k = 0; k < 2; ++k) dst[m][k] = *(const PG8_LAS bf16x8*)(lds + PG8_SA(b, h) + aoff + m * 2048 + k * 1024); } while (0)
; #define PG8_MMA(ai, bj, At, Bt) do { __builtin_amdgcn_s_setprio(1); _Pragma("unroll") for (int m = 0; m < 4; ++m) _Pragma("unroll") for (int n = 0; n < 2; ++n) _Pragma("unroll") for (int k = 0; k < 2; ++k) \
;         acc[ai][bj][m][n] = __builtin_amdgcn_mfma_f32_16x16x32_bf16(Bt[n][k], At[m][k], acc[ai][bj][m][n], 0, 0, 0); __builtin_amdgcn_s_setprio(0); } while (0)
; #define PG8_WAIT_V(n) asm volatile("s_waitcnt vmcnt(" #n ")" ::: "memory")
; #define PG8_WAIT_L(n) asm volatile("s_waitcnt lgkmcnt(" #n ")" ::: "memory")
; #define PG8_BAR __builtin_amdgcn_s_barrier()
; #define PG8_SCHED __builtin_amdgcn_sched_barrier(0)
; template <class Epi, class Sched, bool ALIGN_EPI = false, bool SP2 = false>
; __device__ __forceinline__ void gemm_phase(PG8_LAS unsigned char* lds, const Gemm g, const Sched& S, const Epi& E) {
;     ...
;         for (int t = 0; t < nt; t += 2) {
;             const bool last = (t == nt - 2);
;             const char* a1 = cA + (size_t)(t + 1) * kstep;
;             const char* a2 = last ? nA : cA + (size_t)(t + 2) * kstep; const char* b2 = last ? nB : cB + (size_t)(t + 2) * kstep;
;             const char* a3 = a2 + kstep; const char* b3 = b2 + kstep;
;             if (last && has_next) S.a_ready(nxt);
;     ...
;             PG8_LDA(At, 1, 1); PG8_STAGE(PG8_SB(1, 0), b3, voffB); PG8_STAGE(PG8_SB(1, 1), b3 + hstepB, voffB); PG8_STAGE(PG8_SA(1, 0), a3, voffA);
;             PG8_WAIT_V(8); PG8_WAIT_L(0); PG8_BAR; PG8_MMA(1, 0, At, B0); PG8_MMA(1, 1, At, B1); PG8_BAR; PG8_SCHED;
	s_add_i32 s20, s68, s39
	v_lshl_add_u64 v[210:211], v[210:211], 0, s[8:9]
	s_mov_b32 m0, s20
	ds_read_b128 v[178:181], v164 offset:49152
	ds_read_b128 v[182:185], v164 offset:50176
	ds_read_b128 v[186:189], v164 offset:51200
	ds_read_b128 v[190:193], v164 offset:52224
	ds_read_b128 v[194:197], v164 offset:53248
	ds_read_b128 v[198:201], v164 offset:54272
	ds_read_b128 v[202:205], v164 offset:55296
	ds_read_b128 v[206:209], v164 offset:56320
	global_load_lds_dwordx4 v[210:211], off
	s_add_i32 m0, s20, 0x2000
	s_add_u32 s20, s24, 0xb0080
	v_lshl_add_u64 v[210:211], v[212:213], 0, s[8:9]
	s_addc_u32 s21, s25, 0
	s_add_i32 s24, s69, s39
	global_load_lds_dwordx4 v[210:211], off
	v_lshl_add_u64 v[210:211], s[20:21], 0, v[148:149]
	s_mov_b32 m0, s24
	s_nop 0
	global_load_lds_dwordx4 v[210:211], off
	v_lshl_add_u64 v[210:211], s[20:21], 0, v[146:147]
	s_add_i32 m0, s24, 0x2000
	s_nop 0
	global_load_lds_dwordx4 v[210:211], off
	v_lshl_add_u64 v[210:211], v[214:215], 0, s[8:9]
	s_mov_b32 m0, s51
	s_nop 0
	global_load_lds_dwordx4 v[210:211], off
	v_lshl_add_u64 v[210:211], v[216:217], 0, s[8:9]
	s_mov_b32 m0, s52
	s_nop 0
	global_load_lds_dwordx4 v[210:211], off
	s_waitcnt vmcnt(8)
	s_waitcnt lgkmcnt(0)
	s_barrier
	s_setprio 1
	s_waitcnt lgkmcnt(0)
	v_mfma_f32_16x16x32_bf16 v[62:65], v[130:133], v[178:181], v[62:65]
	v_mfma_f32_16x16x32_bf16 v[58:61], v[138:141], v[178:181], v[58:61]
	v_mfma_f32_16x16x32_bf16 v[54:57], v[130:133], v[186:189], v[54:57]
	v_mfma_f32_16x16x32_bf16 v[50:53], v[138:141], v[186:189], v[50:53]
	v_mfma_f32_16x16x32_bf16 v[46:49], v[130:133], v[194:197], v[46:49]
	v_mfma_f32_16x16x32_bf16 v[38:41], v[138:141], v[194:197], v[38:41]
	v_mfma_f32_16x16x32_bf16 v[18:21], v[130:133], v[202:205], v[18:21]
	v_mfma_f32_16x16x32_bf16 v[10:13], v[138:141], v[202:205], v[10:13]
	v_mfma_f32_16x16x32_bf16 v[62:65], v[134:137], v[182:185], v[62:65]
	v_mfma_f32_16x16x32_bf16 v[58:61], v[142:145], v[182:185], v[58:61]
	v_mfma_f32_16x16x32_bf16 v[54:57], v[134:137], v[190:193], v[54:57]
	v_mfma_f32_16x16x32_bf16 v[50:53], v[142:145], v[190:193], v[50:53]
	v_mfma_f32_16x16x32_bf16 v[46:49], v[134:137], v[198:201], v[46:49]
	v_mfma_f32_16x16x32_bf16 v[38:41], v[142:145], v[198:201], v[38:41]
	v_mfma_f32_16x16x32_bf16 v[18:21], v[134:137], v[206:209], v[18:21]
	v_mfma_f32_16x16x32_bf16 v[10:13], v[142:145], v[206:209], v[10:13]
	v_mfma_f32_16x16x32_bf16 v[42:45], v[156:159], v[178:181], v[42:45]
	v_mfma_f32_16x16x32_bf16 v[34:37], v[170:173], v[178:181], v[34:37]
	v_mfma_f32_16x16x32_bf16 v[30:33], v[156:159], v[186:189], v[30:33]
	v_mfma_f32_16x16x32_bf16 v[26:29], v[170:173], v[186:189], v[26:29]
	v_mfma_f32_16x16x32_bf16 v[22:25], v[156:159], v[194:197], v[22:25]
	v_mfma_f32_16x16x32_bf16 v[14:17], v[170:173], v[194:197], v[14:17]
	v_mfma_f32_16x16x32_bf16 v[6:9], v[156:159], v[202:205], v[6:9]
	v_mfma_f32_16x16x32_bf16 v[2:5], v[170:173], v[202:205], v[2:5]
	v_mfma_f32_16x16x32_bf16 v[42:45], v[166:169], v[182:185], v[42:45]
	v_mfma_f32_16x16x32_bf16 v[34:37], v[174:177], v[182:185], v[34:37]
	v_mfma_f32_16x16x32_bf16 v[30:33], v[166:169], v[190:193], v[30:33]
	v_mfma_f32_16x16x32_bf16 v[26:29], v[174:177], v[190:193], v[26:29]
	v_mfma_f32_16x16x32_bf16 v[22:25], v[166:169], v[198:201], v[22:25]
	v_mfma_f32_16x16x32_bf16 v[14:17], v[174:177], v[198:201], v[14:17]
	v_mfma_f32_16x16x32_bf16 v[6:9], v[166:169], v[206:209], v[6:9]
	v_mfma_f32_16x16x32_bf16 v[2:5], v[174:177], v[206:209], v[2:5]
	s_setprio 0
	s_barrier
	s_add_i32 s67, s67, 2
	s_add_u32 s65, s65, 0x100
	s_addc_u32 s66, s66, 0
	s_cmp_lt_u32 s67, 6
	s_mov_b64 s[20:21], s[22:23]
	s_cbranch_scc1 .LBB0_1921
	s_andn2_b64 vcc, exec, s[10:11]
	s_cbranch_vccnz .LBB0_1924
	s_barrier

; #define PG8_STAGE(bufoff, gbase, voff) do { _Pragma("unroll") for (int _i = 0; _i < 2; ++_i) \
;         __builtin_amdgcn_global_load_lds((const unsigned*)((const char*)(gbase) + (voff)[_i]), (PG8_LAS unsigned*)(lds + (bufoff) + ldsw + _i * 8192), 16, 0, 0); } while (0)
; #define PG8_LDA(dst, b, h) do { _Pragma("unroll") for (int m = 0; m < 4; ++m) _Pragma("unroll") for (int k = 0; k < 2; ++k) dst[m][k] = *(const PG8_LAS bf16x8*)(lds + PG8_SA(b, h) + aoff + m * 2048 + k * 1024); } while (0)
; #define PG8_LDB(dst, b, h) do { _Pragma("unroll") for (int n = 0; n < 2; ++n) _Pragma("unroll") for (int k = 0; k < 2; ++k) dst[n][k] = *(const PG8_LAS bf16x8*)(lds + PG8_SB(b, h) + boff + n * 2048 + k * 1024); } while (0)
; #define PG8_MMA(ai, bj, At, Bt) do { __builtin_amdgcn_s_setprio(1); _Pragma("unroll") for (int m = 0; m < 4; ++m) _Pragma("unroll") for (int n = 0; n < 2; ++n) _Pragma("unroll") for (int k = 0; k < 2; ++k) \
;         acc[ai][bj][m][n] = __builtin_amdgcn_mfma_f32_16x16x32_bf16(Bt[n][k], At[m][k], acc[ai][bj][m][n], 0, 0, 0); __builtin_amdgcn_s_setprio(0); } while (0)
; #define PG8_WAIT_V(n) asm volatile("s_waitcnt vmcnt(" #n ")" ::: "memory")
; #define PG8_WAIT_L(n) asm volatile("s_waitcnt lgkmcnt(" #n ")" ::: "memory")
; #define PG8_BAR __builtin_amdgcn_s_barrier()
; #define PG8_SCHED __builtin_amdgcn_sched_barrier(0)
; template <class Epi, class Sched, bool ALIGN_EPI = false, bool SP2 = false>
; __device__ __forceinline__ void gemm_phase(PG8_LAS unsigned char* lds, const Gemm g, const Sched& S, const Epi& E) {
;     ...
;             PG8_LDB(B0, 0, 0); PG8_LDB(B1, 0, 1); PG8_SCHED; PG8_LDA(At, 0, 0); PG8_STAGE(PG8_SA(1, 1), a1 + hstepA, voffA);
;             PG8_WAIT_V(8); PG8_WAIT_L(0); PG8_BAR; PG8_MMA(0, 0, At, B0); PG8_MMA(0, 1, At, B1); PG8_BAR; PG8_SCHED;
;             PG8_LDA(At, 0, 1); PG8_STAGE(PG8_SB(0, 0), b2, voffB); PG8_STAGE(PG8_SB(0, 1), b2 + hstepB, voffB); PG8_STAGE(PG8_SA(0, 0), a2, voffA);
.LBB0_1945:
	ds_read_b128 v[130:133], v162
	ds_read_b128 v[134:137], v162 offset:1024
	ds_read_b128 v[138:141], v162 offset:2048
	ds_read_b128 v[142:145], v162 offset:3072
	ds_read_b128 v[156:159], v163
	ds_read_b128 v[166:169], v163 offset:1024
	ds_read_b128 v[170:173], v163 offset:2048
	ds_read_b128 v[174:177], v163 offset:3072
	s_add_u32 s22, s20, 0x100
	s_addc_u32 s23, s21, 0
	s_cmp_eq_u32 s68, 4
	s_cselect_b32 s27, s19, s23
	s_cselect_b32 s26, s18, s22
	s_cselect_b32 s25, s1, s67
	s_cselect_b32 s24, s0, s66
	v_lshl_add_u64 v[210:211], s[20:21], 0, v[154:155]
	s_add_i32 m0, s42, 0xc000
	ds_read_b128 v[178:181], v164
	ds_read_b128 v[182:185], v164 offset:1024
	ds_read_b128 v[186:189], v164 offset:2048
	ds_read_b128 v[190:193], v164 offset:3072
	ds_read_b128 v[194:197], v164 offset:4096
	ds_read_b128 v[198:201], v164 offset:5120
	ds_read_b128 v[202:205], v164 offset:6144
	ds_read_b128 v[206:209], v164 offset:7168
	global_load_lds_dwordx4 v[210:211], off
	v_lshl_add_u64 v[210:211], s[20:21], 0, v[152:153]
	s_add_i32 m0, s42, 0xe000
	s_nop 0
	global_load_lds_dwordx4 v[210:211], off
	s_waitcnt vmcnt(8)
	s_waitcnt lgkmcnt(0)
	s_barrier
	s_setprio 1
	s_waitcnt lgkmcnt(0)
	v_mfma_f32_16x16x32_bf16 v[126:129], v[130:133], v[178:181], v[126:129]
	v_mfma_f32_16x16x32_bf16 v[122:125], v[138:141], v[178:181], v[122:125]
	v_mfma_f32_16x16x32_bf16 v[118:121], v[130:133], v[186:189], v[118:121]
	v_mfma_f32_16x16x32_bf16 v[114:117], v[138:141], v[186:189], v[114:117]
	v_mfma_f32_16x16x32_bf16 v[102:105], v[130:133], v[194:197], v[102:105]
	v_mfma_f32_16x16x32_bf16 v[90:93], v[138:141], v[194:197], v[90:93]
	v_mfma_f32_16x16x32_bf16 v[82:85], v[130:133], v[202:205], v[82:85]
	v_mfma_f32_16x16x32_bf16 v[74:77], v[138:141], v[202:205], v[74:77]
	v_mfma_f32_16x16x32_bf16 v[126:129], v[134:137], v[182:185], v[126:129]
	v_mfma_f32_16x16x32_bf16 v[122:125], v[142:145], v[182:185], v[122:125]
	v_mfma_f32_16x16x32_bf16 v[118:121], v[134:137], v[190:193], v[118:121]
	v_mfma_f32_16x16x32_bf16 v[114:117], v[142:145], v[190:193], v[114:117]
	v_mfma_f32_16x16x32_bf16 v[102:105], v[134:137], v[198:201], v[102:105]
	v_mfma_f32_16x16x32_bf16 v[90:93], v[142:145], v[198:201], v[90:93]
	v_mfma_f32_16x16x32_bf16 v[82:85], v[134:137], v[206:209], v[82:85]
	v_mfma_f32_16x16x32_bf16 v[74:77], v[142:145], v[206:209], v[74:77]
	v_mfma_f32_16x16x32_bf16 v[110:113], v[156:159], v[178:181], v[110:113]
	v_mfma_f32_16x16x32_bf16 v[106:109], v[170:173], v[178:181], v[106:109]
	v_mfma_f32_16x16x32_bf16 v[98:101], v[156:159], v[186:189], v[98:101]
	v_mfma_f32_16x16x32_bf16 v[94:97], v[170:173], v[186:189], v[94:97]
	v_mfma_f32_16x16x32_bf16 v[86:89], v[156:159], v[194:197], v[86:89]
	v_mfma_f32_16x16x32_bf16 v[78:81], v[170:173], v[194:197], v[78:81]
	v_mfma_f32_16x16x32_bf16 v[70:73], v[156:159], v[202:205], v[70:73]
	v_mfma_f32_16x16x32_bf16 v[66:69], v[170:173], v[202:205], v[66:69]
	v_mfma_f32_16x16x32_bf16 v[110:113], v[166:169], v[182:185], v[110:113]
	v_mfma_f32_16x16x32_bf16 v[106:109], v[174:177], v[182:185], v[106:109]
	v_mfma_f32_16x16x32_bf16 v[98:101], v[166:169], v[190:193], v[98:101]
	v_mfma_f32_16x16x32_bf16 v[94:97], v[174:177], v[190:193], v[94:97]
	v_mfma_f32_16x16x32_bf16 v[86:89], v[166:169], v[198:201], v[86:89]
	v_mfma_f32_16x16x32_bf16 v[78:81], v[174:177], v[198:201], v[78:81]
	v_mfma_f32_16x16x32_bf16 v[70:73], v[166:169], v[206:209], v[70:73]
	v_mfma_f32_16x16x32_bf16 v[66:69], v[174:177], v[206:209], v[66:69]
	s_setprio 0
	s_barrier
	s_add_i32 s20, s54, s40
	v_lshl_add_u64 v[210:211], s[24:25], 0, v[148:149]
	s_mov_b32 m0, s20
	ds_read_b128 v[178:181], v164 offset:16384
	ds_read_b128 v[182:185], v164 offset:17408
	ds_read_b128 v[186:189], v164 offset:18432
	ds_read_b128 v[190:193], v164 offset:19456
	ds_read_b128 v[194:197], v164 offset:20480
	ds_read_b128 v[198:201], v164 offset:21504
	ds_read_b128 v[202:205], v164 offset:22528
	ds_read_b128 v[206:209], v164 offset:23552
	global_load_lds_dwordx4 v[210:211], off
	s_add_i32 m0, s20, 0x2000
	s_add_u32 s20, s24, 0xb0000
	v_lshl_add_u64 v[212:213], s[24:25], 0, v[146:147]
	s_addc_u32 s21, s25, 0
	s_add_i32 s69, s55, s40
	global_load_lds_dwordx4 v[212:213], off
	v_lshl_add_u64 v[214:215], s[20:21], 0, v[148:149]
	s_mov_b32 m0, s69
	v_lshl_add_u64 v[216:217], s[26:27], 0, v[146:147]
	global_load_lds_dwordx4 v[214:215], off
	v_lshl_add_u64 v[214:215], s[20:21], 0, v[146:147]
	s_add_i32 m0, s69, 0x2000
	s_nop 0
	global_load_lds_dwordx4 v[214:215], off
	v_lshl_add_u64 v[214:215], s[26:27], 0, v[148:149]
	s_mov_b32 m0, s42
	s_nop 0
	global_load_lds_dwordx4 v[214:215], off
	s_mov_b32 m0, s43
	s_nop 0
	global_load_lds_dwordx4 v[216:217], off
	s_waitcnt vmcnt(8)
	s_waitcnt lgkmcnt(0)
	s_barrier
; #define PG8_STAGE(bufoff, gbase, voff) do { _Pragma("unroll") for (int _i = 0; _i < 2; ++_i) \
;         __builtin_amdgcn_global_load_lds((const unsigned*)((const char*)(gbase) + (voff)[_i]), (PG8_LAS unsigned*)(lds + (bufoff) + ldsw + _i * 8192), 16, 0, 0); } while (0)
; #define PG8_LDA(dst, b, h) do { _Pragma("unroll") for (int m = 0; m < 4; ++m) _Pragma("unroll") for (int k = 0; k < 2; ++k) dst[m][k] = *(const PG8_LAS bf16x8*)(lds + PG8_SA(b, h) + aoff + m * 2048 + k * 1024); } while (0)
; #define PG8_LDB(dst, b, h) do { _Pragma("unroll") for (int n = 0; n < 2; ++n) _Pragma("unroll") for (int k = 0; k < 2; ++k) dst[n][k] = *(const PG8_LAS bf16x8*)(lds + PG8_SB(b, h) + boff + n * 2048 + k * 1024); } while (0)
; #define PG8_MMA(ai, bj, At, Bt) do { __builtin_amdgcn_s_setprio(1); _Pragma("unroll") for (int m = 0; m < 4; ++m) _Pragma("unroll") for (int n = 0; n < 2; ++n) _Pragma("unroll") for (int k = 0; k < 2; ++k) \
;         acc[ai][bj][m][n] = __builtin_amdgcn_mfma_f32_16x16x32_bf16(Bt[n][k], At[m][k], acc[ai][bj][m][n], 0, 0, 0); __builtin_amdgcn_s_setprio(0); } while (0)
; #define PG8_WAIT_V(n) asm volatile("s_waitcnt vmcnt(" #n ")" ::: "memory")
; #define PG8_WAIT_L(n) asm volatile("s_waitcnt lgkmcnt(" #n ")" ::: "memory")
; #define PG8_BAR __builtin_amdgcn_s_barrier()
; #define PG8_SCHED __builtin_amdgcn_sched_barrier(0)
; template <class Epi, class Sched, bool ALIGN_EPI = false, bool SP2 = false>
; __device__ __forceinline__ void gemm_phase(PG8_LAS unsigned char* lds, const Gemm g, const Sched& S, const Epi& E) {
;     ...
;             PG8_WAIT_V(8); PG8_WAIT_L(0); PG8_BAR; PG8_MMA(1, 0, At, B0); PG8_MMA(1, 1, At, B1); PG8_BAR; PG8_SCHED;
;             PG8_LDB(B0, 1, 0); PG8_LDB(B1, 1, 1); PG8_SCHED; PG8_LDA(At, 1, 0); PG8_STAGE(PG8_SA(0, 1), a2 + hstepA, voffA);
;             PG8_WAIT_V(8); PG8_WAIT_L(0); PG8_BAR; PG8_MMA(0, 0, At, B0); PG8_MMA(0, 1, At, B1); PG8_BAR; PG8_SCHED;
	s_setprio 1
	s_waitcnt lgkmcnt(0)
	v_mfma_f32_16x16x32_bf16 v[62:65], v[130:133], v[178:181], v[62:65]
	v_mfma_f32_16x16x32_bf16 v[58:61], v[138:141], v[178:181], v[58:61]
	v_mfma_f32_16x16x32_bf16 v[54:57], v[130:133], v[186:189], v[54:57]
	v_mfma_f32_16x16x32_bf16 v[50:53], v[138:141], v[186:189], v[50:53]
	v_mfma_f32_16x16x32_bf16 v[46:49], v[130:133], v[194:197], v[46:49]
	v_mfma_f32_16x16x32_bf16 v[38:41], v[138:141], v[194:197], v[38:41]
	v_mfma_f32_16x16x32_bf16 v[18:21], v[130:133], v[202:205], v[18:21]
	v_mfma_f32_16x16x32_bf16 v[10:13], v[138:141], v[202:205], v[10:13]
	v_mfma_f32_16x16x32_bf16 v[62:65], v[134:137], v[182:185], v[62:65]
	v_mfma_f32_16x16x32_bf16 v[58:61], v[142:145], v[182:185], v[58:61]
	v_mfma_f32_16x16x32_bf16 v[54:57], v[134:137], v[190:193], v[54:57]
	v_mfma_f32_16x16x32_bf16 v[50:53], v[142:145], v[190:193], v[50:53]
	v_mfma_f32_16x16x32_bf16 v[46:49], v[134:137], v[198:201], v[46:49]
	v_mfma_f32_16x16x32_bf16 v[38:41], v[142:145], v[198:201], v[38:41]
	v_mfma_f32_16x16x32_bf16 v[18:21], v[134:137], v[206:209], v[18:21]
	v_mfma_f32_16x16x32_bf16 v[10:13], v[142:145], v[206:209], v[10:13]
	v_mfma_f32_16x16x32_bf16 v[42:45], v[156:159], v[178:181], v[42:45]
	v_mfma_f32_16x16x32_bf16 v[34:37], v[170:173], v[178:181], v[34:37]
	v_mfma_f32_16x16x32_bf16 v[30:33], v[156:159], v[186:189], v[30:33]
	v_mfma_f32_16x16x32_bf16 v[26:29], v[170:173], v[186:189], v[26:29]
	v_mfma_f32_16x16x32_bf16 v[22:25], v[156:159], v[194:197], v[22:25]
	v_mfma_f32_16x16x32_bf16 v[14:17], v[170:173], v[194:197], v[14:17]
	v_mfma_f32_16x16x32_bf16 v[6:9], v[156:159], v[202:205], v[6:9]
	v_mfma_f32_16x16x32_bf16 v[2:5], v[170:173], v[202:205], v[2:5]
	v_mfma_f32_16x16x32_bf16 v[42:45], v[166:169], v[182:185], v[42:45]
	v_mfma_f32_16x16x32_bf16 v[34:37], v[174:177], v[182:185], v[34:37]
	v_mfma_f32_16x16x32_bf16 v[30:33], v[166:169], v[190:193], v[30:33]
	v_mfma_f32_16x16x32_bf16 v[26:29], v[174:177], v[190:193], v[26:29]
	v_mfma_f32_16x16x32_bf16 v[22:25], v[166:169], v[198:201], v[22:25]
	v_mfma_f32_16x16x32_bf16 v[14:17], v[174:177], v[198:201], v[14:17]
	v_mfma_f32_16x16x32_bf16 v[6:9], v[166:169], v[206:209], v[6:9]
	v_mfma_f32_16x16x32_bf16 v[2:5], v[174:177], v[206:209], v[2:5]
	s_setprio 0
	s_barrier
	s_add_i32 s69, 0, 0x18000
	s_add_i32 s70, 0, 0x1c000
	v_add_u32_e32 v142, s69, v1
	v_add_u32_e32 v174, s70, v1
	ds_read_b128 v[130:133], v142
	ds_read_b128 v[134:137], v142 offset:1024
	ds_read_b128 v[138:141], v142 offset:2048
	ds_read_b128 v[142:145], v142 offset:3072
	ds_read_b128 v[156:159], v174
	ds_read_b128 v[166:169], v174 offset:1024
	ds_read_b128 v[170:173], v174 offset:2048
	ds_read_b128 v[174:177], v174 offset:3072
	s_add_u32 s20, s26, 0xb0000
	s_addc_u32 s21, s27, 0
	s_mov_b32 m0, s44
	v_lshl_add_u64 v[218:219], s[20:21], 0, v[148:149]
	ds_read_b128 v[178:181], v164 offset:32768
	ds_read_b128 v[182:185], v164 offset:33792
	ds_read_b128 v[186:189], v164 offset:34816
	ds_read_b128 v[190:193], v164 offset:35840
	ds_read_b128 v[194:197], v164 offset:36864
	ds_read_b128 v[198:201], v164 offset:37888
	ds_read_b128 v[202:205], v164 offset:38912
	ds_read_b128 v[206:209], v164 offset:39936
	global_load_lds_dwordx4 v[218:219], off
	v_lshl_add_u64 v[218:219], s[20:21], 0, v[146:147]
	s_mov_b32 m0, s45
	s_nop 0
	global_load_lds_dwordx4 v[218:219], off
	s_waitcnt vmcnt(8)
	s_waitcnt lgkmcnt(0)
	s_barrier
	s_setprio 1
	s_waitcnt lgkmcnt(0)
	v_mfma_f32_16x16x32_bf16 v[126:129], v[130:133], v[178:181], v[126:129]
	v_mfma_f32_16x16x32_bf16 v[122:125], v[138:141], v[178:181], v[122:125]
	v_mfma_f32_16x16x32_bf16 v[118:121], v[130:133], v[186:189], v[118:121]
	v_mfma_f32_16x16x32_bf16 v[114:117], v[138:141], v[186:189], v[114:117]
	v_mfma_f32_16x16x32_bf16 v[102:105], v[130:133], v[194:197], v[102:105]
	v_mfma_f32_16x16x32_bf16 v[90:93], v[138:141], v[194:197], v[90:93]
	v_mfma_f32_16x16x32_bf16 v[82:85], v[130:133], v[202:205], v[82:85]
	v_mfma_f32_16x16x32_bf16 v[74:77], v[138:141], v[202:205], v[74:77]
	v_mfma_f32_16x16x32_bf16 v[126:129], v[134:137], v[182:185], v[126:129]
	v_mfma_f32_16x16x32_bf16 v[122:125], v[142:145], v[182:185], v[122:125]
	v_mfma_f32_16x16x32_bf16 v[118:121], v[134:137], v[190:193], v[118:121]
	v_mfma_f32_16x16x32_bf16 v[114:117], v[142:145], v[190:193], v[114:117]
	v_mfma_f32_16x16x32_bf16 v[102:105], v[134:137], v[198:201], v[102:105]
	v_mfma_f32_16x16x32_bf16 v[90:93], v[142:145], v[198:201], v[90:93]
	v_mfma_f32_16x16x32_bf16 v[82:85], v[134:137], v[206:209], v[82:85]
	v_mfma_f32_16x16x32_bf16 v[74:77], v[142:145], v[206:209], v[74:77]
	v_mfma_f32_16x16x32_bf16 v[110:113], v[156:159], v[178:181], v[110:113]
	v_mfma_f32_16x16x32_bf16 v[106:109], v[170:173], v[178:181], v[106:109]
	v_mfma_f32_16x16x32_bf16 v[98:101], v[156:159], v[186:189], v[98:101]
	v_mfma_f32_16x16x32_bf16 v[94:97], v[170:173], v[186:189], v[94:97]
	v_mfma_f32_16x16x32_bf16 v[86:89], v[156:159], v[194:197], v[86:89]
	v_mfma_f32_16x16x32_bf16 v[78:81], v[170:173], v[194:197], v[78:81]
	v_mfma_f32_16x16x32_bf16 v[70:73], v[156:159], v[202:205], v[70:73]
	v_mfma_f32_16x16x32_bf16 v[66:69], v[170:173], v[202:205], v[66:69]
	v_mfma_f32_16x16x32_bf16 v[110:113], v[166:169], v[182:185], v[110:113]
	v_mfma_f32_16x16x32_bf16 v[106:109], v[174:177], v[182:185], v[106:109]
	v_mfma_f32_16x16x32_bf16 v[98:101], v[166:169], v[190:193], v[98:101]
	v_mfma_f32_16x16x32_bf16 v[94:97], v[174:177], v[190:193], v[94:97]
	v_mfma_f32_16x16x32_bf16 v[86:89], v[166:169], v[198:201], v[86:89]
	v_mfma_f32_16x16x32_bf16 v[78:81], v[174:177], v[198:201], v[78:81]
	v_mfma_f32_16x16x32_bf16 v[70:73], v[166:169], v[206:209], v[70:73]
	v_mfma_f32_16x16x32_bf16 v[66:69], v[174:177], v[206:209], v[66:69]
	s_setprio 0
	s_barrier
; #define PG8_STAGE(bufoff, gbase, voff) do { _Pragma("unroll") for (int _i = 0; _i < 2; ++_i) \
;         __builtin_amdgcn_global_load_lds((const unsigned*)((const char*)(gbase) + (voff)[_i]), (PG8_LAS unsigned*)(lds + (bufoff) + ldsw + _i * 8192), 16, 0, 0); } while (0)
; #define PG8_LDA(dst, b, h) do { _Pragma("unroll") for (int m = 0; m < 4; ++m) _Pragma("unroll") for (int k = 0; k < 2; ++k) dst[m][k] = *(const PG8_LAS bf16x8*)(lds + PG8_SA(b, h) + aoff + m * 2048 + k * 1024); } while (0)
; #define PG8_MMA(ai, bj, At, Bt) do { __builtin_amdgcn_s_setprio(1); _Pragma("unroll") for (int m = 0; m < 4; ++m) _Pragma("unroll") for (int n = 0; n < 2; ++n) _Pragma("unroll") for (int k = 0; k < 2; ++k) \
;         acc[ai][bj][m][n] = __builtin_amdgcn_mfma_f32_16x16x32_bf16(Bt[n][k], At[m][k], acc[ai][bj][m][n], 0, 0, 0); __builtin_amdgcn_s_setprio(0); } while (0)
; #define PG8_WAIT_V(n) asm volatile("s_waitcnt vmcnt(" #n ")" ::: "memory")
; #define PG8_WAIT_L(n) asm volatile("s_waitcnt lgkmcnt(" #n ")" ::: "memory")
; #define PG8_BAR __builtin_amdgcn_s_barrier()
; #define PG8_SCHED __builtin_amdgcn_sched_barrier(0)
; template <class Epi, class Sched, bool ALIGN_EPI = false, bool SP2 = false>
; __device__ __forceinline__ void gemm_phase(PG8_LAS unsigned char* lds, const Gemm g, const Sched& S, const Epi& E) {
;     ...
;         for (int t = 0; t < nt; t += 2) {
;             const bool last = (t == nt - 2);
;             const char* a1 = cA + (size_t)(t + 1) * kstep;
;             const char* a2 = last ? nA : cA + (size_t)(t + 2) * kstep; const char* b2 = last ? nB : cB + (size_t)(t + 2) * kstep;
;             const char* a3 = a2 + kstep; const char* b3 = b2 + kstep;
;             if (last && has_next) S.a_ready(nxt);
;     ...
;             PG8_LDA(At, 1, 1); PG8_STAGE(PG8_SB(1, 0), b3, voffB); PG8_STAGE(PG8_SB(1, 1), b3 + hstepB, voffB); PG8_STAGE(PG8_SA(1, 0), a3, voffA);
;             PG8_WAIT_V(8); PG8_WAIT_L(0); PG8_BAR; PG8_MMA(1, 0, At, B0); PG8_MMA(1, 1, At, B1); PG8_BAR; PG8_SCHED;
	s_add_i32 s20, s69, s40
	v_lshl_add_u64 v[210:211], v[210:211], 0, s[8:9]
	s_mov_b32 m0, s20
	ds_read_b128 v[178:181], v164 offset:49152
	ds_read_b128 v[182:185], v164 offset:50176
	ds_read_b128 v[186:189], v164 offset:51200
	ds_read_b128 v[190:193], v164 offset:52224
	ds_read_b128 v[194:197], v164 offset:53248
	ds_read_b128 v[198:201], v164 offset:54272
	ds_read_b128 v[202:205], v164 offset:55296
	ds_read_b128 v[206:209], v164 offset:56320
	global_load_lds_dwordx4 v[210:211], off
	s_add_i32 m0, s20, 0x2000
	s_add_u32 s20, s24, 0xb0080
	v_lshl_add_u64 v[210:211], v[212:213], 0, s[8:9]
	s_addc_u32 s21, s25, 0
	s_add_i32 s24, s70, s40
	global_load_lds_dwordx4 v[210:211], off
	v_lshl_add_u64 v[210:211], s[20:21], 0, v[148:149]
	s_mov_b32 m0, s24
	s_nop 0
	global_load_lds_dwordx4 v[210:211], off
	v_lshl_add_u64 v[210:211], s[20:21], 0, v[146:147]
	s_add_i32 m0, s24, 0x2000
	s_nop 0
	global_load_lds_dwordx4 v[210:211], off
	v_lshl_add_u64 v[210:211], v[214:215], 0, s[8:9]
	s_mov_b32 m0, s51
	s_nop 0
	global_load_lds_dwordx4 v[210:211], off
	v_lshl_add_u64 v[210:211], v[216:217], 0, s[8:9]
	s_mov_b32 m0, s52
	s_nop 0
	global_load_lds_dwordx4 v[210:211], off
	s_waitcnt vmcnt(8)
	s_waitcnt lgkmcnt(0)
	s_barrier
	s_setprio 1
	s_waitcnt lgkmcnt(0)
	v_mfma_f32_16x16x32_bf16 v[62:65], v[130:133], v[178:181], v[62:65]
	v_mfma_f32_16x16x32_bf16 v[58:61], v[138:141], v[178:181], v[58:61]
	v_mfma_f32_16x16x32_bf16 v[54:57], v[130:133], v[186:189], v[54:57]
	v_mfma_f32_16x16x32_bf16 v[50:53], v[138:141], v[186:189], v[50:53]
	v_mfma_f32_16x16x32_bf16 v[46:49], v[130:133], v[194:197], v[46:49]
	v_mfma_f32_16x16x32_bf16 v[38:41], v[138:141], v[194:197], v[38:41]
	v_mfma_f32_16x16x32_bf16 v[18:21], v[130:133], v[202:205], v[18:21]
	v_mfma_f32_16x16x32_bf16 v[10:13], v[138:141], v[202:205], v[10:13]
	v_mfma_f32_16x16x32_bf16 v[62:65], v[134:137], v[182:185], v[62:65]
	v_mfma_f32_16x16x32_bf16 v[58:61], v[142:145], v[182:185], v[58:61]
	v_mfma_f32_16x16x32_bf16 v[54:57], v[134:137], v[190:193], v[54:57]
	v_mfma_f32_16x16x32_bf16 v[50:53], v[142:145], v[190:193], v[50:53]
	v_mfma_f32_16x16x32_bf16 v[46:49], v[134:137], v[198:201], v[46:49]
	v_mfma_f32_16x16x32_bf16 v[38:41], v[142:145], v[198:201], v[38:41]
	v_mfma_f32_16x16x32_bf16 v[18:21], v[134:137], v[206:209], v[18:21]
	v_mfma_f32_16x16x32_bf16 v[10:13], v[142:145], v[206:209], v[10:13]
	v_mfma_f32_16x16x32_bf16 v[42:45], v[156:159], v[178:181], v[42:45]
	v_mfma_f32_16x16x32_bf16 v[34:37], v[170:173], v[178:181], v[34:37]
	v_mfma_f32_16x16x32_bf16 v[30:33], v[156:159], v[186:189], v[30:33]
	v_mfma_f32_16x16x32_bf16 v[26:29], v[170:173], v[186:189], v[26:29]
	v_mfma_f32_16x16x32_bf16 v[22:25], v[156:159], v[194:197], v[22:25]
	v_mfma_f32_16x16x32_bf16 v[14:17], v[170:173], v[194:197], v[14:17]
	v_mfma_f32_16x16x32_bf16 v[6:9], v[156:159], v[202:205], v[6:9]
	v_mfma_f32_16x16x32_bf16 v[2:5], v[170:173], v[202:205], v[2:5]
	v_mfma_f32_16x16x32_bf16 v[42:45], v[166:169], v[182:185], v[42:45]
	v_mfma_f32_16x16x32_bf16 v[34:37], v[174:177], v[182:185], v[34:37]
	v_mfma_f32_16x16x32_bf16 v[30:33], v[166:169], v[190:193], v[30:33]
	v_mfma_f32_16x16x32_bf16 v[26:29], v[174:177], v[190:193], v[26:29]
	v_mfma_f32_16x16x32_bf16 v[22:25], v[166:169], v[198:201], v[22:25]
	v_mfma_f32_16x16x32_bf16 v[14:17], v[174:177], v[198:201], v[14:17]
	v_mfma_f32_16x16x32_bf16 v[6:9], v[166:169], v[206:209], v[6:9]
	v_mfma_f32_16x16x32_bf16 v[2:5], v[174:177], v[206:209], v[2:5]
	s_setprio 0
	s_barrier
	s_add_i32 s68, s68, 2
	s_add_u32 s66, s66, 0x100
	s_addc_u32 s67, s67, 0
	s_cmp_lt_u32 s68, 6
	s_mov_b64 s[20:21], s[22:23]
	s_cbranch_scc1 .LBB0_1945
	s_andn2_b64 vcc, exec, s[10:11]
	s_cbranch_vccnz .LBB0_1948
	s_barrier

; #define PG8_STAGE(bufoff, gbase, voff) do { _Pragma("unroll") for (int _i = 0; _i < 2; ++_i) \
;         __builtin_amdgcn_global_load_lds((const unsigned*)((const char*)(gbase) + (voff)[_i]), (PG8_LAS unsigned*)(lds + (bufoff) + ldsw + _i * 8192), 16, 0, 0); } while (0)
; #define PG8_LDA(dst, b, h) do { _Pragma("unroll") for (int m = 0; m < 4; ++m) _Pragma("unroll") for (int k = 0; k < 2; ++k) dst[m][k] = *(const PG8_LAS bf16x8*)(lds + PG8_SA(b, h) + aoff + m * 2048 + k * 1024); } while (0)
; #define PG8_LDB(dst, b, h) do { _Pragma("unroll") for (int n = 0; n < 2; ++n) _Pragma("unroll") for (int k = 0; k < 2; ++k) dst[n][k] = *(const PG8_LAS bf16x8*)(lds + PG8_SB(b, h) + boff + n * 2048 + k * 1024); } while (0)
; #define PG8_MMA(ai, bj, At, Bt) do { __builtin_amdgcn_s_setprio(1); _Pragma("unroll") for (int m = 0; m < 4; ++m) _Pragma("unroll") for (int n = 0; n < 2; ++n) _Pragma("unroll") for (int k = 0; k < 2; ++k) \
;         acc[ai][bj][m][n] = __builtin_amdgcn_mfma_f32_16x16x32_bf16(Bt[n][k], At[m][k], acc[ai][bj][m][n], 0, 0, 0); __builtin_amdgcn_s_setprio(0); } while (0)
; template <class Epi, class Sched, bool ALIGN_EPI = false, bool SP2 = false>
; __device__ __forceinline__ void gemm_phase(PG8_LAS unsigned char* lds, const Gemm g, const Sched& S, const Epi& E) {
;     ...
;         const bool has_next = S.next(ui + 1, nxt);
;         const char* nA = has_next ? (const char*)g.A + (size_t)nxt.pm * tstepA : cA; const char* nB = has_next ? (const char*)g.Bt + (size_t)nxt.pn * tstepB : cB;
; #pragma unroll 1
;         for (int t = 0; t < nt; t += 2) {
;             const bool last = (t == nt - 2);
;             const char* a1 = cA + (size_t)(t + 1) * kstep;
;             const char* a2 = last ? nA : cA + (size_t)(t + 2) * kstep; const char* b2 = last ? nB : cB + (size_t)(t + 2) * kstep;
;             const char* a3 = a2 + kstep; const char* b3 = b2 + kstep;
;             if (last && has_next) S.a_ready(nxt);
;             if constexpr (SP2) {
;             PG8_LDB(B0, 0, 0); PG8_LDB(B1, 0, 1); PG8_SCHED; PG8_LDA(At, 0, 0); PG8_STAGE(PG8_SA(1, 1), a1 + hstepA, voffA);
;             PG8_WAIT_V(8); PG8_WAIT_L(0); PG8_BAR; PG8_MMA(0, 0, At, B0); PG8_MMA(0, 1, At, B1); PG8_BAR; PG8_SCHED;
;             PG8_LDA(At, 0, 1); PG8_STAGE(PG8_SB(0, 0), b2, voffB); PG8_STAGE(PG8_SB(0, 1), b2 + hstepB, voffB); PG8_STAGE(PG8_SA(0, 0), a2, voffA);
.LBB0_2017:
	s_add_u32 s66, s22, s65
	ds_read_b128 v[130:133], v158
	ds_read_b128 v[134:137], v158 offset:1024
	ds_read_b128 v[138:141], v158 offset:2048
	ds_read_b128 v[142:145], v158 offset:3072
	ds_read_b128 v[152:155], v159
	ds_read_b128 v[162:165], v159 offset:1024
	ds_read_b128 v[166:169], v159 offset:2048
	ds_read_b128 v[170:173], v159 offset:3072
	s_addc_u32 s67, s23, 0
	s_add_u32 s68, s66, 0x100
	s_addc_u32 s69, s67, 0
	s_and_b64 s[28:29], s[26:27], exec
	s_cselect_b32 s29, s19, s69
	s_cselect_b32 s28, s18, s68
	s_add_u32 s65, s20, s65
	s_addc_u32 s68, s21, 0
	s_add_u32 s65, s65, 0x100
	s_addc_u32 s68, s68, 0
	s_and_b64 s[26:27], s[26:27], exec
	s_cselect_b32 s27, s1, s68
	s_cselect_b32 s26, s0, s65
	s_add_u32 s66, s66, 0xb0080
	s_addc_u32 s67, s67, 0
	v_lshl_add_u64 v[206:207], s[66:67], 0, v[148:149]
	s_add_i32 m0, s41, 0xc000
	ds_read_b128 v[174:177], v160
	ds_read_b128 v[178:181], v160 offset:1024
	ds_read_b128 v[182:185], v160 offset:2048
	ds_read_b128 v[186:189], v160 offset:3072
	ds_read_b128 v[190:193], v160 offset:4096
	ds_read_b128 v[194:197], v160 offset:5120
	ds_read_b128 v[198:201], v160 offset:6144
	ds_read_b128 v[202:205], v160 offset:7168
	global_load_lds_dwordx4 v[206:207], off
	v_lshl_add_u64 v[206:207], s[66:67], 0, v[146:147]
	s_add_i32 m0, s41, 0xe000
	s_nop 0
	global_load_lds_dwordx4 v[206:207], off
	s_waitcnt vmcnt(8)
	s_waitcnt lgkmcnt(0)
	s_barrier
	s_setprio 1
	s_waitcnt lgkmcnt(0)
	v_mfma_f32_16x16x32_bf16 v[126:129], v[130:133], v[174:177], v[126:129]
	v_mfma_f32_16x16x32_bf16 v[122:125], v[138:141], v[174:177], v[122:125]
	v_mfma_f32_16x16x32_bf16 v[118:121], v[130:133], v[182:185], v[118:121]
	v_mfma_f32_16x16x32_bf16 v[114:117], v[138:141], v[182:185], v[114:117]
	v_mfma_f32_16x16x32_bf16 v[102:105], v[130:133], v[190:193], v[102:105]
	v_mfma_f32_16x16x32_bf16 v[90:93], v[138:141], v[190:193], v[90:93]
	v_mfma_f32_16x16x32_bf16 v[82:85], v[130:133], v[198:201], v[82:85]
	v_mfma_f32_16x16x32_bf16 v[74:77], v[138:141], v[198:201], v[74:77]
	v_mfma_f32_16x16x32_bf16 v[126:129], v[134:137], v[178:181], v[126:129]
	v_mfma_f32_16x16x32_bf16 v[122:125], v[142:145], v[178:181], v[122:125]
	v_mfma_f32_16x16x32_bf16 v[118:121], v[134:137], v[186:189], v[118:121]
	v_mfma_f32_16x16x32_bf16 v[114:117], v[142:145], v[186:189], v[114:117]
	v_mfma_f32_16x16x32_bf16 v[102:105], v[134:137], v[194:197], v[102:105]
	v_mfma_f32_16x16x32_bf16 v[90:93], v[142:145], v[194:197], v[90:93]
	v_mfma_f32_16x16x32_bf16 v[82:85], v[134:137], v[202:205], v[82:85]
	v_mfma_f32_16x16x32_bf16 v[74:77], v[142:145], v[202:205], v[74:77]
	v_mfma_f32_16x16x32_bf16 v[110:113], v[152:155], v[174:177], v[110:113]
	v_mfma_f32_16x16x32_bf16 v[106:109], v[166:169], v[174:177], v[106:109]
	v_mfma_f32_16x16x32_bf16 v[98:101], v[152:155], v[182:185], v[98:101]
	v_mfma_f32_16x16x32_bf16 v[94:97], v[166:169], v[182:185], v[94:97]
	v_mfma_f32_16x16x32_bf16 v[86:89], v[152:155], v[190:193], v[86:89]
	v_mfma_f32_16x16x32_bf16 v[78:81], v[166:169], v[190:193], v[78:81]
	v_mfma_f32_16x16x32_bf16 v[70:73], v[152:155], v[198:201], v[70:73]
	v_mfma_f32_16x16x32_bf16 v[66:69], v[166:169], v[198:201], v[66:69]
	v_mfma_f32_16x16x32_bf16 v[110:113], v[162:165], v[178:181], v[110:113]
	v_mfma_f32_16x16x32_bf16 v[106:109], v[170:173], v[178:181], v[106:109]
	v_mfma_f32_16x16x32_bf16 v[98:101], v[162:165], v[186:189], v[98:101]
	v_mfma_f32_16x16x32_bf16 v[94:97], v[170:173], v[186:189], v[94:97]
	v_mfma_f32_16x16x32_bf16 v[86:89], v[162:165], v[194:197], v[86:89]
	v_mfma_f32_16x16x32_bf16 v[78:81], v[170:173], v[194:197], v[78:81]
	v_mfma_f32_16x16x32_bf16 v[70:73], v[162:165], v[202:205], v[70:73]
	v_mfma_f32_16x16x32_bf16 v[66:69], v[170:173], v[202:205], v[66:69]
	s_setprio 0
	s_barrier
	s_add_i32 s65, s53, s39
	v_lshl_add_u64 v[206:207], s[26:27], 0, v[148:149]
	s_mov_b32 m0, s65
	ds_read_b128 v[174:177], v160 offset:16384
	ds_read_b128 v[178:181], v160 offset:17408
	ds_read_b128 v[182:185], v160 offset:18432
	ds_read_b128 v[186:189], v160 offset:19456
	ds_read_b128 v[190:193], v160 offset:20480
	ds_read_b128 v[194:197], v160 offset:21504
	ds_read_b128 v[198:201], v160 offset:22528
	ds_read_b128 v[202:205], v160 offset:23552
	global_load_lds_dwordx4 v[206:207], off
	s_add_i32 m0, s65, 0x2000
	s_add_u32 s66, s26, 0xb0000
	v_lshl_add_u64 v[208:209], s[26:27], 0, v[146:147]
	s_addc_u32 s67, s27, 0
	s_add_i32 s65, s54, s39
	global_load_lds_dwordx4 v[208:209], off
	v_lshl_add_u64 v[210:211], s[66:67], 0, v[148:149]
	s_mov_b32 m0, s65
	v_lshl_add_u64 v[212:213], s[28:29], 0, v[146:147]
	global_load_lds_dwordx4 v[210:211], off
	v_lshl_add_u64 v[210:211], s[66:67], 0, v[146:147]
	s_add_i32 m0, s65, 0x2000
	s_nop 0
	global_load_lds_dwordx4 v[210:211], off
	v_lshl_add_u64 v[210:211], s[28:29], 0, v[148:149]
	s_mov_b32 m0, s41
	s_nop 0
	global_load_lds_dwordx4 v[210:211], off
	s_mov_b32 m0, s42
	s_nop 0
	global_load_lds_dwordx4 v[212:213], off
	s_waitcnt vmcnt(8)
	s_waitcnt lgkmcnt(0)
	s_barrier
; #define PG8_STAGE(bufoff, gbase, voff) do { _Pragma("unroll") for (int _i = 0; _i < 2; ++_i) \
;         __builtin_amdgcn_global_load_lds((const unsigned*)((const char*)(gbase) + (voff)[_i]), (PG8_LAS unsigned*)(lds + (bufoff) + ldsw + _i * 8192), 16, 0, 0); } while (0)
; #define PG8_LDA(dst, b, h) do { _Pragma("unroll") for (int m = 0; m < 4; ++m) _Pragma("unroll") for (int k = 0; k < 2; ++k) dst[m][k] = *(const PG8_LAS bf16x8*)(lds + PG8_SA(b, h) + aoff + m * 2048 + k * 1024); } while (0)
; #define PG8_LDB(dst, b, h) do { _Pragma("unroll") for (int n = 0; n < 2; ++n) _Pragma("unroll") for (int k = 0; k < 2; ++k) dst[n][k] = *(const PG8_LAS bf16x8*)(lds + PG8_SB(b, h) + boff + n * 2048 + k * 1024); } while (0)
; #define PG8_MMA(ai, bj, At, Bt) do { __builtin_amdgcn_s_setprio(1); _Pragma("unroll") for (int m = 0; m < 4; ++m) _Pragma("unroll") for (int n = 0; n < 2; ++n) _Pragma("unroll") for (int k = 0; k < 2; ++k) \
;         acc[ai][bj][m][n] = __builtin_amdgcn_mfma_f32_16x16x32_bf16(Bt[n][k], At[m][k], acc[ai][bj][m][n], 0, 0, 0); __builtin_amdgcn_s_setprio(0); } while (0)
; #define PG8_WAIT_V(n) asm volatile("s_waitcnt vmcnt(" #n ")" ::: "memory")
; #define PG8_WAIT_L(n) asm volatile("s_waitcnt lgkmcnt(" #n ")" ::: "memory")
; #define PG8_BAR __builtin_amdgcn_s_barrier()
; #define PG8_SCHED __builtin_amdgcn_sched_barrier(0)
; template <class Epi, class Sched, bool ALIGN_EPI = false, bool SP2 = false>
; __device__ __forceinline__ void gemm_phase(PG8_LAS unsigned char* lds, const Gemm g, const Sched& S, const Epi& E) {
;     ...
;             PG8_WAIT_V(8); PG8_WAIT_L(0); PG8_BAR; PG8_MMA(1, 0, At, B0); PG8_MMA(1, 1, At, B1); PG8_BAR; PG8_SCHED;
;             PG8_LDB(B0, 1, 0); PG8_LDB(B1, 1, 1); PG8_SCHED; PG8_LDA(At, 1, 0); PG8_STAGE(PG8_SA(0, 1), a2 + hstepA, voffA);
;             PG8_WAIT_V(8); PG8_WAIT_L(0); PG8_BAR; PG8_MMA(0, 0, At, B0); PG8_MMA(0, 1, At, B1); PG8_BAR; PG8_SCHED;
	s_setprio 1
	s_waitcnt lgkmcnt(0)
	v_mfma_f32_16x16x32_bf16 v[62:65], v[130:133], v[174:177], v[62:65]
	v_mfma_f32_16x16x32_bf16 v[58:61], v[138:141], v[174:177], v[58:61]
	v_mfma_f32_16x16x32_bf16 v[54:57], v[130:133], v[182:185], v[54:57]
	v_mfma_f32_16x16x32_bf16 v[50:53], v[138:141], v[182:185], v[50:53]
	v_mfma_f32_16x16x32_bf16 v[46:49], v[130:133], v[190:193], v[46:49]
	v_mfma_f32_16x16x32_bf16 v[38:41], v[138:141], v[190:193], v[38:41]
	v_mfma_f32_16x16x32_bf16 v[18:21], v[130:133], v[198:201], v[18:21]
	v_mfma_f32_16x16x32_bf16 v[10:13], v[138:141], v[198:201], v[10:13]
	v_mfma_f32_16x16x32_bf16 v[62:65], v[134:137], v[178:181], v[62:65]
	v_mfma_f32_16x16x32_bf16 v[58:61], v[142:145], v[178:181], v[58:61]
	v_mfma_f32_16x16x32_bf16 v[54:57], v[134:137], v[186:189], v[54:57]
	v_mfma_f32_16x16x32_bf16 v[50:53], v[142:145], v[186:189], v[50:53]
	v_mfma_f32_16x16x32_bf16 v[46:49], v[134:137], v[194:197], v[46:49]
	v_mfma_f32_16x16x32_bf16 v[38:41], v[142:145], v[194:197], v[38:41]
	v_mfma_f32_16x16x32_bf16 v[18:21], v[134:137], v[202:205], v[18:21]
	v_mfma_f32_16x16x32_bf16 v[10:13], v[142:145], v[202:205], v[10:13]
	v_mfma_f32_16x16x32_bf16 v[42:45], v[152:155], v[174:177], v[42:45]
	v_mfma_f32_16x16x32_bf16 v[34:37], v[166:169], v[174:177], v[34:37]
	v_mfma_f32_16x16x32_bf16 v[30:33], v[152:155], v[182:185], v[30:33]
	v_mfma_f32_16x16x32_bf16 v[26:29], v[166:169], v[182:185], v[26:29]
	v_mfma_f32_16x16x32_bf16 v[22:25], v[152:155], v[190:193], v[22:25]
	v_mfma_f32_16x16x32_bf16 v[14:17], v[166:169], v[190:193], v[14:17]
	v_mfma_f32_16x16x32_bf16 v[6:9], v[152:155], v[198:201], v[6:9]
	v_mfma_f32_16x16x32_bf16 v[2:5], v[166:169], v[198:201], v[2:5]
	v_mfma_f32_16x16x32_bf16 v[42:45], v[162:165], v[178:181], v[42:45]
	v_mfma_f32_16x16x32_bf16 v[34:37], v[170:173], v[178:181], v[34:37]
	v_mfma_f32_16x16x32_bf16 v[30:33], v[162:165], v[186:189], v[30:33]
	v_mfma_f32_16x16x32_bf16 v[26:29], v[170:173], v[186:189], v[26:29]
	v_mfma_f32_16x16x32_bf16 v[22:25], v[162:165], v[194:197], v[22:25]
	v_mfma_f32_16x16x32_bf16 v[14:17], v[170:173], v[194:197], v[14:17]
	v_mfma_f32_16x16x32_bf16 v[6:9], v[162:165], v[202:205], v[6:9]
	v_mfma_f32_16x16x32_bf16 v[2:5], v[170:173], v[202:205], v[2:5]
	s_setprio 0
	s_barrier
	s_add_i32 s65, 0, 0x18000
	s_add_i32 s66, 0, 0x1c000
	v_add_u32_e32 v142, s65, v1
	v_add_u32_e32 v170, s66, v1
	ds_read_b128 v[130:133], v142
	ds_read_b128 v[134:137], v142 offset:1024
	ds_read_b128 v[138:141], v142 offset:2048
	ds_read_b128 v[142:145], v142 offset:3072
	ds_read_b128 v[152:155], v170
	ds_read_b128 v[162:165], v170 offset:1024
	ds_read_b128 v[166:169], v170 offset:2048
	ds_read_b128 v[170:173], v170 offset:3072
	s_add_u32 s28, s28, 0xb0000
	s_addc_u32 s29, s29, 0
	s_mov_b32 m0, s43
	v_lshl_add_u64 v[214:215], s[28:29], 0, v[148:149]
	ds_read_b128 v[174:177], v160 offset:32768
	ds_read_b128 v[178:181], v160 offset:33792
	ds_read_b128 v[182:185], v160 offset:34816
	ds_read_b128 v[186:189], v160 offset:35840
	ds_read_b128 v[190:193], v160 offset:36864
	ds_read_b128 v[194:197], v160 offset:37888
	ds_read_b128 v[198:201], v160 offset:38912
	ds_read_b128 v[202:205], v160 offset:39936
	global_load_lds_dwordx4 v[214:215], off
	v_lshl_add_u64 v[214:215], s[28:29], 0, v[146:147]
	s_mov_b32 m0, s44
	s_nop 0
	global_load_lds_dwordx4 v[214:215], off
	s_waitcnt vmcnt(8)
	s_waitcnt lgkmcnt(0)
	s_barrier
	s_setprio 1
	s_waitcnt lgkmcnt(0)
	v_mfma_f32_16x16x32_bf16 v[126:129], v[130:133], v[174:177], v[126:129]
	v_mfma_f32_16x16x32_bf16 v[122:125], v[138:141], v[174:177], v[122:125]
	v_mfma_f32_16x16x32_bf16 v[118:121], v[130:133], v[182:185], v[118:121]
	v_mfma_f32_16x16x32_bf16 v[114:117], v[138:141], v[182:185], v[114:117]
	v_mfma_f32_16x16x32_bf16 v[102:105], v[130:133], v[190:193], v[102:105]
	v_mfma_f32_16x16x32_bf16 v[90:93], v[138:141], v[190:193], v[90:93]
	v_mfma_f32_16x16x32_bf16 v[82:85], v[130:133], v[198:201], v[82:85]
	v_mfma_f32_16x16x32_bf16 v[74:77], v[138:141], v[198:201], v[74:77]
	v_mfma_f32_16x16x32_bf16 v[126:129], v[134:137], v[178:181], v[126:129]
	v_mfma_f32_16x16x32_bf16 v[122:125], v[142:145], v[178:181], v[122:125]
	v_mfma_f32_16x16x32_bf16 v[118:121], v[134:137], v[186:189], v[118:121]
	v_mfma_f32_16x16x32_bf16 v[114:117], v[142:145], v[186:189], v[114:117]
	v_mfma_f32_16x16x32_bf16 v[102:105], v[134:137], v[194:197], v[102:105]
	v_mfma_f32_16x16x32_bf16 v[90:93], v[142:145], v[194:197], v[90:93]
	v_mfma_f32_16x16x32_bf16 v[82:85], v[134:137], v[202:205], v[82:85]
	v_mfma_f32_16x16x32_bf16 v[74:77], v[142:145], v[202:205], v[74:77]
	v_mfma_f32_16x16x32_bf16 v[110:113], v[152:155], v[174:177], v[110:113]
	v_mfma_f32_16x16x32_bf16 v[106:109], v[166:169], v[174:177], v[106:109]
	v_mfma_f32_16x16x32_bf16 v[98:101], v[152:155], v[182:185], v[98:101]
	v_mfma_f32_16x16x32_bf16 v[94:97], v[166:169], v[182:185], v[94:97]
	v_mfma_f32_16x16x32_bf16 v[86:89], v[152:155], v[190:193], v[86:89]
	v_mfma_f32_16x16x32_bf16 v[78:81], v[166:169], v[190:193], v[78:81]
	v_mfma_f32_16x16x32_bf16 v[70:73], v[152:155], v[198:201], v[70:73]
	v_mfma_f32_16x16x32_bf16 v[66:69], v[166:169], v[198:201], v[66:69]
	v_mfma_f32_16x16x32_bf16 v[110:113], v[162:165], v[178:181], v[110:113]
	v_mfma_f32_16x16x32_bf16 v[106:109], v[170:173], v[178:181], v[106:109]
	v_mfma_f32_16x16x32_bf16 v[98:101], v[162:165], v[186:189], v[98:101]
	v_mfma_f32_16x16x32_bf16 v[94:97], v[170:173], v[186:189], v[94:97]
	v_mfma_f32_16x16x32_bf16 v[86:89], v[162:165], v[194:197], v[86:89]
	v_mfma_f32_16x16x32_bf16 v[78:81], v[170:173], v[194:197], v[78:81]
	v_mfma_f32_16x16x32_bf16 v[70:73], v[162:165], v[202:205], v[70:73]
	v_mfma_f32_16x16x32_bf16 v[66:69], v[170:173], v[202:205], v[66:69]
	s_setprio 0
	s_barrier
; #define PG8_STAGE(bufoff, gbase, voff) do { _Pragma("unroll") for (int _i = 0; _i < 2; ++_i) \
;         __builtin_amdgcn_global_load_lds((const unsigned*)((const char*)(gbase) + (voff)[_i]), (PG8_LAS unsigned*)(lds + (bufoff) + ldsw + _i * 8192), 16, 0, 0); } while (0)
; #define PG8_LDA(dst, b, h) do { _Pragma("unroll") for (int m = 0; m < 4; ++m) _Pragma("unroll") for (int k = 0; k < 2; ++k) dst[m][k] = *(const PG8_LAS bf16x8*)(lds + PG8_SA(b, h) + aoff + m * 2048 + k * 1024); } while (0)
; #define PG8_MMA(ai, bj, At, Bt) do { __builtin_amdgcn_s_setprio(1); _Pragma("unroll") for (int m = 0; m < 4; ++m) _Pragma("unroll") for (int n = 0; n < 2; ++n) _Pragma("unroll") for (int k = 0; k < 2; ++k) \
;         acc[ai][bj][m][n] = __builtin_amdgcn_mfma_f32_16x16x32_bf16(Bt[n][k], At[m][k], acc[ai][bj][m][n], 0, 0, 0); __builtin_amdgcn_s_setprio(0); } while (0)
; #define PG8_WAIT_V(n) asm volatile("s_waitcnt vmcnt(" #n ")" ::: "memory")
; #define PG8_WAIT_L(n) asm volatile("s_waitcnt lgkmcnt(" #n ")" ::: "memory")
; #define PG8_BAR __builtin_amdgcn_s_barrier()
; #define PG8_SCHED __builtin_amdgcn_sched_barrier(0)
; template <class Epi, class Sched, bool ALIGN_EPI = false, bool SP2 = false>
; __device__ __forceinline__ void gemm_phase(PG8_LAS unsigned char* lds, const Gemm g, const Sched& S, const Epi& E) {
;     ...
;             PG8_LDA(At, 1, 1); PG8_STAGE(PG8_SB(1, 0), b3, voffB); PG8_STAGE(PG8_SB(1, 1), b3 + hstepB, voffB); PG8_STAGE(PG8_SA(1, 0), a3, voffA);
;             PG8_WAIT_V(8); PG8_WAIT_L(0); PG8_BAR; PG8_MMA(1, 0, At, B0); PG8_MMA(1, 1, At, B1); PG8_BAR; PG8_SCHED;
	s_add_i32 s28, s65, s39
	v_lshl_add_u64 v[206:207], v[206:207], 0, s[8:9]
	s_mov_b32 m0, s28
	ds_read_b128 v[174:177], v160 offset:49152
	ds_read_b128 v[178:181], v160 offset:50176
	ds_read_b128 v[182:185], v160 offset:51200
	ds_read_b128 v[186:189], v160 offset:52224
	ds_read_b128 v[190:193], v160 offset:53248
	ds_read_b128 v[194:197], v160 offset:54272
	ds_read_b128 v[198:201], v160 offset:55296
	ds_read_b128 v[202:205], v160 offset:56320
	global_load_lds_dwordx4 v[206:207], off
	s_add_i32 m0, s28, 0x2000
	s_add_u32 s26, s26, 0xb0080
	v_lshl_add_u64 v[206:207], v[208:209], 0, s[8:9]
	s_addc_u32 s27, s27, 0
	s_add_i32 s28, s66, s39
	global_load_lds_dwordx4 v[206:207], off
	v_lshl_add_u64 v[206:207], s[26:27], 0, v[148:149]
	s_mov_b32 m0, s28
	s_nop 0
	global_load_lds_dwordx4 v[206:207], off
	v_lshl_add_u64 v[206:207], s[26:27], 0, v[146:147]
	s_add_i32 m0, s28, 0x2000
	s_nop 0
	global_load_lds_dwordx4 v[206:207], off
	v_lshl_add_u64 v[206:207], v[210:211], 0, s[8:9]
	s_mov_b32 m0, s51
	s_nop 0
	global_load_lds_dwordx4 v[206:207], off
	v_lshl_add_u64 v[206:207], v[212:213], 0, s[8:9]
	s_mov_b32 m0, s52
	s_nop 0
	global_load_lds_dwordx4 v[206:207], off
	s_waitcnt vmcnt(8)
	s_waitcnt lgkmcnt(0)
	s_barrier
	s_setprio 1
	s_waitcnt lgkmcnt(0)
	v_mfma_f32_16x16x32_bf16 v[62:65], v[130:133], v[174:177], v[62:65]
	v_mfma_f32_16x16x32_bf16 v[58:61], v[138:141], v[174:177], v[58:61]
	v_mfma_f32_16x16x32_bf16 v[54:57], v[130:133], v[182:185], v[54:57]
	v_mfma_f32_16x16x32_bf16 v[50:53], v[138:141], v[182:185], v[50:53]
	v_mfma_f32_16x16x32_bf16 v[46:49], v[130:133], v[190:193], v[46:49]
	v_mfma_f32_16x16x32_bf16 v[38:41], v[138:141], v[190:193], v[38:41]
	v_mfma_f32_16x16x32_bf16 v[18:21], v[130:133], v[198:201], v[18:21]
	v_mfma_f32_16x16x32_bf16 v[10:13], v[138:141], v[198:201], v[10:13]
	v_mfma_f32_16x16x32_bf16 v[62:65], v[134:137], v[178:181], v[62:65]
	v_mfma_f32_16x16x32_bf16 v[58:61], v[142:145], v[178:181], v[58:61]
	v_mfma_f32_16x16x32_bf16 v[54:57], v[134:137], v[186:189], v[54:57]
	v_mfma_f32_16x16x32_bf16 v[50:53], v[142:145], v[186:189], v[50:53]
	v_mfma_f32_16x16x32_bf16 v[46:49], v[134:137], v[194:197], v[46:49]
	v_mfma_f32_16x16x32_bf16 v[38:41], v[142:145], v[194:197], v[38:41]
	v_mfma_f32_16x16x32_bf16 v[18:21], v[134:137], v[202:205], v[18:21]
	v_mfma_f32_16x16x32_bf16 v[10:13], v[142:145], v[202:205], v[10:13]
	v_mfma_f32_16x16x32_bf16 v[42:45], v[152:155], v[174:177], v[42:45]
	v_mfma_f32_16x16x32_bf16 v[34:37], v[166:169], v[174:177], v[34:37]
	v_mfma_f32_16x16x32_bf16 v[30:33], v[152:155], v[182:185], v[30:33]
	v_mfma_f32_16x16x32_bf16 v[26:29], v[166:169], v[182:185], v[26:29]
	v_mfma_f32_16x16x32_bf16 v[22:25], v[152:155], v[190:193], v[22:25]
	v_mfma_f32_16x16x32_bf16 v[14:17], v[166:169], v[190:193], v[14:17]
	v_mfma_f32_16x16x32_bf16 v[6:9], v[152:155], v[198:201], v[6:9]
	v_mfma_f32_16x16x32_bf16 v[2:5], v[166:169], v[198:201], v[2:5]
	v_mfma_f32_16x16x32_bf16 v[42:45], v[162:165], v[178:181], v[42:45]
	v_mfma_f32_16x16x32_bf16 v[34:37], v[170:173], v[178:181], v[34:37]
	v_mfma_f32_16x16x32_bf16 v[30:33], v[162:165], v[186:189], v[30:33]
	v_mfma_f32_16x16x32_bf16 v[26:29], v[170:173], v[186:189], v[26:29]
	v_mfma_f32_16x16x32_bf16 v[22:25], v[162:165], v[194:197], v[22:25]
	v_mfma_f32_16x16x32_bf16 v[14:17], v[170:173], v[194:197], v[14:17]
	v_mfma_f32_16x16x32_bf16 v[6:9], v[162:165], v[202:205], v[6:9]
	v_mfma_f32_16x16x32_bf16 v[2:5], v[170:173], v[202:205], v[2:5]
	s_setprio 0
	s_barrier
	s_movk_i32 s65, 0x100
	s_and_b64 vcc, exec, s[24:25]
	s_mov_b64 s[26:27], -1
	s_mov_b64 s[24:25], 0
	s_cbranch_vccnz .LBB0_2017
	s_andn2_b64 vcc, exec, s[10:11]
	s_cbranch_vccnz .LBB0_2020
	s_barrier

; #define PG8_STAGE(bufoff, gbase, voff) do { _Pragma("unroll") for (int _i = 0; _i < 2; ++_i) \
;         __builtin_amdgcn_global_load_lds((const unsigned*)((const char*)(gbase) + (voff)[_i]), (PG8_LAS unsigned*)(lds + (bufoff) + ldsw + _i * 8192), 16, 0, 0); } while (0)
; #define PG8_LDA(dst, b, h) do { _Pragma("unroll") for (int m = 0; m < 4; ++m) _Pragma("unroll") for (int k = 0; k < 2; ++k) dst[m][k] = *(const PG8_LAS bf16x8*)(lds + PG8_SA(b, h) + aoff + m * 2048 + k * 1024); } while (0)
; #define PG8_LDB(dst, b, h) do { _Pragma("unroll") for (int n = 0; n < 2; ++n) _Pragma("unroll") for (int k = 0; k < 2; ++k) dst[n][k] = *(const PG8_LAS bf16x8*)(lds + PG8_SB(b, h) + boff + n * 2048 + k * 1024); } while (0)
; #define PG8_MMA(ai, bj, At, Bt) do { __builtin_amdgcn_s_setprio(1); _Pragma("unroll") for (int m = 0; m < 4; ++m) _Pragma("unroll") for (int n = 0; n < 2; ++n) _Pragma("unroll") for (int k = 0; k < 2; ++k) \
;         acc[ai][bj][m][n] = __builtin_amdgcn_mfma_f32_16x16x32_bf16(Bt[n][k], At[m][k], acc[ai][bj][m][n], 0, 0, 0); __builtin_amdgcn_s_setprio(0); } while (0)
; #define PG8_WAIT_V(n) asm volatile("s_waitcnt vmcnt(" #n ")" ::: "memory")
; #define PG8_WAIT_L(n) asm volatile("s_waitcnt lgkmcnt(" #n ")" ::: "memory")
; #define PG8_BAR __builtin_amdgcn_s_barrier()
; #define PG8_SCHED __builtin_amdgcn_sched_barrier(0)
; template <class Epi, class Sched, bool ALIGN_EPI = false, bool SP2 = false>
; __device__ __forceinline__ void gemm_phase(PG8_LAS unsigned char* lds, const Gemm g, const Sched& S, const Epi& E) {
;     ...
;             PG8_LDB(B0, 0, 0); PG8_LDB(B1, 0, 1); PG8_SCHED; PG8_LDA(At, 0, 0); PG8_STAGE(PG8_SA(1, 1), a1 + hstepA, voffA);
;             PG8_WAIT_V(8); PG8_WAIT_L(0); PG8_BAR; PG8_MMA(0, 0, At, B0); PG8_MMA(0, 1, At, B1); PG8_BAR; PG8_SCHED;
;             PG8_LDA(At, 0, 1); PG8_STAGE(PG8_SB(0, 0), b2, voffB); PG8_STAGE(PG8_SB(0, 1), b2 + hstepB, voffB); PG8_STAGE(PG8_SA(0, 0), a2, voffA);
;             PG8_WAIT_V(8); PG8_WAIT_L(0); PG8_BAR; PG8_MMA(1, 0, At, B0); PG8_MMA(1, 1, At, B1); PG8_BAR; PG8_SCHED;
.LBB0_2153:
	ds_read_b128 v[148:151], v156
	ds_read_b128 v[160:163], v156 offset:1024
	ds_read_b128 v[164:167], v156 offset:2048
	ds_read_b128 v[168:171], v156 offset:3072
	ds_read_b128 v[172:175], v157
	ds_read_b128 v[176:179], v157 offset:1024
	ds_read_b128 v[180:183], v157 offset:2048
	ds_read_b128 v[184:187], v157 offset:3072
	s_add_u32 s36, s34, 0xfffc0080
	s_addc_u32 s37, s35, -1
	s_cmp_eq_u32 s59, 12
	s_cselect_b32 s39, s5, s37
	s_cselect_b32 s38, s25, s36
	s_cselect_b32 s37, s23, s58
	s_cselect_b32 s36, s31, s57
	s_add_i32 m0, s44, 0xc000
	ds_read_b128 v[188:191], v158
	ds_read_b128 v[192:195], v158 offset:1024
	ds_read_b128 v[196:199], v158 offset:2048
	ds_read_b128 v[200:203], v158 offset:3072
	ds_read_b128 v[204:207], v158 offset:4096
	ds_read_b128 v[208:211], v158 offset:5120
	ds_read_b128 v[212:215], v158 offset:6144
	ds_read_b128 v[216:219], v158 offset:7168
	global_load_lds_dwordx4 v140, s[34:35]
	s_add_i32 m0, s44, 0xe000
	s_nop 0
	global_load_lds_dwordx4 v142, s[34:35]
	s_waitcnt vmcnt(8)
	s_waitcnt lgkmcnt(0)
	s_barrier
	s_setprio 1
	s_waitcnt lgkmcnt(0)
	v_mfma_f32_16x16x32_bf16 v[126:129], v[148:151], v[188:191], v[126:129]
	v_mfma_f32_16x16x32_bf16 v[122:125], v[164:167], v[188:191], v[122:125]
	v_mfma_f32_16x16x32_bf16 v[110:113], v[148:151], v[196:199], v[110:113]
	v_mfma_f32_16x16x32_bf16 v[106:109], v[164:167], v[196:199], v[106:109]
	v_mfma_f32_16x16x32_bf16 v[94:97], v[148:151], v[204:207], v[94:97]
	v_mfma_f32_16x16x32_bf16 v[90:93], v[164:167], v[204:207], v[90:93]
	v_mfma_f32_16x16x32_bf16 v[78:81], v[148:151], v[212:215], v[78:81]
	v_mfma_f32_16x16x32_bf16 v[74:77], v[164:167], v[212:215], v[74:77]
	v_mfma_f32_16x16x32_bf16 v[126:129], v[160:163], v[192:195], v[126:129]
	v_mfma_f32_16x16x32_bf16 v[122:125], v[168:171], v[192:195], v[122:125]
	v_mfma_f32_16x16x32_bf16 v[110:113], v[160:163], v[200:203], v[110:113]
	v_mfma_f32_16x16x32_bf16 v[106:109], v[168:171], v[200:203], v[106:109]
	v_mfma_f32_16x16x32_bf16 v[94:97], v[160:163], v[208:211], v[94:97]
	v_mfma_f32_16x16x32_bf16 v[90:93], v[168:171], v[208:211], v[90:93]
	v_mfma_f32_16x16x32_bf16 v[78:81], v[160:163], v[216:219], v[78:81]
	v_mfma_f32_16x16x32_bf16 v[74:77], v[168:171], v[216:219], v[74:77]
	v_mfma_f32_16x16x32_bf16 v[118:121], v[172:175], v[188:191], v[118:121]
	v_mfma_f32_16x16x32_bf16 v[114:117], v[180:183], v[188:191], v[114:117]
	v_mfma_f32_16x16x32_bf16 v[102:105], v[172:175], v[196:199], v[102:105]
	v_mfma_f32_16x16x32_bf16 v[98:101], v[180:183], v[196:199], v[98:101]
	v_mfma_f32_16x16x32_bf16 v[86:89], v[172:175], v[204:207], v[86:89]
	v_mfma_f32_16x16x32_bf16 v[82:85], v[180:183], v[204:207], v[82:85]
	v_mfma_f32_16x16x32_bf16 v[70:73], v[172:175], v[212:215], v[70:73]
	v_mfma_f32_16x16x32_bf16 v[66:69], v[180:183], v[212:215], v[66:69]
	v_mfma_f32_16x16x32_bf16 v[118:121], v[176:179], v[192:195], v[118:121]
	v_mfma_f32_16x16x32_bf16 v[114:117], v[184:187], v[192:195], v[114:117]
	v_mfma_f32_16x16x32_bf16 v[102:105], v[176:179], v[200:203], v[102:105]
	v_mfma_f32_16x16x32_bf16 v[98:101], v[184:187], v[200:203], v[98:101]
	v_mfma_f32_16x16x32_bf16 v[86:89], v[176:179], v[208:211], v[86:89]
	v_mfma_f32_16x16x32_bf16 v[82:85], v[184:187], v[208:211], v[82:85]
	v_mfma_f32_16x16x32_bf16 v[70:73], v[176:179], v[216:219], v[70:73]
	v_mfma_f32_16x16x32_bf16 v[66:69], v[184:187], v[216:219], v[66:69]
	s_setprio 0
	s_barrier
	s_add_i32 s60, s54, s43
	s_add_u32 s98, s36, 0x80
	s_addc_u32 s99, s37, 0
	s_mov_b32 m0, s60
	ds_read_b128 v[188:191], v158 offset:16384
	ds_read_b128 v[192:195], v158 offset:17408
	ds_read_b128 v[196:199], v158 offset:18432
	ds_read_b128 v[200:203], v158 offset:19456
	ds_read_b128 v[204:207], v158 offset:20480
	ds_read_b128 v[208:211], v158 offset:21504
	ds_read_b128 v[212:215], v158 offset:22528
	ds_read_b128 v[216:219], v158 offset:23552
	global_load_lds_dwordx4 v132, s[36:37]
	s_add_i32 m0, s60, 0x2000
	s_add_u32 s60, s36, 0x40000
	s_addc_u32 s61, s37, 0
	s_add_i32 s62, s55, s43
	global_load_lds_dwordx4 v136, s[36:37]
	s_mov_b32 m0, s62
	s_nop 0
	global_load_lds_dwordx4 v132, s[60:61]
	s_add_i32 m0, s62, 0x2000
	s_nop 0
	global_load_lds_dwordx4 v136, s[60:61]
	s_add_u32 s100, s38, 0x80
	s_addc_u32 s101, s39, 0
	s_mov_b32 m0, s44
	s_nop 0
	global_load_lds_dwordx4 v130, s[38:39]
	s_mov_b32 m0, s45
	s_nop 0
	global_load_lds_dwordx4 v134, s[38:39]
	s_waitcnt vmcnt(8)
	s_waitcnt lgkmcnt(0)
	s_barrier
	s_setprio 1
	s_waitcnt lgkmcnt(0)
	v_mfma_f32_16x16x32_bf16 v[62:65], v[148:151], v[188:191], v[62:65]
	v_mfma_f32_16x16x32_bf16 v[58:61], v[164:167], v[188:191], v[58:61]
	v_mfma_f32_16x16x32_bf16 v[46:49], v[148:151], v[196:199], v[46:49]
	v_mfma_f32_16x16x32_bf16 v[42:45], v[164:167], v[196:199], v[42:45]
	v_mfma_f32_16x16x32_bf16 v[30:33], v[148:151], v[204:207], v[30:33]
	v_mfma_f32_16x16x32_bf16 v[26:29], v[164:167], v[204:207], v[26:29]
	v_mfma_f32_16x16x32_bf16 v[14:17], v[148:151], v[212:215], v[14:17]
	v_mfma_f32_16x16x32_bf16 v[10:13], v[164:167], v[212:215], v[10:13]
	v_mfma_f32_16x16x32_bf16 v[62:65], v[160:163], v[192:195], v[62:65]
	v_mfma_f32_16x16x32_bf16 v[58:61], v[168:171], v[192:195], v[58:61]
	v_mfma_f32_16x16x32_bf16 v[46:49], v[160:163], v[200:203], v[46:49]
	v_mfma_f32_16x16x32_bf16 v[42:45], v[168:171], v[200:203], v[42:45]
	v_mfma_f32_16x16x32_bf16 v[30:33], v[160:163], v[208:211], v[30:33]
	v_mfma_f32_16x16x32_bf16 v[26:29], v[168:171], v[208:211], v[26:29]
	v_mfma_f32_16x16x32_bf16 v[14:17], v[160:163], v[216:219], v[14:17]
	v_mfma_f32_16x16x32_bf16 v[10:13], v[168:171], v[216:219], v[10:13]
	v_mfma_f32_16x16x32_bf16 v[54:57], v[172:175], v[188:191], v[54:57]
	v_mfma_f32_16x16x32_bf16 v[50:53], v[180:183], v[188:191], v[50:53]
	v_mfma_f32_16x16x32_bf16 v[38:41], v[172:175], v[196:199], v[38:41]
	v_mfma_f32_16x16x32_bf16 v[34:37], v[180:183], v[196:199], v[34:37]
	v_mfma_f32_16x16x32_bf16 v[22:25], v[172:175], v[204:207], v[22:25]
	v_mfma_f32_16x16x32_bf16 v[18:21], v[180:183], v[204:207], v[18:21]
	v_mfma_f32_16x16x32_bf16 v[6:9], v[172:175], v[212:215], v[6:9]
	v_mfma_f32_16x16x32_bf16 v[2:5], v[180:183], v[212:215], v[2:5]
	v_mfma_f32_16x16x32_bf16 v[54:57], v[176:179], v[192:195], v[54:57]
	v_mfma_f32_16x16x32_bf16 v[50:53], v[184:187], v[192:195], v[50:53]
	v_mfma_f32_16x16x32_bf16 v[38:41], v[176:179], v[200:203], v[38:41]
	v_mfma_f32_16x16x32_bf16 v[34:37], v[184:187], v[200:203], v[34:37]
	v_mfma_f32_16x16x32_bf16 v[22:25], v[176:179], v[208:211], v[22:25]
	v_mfma_f32_16x16x32_bf16 v[18:21], v[184:187], v[208:211], v[18:21]
	v_mfma_f32_16x16x32_bf16 v[6:9], v[176:179], v[216:219], v[6:9]
	v_mfma_f32_16x16x32_bf16 v[2:5], v[184:187], v[216:219], v[2:5]
	s_setprio 0
	s_barrier
; #define PG8_STAGE(bufoff, gbase, voff) do { _Pragma("unroll") for (int _i = 0; _i < 2; ++_i) \
;         __builtin_amdgcn_global_load_lds((const unsigned*)((const char*)(gbase) + (voff)[_i]), (PG8_LAS unsigned*)(lds + (bufoff) + ldsw + _i * 8192), 16, 0, 0); } while (0)
; #define PG8_LDA(dst, b, h) do { _Pragma("unroll") for (int m = 0; m < 4; ++m) _Pragma("unroll") for (int k = 0; k < 2; ++k) dst[m][k] = *(const PG8_LAS bf16x8*)(lds + PG8_SA(b, h) + aoff + m * 2048 + k * 1024); } while (0)
; #define PG8_LDB(dst, b, h) do { _Pragma("unroll") for (int n = 0; n < 2; ++n) _Pragma("unroll") for (int k = 0; k < 2; ++k) dst[n][k] = *(const PG8_LAS bf16x8*)(lds + PG8_SB(b, h) + boff + n * 2048 + k * 1024); } while (0)
; #define PG8_MMA(ai, bj, At, Bt) do { __builtin_amdgcn_s_setprio(1); _Pragma("unroll") for (int m = 0; m < 4; ++m) _Pragma("unroll") for (int n = 0; n < 2; ++n) _Pragma("unroll") for (int k = 0; k < 2; ++k) \
;         acc[ai][bj][m][n] = __builtin_amdgcn_mfma_f32_16x16x32_bf16(Bt[n][k], At[m][k], acc[ai][bj][m][n], 0, 0, 0); __builtin_amdgcn_s_setprio(0); } while (0)
; #define PG8_WAIT_V(n) asm volatile("s_waitcnt vmcnt(" #n ")" ::: "memory")
; #define PG8_WAIT_L(n) asm volatile("s_waitcnt lgkmcnt(" #n ")" ::: "memory")
; #define PG8_BAR __builtin_amdgcn_s_barrier()
; #define PG8_SCHED __builtin_amdgcn_sched_barrier(0)
; template <class Epi, class Sched, bool ALIGN_EPI = false, bool SP2 = false>
; __device__ __forceinline__ void gemm_phase(PG8_LAS unsigned char* lds, const Gemm g, const Sched& S, const Epi& E) {
;     ...
;         for (int t = 0; t < nt; t += 2) {
;     ...
;             PG8_LDB(B0, 1, 0); PG8_LDB(B1, 1, 1); PG8_SCHED; PG8_LDA(At, 1, 0); PG8_STAGE(PG8_SA(0, 1), a2 + hstepA, voffA);
;             PG8_WAIT_V(8); PG8_WAIT_L(0); PG8_BAR; PG8_MMA(0, 0, At, B0); PG8_MMA(0, 1, At, B1); PG8_BAR; PG8_SCHED;
;             PG8_LDA(At, 1, 1); PG8_STAGE(PG8_SB(1, 0), b3, voffB); PG8_STAGE(PG8_SB(1, 1), b3 + hstepB, voffB); PG8_STAGE(PG8_SA(1, 0), a3, voffA);
;             PG8_WAIT_V(8); PG8_WAIT_L(0); PG8_BAR; PG8_MMA(1, 0, At, B0); PG8_MMA(1, 1, At, B1); PG8_BAR; PG8_SCHED;
	s_add_i32 s60, 0, 0x18000
	v_add_u32_e32 v138, s60, v154
	s_add_i32 s61, 0, 0x1c000
	ds_read_b128 v[148:151], v138
	ds_read_b128 v[160:163], v138 offset:1024
	ds_read_b128 v[164:167], v138 offset:2048
	ds_read_b128 v[168:171], v138 offset:3072
	v_add_u32_e32 v138, s61, v154
	ds_read_b128 v[172:175], v138
	ds_read_b128 v[176:179], v138 offset:1024
	ds_read_b128 v[180:183], v138 offset:2048
	ds_read_b128 v[184:187], v138 offset:3072
	s_add_u32 s38, s38, 0x40000
	s_addc_u32 s39, s39, 0
	s_mov_b32 m0, s46
	ds_read_b128 v[188:191], v158 offset:32768
	ds_read_b128 v[192:195], v158 offset:33792
	ds_read_b128 v[196:199], v158 offset:34816
	ds_read_b128 v[200:203], v158 offset:35840
	ds_read_b128 v[204:207], v158 offset:36864
	ds_read_b128 v[208:211], v158 offset:37888
	ds_read_b128 v[212:215], v158 offset:38912
	ds_read_b128 v[216:219], v158 offset:39936
	global_load_lds_dwordx4 v130, s[38:39]
	s_mov_b32 m0, s47
	s_nop 0
	global_load_lds_dwordx4 v134, s[38:39]
	s_waitcnt vmcnt(8)
	s_waitcnt lgkmcnt(0)
	s_barrier
	s_setprio 1
	s_waitcnt lgkmcnt(0)
	v_mfma_f32_16x16x32_bf16 v[126:129], v[148:151], v[188:191], v[126:129]
	v_mfma_f32_16x16x32_bf16 v[122:125], v[164:167], v[188:191], v[122:125]
	v_mfma_f32_16x16x32_bf16 v[110:113], v[148:151], v[196:199], v[110:113]
	v_mfma_f32_16x16x32_bf16 v[106:109], v[164:167], v[196:199], v[106:109]
	v_mfma_f32_16x16x32_bf16 v[94:97], v[148:151], v[204:207], v[94:97]
	v_mfma_f32_16x16x32_bf16 v[90:93], v[164:167], v[204:207], v[90:93]
	v_mfma_f32_16x16x32_bf16 v[78:81], v[148:151], v[212:215], v[78:81]
	v_mfma_f32_16x16x32_bf16 v[74:77], v[164:167], v[212:215], v[74:77]
	v_mfma_f32_16x16x32_bf16 v[126:129], v[160:163], v[192:195], v[126:129]
	v_mfma_f32_16x16x32_bf16 v[122:125], v[168:171], v[192:195], v[122:125]
	v_mfma_f32_16x16x32_bf16 v[110:113], v[160:163], v[200:203], v[110:113]
	v_mfma_f32_16x16x32_bf16 v[106:109], v[168:171], v[200:203], v[106:109]
	v_mfma_f32_16x16x32_bf16 v[94:97], v[160:163], v[208:211], v[94:97]
	v_mfma_f32_16x16x32_bf16 v[90:93], v[168:171], v[208:211], v[90:93]
	v_mfma_f32_16x16x32_bf16 v[78:81], v[160:163], v[216:219], v[78:81]
	v_mfma_f32_16x16x32_bf16 v[74:77], v[168:171], v[216:219], v[74:77]
	v_mfma_f32_16x16x32_bf16 v[118:121], v[172:175], v[188:191], v[118:121]
	v_mfma_f32_16x16x32_bf16 v[114:117], v[180:183], v[188:191], v[114:117]
	v_mfma_f32_16x16x32_bf16 v[102:105], v[172:175], v[196:199], v[102:105]
	v_mfma_f32_16x16x32_bf16 v[98:101], v[180:183], v[196:199], v[98:101]
	v_mfma_f32_16x16x32_bf16 v[86:89], v[172:175], v[204:207], v[86:89]
	v_mfma_f32_16x16x32_bf16 v[82:85], v[180:183], v[204:207], v[82:85]
	v_mfma_f32_16x16x32_bf16 v[70:73], v[172:175], v[212:215], v[70:73]
	v_mfma_f32_16x16x32_bf16 v[66:69], v[180:183], v[212:215], v[66:69]
	v_mfma_f32_16x16x32_bf16 v[118:121], v[176:179], v[192:195], v[118:121]
	v_mfma_f32_16x16x32_bf16 v[114:117], v[184:187], v[192:195], v[114:117]
	v_mfma_f32_16x16x32_bf16 v[102:105], v[176:179], v[200:203], v[102:105]
	v_mfma_f32_16x16x32_bf16 v[98:101], v[184:187], v[200:203], v[98:101]
	v_mfma_f32_16x16x32_bf16 v[86:89], v[176:179], v[208:211], v[86:89]
	v_mfma_f32_16x16x32_bf16 v[82:85], v[184:187], v[208:211], v[82:85]
	v_mfma_f32_16x16x32_bf16 v[70:73], v[176:179], v[216:219], v[70:73]
	v_mfma_f32_16x16x32_bf16 v[66:69], v[184:187], v[216:219], v[66:69]
	s_setprio 0
	s_barrier
	s_add_i32 s38, s60, s43
	s_mov_b32 m0, s38
	ds_read_b128 v[188:191], v158 offset:49152
	ds_read_b128 v[192:195], v158 offset:50176
	ds_read_b128 v[196:199], v158 offset:51200
	ds_read_b128 v[200:203], v158 offset:52224
	ds_read_b128 v[204:207], v158 offset:53248
	ds_read_b128 v[208:211], v158 offset:54272
	ds_read_b128 v[212:215], v158 offset:55296
	ds_read_b128 v[216:219], v158 offset:56320
	global_load_lds_dwordx4 v132, s[98:99]
	s_add_i32 m0, s38, 0x2000
	s_add_u32 s36, s36, 0x40080
	s_addc_u32 s37, s37, 0
	s_add_i32 s38, s61, s43
	global_load_lds_dwordx4 v136, s[98:99]
	s_mov_b32 m0, s38
	s_nop 0
	global_load_lds_dwordx4 v132, s[36:37]
	s_add_i32 m0, s38, 0x2000
	s_nop 0
	global_load_lds_dwordx4 v136, s[36:37]
	s_mov_b32 m0, s49
	s_nop 0
	global_load_lds_dwordx4 v130, s[100:101]
	s_mov_b32 m0, s50
	s_nop 0
	global_load_lds_dwordx4 v134, s[100:101]
	s_waitcnt vmcnt(8)
	s_waitcnt lgkmcnt(0)
	s_barrier
	s_setprio 1
	s_waitcnt lgkmcnt(0)
	v_mfma_f32_16x16x32_bf16 v[62:65], v[148:151], v[188:191], v[62:65]
	v_mfma_f32_16x16x32_bf16 v[58:61], v[164:167], v[188:191], v[58:61]
	v_mfma_f32_16x16x32_bf16 v[46:49], v[148:151], v[196:199], v[46:49]
	v_mfma_f32_16x16x32_bf16 v[42:45], v[164:167], v[196:199], v[42:45]
	v_mfma_f32_16x16x32_bf16 v[30:33], v[148:151], v[204:207], v[30:33]
	v_mfma_f32_16x16x32_bf16 v[26:29], v[164:167], v[204:207], v[26:29]
	v_mfma_f32_16x16x32_bf16 v[14:17], v[148:151], v[212:215], v[14:17]
	v_mfma_f32_16x16x32_bf16 v[10:13], v[164:167], v[212:215], v[10:13]
	v_mfma_f32_16x16x32_bf16 v[62:65], v[160:163], v[192:195], v[62:65]
	v_mfma_f32_16x16x32_bf16 v[58:61], v[168:171], v[192:195], v[58:61]
	v_mfma_f32_16x16x32_bf16 v[46:49], v[160:163], v[200:203], v[46:49]
	v_mfma_f32_16x16x32_bf16 v[42:45], v[168:171], v[200:203], v[42:45]
	v_mfma_f32_16x16x32_bf16 v[30:33], v[160:163], v[208:211], v[30:33]
	v_mfma_f32_16x16x32_bf16 v[26:29], v[168:171], v[208:211], v[26:29]
	v_mfma_f32_16x16x32_bf16 v[14:17], v[160:163], v[216:219], v[14:17]
	v_mfma_f32_16x16x32_bf16 v[10:13], v[168:171], v[216:219], v[10:13]
	v_mfma_f32_16x16x32_bf16 v[54:57], v[172:175], v[188:191], v[54:57]
	v_mfma_f32_16x16x32_bf16 v[50:53], v[180:183], v[188:191], v[50:53]
	v_mfma_f32_16x16x32_bf16 v[38:41], v[172:175], v[196:199], v[38:41]
	v_mfma_f32_16x16x32_bf16 v[34:37], v[180:183], v[196:199], v[34:37]
	v_mfma_f32_16x16x32_bf16 v[22:25], v[172:175], v[204:207], v[22:25]
	v_mfma_f32_16x16x32_bf16 v[18:21], v[180:183], v[204:207], v[18:21]
	v_mfma_f32_16x16x32_bf16 v[6:9], v[172:175], v[212:215], v[6:9]
	v_mfma_f32_16x16x32_bf16 v[2:5], v[180:183], v[212:215], v[2:5]
	v_mfma_f32_16x16x32_bf16 v[54:57], v[176:179], v[192:195], v[54:57]
	v_mfma_f32_16x16x32_bf16 v[50:53], v[184:187], v[192:195], v[50:53]
	v_mfma_f32_16x16x32_bf16 v[38:41], v[176:179], v[200:203], v[38:41]
	v_mfma_f32_16x16x32_bf16 v[34:37], v[184:187], v[200:203], v[34:37]
	v_mfma_f32_16x16x32_bf16 v[22:25], v[176:179], v[208:211], v[22:25]
	v_mfma_f32_16x16x32_bf16 v[18:21], v[184:187], v[208:211], v[18:21]
	v_mfma_f32_16x16x32_bf16 v[6:9], v[176:179], v[216:219], v[6:9]
	v_mfma_f32_16x16x32_bf16 v[2:5], v[184:187], v[216:219], v[2:5]
	s_setprio 0
	s_barrier
	s_add_i32 s59, s59, 2
	s_add_u32 s34, s34, 0x100
	s_addc_u32 s35, s35, 0
	s_add_u32 s57, s57, 0x100
	s_addc_u32 s58, s58, 0
	s_cmp_gt_u32 s59, 13
	s_cbranch_scc0 .LBB0_2153
	s_and_b64 vcc, exec, s[14:15]
	s_cbranch_vccz .LBB0_2156
	s_barrier

; #define PG8_STAGE(bufoff, gbase, voff) do { _Pragma("unroll") for (int _i = 0; _i < 2; ++_i) \
;         __builtin_amdgcn_global_load_lds((const unsigned*)((const char*)(gbase) + (voff)[_i]), (PG8_LAS unsigned*)(lds + (bufoff) + ldsw + _i * 8192), 16, 0, 0); } while (0)
; #define PG8_LDA(dst, b, h) do { _Pragma("unroll") for (int m = 0; m < 4; ++m) _Pragma("unroll") for (int k = 0; k < 2; ++k) dst[m][k] = *(const PG8_LAS bf16x8*)(lds + PG8_SA(b, h) + aoff + m * 2048 + k * 1024); } while (0)
; #define PG8_LDB(dst, b, h) do { _Pragma("unroll") for (int n = 0; n < 2; ++n) _Pragma("unroll") for (int k = 0; k < 2; ++k) dst[n][k] = *(const PG8_LAS bf16x8*)(lds + PG8_SB(b, h) + boff + n * 2048 + k * 1024); } while (0)
; #define PG8_MMA(ai, bj, At, Bt) do { __builtin_amdgcn_s_setprio(1); _Pragma("unroll") for (int m = 0; m < 4; ++m) _Pragma("unroll") for (int n = 0; n < 2; ++n) _Pragma("unroll") for (int k = 0; k < 2; ++k) \
;         acc[ai][bj][m][n] = __builtin_amdgcn_mfma_f32_16x16x32_bf16(Bt[n][k], At[m][k], acc[ai][bj][m][n], 0, 0, 0); __builtin_amdgcn_s_setprio(0); } while (0)
; #define PG8_WAIT_V(n) asm volatile("s_waitcnt vmcnt(" #n ")" ::: "memory")
; #define PG8_WAIT_L(n) asm volatile("s_waitcnt lgkmcnt(" #n ")" ::: "memory")
; #define PG8_BAR __builtin_amdgcn_s_barrier()
; #define PG8_SCHED __builtin_amdgcn_sched_barrier(0)
; template <class Epi, class Sched, bool ALIGN_EPI = false, bool SP2 = false>
; __device__ __forceinline__ void gemm_phase(PG8_LAS unsigned char* lds, const Gemm g, const Sched& S, const Epi& E) {
;     ...
;             PG8_LDB(B0, 0, 0); PG8_LDB(B1, 0, 1); PG8_SCHED; PG8_LDA(At, 0, 0); PG8_STAGE(PG8_SA(1, 1), a1 + hstepA, voffA);
;             PG8_WAIT_V(8); PG8_WAIT_L(0); PG8_BAR; PG8_MMA(0, 0, At, B0); PG8_MMA(0, 1, At, B1); PG8_BAR; PG8_SCHED;
;             PG8_LDA(At, 0, 1); PG8_STAGE(PG8_SB(0, 0), b2, voffB); PG8_STAGE(PG8_SB(0, 1), b2 + hstepB, voffB); PG8_STAGE(PG8_SA(0, 0), a2, voffA);
;             PG8_WAIT_V(8); PG8_WAIT_L(0); PG8_BAR; PG8_MMA(1, 0, At, B0); PG8_MMA(1, 1, At, B1); PG8_BAR; PG8_SCHED;
.LBB0_2500:
	v_add_u32_e32 v24, s53, v22
	ds_read_b128 v[34:37], v24
	ds_read_b128 v[38:41], v24 offset:1024
	ds_read_b128 v[42:45], v24 offset:2048
	ds_read_b128 v[46:49], v24 offset:3072
	v_add_u32_e32 v24, s54, v22
	s_add_u32 s30, s0, s28
	ds_read_b128 v[50:53], v24
	ds_read_b128 v[54:57], v24 offset:1024
	ds_read_b128 v[66:69], v24 offset:2048
	ds_read_b128 v[70:73], v24 offset:3072
	s_addc_u32 s31, s1, s29
	s_add_u32 s30, s30, 0x100
	s_addc_u32 s31, s31, 0
	s_add_u32 s61, s56, s28
	s_addc_u32 s62, s57, s29
	s_cmpk_eq_i32 s28, 0x700
	s_cselect_b32 s35, s23, s31
	s_cselect_b32 s34, s58, s30
	s_cselect_b32 s31, s21, s62
	s_cselect_b32 s30, s59, s61
	v_lshl_add_u64 v[24:25], v[18:19], 0, s[28:29]
	s_add_i32 m0, s45, 0xc000
	ds_read_b128 v[162:165], v23
	ds_read_b128 v[166:169], v23 offset:1024
	ds_read_b128 v[194:197], v23 offset:2048
	ds_read_b128 v[198:201], v23 offset:3072
	ds_read_b128 v[202:205], v23 offset:4096
	ds_read_b128 v[206:209], v23 offset:5120
	ds_read_b128 v[210:213], v23 offset:6144
	ds_read_b128 v[216:219], v23 offset:7168
	global_load_lds_dwordx4 v[24:25], off
	v_lshl_add_u64 v[24:25], v[20:21], 0, s[28:29]
	s_add_i32 m0, s45, 0xe000
	s_nop 0
	global_load_lds_dwordx4 v[24:25], off
	s_waitcnt vmcnt(8)
	s_waitcnt lgkmcnt(0)
	s_barrier
	s_setprio 1
	s_waitcnt lgkmcnt(0)
	v_mfma_f32_16x16x32_bf16 v[170:173], v[34:37], v[162:165], v[170:173]
	v_mfma_f32_16x16x32_bf16 v[174:177], v[42:45], v[162:165], v[174:177]
	v_mfma_f32_16x16x32_bf16 v[178:181], v[34:37], v[194:197], v[178:181]
	v_mfma_f32_16x16x32_bf16 v[182:185], v[42:45], v[194:197], v[182:185]
	v_mfma_f32_16x16x32_bf16 v[186:189], v[34:37], v[202:205], v[186:189]
	v_mfma_f32_16x16x32_bf16 v[190:193], v[42:45], v[202:205], v[190:193]
	v_mfma_f32_16x16x32_bf16 v[158:161], v[34:37], v[210:213], v[158:161]
	v_mfma_f32_16x16x32_bf16 v[154:157], v[42:45], v[210:213], v[154:157]
	v_mfma_f32_16x16x32_bf16 v[170:173], v[38:41], v[166:169], v[170:173]
	v_mfma_f32_16x16x32_bf16 v[174:177], v[46:49], v[166:169], v[174:177]
	v_mfma_f32_16x16x32_bf16 v[178:181], v[38:41], v[198:201], v[178:181]
	v_mfma_f32_16x16x32_bf16 v[182:185], v[46:49], v[198:201], v[182:185]
	v_mfma_f32_16x16x32_bf16 v[186:189], v[38:41], v[206:209], v[186:189]
	v_mfma_f32_16x16x32_bf16 v[190:193], v[46:49], v[206:209], v[190:193]
	v_mfma_f32_16x16x32_bf16 v[158:161], v[38:41], v[216:219], v[158:161]
	v_mfma_f32_16x16x32_bf16 v[154:157], v[46:49], v[216:219], v[154:157]
	v_mfma_f32_16x16x32_bf16 v[62:65], v[50:53], v[162:165], v[62:65]
	v_mfma_f32_16x16x32_bf16 v[58:61], v[66:69], v[162:165], v[58:61]
	v_mfma_f32_16x16x32_bf16 v[74:77], v[50:53], v[194:197], v[74:77]
	v_mfma_f32_16x16x32_bf16 v[78:81], v[66:69], v[194:197], v[78:81]
	v_mfma_f32_16x16x32_bf16 v[94:97], v[50:53], v[202:205], v[94:97]
	v_mfma_f32_16x16x32_bf16 v[98:101], v[66:69], v[202:205], v[98:101]
	v_mfma_f32_16x16x32_bf16 v[106:109], v[50:53], v[210:213], v[106:109]
	v_mfma_f32_16x16x32_bf16 v[110:113], v[66:69], v[210:213], v[110:113]
	v_mfma_f32_16x16x32_bf16 v[62:65], v[54:57], v[166:169], v[62:65]
	v_mfma_f32_16x16x32_bf16 v[58:61], v[70:73], v[166:169], v[58:61]
	v_mfma_f32_16x16x32_bf16 v[74:77], v[54:57], v[198:201], v[74:77]
	v_mfma_f32_16x16x32_bf16 v[78:81], v[70:73], v[198:201], v[78:81]
	v_mfma_f32_16x16x32_bf16 v[94:97], v[54:57], v[206:209], v[94:97]
	v_mfma_f32_16x16x32_bf16 v[98:101], v[70:73], v[206:209], v[98:101]
	v_mfma_f32_16x16x32_bf16 v[106:109], v[54:57], v[216:219], v[106:109]
	v_mfma_f32_16x16x32_bf16 v[110:113], v[70:73], v[216:219], v[110:113]
	s_setprio 0
	s_barrier
	s_add_i32 s61, s53, s44
	s_add_u32 s98, s30, 0x80
	s_addc_u32 s99, s31, 0
	s_mov_b32 m0, s61
	ds_read_b128 v[162:165], v23 offset:16384
	ds_read_b128 v[166:169], v23 offset:17408
	ds_read_b128 v[194:197], v23 offset:18432
	ds_read_b128 v[198:201], v23 offset:19456
	ds_read_b128 v[202:205], v23 offset:20480
	ds_read_b128 v[206:209], v23 offset:21504
	ds_read_b128 v[210:213], v23 offset:22528
	ds_read_b128 v[216:219], v23 offset:23552
	global_load_lds_dwordx4 v4, s[30:31]
	s_add_i32 m0, s61, 0x2000
	s_add_u32 s62, s30, 0x40000
	s_addc_u32 s63, s31, 0
	s_add_i32 s61, s54, s44
	global_load_lds_dwordx4 v8, s[30:31]
	s_mov_b32 m0, s61
	s_add_u32 s100, s34, 0x80
	s_addc_u32 s101, s35, 0
	global_load_lds_dwordx4 v4, s[62:63]
	s_add_i32 m0, s61, 0x2000
	s_nop 0
	global_load_lds_dwordx4 v8, s[62:63]
	s_mov_b32 m0, s45
	s_nop 0
	global_load_lds_dwordx4 v2, s[34:35]
	s_mov_b32 m0, s46
	s_nop 0
	global_load_lds_dwordx4 v6, s[34:35]
	s_waitcnt vmcnt(8)
	s_waitcnt lgkmcnt(0)
	s_barrier
; #define PG8_STAGE(bufoff, gbase, voff) do { _Pragma("unroll") for (int _i = 0; _i < 2; ++_i) \
;         __builtin_amdgcn_global_load_lds((const unsigned*)((const char*)(gbase) + (voff)[_i]), (PG8_LAS unsigned*)(lds + (bufoff) + ldsw + _i * 8192), 16, 0, 0); } while (0)
; #define PG8_LDA(dst, b, h) do { _Pragma("unroll") for (int m = 0; m < 4; ++m) _Pragma("unroll") for (int k = 0; k < 2; ++k) dst[m][k] = *(const PG8_LAS bf16x8*)(lds + PG8_SA(b, h) + aoff + m * 2048 + k * 1024); } while (0)
; #define PG8_LDB(dst, b, h) do { _Pragma("unroll") for (int n = 0; n < 2; ++n) _Pragma("unroll") for (int k = 0; k < 2; ++k) dst[n][k] = *(const PG8_LAS bf16x8*)(lds + PG8_SB(b, h) + boff + n * 2048 + k * 1024); } while (0)
; #define PG8_MMA(ai, bj, At, Bt) do { __builtin_amdgcn_s_setprio(1); _Pragma("unroll") for (int m = 0; m < 4; ++m) _Pragma("unroll") for (int n = 0; n < 2; ++n) _Pragma("unroll") for (int k = 0; k < 2; ++k) \
;         acc[ai][bj][m][n] = __builtin_amdgcn_mfma_f32_16x16x32_bf16(Bt[n][k], At[m][k], acc[ai][bj][m][n], 0, 0, 0); __builtin_amdgcn_s_setprio(0); } while (0)
; #define PG8_WAIT_V(n) asm volatile("s_waitcnt vmcnt(" #n ")" ::: "memory")
; #define PG8_WAIT_L(n) asm volatile("s_waitcnt lgkmcnt(" #n ")" ::: "memory")
; #define PG8_BAR __builtin_amdgcn_s_barrier()
; #define PG8_SCHED __builtin_amdgcn_sched_barrier(0)
; template <class Epi, class Sched, bool ALIGN_EPI = false, bool SP2 = false>
; __device__ __forceinline__ void gemm_phase(PG8_LAS unsigned char* lds, const Gemm g, const Sched& S, const Epi& E) {
;     ...
;             PG8_WAIT_V(8); PG8_WAIT_L(0); PG8_BAR; PG8_MMA(1, 0, At, B0); PG8_MMA(1, 1, At, B1); PG8_BAR; PG8_SCHED;
;             PG8_LDB(B0, 1, 0); PG8_LDB(B1, 1, 1); PG8_SCHED; PG8_LDA(At, 1, 0); PG8_STAGE(PG8_SA(0, 1), a2 + hstepA, voffA);
;             PG8_WAIT_V(8); PG8_WAIT_L(0); PG8_BAR; PG8_MMA(0, 0, At, B0); PG8_MMA(0, 1, At, B1); PG8_BAR; PG8_SCHED;
	s_setprio 1
	s_waitcnt lgkmcnt(0)
	v_mfma_f32_16x16x32_bf16 v[150:153], v[34:37], v[162:165], v[150:153]
	v_mfma_f32_16x16x32_bf16 v[146:149], v[42:45], v[162:165], v[146:149]
	v_mfma_f32_16x16x32_bf16 v[142:145], v[34:37], v[194:197], v[142:145]
	v_mfma_f32_16x16x32_bf16 v[138:141], v[42:45], v[194:197], v[138:141]
	v_mfma_f32_16x16x32_bf16 v[134:137], v[34:37], v[202:205], v[134:137]
	v_mfma_f32_16x16x32_bf16 v[130:133], v[42:45], v[202:205], v[130:133]
	v_mfma_f32_16x16x32_bf16 v[34:37], v[34:37], v[210:213], v[90:93]
	v_mfma_f32_16x16x32_bf16 v[150:153], v[38:41], v[166:169], v[150:153]
	v_mfma_f32_16x16x32_bf16 v[146:149], v[46:49], v[166:169], v[146:149]
	v_mfma_f32_16x16x32_bf16 v[142:145], v[38:41], v[198:201], v[142:145]
	v_mfma_f32_16x16x32_bf16 v[138:141], v[46:49], v[198:201], v[138:141]
	v_mfma_f32_16x16x32_bf16 v[134:137], v[38:41], v[206:209], v[134:137]
	v_mfma_f32_16x16x32_bf16 v[130:133], v[46:49], v[206:209], v[130:133]
	v_mfma_f32_16x16x32_bf16 v[34:37], v[38:41], v[216:219], v[34:37]
	v_mfma_f32_16x16x32_bf16 v[38:41], v[42:45], v[210:213], v[82:85]
	v_mfma_f32_16x16x32_bf16 v[38:41], v[46:49], v[216:219], v[38:41]
	v_mfma_f32_16x16x32_bf16 v[82:85], v[50:53], v[194:197], v[122:125]
	v_mfma_f32_16x16x32_bf16 v[122:125], v[54:57], v[198:201], v[82:85]
	v_mfma_f32_16x16x32_bf16 v[82:85], v[66:69], v[194:197], v[126:129]
	v_mfma_f32_16x16x32_bf16 v[126:129], v[70:73], v[198:201], v[82:85]
	v_mfma_f32_16x16x32_bf16 v[82:85], v[50:53], v[202:205], v[102:105]
	v_mfma_f32_16x16x32_bf16 v[102:105], v[54:57], v[206:209], v[82:85]
	v_mfma_f32_16x16x32_bf16 v[82:85], v[66:69], v[202:205], v[86:89]
	v_mfma_f32_16x16x32_bf16 v[30:33], v[50:53], v[210:213], v[30:33]
	v_mfma_f32_16x16x32_bf16 v[24:27], v[66:69], v[210:213], v[26:29]
	v_mfma_f32_16x16x32_bf16 v[42:45], v[50:53], v[162:165], v[114:117]
	v_mfma_f32_16x16x32_bf16 v[46:49], v[66:69], v[162:165], v[118:121]
	v_mfma_f32_16x16x32_bf16 v[86:89], v[70:73], v[206:209], v[82:85]
	v_mfma_f32_16x16x32_bf16 v[30:33], v[54:57], v[216:219], v[30:33]
	v_mfma_f32_16x16x32_bf16 v[24:27], v[70:73], v[216:219], v[24:27]
	v_mfma_f32_16x16x32_bf16 v[42:45], v[54:57], v[166:169], v[42:45]
	v_mfma_f32_16x16x32_bf16 v[46:49], v[70:73], v[166:169], v[46:49]
	s_setprio 0
	s_barrier
	s_add_i32 s61, 0, 0x18000
	v_add_u32_e32 v28, s61, v22
	s_add_i32 s62, 0, 0x1c000
	ds_read_b128 v[50:53], v28
	ds_read_b128 v[54:57], v28 offset:1024
	ds_read_b128 v[66:69], v28 offset:2048
	ds_read_b128 v[70:73], v28 offset:3072
	v_add_u32_e32 v28, s62, v22
	ds_read_b128 v[162:165], v28
	ds_read_b128 v[166:169], v28 offset:1024
	ds_read_b128 v[194:197], v28 offset:2048
	ds_read_b128 v[198:201], v28 offset:3072
	s_add_u32 s34, s34, 0x40000
	s_addc_u32 s35, s35, 0
	s_mov_b32 m0, s48
	ds_read_b128 v[82:85], v23 offset:32768
	ds_read_b128 v[90:93], v23 offset:33792
	ds_read_b128 v[114:117], v23 offset:34816
	ds_read_b128 v[118:121], v23 offset:35840
	ds_read_b128 v[202:205], v23 offset:36864
	ds_read_b128 v[206:209], v23 offset:37888
	ds_read_b128 v[210:213], v23 offset:38912
	ds_read_b128 v[216:219], v23 offset:39936
	global_load_lds_dwordx4 v2, s[34:35]
	s_mov_b32 m0, s49
	s_nop 0
	global_load_lds_dwordx4 v6, s[34:35]
	s_waitcnt vmcnt(8)
	s_waitcnt lgkmcnt(0)
	s_barrier
	s_setprio 1
	s_waitcnt lgkmcnt(0)
	v_mfma_f32_16x16x32_bf16 v[170:173], v[50:53], v[82:85], v[170:173]
	v_mfma_f32_16x16x32_bf16 v[174:177], v[66:69], v[82:85], v[174:177]
	v_mfma_f32_16x16x32_bf16 v[178:181], v[50:53], v[114:117], v[178:181]
	v_mfma_f32_16x16x32_bf16 v[182:185], v[66:69], v[114:117], v[182:185]
	v_mfma_f32_16x16x32_bf16 v[186:189], v[50:53], v[202:205], v[186:189]
	v_mfma_f32_16x16x32_bf16 v[190:193], v[66:69], v[202:205], v[190:193]
	v_mfma_f32_16x16x32_bf16 v[158:161], v[50:53], v[210:213], v[158:161]
	v_mfma_f32_16x16x32_bf16 v[154:157], v[66:69], v[210:213], v[154:157]
	v_mfma_f32_16x16x32_bf16 v[170:173], v[54:57], v[90:93], v[170:173]
	v_mfma_f32_16x16x32_bf16 v[174:177], v[70:73], v[90:93], v[174:177]
	v_mfma_f32_16x16x32_bf16 v[178:181], v[54:57], v[118:121], v[178:181]
	v_mfma_f32_16x16x32_bf16 v[182:185], v[70:73], v[118:121], v[182:185]
	v_mfma_f32_16x16x32_bf16 v[186:189], v[54:57], v[206:209], v[186:189]
	v_mfma_f32_16x16x32_bf16 v[190:193], v[70:73], v[206:209], v[190:193]
	v_mfma_f32_16x16x32_bf16 v[158:161], v[54:57], v[216:219], v[158:161]
	v_mfma_f32_16x16x32_bf16 v[154:157], v[70:73], v[216:219], v[154:157]
	v_mfma_f32_16x16x32_bf16 v[62:65], v[162:165], v[82:85], v[62:65]
	v_mfma_f32_16x16x32_bf16 v[58:61], v[194:197], v[82:85], v[58:61]
	v_mfma_f32_16x16x32_bf16 v[82:85], v[162:165], v[202:205], v[94:97]
	v_mfma_f32_16x16x32_bf16 v[94:97], v[166:169], v[206:209], v[82:85]
	v_mfma_f32_16x16x32_bf16 v[82:85], v[194:197], v[202:205], v[98:101]
	v_mfma_f32_16x16x32_bf16 v[98:101], v[198:201], v[206:209], v[82:85]
	v_mfma_f32_16x16x32_bf16 v[82:85], v[162:165], v[210:213], v[106:109]
	v_mfma_f32_16x16x32_bf16 v[74:77], v[162:165], v[114:117], v[74:77]
	v_mfma_f32_16x16x32_bf16 v[78:81], v[194:197], v[114:117], v[78:81]
	v_mfma_f32_16x16x32_bf16 v[106:109], v[166:169], v[216:219], v[82:85]
	v_mfma_f32_16x16x32_bf16 v[82:85], v[194:197], v[210:213], v[110:113]
	v_mfma_f32_16x16x32_bf16 v[62:65], v[166:169], v[90:93], v[62:65]
	v_mfma_f32_16x16x32_bf16 v[58:61], v[198:201], v[90:93], v[58:61]
	v_mfma_f32_16x16x32_bf16 v[74:77], v[166:169], v[118:121], v[74:77]
	v_mfma_f32_16x16x32_bf16 v[78:81], v[198:201], v[118:121], v[78:81]
	v_mfma_f32_16x16x32_bf16 v[110:113], v[198:201], v[216:219], v[82:85]
	s_setprio 0
	s_barrier
; #define PG8_STAGE(bufoff, gbase, voff) do { _Pragma("unroll") for (int _i = 0; _i < 2; ++_i) \
;         __builtin_amdgcn_global_load_lds((const unsigned*)((const char*)(gbase) + (voff)[_i]), (PG8_LAS unsigned*)(lds + (bufoff) + ldsw + _i * 8192), 16, 0, 0); } while (0)
; #define PG8_LDA(dst, b, h) do { _Pragma("unroll") for (int m = 0; m < 4; ++m) _Pragma("unroll") for (int k = 0; k < 2; ++k) dst[m][k] = *(const PG8_LAS bf16x8*)(lds + PG8_SA(b, h) + aoff + m * 2048 + k * 1024); } while (0)
; #define PG8_MMA(ai, bj, At, Bt) do { __builtin_amdgcn_s_setprio(1); _Pragma("unroll") for (int m = 0; m < 4; ++m) _Pragma("unroll") for (int n = 0; n < 2; ++n) _Pragma("unroll") for (int k = 0; k < 2; ++k) \
;         acc[ai][bj][m][n] = __builtin_amdgcn_mfma_f32_16x16x32_bf16(Bt[n][k], At[m][k], acc[ai][bj][m][n], 0, 0, 0); __builtin_amdgcn_s_setprio(0); } while (0)
; #define PG8_WAIT_V(n) asm volatile("s_waitcnt vmcnt(" #n ")" ::: "memory")
; #define PG8_WAIT_L(n) asm volatile("s_waitcnt lgkmcnt(" #n ")" ::: "memory")
; #define PG8_BAR __builtin_amdgcn_s_barrier()
; #define PG8_SCHED __builtin_amdgcn_sched_barrier(0)
; template <class Epi, class Sched, bool ALIGN_EPI = false, bool SP2 = false>
; __device__ __forceinline__ void gemm_phase(PG8_LAS unsigned char* lds, const Gemm g, const Sched& S, const Epi& E) {
;     ...
;         for (int t = 0; t < nt; t += 2) {
;     ...
;             PG8_LDA(At, 1, 1); PG8_STAGE(PG8_SB(1, 0), b3, voffB); PG8_STAGE(PG8_SB(1, 1), b3 + hstepB, voffB); PG8_STAGE(PG8_SA(1, 0), a3, voffA);
;             PG8_WAIT_V(8); PG8_WAIT_L(0); PG8_BAR; PG8_MMA(1, 0, At, B0); PG8_MMA(1, 1, At, B1); PG8_BAR; PG8_SCHED;
;     ...
;         if (!has_next) break;
; #pragma unroll
;         for (int a = 0; a < 2; ++a)
; #pragma unroll
;             for (int b = 0; b < 2; ++b)
; #pragma unroll
;                 for (int m = 0; m < 4; ++m)
; #pragma unroll
;                     for (int n = 0; n < 2; ++n) acc[a][b][m][n] = (f32x4){0.f, 0.f, 0.f, 0.f};
;         cur = nxt; cA = nA; cB = nB; ++ui;
	s_add_i32 s34, s61, s44
	s_mov_b32 m0, s34
	ds_read_b128 v[118:121], v23 offset:49152
	ds_read_b128 v[202:205], v23 offset:50176
	ds_read_b128 v[206:209], v23 offset:51200
	ds_read_b128 v[210:213], v23 offset:52224
	ds_read_b128 v[216:219], v23 offset:53248
	ds_read_b128 v[220:223], v23 offset:54272
	ds_read_b128 v[224:227], v23 offset:55296
	ds_read_b128 v[228:231], v23 offset:56320
	global_load_lds_dwordx4 v4, s[98:99]
	s_add_i32 m0, s34, 0x2000
	s_add_u32 s30, s30, 0x40080
	s_addc_u32 s31, s31, 0
	s_add_i32 s34, s62, s44
	global_load_lds_dwordx4 v8, s[98:99]
	s_mov_b32 m0, s34
	s_nop 0
	global_load_lds_dwordx4 v4, s[30:31]
	s_add_i32 m0, s34, 0x2000
	s_nop 0
	global_load_lds_dwordx4 v8, s[30:31]
	s_mov_b32 m0, s51
	s_nop 0
	global_load_lds_dwordx4 v2, s[100:101]
	s_mov_b32 m0, s52
	s_nop 0
	global_load_lds_dwordx4 v6, s[100:101]
	s_waitcnt vmcnt(8)
	s_waitcnt lgkmcnt(0)
	s_barrier
	s_setprio 1
	s_waitcnt lgkmcnt(0)
	v_mfma_f32_16x16x32_bf16 v[82:85], v[50:53], v[118:121], v[150:153]
	v_mfma_f32_16x16x32_bf16 v[150:153], v[54:57], v[202:205], v[82:85]
	v_mfma_f32_16x16x32_bf16 v[82:85], v[66:69], v[118:121], v[146:149]
	v_mfma_f32_16x16x32_bf16 v[146:149], v[70:73], v[202:205], v[82:85]
	v_mfma_f32_16x16x32_bf16 v[82:85], v[50:53], v[206:209], v[142:145]
	v_mfma_f32_16x16x32_bf16 v[142:145], v[54:57], v[210:213], v[82:85]
	v_mfma_f32_16x16x32_bf16 v[82:85], v[66:69], v[206:209], v[138:141]
	v_mfma_f32_16x16x32_bf16 v[138:141], v[70:73], v[210:213], v[82:85]
	v_mfma_f32_16x16x32_bf16 v[82:85], v[50:53], v[216:219], v[134:137]
	v_mfma_f32_16x16x32_bf16 v[34:37], v[50:53], v[224:227], v[34:37]
	v_mfma_f32_16x16x32_bf16 v[134:137], v[54:57], v[220:223], v[82:85]
	v_mfma_f32_16x16x32_bf16 v[82:85], v[66:69], v[216:219], v[130:133]
	v_mfma_f32_16x16x32_bf16 v[90:93], v[54:57], v[228:231], v[34:37]
	v_mfma_f32_16x16x32_bf16 v[34:37], v[66:69], v[224:227], v[38:41]
	v_mfma_f32_16x16x32_bf16 v[130:133], v[70:73], v[220:223], v[82:85]
	v_mfma_f32_16x16x32_bf16 v[82:85], v[70:73], v[228:231], v[34:37]
	v_mfma_f32_16x16x32_bf16 v[34:37], v[162:165], v[118:121], v[42:45]
	v_mfma_f32_16x16x32_bf16 v[114:117], v[166:169], v[202:205], v[34:37]
	v_mfma_f32_16x16x32_bf16 v[34:37], v[194:197], v[118:121], v[46:49]
	v_mfma_f32_16x16x32_bf16 v[118:121], v[198:201], v[202:205], v[34:37]
	v_mfma_f32_16x16x32_bf16 v[34:37], v[162:165], v[206:209], v[122:125]
	v_mfma_f32_16x16x32_bf16 v[122:125], v[166:169], v[210:213], v[34:37]
	v_mfma_f32_16x16x32_bf16 v[34:37], v[194:197], v[206:209], v[126:129]
	v_mfma_f32_16x16x32_bf16 v[126:129], v[198:201], v[210:213], v[34:37]
	v_mfma_f32_16x16x32_bf16 v[34:37], v[162:165], v[216:219], v[102:105]
	v_mfma_f32_16x16x32_bf16 v[102:105], v[166:169], v[220:223], v[34:37]
	v_mfma_f32_16x16x32_bf16 v[34:37], v[194:197], v[216:219], v[86:89]
	v_mfma_f32_16x16x32_bf16 v[28:31], v[162:165], v[224:227], v[30:33]
	v_mfma_f32_16x16x32_bf16 v[24:27], v[194:197], v[224:227], v[24:27]
	v_mfma_f32_16x16x32_bf16 v[86:89], v[198:201], v[220:223], v[34:37]
	v_mfma_f32_16x16x32_bf16 v[30:33], v[166:169], v[228:231], v[28:31]
	v_mfma_f32_16x16x32_bf16 v[26:29], v[198:201], v[228:231], v[24:27]
	s_setprio 0
	s_barrier
	s_add_i32 s60, s60, 2
	s_add_u32 s28, s28, 0x100
	s_addc_u32 s29, s29, 0
	s_cmp_gt_u32 s60, 13
	s_cbranch_scc0 .LBB0_2500
	s_add_u32 s28, s56, 0xffffff00
	s_addc_u32 s29, s57, -1
	s_andn2_b64 vcc, exec, s[4:5]
	s_cbranch_vccnz .LBB0_2491
	v_mov_b32_e32 v26, 0
	s_mov_b32 s16, s20
	s_mov_b32 s14, s22
	s_mov_b64 s[0:1], s[26:27]
	s_mov_b32 s50, s55
	v_mov_b32_e32 v27, v26
	v_mov_b32_e32 v28, v26
	v_mov_b32_e32 v29, v26
	v_mov_b32_e32 v30, v26
	v_mov_b32_e32 v31, v26
	v_mov_b32_e32 v32, v26
	v_mov_b32_e32 v33, v26
	v_mov_b32_e32 v86, v26
	v_mov_b32_e32 v87, v26
	v_mov_b32_e32 v88, v26
	v_mov_b32_e32 v89, v26
	v_mov_b32_e32 v102, v26
	v_mov_b32_e32 v103, v26
	v_mov_b32_e32 v104, v26
	v_mov_b32_e32 v105, v26
	v_mov_b32_e32 v126, v26
	v_mov_b32_e32 v127, v26
	v_mov_b32_e32 v128, v26
	v_mov_b32_e32 v129, v26
	v_mov_b32_e32 v122, v26
	v_mov_b32_e32 v123, v26
	v_mov_b32_e32 v124, v26
	v_mov_b32_e32 v125, v26
	v_mov_b32_e32 v118, v26
	v_mov_b32_e32 v119, v26
	v_mov_b32_e32 v120, v26
	v_mov_b32_e32 v121, v26
	v_mov_b32_e32 v114, v26
	v_mov_b32_e32 v115, v26
	v_mov_b32_e32 v116, v26
	v_mov_b32_e32 v117, v26
	v_mov_b32_e32 v82, v26
	v_mov_b32_e32 v83, v26
	v_mov_b32_e32 v84, v26
	v_mov_b32_e32 v85, v26
	v_mov_b32_e32 v90, v26
	v_mov_b32_e32 v91, v26
	v_mov_b32_e32 v92, v26
	v_mov_b32_e32 v93, v26
	v_mov_b32_e32 v130, v26
	v_mov_b32_e32 v131, v26
	v_mov_b32_e32 v132, v26
	v_mov_b32_e32 v133, v26
	v_mov_b32_e32 v134, v26
	v_mov_b32_e32 v135, v26
	v_mov_b32_e32 v136, v26
	v_mov_b32_e32 v137, v26
	v_mov_b32_e32 v138, v26
	v_mov_b32_e32 v139, v26
	v_mov_b32_e32 v140, v26
	v_mov_b32_e32 v141, v26
	v_mov_b32_e32 v142, v26
	v_mov_b32_e32 v143, v26
	v_mov_b32_e32 v144, v26
	v_mov_b32_e32 v145, v26
	v_mov_b32_e32 v146, v26
	v_mov_b32_e32 v147, v26
	v_mov_b32_e32 v148, v26
	v_mov_b32_e32 v149, v26
	v_mov_b32_e32 v150, v26
	v_mov_b32_e32 v151, v26
	v_mov_b32_e32 v152, v26
	v_mov_b32_e32 v153, v26
	v_mov_b32_e32 v110, v26
	v_mov_b32_e32 v111, v26
	v_mov_b32_e32 v112, v26
	v_mov_b32_e32 v113, v26
	v_mov_b32_e32 v106, v26
	v_mov_b32_e32 v107, v26
	v_mov_b32_e32 v108, v26
	v_mov_b32_e32 v109, v26
	v_mov_b32_e32 v98, v26
	v_mov_b32_e32 v99, v26
	v_mov_b32_e32 v100, v26
	v_mov_b32_e32 v101, v26
	v_mov_b32_e32 v94, v26
	v_mov_b32_e32 v95, v26
	v_mov_b32_e32 v96, v26
	v_mov_b32_e32 v97, v26
	v_mov_b32_e32 v78, v26
	v_mov_b32_e32 v79, v26
	v_mov_b32_e32 v80, v26
	v_mov_b32_e32 v81, v26
	v_mov_b32_e32 v74, v26
	v_mov_b32_e32 v75, v26
	v_mov_b32_e32 v76, v26
	v_mov_b32_e32 v77, v26
	v_mov_b32_e32 v58, v26
	v_mov_b32_e32 v59, v26
	v_mov_b32_e32 v60, v26
	v_mov_b32_e32 v61, v26
	v_mov_b32_e32 v62, v26
	v_mov_b32_e32 v63, v26
	v_mov_b32_e32 v64, v26
	v_mov_b32_e32 v65, v26
	v_mov_b32_e32 v154, v26
	v_mov_b32_e32 v155, v26
	v_mov_b32_e32 v156, v26
	v_mov_b32_e32 v157, v26
	v_mov_b32_e32 v158, v26
	v_mov_b32_e32 v159, v26
	v_mov_b32_e32 v160, v26
	v_mov_b32_e32 v161, v26
	v_mov_b32_e32 v190, v26
	v_mov_b32_e32 v191, v26
	v_mov_b32_e32 v192, v26
	v_mov_b32_e32 v193, v26
	v_mov_b32_e32 v186, v26
	v_mov_b32_e32 v187, v26
	v_mov_b32_e32 v188, v26
	v_mov_b32_e32 v189, v26
	v_mov_b32_e32 v182, v26
	v_mov_b32_e32 v183, v26
	v_mov_b32_e32 v184, v26
	v_mov_b32_e32 v185, v26
	v_mov_b32_e32 v178, v26
	v_mov_b32_e32 v179, v26
	v_mov_b32_e32 v180, v26
	v_mov_b32_e32 v181, v26
	v_mov_b32_e32 v174, v26
	v_mov_b32_e32 v175, v26
	v_mov_b32_e32 v176, v26
	v_mov_b32_e32 v177, v26
	v_mov_b32_e32 v170, v26
	v_mov_b32_e32 v171, v26
	v_mov_b32_e32 v172, v26
	v_mov_b32_e32 v173, v26
	s_andn2_b64 vcc, exec, s[2:3]
	s_cbranch_vccnz .LBB0_2492

; #define PG8_STAGE(bufoff, gbase, voff) do { _Pragma("unroll") for (int _i = 0; _i < 2; ++_i) \
;         __builtin_amdgcn_global_load_lds((const unsigned*)((const char*)(gbase) + (voff)[_i]), (PG8_LAS unsigned*)(lds + (bufoff) + ldsw + _i * 8192), 16, 0, 0); } while (0)
; #define PG8_LDA(dst, b, h) do { _Pragma("unroll") for (int m = 0; m < 4; ++m) _Pragma("unroll") for (int k = 0; k < 2; ++k) dst[m][k] = *(const PG8_LAS bf16x8*)(lds + PG8_SA(b, h) + aoff + m * 2048 + k * 1024); } while (0)
; #define PG8_LDB(dst, b, h) do { _Pragma("unroll") for (int n = 0; n < 2; ++n) _Pragma("unroll") for (int k = 0; k < 2; ++k) dst[n][k] = *(const PG8_LAS bf16x8*)(lds + PG8_SB(b, h) + boff + n * 2048 + k * 1024); } while (0)
; #define PG8_MMA(ai, bj, At, Bt) do { __builtin_amdgcn_s_setprio(1); _Pragma("unroll") for (int m = 0; m < 4; ++m) _Pragma("unroll") for (int n = 0; n < 2; ++n) _Pragma("unroll") for (int k = 0; k < 2; ++k) \
;         acc[ai][bj][m][n] = __builtin_amdgcn_mfma_f32_16x16x32_bf16(Bt[n][k], At[m][k], acc[ai][bj][m][n], 0, 0, 0); __builtin_amdgcn_s_setprio(0); } while (0)
; #define PG8_WAIT_V(n) asm volatile("s_waitcnt vmcnt(" #n ")" ::: "memory")
; #define PG8_WAIT_L(n) asm volatile("s_waitcnt lgkmcnt(" #n ")" ::: "memory")
; #define PG8_BAR __builtin_amdgcn_s_barrier()
; #define PG8_SCHED __builtin_amdgcn_sched_barrier(0)
; template <class Epi, class Sched, bool ALIGN_EPI = false, bool SP2 = false>
; __device__ __forceinline__ void gemm_phase(PG8_LAS unsigned char* lds, const Gemm g, const Sched& S, const Epi& E) {
;     ...
;             PG8_LDB(B0, 0, 0); PG8_LDB(B1, 0, 1); PG8_SCHED; PG8_LDA(At, 0, 0); PG8_STAGE(PG8_SA(1, 1), a1 + hstepA, voffA);
;             PG8_WAIT_V(8); PG8_WAIT_L(0); PG8_BAR; PG8_MMA(0, 0, At, B0); PG8_MMA(0, 1, At, B1); PG8_BAR; PG8_SCHED;
;             PG8_LDA(At, 0, 1); PG8_STAGE(PG8_SB(0, 0), b2, voffB); PG8_STAGE(PG8_SB(0, 1), b2 + hstepB, voffB); PG8_STAGE(PG8_SA(0, 0), a2, voffA);
;             PG8_WAIT_V(8); PG8_WAIT_L(0); PG8_BAR; PG8_MMA(1, 0, At, B0); PG8_MMA(1, 1, At, B1); PG8_BAR; PG8_SCHED;
.LBB0_2613:
	ds_read_b128 v[130:133], v182
	ds_read_b128 v[134:137], v182 offset:1024
	ds_read_b128 v[154:157], v182 offset:2048
	ds_read_b128 v[158:161], v182 offset:3072
	ds_read_b128 v[162:165], v183
	ds_read_b128 v[166:169], v183 offset:1024
	ds_read_b128 v[170:173], v183 offset:2048
	ds_read_b128 v[186:189], v183 offset:3072
	s_add_u32 s44, s42, 0xfffc0080
	s_addc_u32 s45, s43, -1
	s_cmp_eq_u32 s70, 12
	s_cselect_b32 s47, s31, s45
	s_cselect_b32 s46, s39, s44
	s_cselect_b32 s45, s29, s69
	s_cselect_b32 s44, s67, s68
	s_add_i32 m0, s41, 0xc000
	ds_read_b128 v[190:193], v184
	ds_read_b128 v[194:197], v184 offset:1024
	ds_read_b128 v[198:201], v184 offset:2048
	ds_read_b128 v[202:205], v184 offset:3072
	ds_read_b128 v[206:209], v184 offset:4096
	ds_read_b128 v[210:213], v184 offset:5120
	ds_read_b128 v[214:217], v184 offset:6144
	ds_read_b128 v[218:221], v184 offset:7168
	global_load_lds_dwordx4 v146, s[42:43]
	s_add_i32 m0, s41, 0xe000
	s_nop 0
	global_load_lds_dwordx4 v148, s[42:43]
	s_waitcnt vmcnt(8)
	s_waitcnt lgkmcnt(0)
	s_barrier
	s_setprio 1
	s_waitcnt lgkmcnt(0)
	v_mfma_f32_16x16x32_bf16 v[126:129], v[130:133], v[190:193], v[126:129]
	v_mfma_f32_16x16x32_bf16 v[94:97], v[154:157], v[190:193], v[94:97]
	v_mfma_f32_16x16x32_bf16 v[118:121], v[130:133], v[198:201], v[118:121]
	v_mfma_f32_16x16x32_bf16 v[86:89], v[154:157], v[198:201], v[86:89]
	v_mfma_f32_16x16x32_bf16 v[114:117], v[130:133], v[206:209], v[114:117]
	v_mfma_f32_16x16x32_bf16 v[82:85], v[154:157], v[206:209], v[82:85]
	v_mfma_f32_16x16x32_bf16 v[102:105], v[130:133], v[214:217], v[102:105]
	v_mfma_f32_16x16x32_bf16 v[70:73], v[154:157], v[214:217], v[70:73]
	v_mfma_f32_16x16x32_bf16 v[126:129], v[134:137], v[194:197], v[126:129]
	v_mfma_f32_16x16x32_bf16 v[94:97], v[158:161], v[194:197], v[94:97]
	v_mfma_f32_16x16x32_bf16 v[118:121], v[134:137], v[202:205], v[118:121]
	v_mfma_f32_16x16x32_bf16 v[86:89], v[158:161], v[202:205], v[86:89]
	v_mfma_f32_16x16x32_bf16 v[114:117], v[134:137], v[210:213], v[114:117]
	v_mfma_f32_16x16x32_bf16 v[82:85], v[158:161], v[210:213], v[82:85]
	v_mfma_f32_16x16x32_bf16 v[102:105], v[134:137], v[218:221], v[102:105]
	v_mfma_f32_16x16x32_bf16 v[70:73], v[158:161], v[218:221], v[70:73]
	v_mfma_f32_16x16x32_bf16 v[122:125], v[162:165], v[190:193], v[122:125]
	v_mfma_f32_16x16x32_bf16 v[90:93], v[170:173], v[190:193], v[90:93]
	v_mfma_f32_16x16x32_bf16 v[110:113], v[162:165], v[198:201], v[110:113]
	v_mfma_f32_16x16x32_bf16 v[78:81], v[170:173], v[198:201], v[78:81]
	v_mfma_f32_16x16x32_bf16 v[106:109], v[162:165], v[206:209], v[106:109]
	v_mfma_f32_16x16x32_bf16 v[74:77], v[170:173], v[206:209], v[74:77]
	v_mfma_f32_16x16x32_bf16 v[98:101], v[162:165], v[214:217], v[98:101]
	v_mfma_f32_16x16x32_bf16 v[66:69], v[170:173], v[214:217], v[66:69]
	v_mfma_f32_16x16x32_bf16 v[122:125], v[166:169], v[194:197], v[122:125]
	v_mfma_f32_16x16x32_bf16 v[90:93], v[186:189], v[194:197], v[90:93]
	v_mfma_f32_16x16x32_bf16 v[110:113], v[166:169], v[202:205], v[110:113]
	v_mfma_f32_16x16x32_bf16 v[78:81], v[186:189], v[202:205], v[78:81]
	v_mfma_f32_16x16x32_bf16 v[106:109], v[166:169], v[210:213], v[106:109]
	v_mfma_f32_16x16x32_bf16 v[74:77], v[186:189], v[210:213], v[74:77]
	v_mfma_f32_16x16x32_bf16 v[98:101], v[166:169], v[218:221], v[98:101]
	v_mfma_f32_16x16x32_bf16 v[66:69], v[186:189], v[218:221], v[66:69]
	s_setprio 0
	s_barrier
	s_add_i32 s71, s64, s51
	s_add_u32 s98, s44, 0x80
	s_addc_u32 s99, s45, 0
	s_mov_b32 m0, s71
	ds_read_b128 v[190:193], v184 offset:16384
	ds_read_b128 v[194:197], v184 offset:17408
	ds_read_b128 v[198:201], v184 offset:18432
	ds_read_b128 v[202:205], v184 offset:19456
	ds_read_b128 v[206:209], v184 offset:20480
	ds_read_b128 v[210:213], v184 offset:21504
	ds_read_b128 v[214:217], v184 offset:22528
	ds_read_b128 v[218:221], v184 offset:23552
	global_load_lds_dwordx4 v140, s[44:45]
	s_add_i32 m0, s71, 0x2000
	s_add_u32 s72, s44, 0x40000
	s_addc_u32 s73, s45, 0
	s_add_i32 s71, s65, s51
	global_load_lds_dwordx4 v144, s[44:45]
	s_mov_b32 m0, s71
	v_lshl_add_u64 v[226:227], s[46:47], 0, v[142:143]
	global_load_lds_dwordx4 v140, s[72:73]
	s_add_i32 m0, s71, 0x2000
	s_nop 0
	global_load_lds_dwordx4 v144, s[72:73]
	s_add_u32 s100, s46, 0x80
	s_addc_u32 s101, s47, 0
	s_mov_b32 m0, s41
	s_nop 0
	global_load_lds_dwordx4 v138, s[46:47]
	s_mov_b32 m0, s52
	s_nop 0
	global_load_lds_dwordx4 v142, s[46:47]
	s_waitcnt vmcnt(8)
	s_waitcnt lgkmcnt(0)
	s_barrier
	s_setprio 1
	s_waitcnt lgkmcnt(0)
	v_mfma_f32_16x16x32_bf16 v[62:65], v[130:133], v[190:193], v[62:65]
	v_mfma_f32_16x16x32_bf16 v[30:33], v[154:157], v[190:193], v[30:33]
	v_mfma_f32_16x16x32_bf16 v[54:57], v[130:133], v[198:201], v[54:57]
	v_mfma_f32_16x16x32_bf16 v[22:25], v[154:157], v[198:201], v[22:25]
	v_mfma_f32_16x16x32_bf16 v[50:53], v[130:133], v[206:209], v[50:53]
	v_mfma_f32_16x16x32_bf16 v[18:21], v[154:157], v[206:209], v[18:21]
	v_mfma_f32_16x16x32_bf16 v[38:41], v[130:133], v[214:217], v[38:41]
	v_mfma_f32_16x16x32_bf16 v[6:9], v[154:157], v[214:217], v[6:9]
	v_mfma_f32_16x16x32_bf16 v[62:65], v[134:137], v[194:197], v[62:65]
	v_mfma_f32_16x16x32_bf16 v[30:33], v[158:161], v[194:197], v[30:33]
	v_mfma_f32_16x16x32_bf16 v[54:57], v[134:137], v[202:205], v[54:57]
	v_mfma_f32_16x16x32_bf16 v[22:25], v[158:161], v[202:205], v[22:25]
	v_mfma_f32_16x16x32_bf16 v[50:53], v[134:137], v[210:213], v[50:53]
	v_mfma_f32_16x16x32_bf16 v[18:21], v[158:161], v[210:213], v[18:21]
	v_mfma_f32_16x16x32_bf16 v[38:41], v[134:137], v[218:221], v[38:41]
	v_mfma_f32_16x16x32_bf16 v[6:9], v[158:161], v[218:221], v[6:9]
	v_mfma_f32_16x16x32_bf16 v[58:61], v[162:165], v[190:193], v[58:61]
	v_mfma_f32_16x16x32_bf16 v[26:29], v[170:173], v[190:193], v[26:29]
	v_mfma_f32_16x16x32_bf16 v[46:49], v[162:165], v[198:201], v[46:49]
	v_mfma_f32_16x16x32_bf16 v[14:17], v[170:173], v[198:201], v[14:17]
	v_mfma_f32_16x16x32_bf16 v[42:45], v[162:165], v[206:209], v[42:45]
	v_mfma_f32_16x16x32_bf16 v[10:13], v[170:173], v[206:209], v[10:13]
	v_mfma_f32_16x16x32_bf16 v[34:37], v[162:165], v[214:217], v[34:37]
	v_mfma_f32_16x16x32_bf16 v[2:5], v[170:173], v[214:217], v[2:5]
	v_mfma_f32_16x16x32_bf16 v[58:61], v[166:169], v[194:197], v[58:61]
	v_mfma_f32_16x16x32_bf16 v[26:29], v[186:189], v[194:197], v[26:29]
	v_mfma_f32_16x16x32_bf16 v[46:49], v[166:169], v[202:205], v[46:49]
	v_mfma_f32_16x16x32_bf16 v[14:17], v[186:189], v[202:205], v[14:17]
	v_mfma_f32_16x16x32_bf16 v[42:45], v[166:169], v[210:213], v[42:45]
	v_mfma_f32_16x16x32_bf16 v[10:13], v[186:189], v[210:213], v[10:13]
	v_mfma_f32_16x16x32_bf16 v[34:37], v[166:169], v[218:221], v[34:37]
	v_mfma_f32_16x16x32_bf16 v[2:5], v[186:189], v[218:221], v[2:5]
	s_setprio 0
	s_barrier
; #define PG8_STAGE(bufoff, gbase, voff) do { _Pragma("unroll") for (int _i = 0; _i < 2; ++_i) \
;         __builtin_amdgcn_global_load_lds((const unsigned*)((const char*)(gbase) + (voff)[_i]), (PG8_LAS unsigned*)(lds + (bufoff) + ldsw + _i * 8192), 16, 0, 0); } while (0)
; #define PG8_LDA(dst, b, h) do { _Pragma("unroll") for (int m = 0; m < 4; ++m) _Pragma("unroll") for (int k = 0; k < 2; ++k) dst[m][k] = *(const PG8_LAS bf16x8*)(lds + PG8_SA(b, h) + aoff + m * 2048 + k * 1024); } while (0)
; #define PG8_LDB(dst, b, h) do { _Pragma("unroll") for (int n = 0; n < 2; ++n) _Pragma("unroll") for (int k = 0; k < 2; ++k) dst[n][k] = *(const PG8_LAS bf16x8*)(lds + PG8_SB(b, h) + boff + n * 2048 + k * 1024); } while (0)
; #define PG8_MMA(ai, bj, At, Bt) do { __builtin_amdgcn_s_setprio(1); _Pragma("unroll") for (int m = 0; m < 4; ++m) _Pragma("unroll") for (int n = 0; n < 2; ++n) _Pragma("unroll") for (int k = 0; k < 2; ++k) \
;         acc[ai][bj][m][n] = __builtin_amdgcn_mfma_f32_16x16x32_bf16(Bt[n][k], At[m][k], acc[ai][bj][m][n], 0, 0, 0); __builtin_amdgcn_s_setprio(0); } while (0)
; #define PG8_WAIT_V(n) asm volatile("s_waitcnt vmcnt(" #n ")" ::: "memory")
; #define PG8_WAIT_L(n) asm volatile("s_waitcnt lgkmcnt(" #n ")" ::: "memory")
; #define PG8_BAR __builtin_amdgcn_s_barrier()
; #define PG8_SCHED __builtin_amdgcn_sched_barrier(0)
; template <class Epi, class Sched, bool ALIGN_EPI = false, bool SP2 = false>
; __device__ __forceinline__ void gemm_phase(PG8_LAS unsigned char* lds, const Gemm g, const Sched& S, const Epi& E) {
;     ...
;         for (int t = 0; t < nt; t += 2) {
;     ...
;             PG8_LDB(B0, 1, 0); PG8_LDB(B1, 1, 1); PG8_SCHED; PG8_LDA(At, 1, 0); PG8_STAGE(PG8_SA(0, 1), a2 + hstepA, voffA);
;             PG8_WAIT_V(8); PG8_WAIT_L(0); PG8_BAR; PG8_MMA(0, 0, At, B0); PG8_MMA(0, 1, At, B1); PG8_BAR; PG8_SCHED;
;             PG8_LDA(At, 1, 1); PG8_STAGE(PG8_SB(1, 0), b3, voffB); PG8_STAGE(PG8_SB(1, 1), b3 + hstepB, voffB); PG8_STAGE(PG8_SA(1, 0), a3, voffA);
;             PG8_WAIT_V(8); PG8_WAIT_L(0); PG8_BAR; PG8_MMA(1, 0, At, B0); PG8_MMA(1, 1, At, B1); PG8_BAR; PG8_SCHED;
	s_add_i32 s71, 0, 0x18000
	s_add_i32 s72, 0, 0x1c000
	v_add_u32_e32 v158, s71, v176
	v_add_u32_e32 v185, s72, v176
	ds_read_b128 v[130:133], v158
	ds_read_b128 v[134:137], v158 offset:1024
	ds_read_b128 v[154:157], v158 offset:2048
	ds_read_b128 v[158:161], v158 offset:3072
	ds_read_b128 v[162:165], v185
	ds_read_b128 v[166:169], v185 offset:1024
	ds_read_b128 v[170:173], v185 offset:2048
	ds_read_b128 v[186:189], v185 offset:3072
	s_add_u32 s46, s46, 0x40000
	s_addc_u32 s47, s47, 0
	s_mov_b32 m0, s53
	ds_read_b128 v[190:193], v184 offset:32768
	ds_read_b128 v[194:197], v184 offset:33792
	ds_read_b128 v[198:201], v184 offset:34816
	ds_read_b128 v[202:205], v184 offset:35840
	ds_read_b128 v[206:209], v184 offset:36864
	ds_read_b128 v[210:213], v184 offset:37888
	ds_read_b128 v[214:217], v184 offset:38912
	ds_read_b128 v[218:221], v184 offset:39936
	global_load_lds_dwordx4 v138, s[46:47]
	s_mov_b32 m0, s54
	s_nop 0
	global_load_lds_dwordx4 v142, s[46:47]
	s_waitcnt vmcnt(8)
	s_waitcnt lgkmcnt(0)
	s_barrier
	s_setprio 1
	s_waitcnt lgkmcnt(0)
	v_mfma_f32_16x16x32_bf16 v[126:129], v[130:133], v[190:193], v[126:129]
	v_mfma_f32_16x16x32_bf16 v[94:97], v[154:157], v[190:193], v[94:97]
	v_mfma_f32_16x16x32_bf16 v[118:121], v[130:133], v[198:201], v[118:121]
	v_mfma_f32_16x16x32_bf16 v[86:89], v[154:157], v[198:201], v[86:89]
	v_mfma_f32_16x16x32_bf16 v[114:117], v[130:133], v[206:209], v[114:117]
	v_mfma_f32_16x16x32_bf16 v[82:85], v[154:157], v[206:209], v[82:85]
	v_mfma_f32_16x16x32_bf16 v[102:105], v[130:133], v[214:217], v[102:105]
	v_mfma_f32_16x16x32_bf16 v[70:73], v[154:157], v[214:217], v[70:73]
	v_mfma_f32_16x16x32_bf16 v[126:129], v[134:137], v[194:197], v[126:129]
	v_mfma_f32_16x16x32_bf16 v[94:97], v[158:161], v[194:197], v[94:97]
	v_mfma_f32_16x16x32_bf16 v[118:121], v[134:137], v[202:205], v[118:121]
	v_mfma_f32_16x16x32_bf16 v[86:89], v[158:161], v[202:205], v[86:89]
	v_mfma_f32_16x16x32_bf16 v[114:117], v[134:137], v[210:213], v[114:117]
	v_mfma_f32_16x16x32_bf16 v[82:85], v[158:161], v[210:213], v[82:85]
	v_mfma_f32_16x16x32_bf16 v[102:105], v[134:137], v[218:221], v[102:105]
	v_mfma_f32_16x16x32_bf16 v[70:73], v[158:161], v[218:221], v[70:73]
	v_mfma_f32_16x16x32_bf16 v[122:125], v[162:165], v[190:193], v[122:125]
	v_mfma_f32_16x16x32_bf16 v[90:93], v[170:173], v[190:193], v[90:93]
	v_mfma_f32_16x16x32_bf16 v[110:113], v[162:165], v[198:201], v[110:113]
	v_mfma_f32_16x16x32_bf16 v[78:81], v[170:173], v[198:201], v[78:81]
	v_mfma_f32_16x16x32_bf16 v[106:109], v[162:165], v[206:209], v[106:109]
	v_mfma_f32_16x16x32_bf16 v[74:77], v[170:173], v[206:209], v[74:77]
	v_mfma_f32_16x16x32_bf16 v[98:101], v[162:165], v[214:217], v[98:101]
	v_mfma_f32_16x16x32_bf16 v[66:69], v[170:173], v[214:217], v[66:69]
	v_mfma_f32_16x16x32_bf16 v[122:125], v[166:169], v[194:197], v[122:125]
	v_mfma_f32_16x16x32_bf16 v[90:93], v[186:189], v[194:197], v[90:93]
	v_mfma_f32_16x16x32_bf16 v[110:113], v[166:169], v[202:205], v[110:113]
	v_mfma_f32_16x16x32_bf16 v[78:81], v[186:189], v[202:205], v[78:81]
	v_mfma_f32_16x16x32_bf16 v[106:109], v[166:169], v[210:213], v[106:109]
	v_mfma_f32_16x16x32_bf16 v[74:77], v[186:189], v[210:213], v[74:77]
	v_mfma_f32_16x16x32_bf16 v[98:101], v[166:169], v[218:221], v[98:101]
	v_mfma_f32_16x16x32_bf16 v[66:69], v[186:189], v[218:221], v[66:69]
	s_setprio 0
	s_barrier
	s_add_i32 s46, s71, s51
	s_mov_b32 m0, s46
	ds_read_b128 v[190:193], v184 offset:49152
	ds_read_b128 v[194:197], v184 offset:50176
	ds_read_b128 v[198:201], v184 offset:51200
	ds_read_b128 v[202:205], v184 offset:52224
	ds_read_b128 v[206:209], v184 offset:53248
	ds_read_b128 v[210:213], v184 offset:54272
	ds_read_b128 v[214:217], v184 offset:55296
	ds_read_b128 v[218:221], v184 offset:56320
	global_load_lds_dwordx4 v140, s[98:99]
	s_add_i32 m0, s46, 0x2000
	s_add_u32 s44, s44, 0x40080
	s_addc_u32 s45, s45, 0
	s_add_i32 s46, s72, s51
	global_load_lds_dwordx4 v144, s[98:99]
	s_mov_b32 m0, s46
	s_nop 0
	global_load_lds_dwordx4 v140, s[44:45]
	s_add_i32 m0, s46, 0x2000
	s_nop 0
	global_load_lds_dwordx4 v144, s[44:45]
	s_mov_b32 m0, s59
	s_nop 0
	global_load_lds_dwordx4 v138, s[100:101]
	v_lshl_add_u64 v[174:175], v[226:227], 0, s[24:25]
	s_mov_b32 m0, s60
	s_nop 0
	global_load_lds_dwordx4 v142, s[100:101]
	s_waitcnt vmcnt(8)
	s_waitcnt lgkmcnt(0)
	s_barrier
	s_setprio 1
	s_waitcnt lgkmcnt(0)
	v_mfma_f32_16x16x32_bf16 v[62:65], v[130:133], v[190:193], v[62:65]
	v_mfma_f32_16x16x32_bf16 v[30:33], v[154:157], v[190:193], v[30:33]
	v_mfma_f32_16x16x32_bf16 v[54:57], v[130:133], v[198:201], v[54:57]
	v_mfma_f32_16x16x32_bf16 v[22:25], v[154:157], v[198:201], v[22:25]
	v_mfma_f32_16x16x32_bf16 v[50:53], v[130:133], v[206:209], v[50:53]
	v_mfma_f32_16x16x32_bf16 v[18:21], v[154:157], v[206:209], v[18:21]
	v_mfma_f32_16x16x32_bf16 v[38:41], v[130:133], v[214:217], v[38:41]
	v_mfma_f32_16x16x32_bf16 v[6:9], v[154:157], v[214:217], v[6:9]
	v_mfma_f32_16x16x32_bf16 v[62:65], v[134:137], v[194:197], v[62:65]
	v_mfma_f32_16x16x32_bf16 v[30:33], v[158:161], v[194:197], v[30:33]
	v_mfma_f32_16x16x32_bf16 v[54:57], v[134:137], v[202:205], v[54:57]
	v_mfma_f32_16x16x32_bf16 v[22:25], v[158:161], v[202:205], v[22:25]
	v_mfma_f32_16x16x32_bf16 v[50:53], v[134:137], v[210:213], v[50:53]
	v_mfma_f32_16x16x32_bf16 v[18:21], v[158:161], v[210:213], v[18:21]
	v_mfma_f32_16x16x32_bf16 v[38:41], v[134:137], v[218:221], v[38:41]
	v_mfma_f32_16x16x32_bf16 v[6:9], v[158:161], v[218:221], v[6:9]
	v_mfma_f32_16x16x32_bf16 v[58:61], v[162:165], v[190:193], v[58:61]
	v_mfma_f32_16x16x32_bf16 v[26:29], v[170:173], v[190:193], v[26:29]
	v_mfma_f32_16x16x32_bf16 v[46:49], v[162:165], v[198:201], v[46:49]
	v_mfma_f32_16x16x32_bf16 v[14:17], v[170:173], v[198:201], v[14:17]
	v_mfma_f32_16x16x32_bf16 v[42:45], v[162:165], v[206:209], v[42:45]
	v_mfma_f32_16x16x32_bf16 v[10:13], v[170:173], v[206:209], v[10:13]
	v_mfma_f32_16x16x32_bf16 v[34:37], v[162:165], v[214:217], v[34:37]
	v_mfma_f32_16x16x32_bf16 v[2:5], v[170:173], v[214:217], v[2:5]
	v_mfma_f32_16x16x32_bf16 v[58:61], v[166:169], v[194:197], v[58:61]
	v_mfma_f32_16x16x32_bf16 v[26:29], v[186:189], v[194:197], v[26:29]
	v_mfma_f32_16x16x32_bf16 v[46:49], v[166:169], v[202:205], v[46:49]
	v_mfma_f32_16x16x32_bf16 v[14:17], v[186:189], v[202:205], v[14:17]
	v_mfma_f32_16x16x32_bf16 v[42:45], v[166:169], v[210:213], v[42:45]
	v_mfma_f32_16x16x32_bf16 v[10:13], v[186:189], v[210:213], v[10:13]
	v_mfma_f32_16x16x32_bf16 v[34:37], v[166:169], v[218:221], v[34:37]
	v_mfma_f32_16x16x32_bf16 v[2:5], v[186:189], v[218:221], v[2:5]
	s_setprio 0
	s_barrier
	s_add_i32 s70, s70, 2
	s_add_u32 s42, s42, 0x100
	s_addc_u32 s43, s43, 0
	s_add_u32 s68, s68, 0x100
	s_addc_u32 s69, s69, 0
	s_cmp_gt_u32 s70, 13
	s_cbranch_scc0 .LBB0_2613
	s_and_b64 vcc, exec, s[26:27]
	s_cbranch_vccz .LBB0_2616
	s_barrier

; #define PG8_STAGE(bufoff, gbase, voff) do { _Pragma("unroll") for (int _i = 0; _i < 2; ++_i) \
;         __builtin_amdgcn_global_load_lds((const unsigned*)((const char*)(gbase) + (voff)[_i]), (PG8_LAS unsigned*)(lds + (bufoff) + ldsw + _i * 8192), 16, 0, 0); } while (0)
; #define PG8_LDA(dst, b, h) do { _Pragma("unroll") for (int m = 0; m < 4; ++m) _Pragma("unroll") for (int k = 0; k < 2; ++k) dst[m][k] = *(const PG8_LAS bf16x8*)(lds + PG8_SA(b, h) + aoff + m * 2048 + k * 1024); } while (0)
; #define PG8_LDB(dst, b, h) do { _Pragma("unroll") for (int n = 0; n < 2; ++n) _Pragma("unroll") for (int k = 0; k < 2; ++k) dst[n][k] = *(const PG8_LAS bf16x8*)(lds + PG8_SB(b, h) + boff + n * 2048 + k * 1024); } while (0)
; #define PG8_MMA(ai, bj, At, Bt) do { __builtin_amdgcn_s_setprio(1); _Pragma("unroll") for (int m = 0; m < 4; ++m) _Pragma("unroll") for (int n = 0; n < 2; ++n) _Pragma("unroll") for (int k = 0; k < 2; ++k) \
;         acc[ai][bj][m][n] = __builtin_amdgcn_mfma_f32_16x16x32_bf16(Bt[n][k], At[m][k], acc[ai][bj][m][n], 0, 0, 0); __builtin_amdgcn_s_setprio(0); } while (0)
; #define PG8_WAIT_V(n) asm volatile("s_waitcnt vmcnt(" #n ")" ::: "memory")
; #define PG8_WAIT_L(n) asm volatile("s_waitcnt lgkmcnt(" #n ")" ::: "memory")
; #define PG8_BAR __builtin_amdgcn_s_barrier()
; #define PG8_SCHED __builtin_amdgcn_sched_barrier(0)
; template <class Epi, class Sched, bool ALIGN_EPI = false, bool SP2 = false>
; __device__ __forceinline__ void gemm_phase(PG8_LAS unsigned char* lds, const Gemm g, const Sched& S, const Epi& E) {
;     ...
;             PG8_LDB(B0, 0, 0); PG8_LDB(B1, 0, 1); PG8_SCHED; PG8_LDA(At, 0, 0); PG8_STAGE(PG8_SA(1, 1), a1 + hstepA, voffA);
;             PG8_WAIT_V(8); PG8_WAIT_L(0); PG8_BAR; PG8_MMA(0, 0, At, B0); PG8_MMA(0, 1, At, B1); PG8_BAR; PG8_SCHED;
;             PG8_LDA(At, 0, 1); PG8_STAGE(PG8_SB(0, 0), b2, voffB); PG8_STAGE(PG8_SB(0, 1), b2 + hstepB, voffB); PG8_STAGE(PG8_SA(0, 0), a2, voffA);
;             PG8_WAIT_V(8); PG8_WAIT_L(0); PG8_BAR; PG8_MMA(1, 0, At, B0); PG8_MMA(1, 1, At, B1); PG8_BAR; PG8_SCHED;
.LBB0_2807:
	v_add_u32_e32 v68, s49, v58
	ds_read_b128 v[60:63], v68
	ds_read_b128 v[64:67], v68 offset:1024
	ds_read_b128 v[162:165], v68 offset:2048
	ds_read_b128 v[166:169], v68 offset:3072
	v_add_u32_e32 v68, s50, v58
	s_add_u32 s22, s14, s20
	ds_read_b128 v[170:173], v68
	ds_read_b128 v[174:177], v68 offset:1024
	ds_read_b128 v[178:181], v68 offset:2048
	ds_read_b128 v[184:187], v68 offset:3072
	s_addc_u32 s23, s15, s21
	s_add_u32 s22, s22, 0x100
	s_addc_u32 s23, s23, 0
	s_add_u32 s57, s54, s20
	s_addc_u32 s58, s55, s21
	s_cmpk_eq_i32 s20, 0x1500
	s_cselect_b32 s25, s19, s23
	s_cselect_b32 s24, s18, s22
	s_cselect_b32 s23, s1, s58
	s_cselect_b32 s22, s0, s57
	v_lshl_add_u64 v[68:69], v[54:55], 0, s[20:21]
	s_add_i32 m0, s41, 0xc000
	ds_read_b128 v[188:191], v59
	ds_read_b128 v[192:195], v59 offset:1024
	ds_read_b128 v[196:199], v59 offset:2048
	ds_read_b128 v[200:203], v59 offset:3072
	ds_read_b128 v[204:207], v59 offset:4096
	ds_read_b128 v[208:211], v59 offset:5120
	ds_read_b128 v[212:215], v59 offset:6144
	ds_read_b128 v[216:219], v59 offset:7168
	global_load_lds_dwordx4 v[68:69], off
	v_lshl_add_u64 v[68:69], v[56:57], 0, s[20:21]
	s_add_i32 m0, s41, 0xe000
	s_nop 0
	global_load_lds_dwordx4 v[68:69], off
	s_waitcnt vmcnt(8)
	s_waitcnt lgkmcnt(0)
	s_barrier
	s_setprio 1
	s_waitcnt lgkmcnt(0)
	v_mfma_f32_16x16x32_bf16 v[158:161], v[60:63], v[188:191], v[158:161]
	v_mfma_f32_16x16x32_bf16 v[146:149], v[162:165], v[188:191], v[146:149]
	v_mfma_f32_16x16x32_bf16 v[150:153], v[60:63], v[196:199], v[150:153]
	v_mfma_f32_16x16x32_bf16 v[154:157], v[162:165], v[196:199], v[154:157]
	v_mfma_f32_16x16x32_bf16 v[142:145], v[60:63], v[204:207], v[142:145]
	v_mfma_f32_16x16x32_bf16 v[138:141], v[162:165], v[204:207], v[138:141]
	v_mfma_f32_16x16x32_bf16 v[134:137], v[60:63], v[212:215], v[134:137]
	v_mfma_f32_16x16x32_bf16 v[130:133], v[162:165], v[212:215], v[130:133]
	v_mfma_f32_16x16x32_bf16 v[158:161], v[64:67], v[192:195], v[158:161]
	v_mfma_f32_16x16x32_bf16 v[146:149], v[166:169], v[192:195], v[146:149]
	v_mfma_f32_16x16x32_bf16 v[150:153], v[64:67], v[200:203], v[150:153]
	v_mfma_f32_16x16x32_bf16 v[154:157], v[166:169], v[200:203], v[154:157]
	v_mfma_f32_16x16x32_bf16 v[142:145], v[64:67], v[208:211], v[142:145]
	v_mfma_f32_16x16x32_bf16 v[138:141], v[166:169], v[208:211], v[138:141]
	v_mfma_f32_16x16x32_bf16 v[134:137], v[64:67], v[216:219], v[134:137]
	v_mfma_f32_16x16x32_bf16 v[130:133], v[166:169], v[216:219], v[130:133]
	v_mfma_f32_16x16x32_bf16 v[78:81], v[170:173], v[188:191], v[78:81]
	v_mfma_f32_16x16x32_bf16 v[74:77], v[178:181], v[188:191], v[74:77]
	v_mfma_f32_16x16x32_bf16 v[86:89], v[170:173], v[196:199], v[86:89]
	v_mfma_f32_16x16x32_bf16 v[90:93], v[178:181], v[196:199], v[90:93]
	v_mfma_f32_16x16x32_bf16 v[118:121], v[170:173], v[204:207], v[118:121]
	v_mfma_f32_16x16x32_bf16 v[114:117], v[178:181], v[204:207], v[114:117]
	v_mfma_f32_16x16x32_bf16 v[122:125], v[170:173], v[212:215], v[122:125]
	v_mfma_f32_16x16x32_bf16 v[126:129], v[178:181], v[212:215], v[126:129]
	v_mfma_f32_16x16x32_bf16 v[78:81], v[174:177], v[192:195], v[78:81]
	v_mfma_f32_16x16x32_bf16 v[74:77], v[184:187], v[192:195], v[74:77]
	v_mfma_f32_16x16x32_bf16 v[86:89], v[174:177], v[200:203], v[86:89]
	v_mfma_f32_16x16x32_bf16 v[90:93], v[184:187], v[200:203], v[90:93]
	v_mfma_f32_16x16x32_bf16 v[118:121], v[174:177], v[208:211], v[118:121]
	v_mfma_f32_16x16x32_bf16 v[114:117], v[184:187], v[208:211], v[114:117]
	v_mfma_f32_16x16x32_bf16 v[122:125], v[174:177], v[216:219], v[122:125]
	v_mfma_f32_16x16x32_bf16 v[126:129], v[184:187], v[216:219], v[126:129]
	s_setprio 0
	s_barrier
	s_add_i32 s57, s49, s40
	s_add_u32 s98, s22, 0x80
	s_addc_u32 s99, s23, 0
	s_mov_b32 m0, s57
	ds_read_b128 v[188:191], v59 offset:16384
	ds_read_b128 v[192:195], v59 offset:17408
	ds_read_b128 v[196:199], v59 offset:18432
	ds_read_b128 v[200:203], v59 offset:19456
	ds_read_b128 v[204:207], v59 offset:20480
	ds_read_b128 v[208:211], v59 offset:21504
	ds_read_b128 v[212:215], v59 offset:22528
	ds_read_b128 v[216:219], v59 offset:23552
	global_load_lds_dwordx4 v8, s[22:23]
	s_add_i32 m0, s57, 0x2000
	s_add_u32 s58, s22, 0xb0000
	s_addc_u32 s59, s23, 0
	s_add_i32 s57, s50, s40
	global_load_lds_dwordx4 v12, s[22:23]
	s_mov_b32 m0, s57
	s_add_u32 s100, s24, 0x80
	s_addc_u32 s101, s25, 0
	global_load_lds_dwordx4 v8, s[58:59]
	s_add_i32 m0, s57, 0x2000
	s_nop 0
	global_load_lds_dwordx4 v12, s[58:59]
	s_mov_b32 m0, s41
	s_nop 0
	global_load_lds_dwordx4 v6, s[24:25]
	s_mov_b32 m0, s42
	s_nop 0
	global_load_lds_dwordx4 v10, s[24:25]
	s_waitcnt vmcnt(8)
	s_waitcnt lgkmcnt(0)
	s_barrier
; #define PG8_STAGE(bufoff, gbase, voff) do { _Pragma("unroll") for (int _i = 0; _i < 2; ++_i) \
;         __builtin_amdgcn_global_load_lds((const unsigned*)((const char*)(gbase) + (voff)[_i]), (PG8_LAS unsigned*)(lds + (bufoff) + ldsw + _i * 8192), 16, 0, 0); } while (0)
; #define PG8_LDA(dst, b, h) do { _Pragma("unroll") for (int m = 0; m < 4; ++m) _Pragma("unroll") for (int k = 0; k < 2; ++k) dst[m][k] = *(const PG8_LAS bf16x8*)(lds + PG8_SA(b, h) + aoff + m * 2048 + k * 1024); } while (0)
; #define PG8_LDB(dst, b, h) do { _Pragma("unroll") for (int n = 0; n < 2; ++n) _Pragma("unroll") for (int k = 0; k < 2; ++k) dst[n][k] = *(const PG8_LAS bf16x8*)(lds + PG8_SB(b, h) + boff + n * 2048 + k * 1024); } while (0)
; #define PG8_MMA(ai, bj, At, Bt) do { __builtin_amdgcn_s_setprio(1); _Pragma("unroll") for (int m = 0; m < 4; ++m) _Pragma("unroll") for (int n = 0; n < 2; ++n) _Pragma("unroll") for (int k = 0; k < 2; ++k) \
;         acc[ai][bj][m][n] = __builtin_amdgcn_mfma_f32_16x16x32_bf16(Bt[n][k], At[m][k], acc[ai][bj][m][n], 0, 0, 0); __builtin_amdgcn_s_setprio(0); } while (0)
; #define PG8_WAIT_V(n) asm volatile("s_waitcnt vmcnt(" #n ")" ::: "memory")
; #define PG8_WAIT_L(n) asm volatile("s_waitcnt lgkmcnt(" #n ")" ::: "memory")
; #define PG8_BAR __builtin_amdgcn_s_barrier()
; #define PG8_SCHED __builtin_amdgcn_sched_barrier(0)
; template <class Epi, class Sched, bool ALIGN_EPI = false, bool SP2 = false>
; __device__ __forceinline__ void gemm_phase(PG8_LAS unsigned char* lds, const Gemm g, const Sched& S, const Epi& E) {
;     ...
;             PG8_WAIT_V(8); PG8_WAIT_L(0); PG8_BAR; PG8_MMA(1, 0, At, B0); PG8_MMA(1, 1, At, B1); PG8_BAR; PG8_SCHED;
;             PG8_LDB(B0, 1, 0); PG8_LDB(B1, 1, 1); PG8_SCHED; PG8_LDA(At, 1, 0); PG8_STAGE(PG8_SA(0, 1), a2 + hstepA, voffA);
;             PG8_WAIT_V(8); PG8_WAIT_L(0); PG8_BAR; PG8_MMA(0, 0, At, B0); PG8_MMA(0, 1, At, B1); PG8_BAR; PG8_SCHED;
	s_setprio 1
	s_waitcnt lgkmcnt(0)
	v_mfma_f32_16x16x32_bf16 v[110:113], v[60:63], v[188:191], v[110:113]
	v_mfma_f32_16x16x32_bf16 v[106:109], v[162:165], v[188:191], v[106:109]
	v_mfma_f32_16x16x32_bf16 v[102:105], v[60:63], v[196:199], v[102:105]
	v_mfma_f32_16x16x32_bf16 v[98:101], v[162:165], v[196:199], v[98:101]
	v_mfma_f32_16x16x32_bf16 v[46:49], v[60:63], v[204:207], v[46:49]
	v_mfma_f32_16x16x32_bf16 v[42:45], v[162:165], v[204:207], v[42:45]
	v_mfma_f32_16x16x32_bf16 v[38:41], v[60:63], v[212:215], v[38:41]
	v_mfma_f32_16x16x32_bf16 v[34:37], v[162:165], v[212:215], v[34:37]
	v_mfma_f32_16x16x32_bf16 v[110:113], v[64:67], v[192:195], v[110:113]
	v_mfma_f32_16x16x32_bf16 v[106:109], v[166:169], v[192:195], v[106:109]
	v_mfma_f32_16x16x32_bf16 v[102:105], v[64:67], v[200:203], v[102:105]
	v_mfma_f32_16x16x32_bf16 v[98:101], v[166:169], v[200:203], v[98:101]
	v_mfma_f32_16x16x32_bf16 v[46:49], v[64:67], v[208:211], v[46:49]
	v_mfma_f32_16x16x32_bf16 v[42:45], v[166:169], v[208:211], v[42:45]
	v_mfma_f32_16x16x32_bf16 v[38:41], v[64:67], v[216:219], v[38:41]
	v_mfma_f32_16x16x32_bf16 v[34:37], v[166:169], v[216:219], v[34:37]
	v_mfma_f32_16x16x32_bf16 v[68:71], v[170:173], v[196:199], v[70:73]
	v_mfma_f32_16x16x32_bf16 v[50:53], v[178:181], v[196:199], v[50:53]
	v_mfma_f32_16x16x32_bf16 v[30:33], v[170:173], v[204:207], v[30:33]
	v_mfma_f32_16x16x32_bf16 v[26:29], v[178:181], v[204:207], v[26:29]
	v_mfma_f32_16x16x32_bf16 v[22:25], v[170:173], v[212:215], v[22:25]
	v_mfma_f32_16x16x32_bf16 v[2:5], v[178:181], v[212:215], v[2:5]
	v_mfma_f32_16x16x32_bf16 v[60:63], v[170:173], v[188:191], v[94:97]
	v_mfma_f32_16x16x32_bf16 v[64:67], v[178:181], v[188:191], v[82:85]
	v_mfma_f32_16x16x32_bf16 v[68:71], v[174:177], v[200:203], v[68:71]
	v_mfma_f32_16x16x32_bf16 v[50:53], v[184:187], v[200:203], v[50:53]
	v_mfma_f32_16x16x32_bf16 v[30:33], v[174:177], v[208:211], v[30:33]
	v_mfma_f32_16x16x32_bf16 v[26:29], v[184:187], v[208:211], v[26:29]
	v_mfma_f32_16x16x32_bf16 v[22:25], v[174:177], v[216:219], v[22:25]
	v_mfma_f32_16x16x32_bf16 v[2:5], v[184:187], v[216:219], v[2:5]
	v_mfma_f32_16x16x32_bf16 v[60:63], v[174:177], v[192:195], v[60:63]
	v_mfma_f32_16x16x32_bf16 v[64:67], v[184:187], v[192:195], v[64:67]
	s_setprio 0
	s_barrier
	s_add_i32 s57, 0, 0x18000
	v_add_u32_e32 v72, s57, v58
	s_add_i32 s58, 0, 0x1c000
	ds_read_b128 v[82:85], v72
	ds_read_b128 v[94:97], v72 offset:1024
	ds_read_b128 v[162:165], v72 offset:2048
	ds_read_b128 v[166:169], v72 offset:3072
	v_add_u32_e32 v72, s58, v58
	ds_read_b128 v[170:173], v72
	ds_read_b128 v[174:177], v72 offset:1024
	ds_read_b128 v[178:181], v72 offset:2048
	ds_read_b128 v[184:187], v72 offset:3072
	s_add_u32 s24, s24, 0xb0000
	s_addc_u32 s25, s25, 0
	s_mov_b32 m0, s44
	ds_read_b128 v[188:191], v59 offset:32768
	ds_read_b128 v[192:195], v59 offset:33792
	ds_read_b128 v[196:199], v59 offset:34816
	ds_read_b128 v[200:203], v59 offset:35840
	ds_read_b128 v[204:207], v59 offset:36864
	ds_read_b128 v[208:211], v59 offset:37888
	ds_read_b128 v[212:215], v59 offset:38912
	ds_read_b128 v[216:219], v59 offset:39936
	global_load_lds_dwordx4 v6, s[24:25]
	s_mov_b32 m0, s45
	s_nop 0
	global_load_lds_dwordx4 v10, s[24:25]
	s_waitcnt vmcnt(8)
	s_waitcnt lgkmcnt(0)
	s_barrier
	s_setprio 1
	s_waitcnt lgkmcnt(0)
	v_mfma_f32_16x16x32_bf16 v[158:161], v[82:85], v[188:191], v[158:161]
	v_mfma_f32_16x16x32_bf16 v[146:149], v[162:165], v[188:191], v[146:149]
	v_mfma_f32_16x16x32_bf16 v[150:153], v[82:85], v[196:199], v[150:153]
	v_mfma_f32_16x16x32_bf16 v[154:157], v[162:165], v[196:199], v[154:157]
	v_mfma_f32_16x16x32_bf16 v[142:145], v[82:85], v[204:207], v[142:145]
	v_mfma_f32_16x16x32_bf16 v[138:141], v[162:165], v[204:207], v[138:141]
	v_mfma_f32_16x16x32_bf16 v[134:137], v[82:85], v[212:215], v[134:137]
	v_mfma_f32_16x16x32_bf16 v[130:133], v[162:165], v[212:215], v[130:133]
	v_mfma_f32_16x16x32_bf16 v[158:161], v[94:97], v[192:195], v[158:161]
	v_mfma_f32_16x16x32_bf16 v[146:149], v[166:169], v[192:195], v[146:149]
	v_mfma_f32_16x16x32_bf16 v[150:153], v[94:97], v[200:203], v[150:153]
	v_mfma_f32_16x16x32_bf16 v[154:157], v[166:169], v[200:203], v[154:157]
	v_mfma_f32_16x16x32_bf16 v[142:145], v[94:97], v[208:211], v[142:145]
	v_mfma_f32_16x16x32_bf16 v[138:141], v[166:169], v[208:211], v[138:141]
	v_mfma_f32_16x16x32_bf16 v[134:137], v[94:97], v[216:219], v[134:137]
	v_mfma_f32_16x16x32_bf16 v[130:133], v[166:169], v[216:219], v[130:133]
	v_mfma_f32_16x16x32_bf16 v[78:81], v[170:173], v[188:191], v[78:81]
	v_mfma_f32_16x16x32_bf16 v[72:75], v[178:181], v[188:191], v[74:77]
	v_mfma_f32_16x16x32_bf16 v[86:89], v[170:173], v[196:199], v[86:89]
	v_mfma_f32_16x16x32_bf16 v[90:93], v[178:181], v[196:199], v[90:93]
	v_mfma_f32_16x16x32_bf16 v[118:121], v[170:173], v[204:207], v[118:121]
	v_mfma_f32_16x16x32_bf16 v[114:117], v[178:181], v[204:207], v[114:117]
	v_mfma_f32_16x16x32_bf16 v[122:125], v[170:173], v[212:215], v[122:125]
	v_mfma_f32_16x16x32_bf16 v[126:129], v[178:181], v[212:215], v[126:129]
	v_mfma_f32_16x16x32_bf16 v[78:81], v[174:177], v[192:195], v[78:81]
	v_mfma_f32_16x16x32_bf16 v[74:77], v[184:187], v[192:195], v[72:75]
	v_mfma_f32_16x16x32_bf16 v[86:89], v[174:177], v[200:203], v[86:89]
	v_mfma_f32_16x16x32_bf16 v[90:93], v[184:187], v[200:203], v[90:93]
	v_mfma_f32_16x16x32_bf16 v[118:121], v[174:177], v[208:211], v[118:121]
	v_mfma_f32_16x16x32_bf16 v[114:117], v[184:187], v[208:211], v[114:117]
	v_mfma_f32_16x16x32_bf16 v[122:125], v[174:177], v[216:219], v[122:125]
	v_mfma_f32_16x16x32_bf16 v[126:129], v[184:187], v[216:219], v[126:129]
	s_setprio 0
	s_barrier
; #define PG8_STAGE(bufoff, gbase, voff) do { _Pragma("unroll") for (int _i = 0; _i < 2; ++_i) \
;         __builtin_amdgcn_global_load_lds((const unsigned*)((const char*)(gbase) + (voff)[_i]), (PG8_LAS unsigned*)(lds + (bufoff) + ldsw + _i * 8192), 16, 0, 0); } while (0)
; #define PG8_LDA(dst, b, h) do { _Pragma("unroll") for (int m = 0; m < 4; ++m) _Pragma("unroll") for (int k = 0; k < 2; ++k) dst[m][k] = *(const PG8_LAS bf16x8*)(lds + PG8_SA(b, h) + aoff + m * 2048 + k * 1024); } while (0)
; #define PG8_MMA(ai, bj, At, Bt) do { __builtin_amdgcn_s_setprio(1); _Pragma("unroll") for (int m = 0; m < 4; ++m) _Pragma("unroll") for (int n = 0; n < 2; ++n) _Pragma("unroll") for (int k = 0; k < 2; ++k) \
;         acc[ai][bj][m][n] = __builtin_amdgcn_mfma_f32_16x16x32_bf16(Bt[n][k], At[m][k], acc[ai][bj][m][n], 0, 0, 0); __builtin_amdgcn_s_setprio(0); } while (0)
; #define PG8_WAIT_V(n) asm volatile("s_waitcnt vmcnt(" #n ")" ::: "memory")
; #define PG8_WAIT_L(n) asm volatile("s_waitcnt lgkmcnt(" #n ")" ::: "memory")
; #define PG8_BAR __builtin_amdgcn_s_barrier()
; #define PG8_SCHED __builtin_amdgcn_sched_barrier(0)
; template <class Epi, class Sched, bool ALIGN_EPI = false, bool SP2 = false>
; __device__ __forceinline__ void gemm_phase(PG8_LAS unsigned char* lds, const Gemm g, const Sched& S, const Epi& E) {
;     ...
;         for (int t = 0; t < nt; t += 2) {
;     ...
;             PG8_LDA(At, 1, 1); PG8_STAGE(PG8_SB(1, 0), b3, voffB); PG8_STAGE(PG8_SB(1, 1), b3 + hstepB, voffB); PG8_STAGE(PG8_SA(1, 0), a3, voffA);
;             PG8_WAIT_V(8); PG8_WAIT_L(0); PG8_BAR; PG8_MMA(1, 0, At, B0); PG8_MMA(1, 1, At, B1); PG8_BAR; PG8_SCHED;
;     ...
;         if (!has_next) break;
; #pragma unroll
;         for (int a = 0; a < 2; ++a)
; #pragma unroll
;             for (int b = 0; b < 2; ++b)
; #pragma unroll
;                 for (int m = 0; m < 4; ++m)
; #pragma unroll
;                     for (int n = 0; n < 2; ++n) acc[a][b][m][n] = (f32x4){0.f, 0.f, 0.f, 0.f};
;         cur = nxt; cA = nA; cB = nB; ++ui;
	s_add_i32 s24, s57, s40
	s_mov_b32 m0, s24
	ds_read_b128 v[188:191], v59 offset:49152
	ds_read_b128 v[192:195], v59 offset:50176
	ds_read_b128 v[196:199], v59 offset:51200
	ds_read_b128 v[200:203], v59 offset:52224
	ds_read_b128 v[204:207], v59 offset:53248
	ds_read_b128 v[208:211], v59 offset:54272
	ds_read_b128 v[212:215], v59 offset:55296
	ds_read_b128 v[216:219], v59 offset:56320
	global_load_lds_dwordx4 v8, s[98:99]
	s_add_i32 m0, s24, 0x2000
	s_add_u32 s22, s22, 0xb0080
	s_addc_u32 s23, s23, 0
	s_add_i32 s24, s58, s40
	global_load_lds_dwordx4 v12, s[98:99]
	s_mov_b32 m0, s24
	s_nop 0
	global_load_lds_dwordx4 v8, s[22:23]
	s_add_i32 m0, s24, 0x2000
	s_nop 0
	global_load_lds_dwordx4 v12, s[22:23]
	s_mov_b32 m0, s47
	s_nop 0
	global_load_lds_dwordx4 v6, s[100:101]
	s_mov_b32 m0, s48
	s_nop 0
	global_load_lds_dwordx4 v10, s[100:101]
	s_waitcnt vmcnt(8)
	s_waitcnt lgkmcnt(0)
	s_barrier
	s_setprio 1
	s_waitcnt lgkmcnt(0)
	v_mfma_f32_16x16x32_bf16 v[110:113], v[82:85], v[188:191], v[110:113]
	v_mfma_f32_16x16x32_bf16 v[106:109], v[162:165], v[188:191], v[106:109]
	v_mfma_f32_16x16x32_bf16 v[102:105], v[82:85], v[196:199], v[102:105]
	v_mfma_f32_16x16x32_bf16 v[98:101], v[162:165], v[196:199], v[98:101]
	v_mfma_f32_16x16x32_bf16 v[46:49], v[82:85], v[204:207], v[46:49]
	v_mfma_f32_16x16x32_bf16 v[42:45], v[162:165], v[204:207], v[42:45]
	v_mfma_f32_16x16x32_bf16 v[38:41], v[82:85], v[212:215], v[38:41]
	v_mfma_f32_16x16x32_bf16 v[34:37], v[162:165], v[212:215], v[34:37]
	v_mfma_f32_16x16x32_bf16 v[110:113], v[94:97], v[192:195], v[110:113]
	v_mfma_f32_16x16x32_bf16 v[106:109], v[166:169], v[192:195], v[106:109]
	v_mfma_f32_16x16x32_bf16 v[102:105], v[94:97], v[200:203], v[102:105]
	v_mfma_f32_16x16x32_bf16 v[98:101], v[166:169], v[200:203], v[98:101]
	v_mfma_f32_16x16x32_bf16 v[46:49], v[94:97], v[208:211], v[46:49]
	v_mfma_f32_16x16x32_bf16 v[42:45], v[166:169], v[208:211], v[42:45]
	v_mfma_f32_16x16x32_bf16 v[38:41], v[94:97], v[216:219], v[38:41]
	v_mfma_f32_16x16x32_bf16 v[34:37], v[166:169], v[216:219], v[34:37]
	v_mfma_f32_16x16x32_bf16 v[60:63], v[170:173], v[188:191], v[60:63]
	v_mfma_f32_16x16x32_bf16 v[94:97], v[174:177], v[192:195], v[60:63]
	v_mfma_f32_16x16x32_bf16 v[60:63], v[178:181], v[188:191], v[64:67]
	v_mfma_f32_16x16x32_bf16 v[82:85], v[184:187], v[192:195], v[60:63]
	v_mfma_f32_16x16x32_bf16 v[60:63], v[170:173], v[196:199], v[68:71]
	v_mfma_f32_16x16x32_bf16 v[50:53], v[178:181], v[196:199], v[50:53]
	v_mfma_f32_16x16x32_bf16 v[30:33], v[170:173], v[204:207], v[30:33]
	v_mfma_f32_16x16x32_bf16 v[26:29], v[178:181], v[204:207], v[26:29]
	v_mfma_f32_16x16x32_bf16 v[22:25], v[170:173], v[212:215], v[22:25]
	v_mfma_f32_16x16x32_bf16 v[2:5], v[178:181], v[212:215], v[2:5]
	v_mfma_f32_16x16x32_bf16 v[70:73], v[174:177], v[200:203], v[60:63]
	v_mfma_f32_16x16x32_bf16 v[50:53], v[184:187], v[200:203], v[50:53]
	v_mfma_f32_16x16x32_bf16 v[30:33], v[174:177], v[208:211], v[30:33]
	v_mfma_f32_16x16x32_bf16 v[26:29], v[184:187], v[208:211], v[26:29]
	v_mfma_f32_16x16x32_bf16 v[22:25], v[174:177], v[216:219], v[22:25]
	v_mfma_f32_16x16x32_bf16 v[2:5], v[184:187], v[216:219], v[2:5]
	s_setprio 0
	s_barrier
	s_add_i32 s56, s56, 2
	s_add_u32 s20, s20, 0x100
	s_addc_u32 s21, s21, 0
	s_cmp_gt_u32 s56, 41
	s_cbranch_scc0 .LBB0_2807
	s_add_u32 s20, s54, 0xffffff00
	s_addc_u32 s21, s55, -1
	s_and_b64 vcc, exec, s[4:5]
	s_cbranch_vccnz .LBB0_2794
	v_mov_b32_e32 v2, 0
	s_mov_b32 s12, s51
	s_mov_b32 s27, s52
	s_mov_b64 s[14:15], s[18:19]
	s_mov_b32 s46, s53
	v_mov_b32_e32 v3, v2
	v_mov_b32_e32 v4, v2
	v_mov_b32_e32 v5, v2
	v_mov_b32_e32 v22, v2
	v_mov_b32_e32 v23, v2
	v_mov_b32_e32 v24, v2
	v_mov_b32_e32 v25, v2
	v_mov_b32_e32 v26, v2
	v_mov_b32_e32 v27, v2
	v_mov_b32_e32 v28, v2
	v_mov_b32_e32 v29, v2
	v_mov_b32_e32 v30, v2
	v_mov_b32_e32 v31, v2
	v_mov_b32_e32 v32, v2
	v_mov_b32_e32 v33, v2
	v_mov_b32_e32 v50, v2
	v_mov_b32_e32 v51, v2
	v_mov_b32_e32 v52, v2
	v_mov_b32_e32 v53, v2
	v_mov_b32_e32 v70, v2
	v_mov_b32_e32 v71, v2
	v_mov_b32_e32 v72, v2
	v_mov_b32_e32 v73, v2
	v_mov_b32_e32 v82, v2
	v_mov_b32_e32 v83, v2
	v_mov_b32_e32 v84, v2
	v_mov_b32_e32 v85, v2
	v_mov_b32_e32 v94, v2
	v_mov_b32_e32 v95, v2
	v_mov_b32_e32 v96, v2
	v_mov_b32_e32 v97, v2
	v_mov_b32_e32 v34, v2
	v_mov_b32_e32 v35, v2
	v_mov_b32_e32 v36, v2
	v_mov_b32_e32 v37, v2
	v_mov_b32_e32 v38, v2
	v_mov_b32_e32 v39, v2
	v_mov_b32_e32 v40, v2
	v_mov_b32_e32 v41, v2
	v_mov_b32_e32 v42, v2
	v_mov_b32_e32 v43, v2
	v_mov_b32_e32 v44, v2
	v_mov_b32_e32 v45, v2
	v_mov_b32_e32 v46, v2
	v_mov_b32_e32 v47, v2
	v_mov_b32_e32 v48, v2
	v_mov_b32_e32 v49, v2
	v_mov_b32_e32 v98, v2
	v_mov_b32_e32 v99, v2
	v_mov_b32_e32 v100, v2
	v_mov_b32_e32 v101, v2
	v_mov_b32_e32 v102, v2
	v_mov_b32_e32 v103, v2
	v_mov_b32_e32 v104, v2
	v_mov_b32_e32 v105, v2
	v_mov_b32_e32 v106, v2
	v_mov_b32_e32 v107, v2
	v_mov_b32_e32 v108, v2
	v_mov_b32_e32 v109, v2
	v_mov_b32_e32 v110, v2
	v_mov_b32_e32 v111, v2
	v_mov_b32_e32 v112, v2
	v_mov_b32_e32 v113, v2
	v_mov_b32_e32 v126, v2
	v_mov_b32_e32 v127, v2
	v_mov_b32_e32 v128, v2
	v_mov_b32_e32 v129, v2
	v_mov_b32_e32 v122, v2
	v_mov_b32_e32 v123, v2
	v_mov_b32_e32 v124, v2
	v_mov_b32_e32 v125, v2
	v_mov_b32_e32 v114, v2
	v_mov_b32_e32 v115, v2
	v_mov_b32_e32 v116, v2
	v_mov_b32_e32 v117, v2
	v_mov_b32_e32 v118, v2
	v_mov_b32_e32 v119, v2
	v_mov_b32_e32 v120, v2
	v_mov_b32_e32 v121, v2
	v_mov_b32_e32 v90, v2
	v_mov_b32_e32 v91, v2
	v_mov_b32_e32 v92, v2
	v_mov_b32_e32 v93, v2
	v_mov_b32_e32 v86, v2
	v_mov_b32_e32 v87, v2
	v_mov_b32_e32 v88, v2
	v_mov_b32_e32 v89, v2
	v_mov_b32_e32 v74, v2
	v_mov_b32_e32 v75, v2
	v_mov_b32_e32 v76, v2
	v_mov_b32_e32 v77, v2
	v_mov_b32_e32 v78, v2
	v_mov_b32_e32 v79, v2
	v_mov_b32_e32 v80, v2
	v_mov_b32_e32 v81, v2
	v_mov_b32_e32 v130, v2
	v_mov_b32_e32 v131, v2
	v_mov_b32_e32 v132, v2
	v_mov_b32_e32 v133, v2
	v_mov_b32_e32 v134, v2
	v_mov_b32_e32 v135, v2
	v_mov_b32_e32 v136, v2
	v_mov_b32_e32 v137, v2
	v_mov_b32_e32 v138, v2
	v_mov_b32_e32 v139, v2
	v_mov_b32_e32 v140, v2
	v_mov_b32_e32 v141, v2
	v_mov_b32_e32 v142, v2
	v_mov_b32_e32 v143, v2
	v_mov_b32_e32 v144, v2
	v_mov_b32_e32 v145, v2
	v_mov_b32_e32 v154, v2
	v_mov_b32_e32 v155, v2
	v_mov_b32_e32 v156, v2
	v_mov_b32_e32 v157, v2
	v_mov_b32_e32 v150, v2
	v_mov_b32_e32 v151, v2
	v_mov_b32_e32 v152, v2
	v_mov_b32_e32 v153, v2
	v_mov_b32_e32 v146, v2
	v_mov_b32_e32 v147, v2
	v_mov_b32_e32 v148, v2
	v_mov_b32_e32 v149, v2
	v_mov_b32_e32 v158, v2
	v_mov_b32_e32 v159, v2
	v_mov_b32_e32 v160, v2
	v_mov_b32_e32 v161, v2
	s_andn2_b64 vcc, exec, s[2:3]
	s_cbranch_vccnz .LBB0_2795
